# HNAQP2S + nt hint on the Hn (next-norm operand) stores of the residual epilogues
# baseline (speedup 1.0000x reference)
; #define LAS __attribute__((address_space(3)))
; #define ERN_EOFF(q, m) (eb + (unsigned)((((q) & 1) * HALF + (m) * 16) * DM + ERN_COL((q) >> 1)))
;     __device__ __forceinline__ void operator()(const f32x4 (&acc)[2][2][4][2], const Unit& u, int wr, int wc, int fr, int fq) const {
;         const int s = u.pm >> 5, lane = fq * 16 + fr, rr = lane >> 3, pc = lane & 7;
;         const float* __restrict__ xi = xin + (size_t)u.pm * BM * DM; float* __restrict__ xo = xout + (size_t)u.pm * BM * DM; bf16_t* __restrict__ ho = Hn + (size_t)u.pm * BM * DM;
;         LAS unsigned char* st = lds_epi + (wr * 4 + wc) * 2304;
;         LAS float* sst = (LAS float*)(lds_epi + 18432 + (wr * 4 + wc) * 512);
;         const int colr = u.pn * BM + wc * 64 + 4 * pc;
;         const unsigned eb = (unsigned)((wr * 64 + rr) * DM + colr);
;         f32x4 gv[2], gsn[2];
; #pragma unroll
;         for (int bj = 0; bj < 2; ++bj) { gv[bj] = *(const f32x4*)(gate + (size_t)s * MODW + colr + bj * 32) * (0.5f * GS2);
;             if (!PLAIN) gsn[bj] = *(const f32x4*)(gnext + colr + bj * 32) * (*(const f32x4*)(scnext + (size_t)s * MODW + colr + bj * 32) + 1.0f); else gsn[bj] = gv[bj]; }
;         const unsigned wr_off = (unsigned)(fr * 144 + 16 * fq), rd_off = (unsigned)(rr * 144 + pc * 16);
;         const bool odd = (rr & 1) != 0;
;         f32x4 xb[2][2][2];
;     ...
;         ERN_LOADX(0);
; #pragma unroll
;         for (int g = 0; g < 8; ++g) { const int ai = g >> 2, m = g & 3;
;             if (g + 1 < 8) ERN_LOADX(g + 1);
;             float sq0 = 0.f, sq1 = 0.f; u32x2 hw[2][2];
; #pragma unroll
;             for (int bj = 0; bj < 2; ++bj) {
;                 *(LAS f32x4*)(st + wr_off) = acc[ai][bj][m][0]; *(LAS f32x4*)(st + wr_off + 64) = acc[ai][bj][m][1];
;                 const f32x4 a0 = *(const LAS f32x4*)(st + rd_off), a1 = *(const LAS f32x4*)(st + rd_off + 8 * 144);
;                 { const f32x4 xv = xb[g & 1][bj][0] + gv[bj] * a0; __builtin_nontemporal_store(xv, (f32x4*)((char*)xo + 4u * ERN_EOFF(g, bj, 0)));
;                   sq0 += (xv.x * xv.x + xv.y * xv.y) + (xv.z * xv.z + xv.w * xv.w);
;                   const f32x4 hv = xv * gsn[bj]; hw[bj][0].x = cvt_pk_bf16(hv.x, hv.y); hw[bj][0].y = cvt_pk_bf16(hv.z, hv.w); }
;                 { const f32x4 xv = xb[g & 1][bj][1] + gv[bj] * a1; __builtin_nontemporal_store(xv, (f32x4*)((char*)xo + 4u * ERN_EOFF(g, bj, 1)));
.LBB0_320:
	s_ashr_i32 s12, s4, 5
	s_ashr_i32 s5, s4, 31
	v_lshl_or_b32 v130, s0, 8, v192
	s_mul_i32 s14, s12, 0x12000
	s_mul_hi_i32 s0, s12, 0x12000
	s_add_u32 s12, s35, s14
	v_ashrrev_i32_e32 v131, 31, v130
	s_addc_u32 s13, s36, s0
	v_lshlrev_b64 v[132:133], 2, v[130:131]
	v_lshl_add_u64 v[134:135], s[12:13], 0, v[132:133]
	s_add_u32 s12, s37, s14
	s_addc_u32 s13, s60, s0
	v_lshl_add_u64 v[136:137], s[46:47], 0, v[132:133]
	v_lshl_add_u64 v[132:133], s[12:13], 0, v[132:133]
	s_lshl_b64 s[54:55], s[4:5], 21
	v_readlane_b32 s12, v253, 2
	v_readlane_b32 s13, v253, 3
	s_add_u32 s58, s12, s54
	v_add_u32_e32 v202, v130, v193
	s_addc_u32 s59, s13, s55
	v_lshlrev_b32_e32 v207, 2, v202
	global_load_dwordx4 v[170:173], v[136:137], off
	global_load_dwordx4 v[166:169], v[134:135], off
	global_load_dwordx4 v[174:177], v[134:135], off offset:128
	global_load_dwordx4 v[186:189], v[132:133], off
	global_load_dwordx4 v[208:211], v[132:133], off offset:128
	global_load_dwordx4 v[212:215], v207, s[58:59]
	v_add_u32_e32 v130, 0x10000, v207
	global_load_dwordx4 v[216:219], v130, s[58:59]
	global_load_dwordx4 v[220:223], v[136:137], off offset:128
	global_load_dwordx4 v[224:227], v207, s[58:59] offset:128
	v_add_u32_e32 v206, 0x10080, v207
	v_add_u32_e32 v130, 0x20000, v207
	global_load_dwordx4 v[228:231], v206, s[58:59]
	v_add_u32_e32 v154, 0x30000, v207
	v_add_u32_e32 v184, 0x20080, v207
	v_add_u32_e32 v182, 0x30080, v207
	global_load_dwordx4 v[142:145], v130, s[58:59]
	global_load_dwordx4 v[138:141], v154, s[58:59]
	global_load_dwordx4 v[134:137], v184, s[58:59]
	s_nop 0
	global_load_dwordx4 v[130:133], v182, s[58:59]
	ds_write_b128 v200, v[126:129]
	ds_write_b128 v200, v[122:125] offset:64
	v_and_b32_e32 v127, 64, v199
	ds_read_b128 v[122:125], v201
	ds_read_b128 v[232:235], v201 offset:1152
	v_xor_b32_e32 v126, 8, v199
	v_add_u32_e32 v183, 64, v127
	v_cmp_lt_i32_e32 vcc, v126, v183
	v_add_u32_e32 v185, 0x4000, v202
	s_add_u32 s56, s90, s54
	v_cndmask_b32_e32 v126, v199, v126, vcc
	v_lshlrev_b32_e32 v203, 2, v126
	v_lshlrev_b32_e32 v236, 2, v185
	s_addc_u32 s57, s91, s55
	s_lshl_b64 s[12:13], s[4:5], 20
	s_add_u32 s54, s93, s12
	v_readlane_b32 s16, v253, 6
	v_readlane_b32 s17, v253, 7
	s_addc_u32 s55, s92, s13
	v_readlane_b32 s14, v253, 4
	v_readlane_b32 s15, v253, 5
	v_readlane_b32 s18, v253, 8
	v_readlane_b32 s19, v253, 9
	v_readlane_b32 s20, v253, 10
	v_readlane_b32 s21, v253, 11
	v_readlane_b32 s22, v253, 12
	v_readlane_b32 s23, v253, 13
	v_readlane_b32 s24, v253, 14
	v_readlane_b32 s25, v253, 15
	v_readlane_b32 s26, v253, 16
	v_readlane_b32 s27, v253, 17
	s_waitcnt vmcnt(0)
	v_pk_mul_f32 v[180:181], v[166:167], 0.5 op_sel_hi:[1,0]
	v_pk_mul_f32 v[178:179], v[168:169], 0.5 op_sel_hi:[1,0]
	v_pk_add_f32 v[126:127], v[188:189], 1.0 op_sel_hi:[1,0]
	v_pk_add_f32 v[128:129], v[186:187], 1.0 op_sel_hi:[1,0]
	v_pk_mul_f32 v[166:167], v[176:177], 0.5 op_sel_hi:[1,0]
	v_pk_mul_f32 v[168:169], v[174:175], 0.5 op_sel_hi:[1,0]
	v_pk_mul_f32 v[174:175], v[172:173], v[126:127]
	v_pk_mul_f32 v[176:177], v[170:171], v[128:129]
	s_waitcnt lgkmcnt(1)
	v_pk_fma_f32 v[126:127], v[180:181], v[122:123], v[212:213]
	s_waitcnt lgkmcnt(0)
	v_pk_fma_f32 v[122:123], v[180:181], v[232:233], v[216:217]
	v_pk_fma_f32 v[128:129], v[178:179], v[124:125], v[214:215]
	v_pk_fma_f32 v[124:125], v[178:179], v[234:235], v[218:219]
	v_pk_mul_f32 v[186:187], v[176:177], v[122:123]
	global_store_dwordx4 v207, v[126:129], s[56:57] nt
	v_pk_mul_f32 v[170:171], v[174:175], v[128:129]
	v_pk_mul_f32 v[172:173], v[176:177], v[126:127]
	v_pk_mul_f32 v[204:205], v[174:175], v[124:125]
	v_cvt_pk_bf16_f32 v188, v172, v173
	v_cvt_pk_bf16_f32 v189, v170, v171
	global_store_dwordx4 v236, v[122:125], s[56:57] nt
	v_cvt_pk_bf16_f32 v186, v186, v187
	v_cvt_pk_bf16_f32 v187, v204, v205
	ds_write_b128 v200, v[118:121]
	ds_write_b128 v200, v[114:117] offset:64
	ds_read_b128 v[114:117], v201
	v_pk_add_f32 v[190:191], v[210:211], 1.0 op_sel_hi:[1,0]
	v_pk_add_f32 v[118:119], v[208:209], 1.0 op_sel_hi:[1,0]
	ds_read_b128 v[208:211], v201 offset:1152
	v_pk_mul_f32 v[170:171], v[222:223], v[190:191]
	v_pk_mul_f32 v[172:173], v[220:221], v[118:119]
	s_waitcnt lgkmcnt(1)
	v_pk_fma_f32 v[120:121], v[166:167], v[116:117], v[226:227]
	v_pk_fma_f32 v[118:119], v[168:169], v[114:115], v[224:225]
	v_pk_mul_f32 v[190:191], v[170:171], v[120:121]
	v_pk_mul_f32 v[204:205], v[172:173], v[118:119]
	global_store_dwordx4 v207, v[118:121], s[56:57] offset:128 nt
	v_cvt_pk_bf16_f32 v204, v204, v205
	v_cvt_pk_bf16_f32 v191, v190, v191
	ds_bpermute_b32 v190, v203, v204
	ds_bpermute_b32 v191, v203, v191
	s_waitcnt lgkmcnt(2)
	v_pk_fma_f32 v[116:117], v[166:167], v[210:211], v[230:231]
	v_pk_fma_f32 v[114:115], v[168:169], v[208:209], v[228:229]
	global_store_dwordx4 v206, v[114:117], s[56:57] nt
	v_pk_mul_f32 v[204:205], v[172:173], v[114:115]
	v_lshlrev_b32_e32 v206, 1, v202
	v_pk_mul_f32 v[208:209], v[170:171], v[116:117]
	v_cvt_pk_bf16_f32 v204, v204, v205
	s_nop 0
	v_cvt_pk_bf16_f32 v205, v208, v209
	s_waitcnt lgkmcnt(0)
	v_add_u32_e32 v250, 0xfffff040, v206
	v_cndmask_b32_e64 v250, v206, v250, s[40:41]
	v_cndmask_b32_e64 v248, v188, v190, s[40:41]
	v_cndmask_b32_e64 v249, v189, v191, s[40:41]
	global_store_dwordx2 v250, v[248:249], s[54:55] nt
	v_cndmask_b32_e64 v246, v190, v188, s[40:41]
	v_cndmask_b32_e64 v247, v191, v189, s[40:41]
	s_waitcnt lgkmcnt(1)
	v_add_u32_e32 v190, 0x1040, v206
	v_cndmask_b32_e64 v190, v206, v190, s[38:39]
	global_store_dwordx2 v190, v[246:247], s[54:55] nt
	ds_bpermute_b32 v188, v203, v204
	ds_bpermute_b32 v189, v203, v205
	v_lshlrev_b32_e32 v190, 1, v185
	s_waitcnt lgkmcnt(0)
; #define LAS __attribute__((address_space(3)))
; #define ERN_EOFF(q, m) (eb + (unsigned)((((q) & 1) * HALF + (m) * 16) * DM + ERN_COL((q) >> 1)))
;     __device__ __forceinline__ void operator()(const f32x4 (&acc)[2][2][4][2], const Unit& u, int wr, int wc, int fr, int fq) const {
;     ...
;         for (int g = 0; g < 8; ++g) { const int ai = g >> 2, m = g & 3;
;             if (g + 1 < 8) ERN_LOADX(g + 1);
;             float sq0 = 0.f, sq1 = 0.f; u32x2 hw[2][2];
; #pragma unroll
;             for (int bj = 0; bj < 2; ++bj) {
;                 *(LAS f32x4*)(st + wr_off) = acc[ai][bj][m][0]; *(LAS f32x4*)(st + wr_off + 64) = acc[ai][bj][m][1];
;                 const f32x4 a0 = *(const LAS f32x4*)(st + rd_off), a1 = *(const LAS f32x4*)(st + rd_off + 8 * 144);
;                 { const f32x4 xv = xb[g & 1][bj][0] + gv[bj] * a0; __builtin_nontemporal_store(xv, (f32x4*)((char*)xo + 4u * ERN_EOFF(g, bj, 0)));
;                   sq0 += (xv.x * xv.x + xv.y * xv.y) + (xv.z * xv.z + xv.w * xv.w);
;                   const f32x4 hv = xv * gsn[bj]; hw[bj][0].x = cvt_pk_bf16(hv.x, hv.y); hw[bj][0].y = cvt_pk_bf16(hv.z, hv.w); }
;                 { const f32x4 xv = xb[g & 1][bj][1] + gv[bj] * a1; __builtin_nontemporal_store(xv, (f32x4*)((char*)xo + 4u * ERN_EOFF(g, bj, 1)));
;                   sq1 += (xv.x * xv.x + xv.y * xv.y) + (xv.z * xv.z + xv.w * xv.w);
;                   const f32x4 hv = xv * gsn[bj]; hw[bj][1].x = cvt_pk_bf16(hv.x, hv.y); hw[bj][1].y = cvt_pk_bf16(hv.z, hv.w); }
;             }
;             if (!NOH && !PLAIN) {
; #pragma unroll
;                 for (int rh = 0; rh < 2; ++rh) { u32x2 rv; rv.x = __shfl_xor(hw[1][rh].x, 8); rv.y = __shfl_xor(hw[1][rh].y, 8);
;                     const unsigned e0 = ERN_EOFF(g, 0, rh);
;                     const unsigned ee = odd ? (e0 - DM + 32) : e0, eo2 = odd ? e0 : (e0 + DM + 32);
;                     *(u32x2*)((char*)ho + 2u * ee) = odd ? rv : hw[0][rh];
;                     *(u32x2*)((char*)ho + 2u * eo2) = odd ? hw[0][rh] : rv; }
;             }
;             if (!PLAIN) { sq0 += __shfl_xor(sq0, 1); sq0 += __shfl_xor(sq0, 2); sq0 += __shfl_xor(sq0, 4);
;             sq1 += __shfl_xor(sq1, 1); sq1 += __shfl_xor(sq1, 2); sq1 += __shfl_xor(sq1, 4); }
;             if (!PLAIN && pc == 0) { sst[g * 16 + rr] = sq0; sst[g * 16 + 8 + rr] = sq1; }
	v_add_u32_e32 v250, 0xfffff040, v190
	v_cndmask_b32_e64 v250, v190, v250, s[40:41]
	v_cndmask_b32_e64 v248, v186, v188, s[40:41]
	v_cndmask_b32_e64 v249, v187, v189, s[40:41]
	global_store_dwordx2 v250, v[248:249], s[54:55] nt
	v_cndmask_b32_e64 v246, v188, v186, s[40:41]
	v_cndmask_b32_e64 v247, v189, v187, s[40:41]
	v_mul_f32_e32 v119, v119, v119
	v_mul_f32_e32 v127, v127, v127
	v_mul_f32_e32 v129, v129, v129
	v_fmac_f32_e32 v119, v118, v118
	v_mul_f32_e32 v118, v121, v121
	v_fmac_f32_e32 v129, v128, v128
	v_fmac_f32_e32 v118, v120, v120
	v_mul_f32_e32 v115, v115, v115
	v_fmac_f32_e32 v127, v126, v126
	v_add_f32_e32 v118, v119, v118
	v_fmac_f32_e32 v115, v114, v114
	v_mul_f32_e32 v114, v117, v117
	v_add_f32_e32 v117, v127, v129
	v_add_f32_e32 v117, v117, v118
	v_xor_b32_e32 v118, 1, v199
	v_cmp_lt_i32_e32 vcc, v118, v183
	v_mul_f32_e32 v123, v123, v123
	v_mul_f32_e32 v125, v125, v125
	v_cndmask_b32_e32 v118, v199, v118, vcc
	v_lshlrev_b32_e32 v204, 2, v118
	ds_bpermute_b32 v118, v204, v117
	v_fmac_f32_e32 v114, v116, v116
	v_fmac_f32_e32 v125, v124, v124
	v_fmac_f32_e32 v123, v122, v122
	v_add_f32_e32 v114, v115, v114
	s_waitcnt lgkmcnt(0)
	v_add_f32_e32 v116, v117, v118
	v_xor_b32_e32 v117, 2, v199
	v_cmp_lt_i32_e32 vcc, v117, v183
	v_add_f32_e32 v115, v123, v125
	v_add_f32_e32 v115, v115, v114
	v_cndmask_b32_e32 v117, v199, v117, vcc
	v_lshlrev_b32_e32 v205, 2, v117
	ds_bpermute_b32 v117, v205, v116
	ds_bpermute_b32 v118, v204, v115
	s_waitcnt lgkmcnt(1)
	v_add_f32_e32 v114, v116, v117
	s_waitcnt lgkmcnt(0)
	v_add_f32_e32 v117, v115, v118
	ds_bpermute_b32 v118, v205, v117
	v_xor_b32_e32 v116, 4, v199
	v_cmp_lt_i32_e32 vcc, v116, v183
	s_nop 1
	v_cndmask_b32_e32 v115, v199, v116, vcc
	v_lshlrev_b32_e32 v206, 2, v115
	s_waitcnt lgkmcnt(0)
	v_add_f32_e32 v116, v117, v118
	ds_bpermute_b32 v115, v206, v114
	ds_bpermute_b32 v117, v206, v116
	v_add_u32_e32 v118, 0x1040, v190
	v_cndmask_b32_e64 v118, v190, v118, s[38:39]
	global_store_dwordx2 v118, v[246:247], s[54:55] nt
	s_and_saveexec_b64 s[16:17], s[42:43]
	s_cbranch_execz .LBB0_330
	s_waitcnt lgkmcnt(1)
	v_add_f32_e32 v114, v114, v115
	s_waitcnt lgkmcnt(0)
	v_add_f32_e32 v115, v116, v117
	ds_write2_b32 v194, v114, v115 offset1:8
.LBB0_330:
	s_or_b64 exec, exec, s[16:17]
	v_add_u32_e32 v114, 0x40000, v207
	v_add_u32_e32 v190, 0x50000, v207
	v_add_u32_e32 v188, 0x40080, v207
	global_load_dwordx4 v[122:125], v190, s[58:59]
	global_load_dwordx4 v[118:121], v188, s[58:59]
	v_add_u32_e32 v186, 0x50080, v207
	global_load_dwordx4 v[126:129], v114, s[58:59]
	s_waitcnt lgkmcnt(0)
	global_load_dwordx4 v[114:117], v186, s[58:59]
	ds_write_b128 v200, v[110:113]
	ds_write_b128 v200, v[106:109] offset:64
	ds_read_b128 v[106:109], v201
	ds_read_b128 v[110:113], v201 offset:1152
	v_mov_b32_e32 v185, v155
	v_mov_b32_e32 v183, v155
	s_waitcnt lgkmcnt(1)
	v_pk_fma_f32 v[108:109], v[178:179], v[108:109], v[144:145]
	v_add_u32_e32 v144, 0x8000, v202
	v_pk_fma_f32 v[106:107], v[180:181], v[106:107], v[142:143]
	v_lshlrev_b32_e32 v142, 2, v144
	global_store_dwordx4 v142, v[106:109], s[56:57] nt
	v_pk_mul_f32 v[142:143], v[176:177], v[106:107]
	s_waitcnt lgkmcnt(0)
	v_pk_fma_f32 v[112:113], v[178:179], v[112:113], v[140:141]
	v_pk_fma_f32 v[110:111], v[180:181], v[110:111], v[138:139]
	v_lshl_add_u64 v[138:139], s[56:57], 0, v[154:155]
	v_pk_mul_f32 v[208:209], v[174:175], v[108:109]
	v_cvt_pk_bf16_f32 v142, v142, v143
	v_pk_mul_f32 v[140:141], v[174:175], v[112:113]
	v_cvt_pk_bf16_f32 v143, v208, v209
	global_store_dwordx4 v[138:139], v[110:113], off nt
	v_pk_mul_f32 v[138:139], v[176:177], v[110:111]
	s_nop 0
	v_cvt_pk_bf16_f32 v138, v138, v139
	v_cvt_pk_bf16_f32 v139, v140, v141
	ds_write_b128 v200, v[102:105]
	ds_write_b128 v200, v[98:101] offset:64
	ds_read_b128 v[98:101], v201
	ds_read_b128 v[102:105], v201 offset:1152
	s_waitcnt lgkmcnt(1)
	v_pk_fma_f32 v[98:99], v[168:169], v[98:99], v[134:135]
	v_pk_fma_f32 v[100:101], v[166:167], v[100:101], v[136:137]
	v_lshl_add_u64 v[134:135], s[56:57], 0, v[184:185]
	v_pk_mul_f32 v[136:137], v[172:173], v[98:99]
	s_waitcnt lgkmcnt(0)
	v_pk_fma_f32 v[104:105], v[166:167], v[104:105], v[132:133]
	v_pk_fma_f32 v[102:103], v[168:169], v[102:103], v[130:131]
	v_lshl_add_u64 v[130:131], s[56:57], 0, v[182:183]
	global_store_dwordx4 v[134:135], v[98:101], off nt
	v_pk_mul_f32 v[134:135], v[170:171], v[100:101]
	v_cvt_pk_bf16_f32 v136, v136, v137
	v_pk_mul_f32 v[132:133], v[172:173], v[102:103]
	v_cvt_pk_bf16_f32 v137, v134, v135
	global_store_dwordx4 v[130:131], v[102:105], off nt
	ds_bpermute_b32 v130, v203, v136
	ds_bpermute_b32 v131, v203, v137
	v_pk_mul_f32 v[134:135], v[170:171], v[104:105]
	v_cvt_pk_bf16_f32 v132, v132, v133
	s_nop 0
	v_cvt_pk_bf16_f32 v133, v134, v135
	v_lshlrev_b32_e32 v134, 1, v144
	s_waitcnt lgkmcnt(0)
	v_add_u32_e32 v250, 0xfffff040, v134
	v_cndmask_b32_e64 v250, v134, v250, s[40:41]
	v_cndmask_b32_e64 v248, v142, v130, s[40:41]
	v_cndmask_b32_e64 v249, v143, v131, s[40:41]
	global_store_dwordx2 v250, v[248:249], s[54:55] nt
	v_cndmask_b32_e64 v246, v130, v142, s[40:41]
	v_cndmask_b32_e64 v247, v131, v143, s[40:41]
	s_waitcnt lgkmcnt(1)
	v_add_u32_e32 v130, 0x1040, v134
	v_cndmask_b32_e64 v130, v134, v130, s[38:39]
	global_store_dwordx2 v130, v[246:247], s[54:55] nt
	ds_bpermute_b32 v130, v203, v132
	s_waitcnt lgkmcnt(1)
	ds_bpermute_b32 v131, v203, v133
	v_add_u32_e32 v133, 0xc000, v202
	v_lshlrev_b32_e32 v132, 1, v133
	s_waitcnt lgkmcnt(0)
; #define LAS __attribute__((address_space(3)))
; #define ERN_EOFF(q, m) (eb + (unsigned)((((q) & 1) * HALF + (m) * 16) * DM + ERN_COL((q) >> 1)))
;     __device__ __forceinline__ void operator()(const f32x4 (&acc)[2][2][4][2], const Unit& u, int wr, int wc, int fr, int fq) const {
;     ...
;         for (int g = 0; g < 8; ++g) { const int ai = g >> 2, m = g & 3;
;             if (g + 1 < 8) ERN_LOADX(g + 1);
;             float sq0 = 0.f, sq1 = 0.f; u32x2 hw[2][2];
; #pragma unroll
;             for (int bj = 0; bj < 2; ++bj) {
;                 *(LAS f32x4*)(st + wr_off) = acc[ai][bj][m][0]; *(LAS f32x4*)(st + wr_off + 64) = acc[ai][bj][m][1];
;                 const f32x4 a0 = *(const LAS f32x4*)(st + rd_off), a1 = *(const LAS f32x4*)(st + rd_off + 8 * 144);
;                 { const f32x4 xv = xb[g & 1][bj][0] + gv[bj] * a0; __builtin_nontemporal_store(xv, (f32x4*)((char*)xo + 4u * ERN_EOFF(g, bj, 0)));
;                   sq0 += (xv.x * xv.x + xv.y * xv.y) + (xv.z * xv.z + xv.w * xv.w);
;                   const f32x4 hv = xv * gsn[bj]; hw[bj][0].x = cvt_pk_bf16(hv.x, hv.y); hw[bj][0].y = cvt_pk_bf16(hv.z, hv.w); }
;                 { const f32x4 xv = xb[g & 1][bj][1] + gv[bj] * a1; __builtin_nontemporal_store(xv, (f32x4*)((char*)xo + 4u * ERN_EOFF(g, bj, 1)));
;                   sq1 += (xv.x * xv.x + xv.y * xv.y) + (xv.z * xv.z + xv.w * xv.w);
;                   const f32x4 hv = xv * gsn[bj]; hw[bj][1].x = cvt_pk_bf16(hv.x, hv.y); hw[bj][1].y = cvt_pk_bf16(hv.z, hv.w); }
;             }
;             if (!NOH && !PLAIN) {
; #pragma unroll
;                 for (int rh = 0; rh < 2; ++rh) { u32x2 rv; rv.x = __shfl_xor(hw[1][rh].x, 8); rv.y = __shfl_xor(hw[1][rh].y, 8);
;                     const unsigned e0 = ERN_EOFF(g, 0, rh);
;                     const unsigned ee = odd ? (e0 - DM + 32) : e0, eo2 = odd ? e0 : (e0 + DM + 32);
;                     *(u32x2*)((char*)ho + 2u * ee) = odd ? rv : hw[0][rh];
;                     *(u32x2*)((char*)ho + 2u * eo2) = odd ? hw[0][rh] : rv; }
;             }
;             if (!PLAIN) { sq0 += __shfl_xor(sq0, 1); sq0 += __shfl_xor(sq0, 2); sq0 += __shfl_xor(sq0, 4);
;             sq1 += __shfl_xor(sq1, 1); sq1 += __shfl_xor(sq1, 2); sq1 += __shfl_xor(sq1, 4); }
;             if (!PLAIN && pc == 0) { sst[g * 16 + rr] = sq0; sst[g * 16 + 8 + rr] = sq1; }
	v_add_u32_e32 v250, 0xfffff040, v132
	v_cndmask_b32_e64 v250, v132, v250, s[40:41]
	v_cndmask_b32_e64 v248, v138, v130, s[40:41]
	v_cndmask_b32_e64 v249, v139, v131, s[40:41]
	global_store_dwordx2 v250, v[248:249], s[54:55] nt
	v_cndmask_b32_e64 v246, v130, v138, s[40:41]
	v_cndmask_b32_e64 v247, v131, v139, s[40:41]
	v_mul_f32_e32 v99, v99, v99
	v_fmac_f32_e32 v99, v98, v98
	v_mul_f32_e32 v98, v101, v101
	v_mul_f32_e32 v109, v109, v109
	v_fmac_f32_e32 v98, v100, v100
	v_mul_f32_e32 v107, v107, v107
	v_fmac_f32_e32 v109, v108, v108
	v_mul_f32_e32 v108, v111, v111
	v_mul_f32_e32 v111, v113, v113
	v_add_f32_e32 v98, v99, v98
	v_mul_f32_e32 v99, v103, v103
	v_mul_f32_e32 v100, v105, v105
	v_fmac_f32_e32 v111, v112, v112
	v_fmac_f32_e32 v99, v102, v102
	v_fmac_f32_e32 v100, v104, v104
	v_fmac_f32_e32 v107, v106, v106
	v_fmac_f32_e32 v108, v110, v110
	v_add_f32_e32 v99, v99, v100
	v_add_f32_e32 v100, v107, v109
	v_add_f32_e32 v101, v108, v111
	v_add_f32_e32 v98, v100, v98
	v_add_f32_e32 v99, v101, v99
	ds_bpermute_b32 v100, v204, v98
	ds_bpermute_b32 v101, v204, v99
	s_waitcnt lgkmcnt(1)
	v_add_f32_e32 v98, v98, v100
	s_waitcnt lgkmcnt(0)
	v_add_f32_e32 v101, v99, v101
	ds_bpermute_b32 v100, v205, v98
	ds_bpermute_b32 v102, v205, v101
	s_waitcnt lgkmcnt(1)
	v_add_f32_e32 v98, v98, v100
	s_waitcnt lgkmcnt(0)
	v_add_f32_e32 v100, v101, v102
	ds_bpermute_b32 v99, v206, v98
	ds_bpermute_b32 v101, v206, v100
	v_add_u32_e32 v102, 0x1040, v132
	v_cndmask_b32_e64 v102, v132, v102, s[38:39]
	global_store_dwordx2 v102, v[246:247], s[54:55] nt
	s_and_saveexec_b64 s[16:17], s[42:43]
	s_cbranch_execz .LBB0_340
	s_waitcnt lgkmcnt(1)
	v_add_f32_e32 v98, v98, v99
	s_waitcnt lgkmcnt(0)
	v_add_f32_e32 v99, v100, v101
	ds_write2_b32 v194, v98, v99 offset0:16 offset1:24
.LBB0_340:
	s_or_b64 exec, exec, s[16:17]
	v_add_u32_e32 v98, 0x60000, v207
	v_add_u32_e32 v154, 0x70000, v207
	v_add_u32_e32 v132, 0x60080, v207
	global_load_dwordx4 v[106:109], v154, s[58:59]
	global_load_dwordx4 v[102:105], v132, s[58:59]
	v_add_u32_e32 v130, 0x70080, v207
	global_load_dwordx4 v[110:113], v98, s[58:59]
	s_waitcnt lgkmcnt(0)
	global_load_dwordx4 v[98:101], v130, s[58:59]
	ds_write_b128 v200, v[94:97]
	ds_write_b128 v200, v[90:93] offset:64
	ds_read_b128 v[90:93], v201
	ds_read_b128 v[94:97], v201 offset:1152
	v_mov_b32_e32 v191, v155
	v_mov_b32_e32 v189, v155
	v_mov_b32_e32 v187, v155
	s_waitcnt vmcnt(11) lgkmcnt(1)
	v_pk_fma_f32 v[92:93], v[178:179], v[92:93], v[128:129]
	v_add_u32_e32 v128, 0x10000, v202
	v_pk_fma_f32 v[90:91], v[180:181], v[90:91], v[126:127]
	v_lshlrev_b32_e32 v126, 2, v128
	global_store_dwordx4 v126, v[90:93], s[56:57] nt
	v_pk_mul_f32 v[126:127], v[176:177], v[90:91]
	s_waitcnt lgkmcnt(0)
	v_pk_fma_f32 v[96:97], v[178:179], v[96:97], v[124:125]
	v_pk_fma_f32 v[94:95], v[180:181], v[94:95], v[122:123]
	v_lshl_add_u64 v[122:123], s[56:57], 0, v[190:191]
	v_pk_mul_f32 v[134:135], v[174:175], v[92:93]
	v_cvt_pk_bf16_f32 v126, v126, v127
	v_pk_mul_f32 v[124:125], v[174:175], v[96:97]
	v_cvt_pk_bf16_f32 v127, v134, v135
	global_store_dwordx4 v[122:123], v[94:97], off nt
	v_pk_mul_f32 v[122:123], v[176:177], v[94:95]
	s_nop 0
	v_cvt_pk_bf16_f32 v122, v122, v123
	v_cvt_pk_bf16_f32 v123, v124, v125
	ds_write_b128 v200, v[86:89]
	ds_write_b128 v200, v[82:85] offset:64
	ds_read_b128 v[82:85], v201
	ds_read_b128 v[86:89], v201 offset:1152
	s_waitcnt lgkmcnt(1)
	v_pk_fma_f32 v[82:83], v[168:169], v[82:83], v[118:119]
	v_pk_fma_f32 v[84:85], v[166:167], v[84:85], v[120:121]
	v_lshl_add_u64 v[118:119], s[56:57], 0, v[188:189]
	v_pk_mul_f32 v[120:121], v[172:173], v[82:83]
	s_waitcnt vmcnt(12) lgkmcnt(0)
	v_pk_fma_f32 v[88:89], v[166:167], v[88:89], v[116:117]
	v_pk_fma_f32 v[86:87], v[168:169], v[86:87], v[114:115]
	v_lshl_add_u64 v[114:115], s[56:57], 0, v[186:187]
	global_store_dwordx4 v[118:119], v[82:85], off nt
	v_pk_mul_f32 v[118:119], v[170:171], v[84:85]
	v_cvt_pk_bf16_f32 v120, v120, v121
	v_pk_mul_f32 v[116:117], v[172:173], v[86:87]
	v_cvt_pk_bf16_f32 v121, v118, v119
	global_store_dwordx4 v[114:115], v[86:89], off nt
	ds_bpermute_b32 v114, v203, v120
	ds_bpermute_b32 v115, v203, v121
	v_pk_mul_f32 v[118:119], v[170:171], v[88:89]
	v_cvt_pk_bf16_f32 v116, v116, v117
	s_nop 0
	v_cvt_pk_bf16_f32 v117, v118, v119
	v_lshlrev_b32_e32 v118, 1, v128
	s_waitcnt lgkmcnt(0)
	v_add_u32_e32 v250, 0xfffff040, v118
	v_cndmask_b32_e64 v250, v118, v250, s[40:41]
	v_cndmask_b32_e64 v248, v126, v114, s[40:41]
	v_cndmask_b32_e64 v249, v127, v115, s[40:41]
	global_store_dwordx2 v250, v[248:249], s[54:55] nt
	v_cndmask_b32_e64 v246, v114, v126, s[40:41]
	v_cndmask_b32_e64 v247, v115, v127, s[40:41]
	s_waitcnt lgkmcnt(1)
	v_add_u32_e32 v114, 0x1040, v118
	v_cndmask_b32_e64 v114, v118, v114, s[38:39]
	global_store_dwordx2 v114, v[246:247], s[54:55] nt
	ds_bpermute_b32 v114, v203, v116
	s_waitcnt lgkmcnt(1)
	ds_bpermute_b32 v115, v203, v117
	v_add_u32_e32 v117, 0x14000, v202
	v_lshlrev_b32_e32 v116, 1, v117
	s_waitcnt lgkmcnt(0)
	v_add_u32_e32 v250, 0xfffff040, v116
	v_cndmask_b32_e64 v250, v116, v250, s[40:41]
	v_cndmask_b32_e64 v248, v122, v114, s[40:41]
	v_cndmask_b32_e64 v249, v123, v115, s[40:41]
	global_store_dwordx2 v250, v[248:249], s[54:55] nt
	v_cndmask_b32_e64 v246, v114, v122, s[40:41]
	v_cndmask_b32_e64 v247, v115, v123, s[40:41]
	v_mul_f32_e32 v83, v83, v83
	v_fmac_f32_e32 v83, v82, v82
	v_mul_f32_e32 v82, v85, v85
	v_mul_f32_e32 v93, v93, v93
	v_fmac_f32_e32 v82, v84, v84
	v_mul_f32_e32 v91, v91, v91
	v_fmac_f32_e32 v93, v92, v92
	v_mul_f32_e32 v92, v95, v95
	v_mul_f32_e32 v95, v97, v97
	v_add_f32_e32 v82, v83, v82
	v_mul_f32_e32 v83, v87, v87
	v_mul_f32_e32 v84, v89, v89
	v_fmac_f32_e32 v95, v96, v96
	v_fmac_f32_e32 v83, v86, v86
	v_fmac_f32_e32 v84, v88, v88
	v_fmac_f32_e32 v91, v90, v90
	v_fmac_f32_e32 v92, v94, v94
	v_add_f32_e32 v83, v83, v84
	v_add_f32_e32 v84, v91, v93
	v_add_f32_e32 v85, v92, v95
	v_add_f32_e32 v82, v84, v82
	v_add_f32_e32 v83, v85, v83
	ds_bpermute_b32 v84, v204, v82
	ds_bpermute_b32 v85, v204, v83
	s_waitcnt lgkmcnt(1)
	v_add_f32_e32 v82, v82, v84
	s_waitcnt lgkmcnt(0)
	v_add_f32_e32 v85, v83, v85
	ds_bpermute_b32 v84, v205, v82
	ds_bpermute_b32 v86, v205, v85
	s_waitcnt lgkmcnt(1)
	v_add_f32_e32 v82, v82, v84
	s_waitcnt lgkmcnt(0)
	v_add_f32_e32 v84, v85, v86
	ds_bpermute_b32 v83, v206, v82
	ds_bpermute_b32 v85, v206, v84
	v_add_u32_e32 v86, 0x1040, v116
	v_cndmask_b32_e64 v86, v116, v86, s[38:39]
	global_store_dwordx2 v86, v[246:247], s[54:55] nt
	s_and_saveexec_b64 s[16:17], s[42:43]
	s_cbranch_execz .LBB0_350
	s_waitcnt lgkmcnt(1)
	v_add_f32_e32 v82, v82, v83
	s_waitcnt lgkmcnt(0)
	v_add_f32_e32 v83, v84, v85
	ds_write2_b32 v194, v82, v83 offset0:32 offset1:40
; #define LAS __attribute__((address_space(3)))
; #define ERN_EOFF(q, m) (eb + (unsigned)((((q) & 1) * HALF + (m) * 16) * DM + ERN_COL((q) >> 1)))
;     __device__ __forceinline__ void operator()(const f32x4 (&acc)[2][2][4][2], const Unit& u, int wr, int wc, int fr, int fq) const {
;     ...
;         for (int g = 0; g < 8; ++g) { const int ai = g >> 2, m = g & 3;
;             if (g + 1 < 8) ERN_LOADX(g + 1);
;             float sq0 = 0.f, sq1 = 0.f; u32x2 hw[2][2];
; #pragma unroll
;             for (int bj = 0; bj < 2; ++bj) {
;                 *(LAS f32x4*)(st + wr_off) = acc[ai][bj][m][0]; *(LAS f32x4*)(st + wr_off + 64) = acc[ai][bj][m][1];
;                 const f32x4 a0 = *(const LAS f32x4*)(st + rd_off), a1 = *(const LAS f32x4*)(st + rd_off + 8 * 144);
;                 { const f32x4 xv = xb[g & 1][bj][0] + gv[bj] * a0; __builtin_nontemporal_store(xv, (f32x4*)((char*)xo + 4u * ERN_EOFF(g, bj, 0)));
;                   sq0 += (xv.x * xv.x + xv.y * xv.y) + (xv.z * xv.z + xv.w * xv.w);
;                   const f32x4 hv = xv * gsn[bj]; hw[bj][0].x = cvt_pk_bf16(hv.x, hv.y); hw[bj][0].y = cvt_pk_bf16(hv.z, hv.w); }
;                 { const f32x4 xv = xb[g & 1][bj][1] + gv[bj] * a1; __builtin_nontemporal_store(xv, (f32x4*)((char*)xo + 4u * ERN_EOFF(g, bj, 1)));
;                   sq1 += (xv.x * xv.x + xv.y * xv.y) + (xv.z * xv.z + xv.w * xv.w);
;                   const f32x4 hv = xv * gsn[bj]; hw[bj][1].x = cvt_pk_bf16(hv.x, hv.y); hw[bj][1].y = cvt_pk_bf16(hv.z, hv.w); }
;             }
;             if (!NOH && !PLAIN) {
; #pragma unroll
;                 for (int rh = 0; rh < 2; ++rh) { u32x2 rv; rv.x = __shfl_xor(hw[1][rh].x, 8); rv.y = __shfl_xor(hw[1][rh].y, 8);
;                     const unsigned e0 = ERN_EOFF(g, 0, rh);
;                     const unsigned ee = odd ? (e0 - DM + 32) : e0, eo2 = odd ? e0 : (e0 + DM + 32);
;                     *(u32x2*)((char*)ho + 2u * ee) = odd ? rv : hw[0][rh];
;                     *(u32x2*)((char*)ho + 2u * eo2) = odd ? hw[0][rh] : rv; }
;             }
;             if (!PLAIN) { sq0 += __shfl_xor(sq0, 1); sq0 += __shfl_xor(sq0, 2); sq0 += __shfl_xor(sq0, 4);
;             sq1 += __shfl_xor(sq1, 1); sq1 += __shfl_xor(sq1, 2); sq1 += __shfl_xor(sq1, 4); }
;             if (!PLAIN && pc == 0) { sst[g * 16 + rr] = sq0; sst[g * 16 + 8 + rr] = sq1; }
.LBB0_350:
	s_or_b64 exec, exec, s[16:17]
	v_add_u32_e32 v82, 0x100000, v207
	s_waitcnt lgkmcnt(1)
	v_add_u32_e32 v83, 0x110000, v207
	v_add_u32_e32 v116, 0x100080, v207
	global_load_dwordx4 v[94:97], v82, s[58:59]
	global_load_dwordx4 v[90:93], v83, s[58:59]
	v_add_u32_e32 v114, 0x110080, v207
	global_load_dwordx4 v[86:89], v116, s[58:59]
	s_waitcnt lgkmcnt(0)
	global_load_dwordx4 v[82:85], v114, s[58:59]
	ds_write_b128 v200, v[78:81]
	ds_write_b128 v200, v[74:77] offset:64
	ds_read_b128 v[74:77], v201
	ds_read_b128 v[78:81], v201 offset:1152
	v_mov_b32_e32 v133, v155
	v_mov_b32_e32 v131, v155
	s_waitcnt vmcnt(11) lgkmcnt(1)
	v_pk_fma_f32 v[76:77], v[178:179], v[76:77], v[112:113]
	v_add_u32_e32 v112, 0x18000, v202
	v_pk_fma_f32 v[74:75], v[180:181], v[74:75], v[110:111]
	v_lshlrev_b32_e32 v110, 2, v112
	global_store_dwordx4 v110, v[74:77], s[56:57] nt
	v_pk_mul_f32 v[110:111], v[176:177], v[74:75]
	s_waitcnt lgkmcnt(0)
	v_pk_fma_f32 v[80:81], v[178:179], v[80:81], v[108:109]
	v_pk_fma_f32 v[78:79], v[180:181], v[78:79], v[106:107]
	v_lshl_add_u64 v[106:107], s[56:57], 0, v[154:155]
	v_pk_mul_f32 v[118:119], v[174:175], v[76:77]
	v_cvt_pk_bf16_f32 v110, v110, v111
	v_pk_mul_f32 v[108:109], v[174:175], v[80:81]
	v_cvt_pk_bf16_f32 v111, v118, v119
	global_store_dwordx4 v[106:107], v[78:81], off nt
	v_pk_mul_f32 v[106:107], v[176:177], v[78:79]
	s_nop 0
	v_cvt_pk_bf16_f32 v106, v106, v107
	v_cvt_pk_bf16_f32 v107, v108, v109
	ds_write_b128 v200, v[70:73]
	ds_write_b128 v200, v[66:69] offset:64
	ds_read_b128 v[66:69], v201
	ds_read_b128 v[70:73], v201 offset:1152
	s_waitcnt lgkmcnt(1)
	v_pk_fma_f32 v[66:67], v[168:169], v[66:67], v[102:103]
	v_pk_fma_f32 v[68:69], v[166:167], v[68:69], v[104:105]
	v_lshl_add_u64 v[102:103], s[56:57], 0, v[132:133]
	v_pk_mul_f32 v[104:105], v[172:173], v[66:67]
	s_waitcnt vmcnt(12) lgkmcnt(0)
	v_pk_fma_f32 v[72:73], v[166:167], v[72:73], v[100:101]
	v_pk_fma_f32 v[70:71], v[168:169], v[70:71], v[98:99]
	v_lshl_add_u64 v[98:99], s[56:57], 0, v[130:131]
	global_store_dwordx4 v[102:103], v[66:69], off nt
	v_pk_mul_f32 v[102:103], v[170:171], v[68:69]
	v_cvt_pk_bf16_f32 v104, v104, v105
	v_pk_mul_f32 v[100:101], v[172:173], v[70:71]
	v_cvt_pk_bf16_f32 v105, v102, v103
	global_store_dwordx4 v[98:99], v[70:73], off nt
	ds_bpermute_b32 v98, v203, v104
	ds_bpermute_b32 v99, v203, v105
	v_pk_mul_f32 v[102:103], v[170:171], v[72:73]
	v_cvt_pk_bf16_f32 v100, v100, v101
	s_nop 0
	v_cvt_pk_bf16_f32 v101, v102, v103
	v_lshlrev_b32_e32 v102, 1, v112
	s_waitcnt lgkmcnt(0)
	v_add_u32_e32 v250, 0xfffff040, v102
	v_cndmask_b32_e64 v250, v102, v250, s[40:41]
	v_cndmask_b32_e64 v248, v110, v98, s[40:41]
	v_cndmask_b32_e64 v249, v111, v99, s[40:41]
	global_store_dwordx2 v250, v[248:249], s[54:55] nt
	v_cndmask_b32_e64 v246, v98, v110, s[40:41]
	v_cndmask_b32_e64 v247, v99, v111, s[40:41]
	s_waitcnt lgkmcnt(1)
	v_add_u32_e32 v98, 0x1040, v102
	v_cndmask_b32_e64 v98, v102, v98, s[38:39]
	global_store_dwordx2 v98, v[246:247], s[54:55] nt
	ds_bpermute_b32 v98, v203, v100
	s_waitcnt lgkmcnt(1)
	ds_bpermute_b32 v99, v203, v101
	v_add_u32_e32 v101, 0x1c000, v202
	v_lshlrev_b32_e32 v100, 1, v101
	s_waitcnt lgkmcnt(0)
	v_add_u32_e32 v250, 0xfffff040, v100
	v_cndmask_b32_e64 v250, v100, v250, s[40:41]
	v_cndmask_b32_e64 v248, v106, v98, s[40:41]
	v_cndmask_b32_e64 v249, v107, v99, s[40:41]
	global_store_dwordx2 v250, v[248:249], s[54:55] nt
	v_cndmask_b32_e64 v246, v98, v106, s[40:41]
	v_cndmask_b32_e64 v247, v99, v107, s[40:41]
	v_mul_f32_e32 v67, v67, v67
	v_fmac_f32_e32 v67, v66, v66
	v_mul_f32_e32 v66, v69, v69
	v_mul_f32_e32 v77, v77, v77
	v_fmac_f32_e32 v66, v68, v68
	v_mul_f32_e32 v75, v75, v75
	v_fmac_f32_e32 v77, v76, v76
	v_mul_f32_e32 v76, v79, v79
	v_mul_f32_e32 v79, v81, v81
	v_add_f32_e32 v66, v67, v66
	v_mul_f32_e32 v67, v71, v71
	v_mul_f32_e32 v68, v73, v73
	v_fmac_f32_e32 v79, v80, v80
	v_fmac_f32_e32 v67, v70, v70
	v_fmac_f32_e32 v68, v72, v72
	v_fmac_f32_e32 v75, v74, v74
	v_fmac_f32_e32 v76, v78, v78
	v_add_f32_e32 v67, v67, v68
	v_add_f32_e32 v68, v75, v77
	v_add_f32_e32 v69, v76, v79
	v_add_f32_e32 v66, v68, v66
	v_add_f32_e32 v67, v69, v67
	ds_bpermute_b32 v68, v204, v66
	ds_bpermute_b32 v69, v204, v67
	s_waitcnt lgkmcnt(1)
	v_add_f32_e32 v66, v66, v68
	s_waitcnt lgkmcnt(0)
	v_add_f32_e32 v69, v67, v69
	ds_bpermute_b32 v68, v205, v66
	ds_bpermute_b32 v70, v205, v69
	s_waitcnt lgkmcnt(1)
	v_add_f32_e32 v66, v66, v68
	s_waitcnt lgkmcnt(0)
	v_add_f32_e32 v68, v69, v70
	ds_bpermute_b32 v67, v206, v66
	ds_bpermute_b32 v69, v206, v68
	v_add_u32_e32 v70, 0x1040, v100
	v_cndmask_b32_e64 v70, v100, v70, s[38:39]
	global_store_dwordx2 v70, v[246:247], s[54:55] nt
	s_and_saveexec_b64 s[16:17], s[42:43]
	s_cbranch_execz .LBB0_360
	s_waitcnt lgkmcnt(1)
	v_add_f32_e32 v66, v66, v67
	s_waitcnt lgkmcnt(0)
	v_add_f32_e32 v67, v68, v69
	ds_write2_b32 v194, v66, v67 offset0:48 offset1:56
; #define LAS __attribute__((address_space(3)))
; #define ERN_EOFF(q, m) (eb + (unsigned)((((q) & 1) * HALF + (m) * 16) * DM + ERN_COL((q) >> 1)))
;     __device__ __forceinline__ void operator()(const f32x4 (&acc)[2][2][4][2], const Unit& u, int wr, int wc, int fr, int fq) const {
;     ...
;         for (int g = 0; g < 8; ++g) { const int ai = g >> 2, m = g & 3;
;             if (g + 1 < 8) ERN_LOADX(g + 1);
;             float sq0 = 0.f, sq1 = 0.f; u32x2 hw[2][2];
; #pragma unroll
;             for (int bj = 0; bj < 2; ++bj) {
;                 *(LAS f32x4*)(st + wr_off) = acc[ai][bj][m][0]; *(LAS f32x4*)(st + wr_off + 64) = acc[ai][bj][m][1];
;                 const f32x4 a0 = *(const LAS f32x4*)(st + rd_off), a1 = *(const LAS f32x4*)(st + rd_off + 8 * 144);
;                 { const f32x4 xv = xb[g & 1][bj][0] + gv[bj] * a0; __builtin_nontemporal_store(xv, (f32x4*)((char*)xo + 4u * ERN_EOFF(g, bj, 0)));
;                   sq0 += (xv.x * xv.x + xv.y * xv.y) + (xv.z * xv.z + xv.w * xv.w);
;                   const f32x4 hv = xv * gsn[bj]; hw[bj][0].x = cvt_pk_bf16(hv.x, hv.y); hw[bj][0].y = cvt_pk_bf16(hv.z, hv.w); }
;                 { const f32x4 xv = xb[g & 1][bj][1] + gv[bj] * a1; __builtin_nontemporal_store(xv, (f32x4*)((char*)xo + 4u * ERN_EOFF(g, bj, 1)));
;                   sq1 += (xv.x * xv.x + xv.y * xv.y) + (xv.z * xv.z + xv.w * xv.w);
;                   const f32x4 hv = xv * gsn[bj]; hw[bj][1].x = cvt_pk_bf16(hv.x, hv.y); hw[bj][1].y = cvt_pk_bf16(hv.z, hv.w); }
;             }
;             if (!NOH && !PLAIN) {
; #pragma unroll
;                 for (int rh = 0; rh < 2; ++rh) { u32x2 rv; rv.x = __shfl_xor(hw[1][rh].x, 8); rv.y = __shfl_xor(hw[1][rh].y, 8);
;                     const unsigned e0 = ERN_EOFF(g, 0, rh);
;                     const unsigned ee = odd ? (e0 - DM + 32) : e0, eo2 = odd ? e0 : (e0 + DM + 32);
;                     *(u32x2*)((char*)ho + 2u * ee) = odd ? rv : hw[0][rh];
;                     *(u32x2*)((char*)ho + 2u * eo2) = odd ? hw[0][rh] : rv; }
;             }
;             if (!PLAIN) { sq0 += __shfl_xor(sq0, 1); sq0 += __shfl_xor(sq0, 2); sq0 += __shfl_xor(sq0, 4);
;             sq1 += __shfl_xor(sq1, 1); sq1 += __shfl_xor(sq1, 2); sq1 += __shfl_xor(sq1, 4); }
;             if (!PLAIN && pc == 0) { sst[g * 16 + rr] = sq0; sst[g * 16 + 8 + rr] = sq1; }
.LBB0_360:
	s_or_b64 exec, exec, s[16:17]
	v_add_u32_e32 v154, 0x120000, v207
	v_add_u32_e32 v100, 0x120080, v207
	v_add_u32_e32 v102, 0x130000, v207
	global_load_dwordx4 v[78:81], v154, s[58:59]
	global_load_dwordx4 v[74:77], v102, s[58:59]
	v_add_u32_e32 v98, 0x130080, v207
	global_load_dwordx4 v[70:73], v100, s[58:59]
	s_waitcnt lgkmcnt(0)
	global_load_dwordx4 v[66:69], v98, s[58:59]
	ds_write_b128 v200, v[62:65]
	ds_write_b128 v200, v[58:61] offset:64
	ds_read_b128 v[58:61], v201
	ds_read_b128 v[62:65], v201 offset:1152
	v_mov_b32_e32 v117, v155
	v_mov_b32_e32 v115, v155
	s_waitcnt vmcnt(13) lgkmcnt(1)
	v_pk_fma_f32 v[60:61], v[178:179], v[60:61], v[96:97]
	v_add_u32_e32 v96, 0x40000, v202
	v_pk_fma_f32 v[58:59], v[180:181], v[58:59], v[94:95]
	v_lshlrev_b32_e32 v94, 2, v96
	s_waitcnt vmcnt(12) lgkmcnt(0)
	v_pk_fma_f32 v[64:65], v[178:179], v[64:65], v[92:93]
	v_add_u32_e32 v92, 0x44000, v202
	global_store_dwordx4 v94, v[58:61], s[56:57] nt
	v_pk_mul_f32 v[94:95], v[176:177], v[58:59]
	v_pk_fma_f32 v[62:63], v[180:181], v[62:63], v[90:91]
	v_lshlrev_b32_e32 v90, 2, v92
	v_pk_mul_f32 v[104:105], v[174:175], v[60:61]
	v_cvt_pk_bf16_f32 v94, v94, v95
	s_nop 0
	v_cvt_pk_bf16_f32 v95, v104, v105
	global_store_dwordx4 v90, v[62:65], s[56:57] nt
	v_pk_mul_f32 v[90:91], v[176:177], v[62:63]
	v_pk_mul_f32 v[104:105], v[174:175], v[64:65]
	v_cvt_pk_bf16_f32 v90, v90, v91
	s_nop 0
	v_cvt_pk_bf16_f32 v91, v104, v105
	ds_write_b128 v200, v[54:57]
	ds_write_b128 v200, v[50:53] offset:64
	ds_read_b128 v[50:53], v201
	ds_read_b128 v[54:57], v201 offset:1152
	s_waitcnt vmcnt(13) lgkmcnt(1)
	v_pk_fma_f32 v[50:51], v[168:169], v[50:51], v[86:87]
	v_pk_fma_f32 v[52:53], v[166:167], v[52:53], v[88:89]
	v_lshl_add_u64 v[86:87], s[56:57], 0, v[116:117]
	v_pk_mul_f32 v[88:89], v[172:173], v[50:51]
	s_waitcnt vmcnt(12) lgkmcnt(0)
	v_pk_fma_f32 v[56:57], v[166:167], v[56:57], v[84:85]
	v_pk_fma_f32 v[54:55], v[168:169], v[54:55], v[82:83]
	v_lshl_add_u64 v[82:83], s[56:57], 0, v[114:115]
	global_store_dwordx4 v[86:87], v[50:53], off nt
	v_pk_mul_f32 v[86:87], v[170:171], v[52:53]
	v_cvt_pk_bf16_f32 v88, v88, v89
	v_pk_mul_f32 v[84:85], v[172:173], v[54:55]
	v_cvt_pk_bf16_f32 v89, v86, v87
	global_store_dwordx4 v[82:83], v[54:57], off nt
	ds_bpermute_b32 v82, v203, v88
	ds_bpermute_b32 v83, v203, v89
	v_pk_mul_f32 v[86:87], v[170:171], v[56:57]
	v_cvt_pk_bf16_f32 v84, v84, v85
	s_nop 0
	v_cvt_pk_bf16_f32 v85, v86, v87
	v_lshlrev_b32_e32 v86, 1, v96
	s_waitcnt lgkmcnt(0)
	v_add_u32_e32 v250, 0xfffff040, v86
	v_cndmask_b32_e64 v250, v86, v250, s[40:41]
	v_cndmask_b32_e64 v248, v94, v82, s[40:41]
	v_cndmask_b32_e64 v249, v95, v83, s[40:41]
	global_store_dwordx2 v250, v[248:249], s[54:55] nt
	v_cndmask_b32_e64 v246, v82, v94, s[40:41]
	v_cndmask_b32_e64 v247, v83, v95, s[40:41]
	s_waitcnt lgkmcnt(1)
	v_add_u32_e32 v82, 0x1040, v86
	v_cndmask_b32_e64 v82, v86, v82, s[38:39]
	global_store_dwordx2 v82, v[246:247], s[54:55] nt
	ds_bpermute_b32 v82, v203, v84
	s_waitcnt lgkmcnt(1)
	ds_bpermute_b32 v83, v203, v85
	v_lshlrev_b32_e32 v84, 1, v92
	s_waitcnt lgkmcnt(0)
	v_add_u32_e32 v250, 0xfffff040, v84
	v_cndmask_b32_e64 v250, v84, v250, s[40:41]
	v_cndmask_b32_e64 v248, v90, v82, s[40:41]
	v_cndmask_b32_e64 v249, v91, v83, s[40:41]
	global_store_dwordx2 v250, v[248:249], s[54:55] nt
	v_cndmask_b32_e64 v246, v82, v90, s[40:41]
	v_cndmask_b32_e64 v247, v83, v91, s[40:41]
	v_mul_f32_e32 v51, v51, v51
	v_fmac_f32_e32 v51, v50, v50
	v_mul_f32_e32 v50, v53, v53
	v_mul_f32_e32 v61, v61, v61
	v_fmac_f32_e32 v50, v52, v52
	v_mul_f32_e32 v59, v59, v59
	v_fmac_f32_e32 v61, v60, v60
	v_mul_f32_e32 v60, v63, v63
	v_mul_f32_e32 v63, v65, v65
	v_add_f32_e32 v50, v51, v50
	v_mul_f32_e32 v51, v55, v55
	v_mul_f32_e32 v52, v57, v57
	v_fmac_f32_e32 v63, v64, v64
	v_fmac_f32_e32 v51, v54, v54
	v_fmac_f32_e32 v52, v56, v56
	v_fmac_f32_e32 v59, v58, v58
	v_fmac_f32_e32 v60, v62, v62
	v_add_f32_e32 v51, v51, v52
	v_add_f32_e32 v52, v59, v61
	v_add_f32_e32 v53, v60, v63
	v_add_f32_e32 v50, v52, v50
	v_add_f32_e32 v51, v53, v51
	ds_bpermute_b32 v52, v204, v50
	ds_bpermute_b32 v53, v204, v51
	s_waitcnt lgkmcnt(1)
	v_add_f32_e32 v50, v50, v52
	s_waitcnt lgkmcnt(0)
	v_add_f32_e32 v53, v51, v53
	ds_bpermute_b32 v52, v205, v50
	ds_bpermute_b32 v54, v205, v53
	s_waitcnt lgkmcnt(1)
	v_add_f32_e32 v50, v50, v52
	s_waitcnt lgkmcnt(0)
	v_add_f32_e32 v52, v53, v54
	ds_bpermute_b32 v51, v206, v50
	ds_bpermute_b32 v53, v206, v52
	v_add_u32_e32 v54, 0x1040, v84
	v_cndmask_b32_e64 v54, v84, v54, s[38:39]
	global_store_dwordx2 v54, v[246:247], s[54:55] nt
	s_and_saveexec_b64 s[16:17], s[42:43]
	s_cbranch_execz .LBB0_370
	s_waitcnt lgkmcnt(1)
	v_add_f32_e32 v50, v50, v51
	s_waitcnt lgkmcnt(0)
	v_add_f32_e32 v51, v52, v53
	ds_write2_b32 v194, v50, v51 offset0:64 offset1:72
; #define LAS __attribute__((address_space(3)))
; #define ERN_EOFF(q, m) (eb + (unsigned)((((q) & 1) * HALF + (m) * 16) * DM + ERN_COL((q) >> 1)))
;     __device__ __forceinline__ void operator()(const f32x4 (&acc)[2][2][4][2], const Unit& u, int wr, int wc, int fr, int fq) const {
;     ...
;         for (int g = 0; g < 8; ++g) { const int ai = g >> 2, m = g & 3;
;             if (g + 1 < 8) ERN_LOADX(g + 1);
;             float sq0 = 0.f, sq1 = 0.f; u32x2 hw[2][2];
; #pragma unroll
;             for (int bj = 0; bj < 2; ++bj) {
;                 *(LAS f32x4*)(st + wr_off) = acc[ai][bj][m][0]; *(LAS f32x4*)(st + wr_off + 64) = acc[ai][bj][m][1];
;                 const f32x4 a0 = *(const LAS f32x4*)(st + rd_off), a1 = *(const LAS f32x4*)(st + rd_off + 8 * 144);
;                 { const f32x4 xv = xb[g & 1][bj][0] + gv[bj] * a0; __builtin_nontemporal_store(xv, (f32x4*)((char*)xo + 4u * ERN_EOFF(g, bj, 0)));
;                   sq0 += (xv.x * xv.x + xv.y * xv.y) + (xv.z * xv.z + xv.w * xv.w);
;                   const f32x4 hv = xv * gsn[bj]; hw[bj][0].x = cvt_pk_bf16(hv.x, hv.y); hw[bj][0].y = cvt_pk_bf16(hv.z, hv.w); }
;                 { const f32x4 xv = xb[g & 1][bj][1] + gv[bj] * a1; __builtin_nontemporal_store(xv, (f32x4*)((char*)xo + 4u * ERN_EOFF(g, bj, 1)));
;                   sq1 += (xv.x * xv.x + xv.y * xv.y) + (xv.z * xv.z + xv.w * xv.w);
;                   const f32x4 hv = xv * gsn[bj]; hw[bj][1].x = cvt_pk_bf16(hv.x, hv.y); hw[bj][1].y = cvt_pk_bf16(hv.z, hv.w); }
;             }
;             if (!NOH && !PLAIN) {
; #pragma unroll
;                 for (int rh = 0; rh < 2; ++rh) { u32x2 rv; rv.x = __shfl_xor(hw[1][rh].x, 8); rv.y = __shfl_xor(hw[1][rh].y, 8);
;                     const unsigned e0 = ERN_EOFF(g, 0, rh);
;                     const unsigned ee = odd ? (e0 - DM + 32) : e0, eo2 = odd ? e0 : (e0 + DM + 32);
;                     *(u32x2*)((char*)ho + 2u * ee) = odd ? rv : hw[0][rh];
;                     *(u32x2*)((char*)ho + 2u * eo2) = odd ? hw[0][rh] : rv; }
;             }
;             if (!PLAIN) { sq0 += __shfl_xor(sq0, 1); sq0 += __shfl_xor(sq0, 2); sq0 += __shfl_xor(sq0, 4);
;             sq1 += __shfl_xor(sq1, 1); sq1 += __shfl_xor(sq1, 2); sq1 += __shfl_xor(sq1, 4); }
;             if (!PLAIN && pc == 0) { sst[g * 16 + rr] = sq0; sst[g * 16 + 8 + rr] = sq1; }
.LBB0_370:
	s_or_b64 exec, exec, s[16:17]
	v_add_u32_e32 v88, 0x140000, v207
	v_add_u32_e32 v84, 0x140080, v207
	v_add_u32_e32 v86, 0x150000, v207
	global_load_dwordx4 v[62:65], v88, s[58:59]
	global_load_dwordx4 v[58:61], v86, s[58:59]
	v_add_u32_e32 v82, 0x150080, v207
	global_load_dwordx4 v[54:57], v84, s[58:59]
	s_waitcnt lgkmcnt(0)
	global_load_dwordx4 v[50:53], v82, s[58:59]
	ds_write_b128 v200, v[46:49]
	ds_write_b128 v200, v[42:45] offset:64
	ds_read_b128 v[42:45], v201
	ds_read_b128 v[46:49], v201 offset:1152
	v_mov_b32_e32 v103, v155
	v_mov_b32_e32 v101, v155
	v_mov_b32_e32 v99, v155
	s_waitcnt vmcnt(13) lgkmcnt(1)
	v_pk_fma_f32 v[44:45], v[178:179], v[44:45], v[80:81]
	v_pk_fma_f32 v[42:43], v[180:181], v[42:43], v[78:79]
	v_lshl_add_u64 v[78:79], s[56:57], 0, v[154:155]
	global_store_dwordx4 v[78:79], v[42:45], off nt
	v_pk_mul_f32 v[78:79], v[176:177], v[42:43]
	s_waitcnt vmcnt(13) lgkmcnt(0)
	v_pk_fma_f32 v[48:49], v[178:179], v[48:49], v[76:77]
	v_pk_fma_f32 v[46:47], v[180:181], v[46:47], v[74:75]
	v_lshl_add_u64 v[74:75], s[56:57], 0, v[102:103]
	v_pk_mul_f32 v[80:81], v[174:175], v[44:45]
	v_cvt_pk_bf16_f32 v78, v78, v79
	v_pk_mul_f32 v[76:77], v[174:175], v[48:49]
	v_cvt_pk_bf16_f32 v79, v80, v81
	global_store_dwordx4 v[74:75], v[46:49], off nt
	v_pk_mul_f32 v[74:75], v[176:177], v[46:47]
	s_nop 0
	v_cvt_pk_bf16_f32 v74, v74, v75
	v_cvt_pk_bf16_f32 v75, v76, v77
	ds_write_b128 v200, v[38:41]
	ds_write_b128 v200, v[34:37] offset:64
	ds_read_b128 v[34:37], v201
	ds_read_b128 v[38:41], v201 offset:1152
	s_waitcnt vmcnt(13) lgkmcnt(1)
	v_pk_fma_f32 v[34:35], v[168:169], v[34:35], v[70:71]
	v_pk_fma_f32 v[36:37], v[166:167], v[36:37], v[72:73]
	v_lshl_add_u64 v[70:71], s[56:57], 0, v[100:101]
	v_pk_mul_f32 v[72:73], v[172:173], v[34:35]
	s_waitcnt vmcnt(12) lgkmcnt(0)
	v_pk_fma_f32 v[40:41], v[166:167], v[40:41], v[68:69]
	v_pk_fma_f32 v[38:39], v[168:169], v[38:39], v[66:67]
	v_lshl_add_u64 v[66:67], s[56:57], 0, v[98:99]
	global_store_dwordx4 v[70:71], v[34:37], off nt
	v_pk_mul_f32 v[70:71], v[170:171], v[36:37]
	v_cvt_pk_bf16_f32 v72, v72, v73
	v_pk_mul_f32 v[68:69], v[172:173], v[38:39]
	v_cvt_pk_bf16_f32 v73, v70, v71
	global_store_dwordx4 v[66:67], v[38:41], off nt
	ds_bpermute_b32 v66, v203, v72
	ds_bpermute_b32 v67, v203, v73
	v_pk_mul_f32 v[70:71], v[170:171], v[40:41]
	v_cvt_pk_bf16_f32 v68, v68, v69
	s_nop 0
	v_cvt_pk_bf16_f32 v69, v70, v71
	v_add_u32_e32 v71, 0x48000, v202
	v_lshlrev_b32_e32 v70, 1, v71
	s_waitcnt lgkmcnt(0)
	v_add_u32_e32 v250, 0xfffff040, v70
	v_cndmask_b32_e64 v250, v70, v250, s[40:41]
	v_cndmask_b32_e64 v248, v78, v66, s[40:41]
	v_cndmask_b32_e64 v249, v79, v67, s[40:41]
	global_store_dwordx2 v250, v[248:249], s[54:55] nt
	v_cndmask_b32_e64 v246, v66, v78, s[40:41]
	v_cndmask_b32_e64 v247, v67, v79, s[40:41]
	s_waitcnt lgkmcnt(1)
	v_add_u32_e32 v66, 0x1040, v70
	v_cndmask_b32_e64 v66, v70, v66, s[38:39]
	global_store_dwordx2 v66, v[246:247], s[54:55] nt
	ds_bpermute_b32 v66, v203, v68
	s_waitcnt lgkmcnt(1)
	ds_bpermute_b32 v67, v203, v69
	v_add_u32_e32 v69, 0x4c000, v202
	v_lshlrev_b32_e32 v68, 1, v69
	s_waitcnt lgkmcnt(0)
	v_add_u32_e32 v250, 0xfffff040, v68
	v_cndmask_b32_e64 v250, v68, v250, s[40:41]
	v_cndmask_b32_e64 v248, v74, v66, s[40:41]
	v_cndmask_b32_e64 v249, v75, v67, s[40:41]
	global_store_dwordx2 v250, v[248:249], s[54:55] nt
	v_cndmask_b32_e64 v246, v66, v74, s[40:41]
	v_cndmask_b32_e64 v247, v67, v75, s[40:41]
	v_mul_f32_e32 v35, v35, v35
	v_fmac_f32_e32 v35, v34, v34
	v_mul_f32_e32 v34, v37, v37
	v_mul_f32_e32 v45, v45, v45
	v_fmac_f32_e32 v34, v36, v36
	v_mul_f32_e32 v43, v43, v43
	v_fmac_f32_e32 v45, v44, v44
	v_mul_f32_e32 v44, v47, v47
	v_mul_f32_e32 v47, v49, v49
	v_add_f32_e32 v34, v35, v34
	v_mul_f32_e32 v35, v39, v39
	v_mul_f32_e32 v36, v41, v41
	v_fmac_f32_e32 v47, v48, v48
	v_fmac_f32_e32 v35, v38, v38
	v_fmac_f32_e32 v36, v40, v40
	v_fmac_f32_e32 v43, v42, v42
	v_fmac_f32_e32 v44, v46, v46
	v_add_f32_e32 v35, v35, v36
	v_add_f32_e32 v36, v43, v45
	v_add_f32_e32 v37, v44, v47
	v_add_f32_e32 v34, v36, v34
	v_add_f32_e32 v35, v37, v35
	ds_bpermute_b32 v36, v204, v34
	ds_bpermute_b32 v37, v204, v35
	s_waitcnt lgkmcnt(1)
	v_add_f32_e32 v34, v34, v36
	s_waitcnt lgkmcnt(0)
	v_add_f32_e32 v37, v35, v37
	ds_bpermute_b32 v36, v205, v34
	ds_bpermute_b32 v38, v205, v37
	s_waitcnt lgkmcnt(1)
	v_add_f32_e32 v34, v34, v36
	s_waitcnt lgkmcnt(0)
	v_add_f32_e32 v36, v37, v38
	ds_bpermute_b32 v35, v206, v34
	ds_bpermute_b32 v37, v206, v36
	v_add_u32_e32 v38, 0x1040, v68
	v_cndmask_b32_e64 v38, v68, v38, s[38:39]
	global_store_dwordx2 v38, v[246:247], s[54:55] nt
	s_and_saveexec_b64 s[16:17], s[42:43]
	s_cbranch_execz .LBB0_380
	s_waitcnt lgkmcnt(1)
	v_add_f32_e32 v34, v34, v35
	s_waitcnt lgkmcnt(0)
	v_add_f32_e32 v35, v36, v37
	ds_write2_b32 v194, v34, v35 offset0:80 offset1:88
; #define LAS __attribute__((address_space(3)))
; #define ERN_EOFF(q, m) (eb + (unsigned)((((q) & 1) * HALF + (m) * 16) * DM + ERN_COL((q) >> 1)))
;     __device__ __forceinline__ void operator()(const f32x4 (&acc)[2][2][4][2], const Unit& u, int wr, int wc, int fr, int fq) const {
;     ...
;         for (int g = 0; g < 8; ++g) { const int ai = g >> 2, m = g & 3;
;             if (g + 1 < 8) ERN_LOADX(g + 1);
;             float sq0 = 0.f, sq1 = 0.f; u32x2 hw[2][2];
; #pragma unroll
;             for (int bj = 0; bj < 2; ++bj) {
;                 *(LAS f32x4*)(st + wr_off) = acc[ai][bj][m][0]; *(LAS f32x4*)(st + wr_off + 64) = acc[ai][bj][m][1];
;                 const f32x4 a0 = *(const LAS f32x4*)(st + rd_off), a1 = *(const LAS f32x4*)(st + rd_off + 8 * 144);
;                 { const f32x4 xv = xb[g & 1][bj][0] + gv[bj] * a0; __builtin_nontemporal_store(xv, (f32x4*)((char*)xo + 4u * ERN_EOFF(g, bj, 0)));
;                   sq0 += (xv.x * xv.x + xv.y * xv.y) + (xv.z * xv.z + xv.w * xv.w);
;                   const f32x4 hv = xv * gsn[bj]; hw[bj][0].x = cvt_pk_bf16(hv.x, hv.y); hw[bj][0].y = cvt_pk_bf16(hv.z, hv.w); }
;                 { const f32x4 xv = xb[g & 1][bj][1] + gv[bj] * a1; __builtin_nontemporal_store(xv, (f32x4*)((char*)xo + 4u * ERN_EOFF(g, bj, 1)));
;                   sq1 += (xv.x * xv.x + xv.y * xv.y) + (xv.z * xv.z + xv.w * xv.w);
;                   const f32x4 hv = xv * gsn[bj]; hw[bj][1].x = cvt_pk_bf16(hv.x, hv.y); hw[bj][1].y = cvt_pk_bf16(hv.z, hv.w); }
;             }
;             if (!NOH && !PLAIN) {
; #pragma unroll
;                 for (int rh = 0; rh < 2; ++rh) { u32x2 rv; rv.x = __shfl_xor(hw[1][rh].x, 8); rv.y = __shfl_xor(hw[1][rh].y, 8);
;                     const unsigned e0 = ERN_EOFF(g, 0, rh);
;                     const unsigned ee = odd ? (e0 - DM + 32) : e0, eo2 = odd ? e0 : (e0 + DM + 32);
;                     *(u32x2*)((char*)ho + 2u * ee) = odd ? rv : hw[0][rh];
;                     *(u32x2*)((char*)ho + 2u * eo2) = odd ? hw[0][rh] : rv; }
;             }
;             if (!PLAIN) { sq0 += __shfl_xor(sq0, 1); sq0 += __shfl_xor(sq0, 2); sq0 += __shfl_xor(sq0, 4);
;             sq1 += __shfl_xor(sq1, 1); sq1 += __shfl_xor(sq1, 2); sq1 += __shfl_xor(sq1, 4); }
;             if (!PLAIN && pc == 0) { sst[g * 16 + rr] = sq0; sst[g * 16 + 8 + rr] = sq1; }
.LBB0_380:
	s_or_b64 exec, exec, s[16:17]
	v_add_u32_e32 v154, 0x160000, v207
	v_add_u32_e32 v68, 0x160080, v207
	v_add_u32_e32 v70, 0x170000, v207
	global_load_dwordx4 v[46:49], v154, s[58:59]
	global_load_dwordx4 v[42:45], v70, s[58:59]
	v_add_u32_e32 v66, 0x170080, v207
	global_load_dwordx4 v[38:41], v68, s[58:59]
	s_waitcnt lgkmcnt(0)
	global_load_dwordx4 v[34:37], v66, s[58:59]
	ds_write_b128 v200, v[30:33]
	ds_write_b128 v200, v[26:29] offset:64
	ds_read_b128 v[26:29], v201
	ds_read_b128 v[30:33], v201 offset:1152
	v_mov_b32_e32 v89, v155
	v_mov_b32_e32 v87, v155
	v_mov_b32_e32 v85, v155
	s_waitcnt vmcnt(13) lgkmcnt(1)
	v_pk_fma_f32 v[28:29], v[178:179], v[28:29], v[64:65]
	v_pk_fma_f32 v[26:27], v[180:181], v[26:27], v[62:63]
	v_lshl_add_u64 v[62:63], s[56:57], 0, v[88:89]
	global_store_dwordx4 v[62:63], v[26:29], off nt
	v_pk_mul_f32 v[62:63], v[176:177], v[26:27]
	s_waitcnt vmcnt(13) lgkmcnt(0)
	v_pk_fma_f32 v[32:33], v[178:179], v[32:33], v[60:61]
	v_pk_fma_f32 v[30:31], v[180:181], v[30:31], v[58:59]
	v_lshl_add_u64 v[58:59], s[56:57], 0, v[86:87]
	v_pk_mul_f32 v[64:65], v[174:175], v[28:29]
	v_cvt_pk_bf16_f32 v62, v62, v63
	v_pk_mul_f32 v[60:61], v[174:175], v[32:33]
	v_cvt_pk_bf16_f32 v63, v64, v65
	global_store_dwordx4 v[58:59], v[30:33], off nt
	v_pk_mul_f32 v[58:59], v[176:177], v[30:31]
	v_mov_b32_e32 v83, v155
	v_cvt_pk_bf16_f32 v58, v58, v59
	v_cvt_pk_bf16_f32 v59, v60, v61
	ds_write_b128 v200, v[22:25]
	ds_write_b128 v200, v[18:21] offset:64
	ds_read_b128 v[18:21], v201
	ds_read_b128 v[22:25], v201 offset:1152
	s_waitcnt vmcnt(13) lgkmcnt(1)
	v_pk_fma_f32 v[18:19], v[168:169], v[18:19], v[54:55]
	v_pk_fma_f32 v[20:21], v[166:167], v[20:21], v[56:57]
	v_lshl_add_u64 v[54:55], s[56:57], 0, v[84:85]
	v_pk_mul_f32 v[56:57], v[172:173], v[18:19]
	s_waitcnt vmcnt(12) lgkmcnt(0)
	v_pk_fma_f32 v[24:25], v[166:167], v[24:25], v[52:53]
	v_pk_fma_f32 v[22:23], v[168:169], v[22:23], v[50:51]
	v_lshl_add_u64 v[50:51], s[56:57], 0, v[82:83]
	global_store_dwordx4 v[54:55], v[18:21], off nt
	v_pk_mul_f32 v[54:55], v[170:171], v[20:21]
	v_cvt_pk_bf16_f32 v56, v56, v57
	v_pk_mul_f32 v[52:53], v[172:173], v[22:23]
	v_cvt_pk_bf16_f32 v57, v54, v55
	global_store_dwordx4 v[50:51], v[22:25], off nt
	ds_bpermute_b32 v50, v203, v56
	ds_bpermute_b32 v51, v203, v57
	v_pk_mul_f32 v[54:55], v[170:171], v[24:25]
	v_cvt_pk_bf16_f32 v52, v52, v53
	s_nop 0
	v_cvt_pk_bf16_f32 v53, v54, v55
	v_add_u32_e32 v55, 0x50000, v202
	v_lshlrev_b32_e32 v54, 1, v55
	s_waitcnt lgkmcnt(0)
	v_add_u32_e32 v250, 0xfffff040, v54
	v_cndmask_b32_e64 v250, v54, v250, s[40:41]
	v_cndmask_b32_e64 v248, v62, v50, s[40:41]
	v_cndmask_b32_e64 v249, v63, v51, s[40:41]
	global_store_dwordx2 v250, v[248:249], s[54:55] nt
	v_cndmask_b32_e64 v246, v50, v62, s[40:41]
	v_cndmask_b32_e64 v247, v51, v63, s[40:41]
	s_waitcnt lgkmcnt(1)
	v_add_u32_e32 v50, 0x1040, v54
	v_cndmask_b32_e64 v50, v54, v50, s[38:39]
	global_store_dwordx2 v50, v[246:247], s[54:55] nt
	ds_bpermute_b32 v50, v203, v52
	s_waitcnt lgkmcnt(1)
	ds_bpermute_b32 v51, v203, v53
	v_add_u32_e32 v53, 0x54000, v202
	v_lshlrev_b32_e32 v52, 1, v53
	s_waitcnt lgkmcnt(0)
	v_add_u32_e32 v250, 0xfffff040, v52
	v_cndmask_b32_e64 v250, v52, v250, s[40:41]
	v_cndmask_b32_e64 v248, v58, v50, s[40:41]
	v_cndmask_b32_e64 v249, v59, v51, s[40:41]
	global_store_dwordx2 v250, v[248:249], s[54:55] nt
	v_cndmask_b32_e64 v246, v50, v58, s[40:41]
	v_cndmask_b32_e64 v247, v51, v59, s[40:41]
	v_mul_f32_e32 v19, v19, v19
	v_fmac_f32_e32 v19, v18, v18
	v_mul_f32_e32 v18, v21, v21
	v_mul_f32_e32 v29, v29, v29
	v_fmac_f32_e32 v18, v20, v20
	v_mul_f32_e32 v27, v27, v27
	v_fmac_f32_e32 v29, v28, v28
	v_mul_f32_e32 v28, v31, v31
	v_mul_f32_e32 v31, v33, v33
	v_add_f32_e32 v18, v19, v18
	v_mul_f32_e32 v19, v23, v23
	v_mul_f32_e32 v20, v25, v25
	v_fmac_f32_e32 v31, v32, v32
	v_fmac_f32_e32 v19, v22, v22
	v_fmac_f32_e32 v20, v24, v24
	v_fmac_f32_e32 v27, v26, v26
	v_fmac_f32_e32 v28, v30, v30
	v_add_f32_e32 v19, v19, v20
	v_add_f32_e32 v20, v27, v29
	v_add_f32_e32 v21, v28, v31
	v_add_f32_e32 v18, v20, v18
	v_add_f32_e32 v19, v21, v19
	ds_bpermute_b32 v20, v204, v18
	ds_bpermute_b32 v21, v204, v19
	s_waitcnt lgkmcnt(1)
	v_add_f32_e32 v18, v18, v20
	s_waitcnt lgkmcnt(0)
	v_add_f32_e32 v21, v19, v21
	ds_bpermute_b32 v20, v205, v18
	ds_bpermute_b32 v22, v205, v21
	s_waitcnt lgkmcnt(1)
	v_add_f32_e32 v18, v18, v20
	s_waitcnt lgkmcnt(0)
	v_add_f32_e32 v20, v21, v22
	ds_bpermute_b32 v19, v206, v18
	ds_bpermute_b32 v21, v206, v20
	v_add_u32_e32 v22, 0x1040, v52
	v_cndmask_b32_e64 v22, v52, v22, s[38:39]
	global_store_dwordx2 v22, v[246:247], s[54:55] nt
	s_and_saveexec_b64 s[16:17], s[42:43]
	s_cbranch_execz .LBB0_390
	s_waitcnt lgkmcnt(1)
	v_add_f32_e32 v18, v18, v19
	s_waitcnt lgkmcnt(0)
	v_add_f32_e32 v19, v20, v21
	ds_write2_b32 v194, v18, v19 offset0:96 offset1:104
; #define LAS __attribute__((address_space(3)))
; #define ERN_EOFF(q, m) (eb + (unsigned)((((q) & 1) * HALF + (m) * 16) * DM + ERN_COL((q) >> 1)))
;     __device__ __forceinline__ void operator()(const f32x4 (&acc)[2][2][4][2], const Unit& u, int wr, int wc, int fr, int fq) const {
;     ...
;         for (int g = 0; g < 8; ++g) { const int ai = g >> 2, m = g & 3;
;             if (g + 1 < 8) ERN_LOADX(g + 1);
;             float sq0 = 0.f, sq1 = 0.f; u32x2 hw[2][2];
; #pragma unroll
;             for (int bj = 0; bj < 2; ++bj) {
;                 *(LAS f32x4*)(st + wr_off) = acc[ai][bj][m][0]; *(LAS f32x4*)(st + wr_off + 64) = acc[ai][bj][m][1];
;                 const f32x4 a0 = *(const LAS f32x4*)(st + rd_off), a1 = *(const LAS f32x4*)(st + rd_off + 8 * 144);
;                 { const f32x4 xv = xb[g & 1][bj][0] + gv[bj] * a0; __builtin_nontemporal_store(xv, (f32x4*)((char*)xo + 4u * ERN_EOFF(g, bj, 0)));
;                   sq0 += (xv.x * xv.x + xv.y * xv.y) + (xv.z * xv.z + xv.w * xv.w);
;                   const f32x4 hv = xv * gsn[bj]; hw[bj][0].x = cvt_pk_bf16(hv.x, hv.y); hw[bj][0].y = cvt_pk_bf16(hv.z, hv.w); }
;                 { const f32x4 xv = xb[g & 1][bj][1] + gv[bj] * a1; __builtin_nontemporal_store(xv, (f32x4*)((char*)xo + 4u * ERN_EOFF(g, bj, 1)));
;                   sq1 += (xv.x * xv.x + xv.y * xv.y) + (xv.z * xv.z + xv.w * xv.w);
;                   const f32x4 hv = xv * gsn[bj]; hw[bj][1].x = cvt_pk_bf16(hv.x, hv.y); hw[bj][1].y = cvt_pk_bf16(hv.z, hv.w); }
;             }
;             if (!NOH && !PLAIN) {
; #pragma unroll
;                 for (int rh = 0; rh < 2; ++rh) { u32x2 rv; rv.x = __shfl_xor(hw[1][rh].x, 8); rv.y = __shfl_xor(hw[1][rh].y, 8);
;                     const unsigned e0 = ERN_EOFF(g, 0, rh);
;                     const unsigned ee = odd ? (e0 - DM + 32) : e0, eo2 = odd ? e0 : (e0 + DM + 32);
;                     *(u32x2*)((char*)ho + 2u * ee) = odd ? rv : hw[0][rh];
;                     *(u32x2*)((char*)ho + 2u * eo2) = odd ? hw[0][rh] : rv; }
;             }
;             if (!PLAIN) { sq0 += __shfl_xor(sq0, 1); sq0 += __shfl_xor(sq0, 2); sq0 += __shfl_xor(sq0, 4);
;             sq1 += __shfl_xor(sq1, 1); sq1 += __shfl_xor(sq1, 2); sq1 += __shfl_xor(sq1, 4); }
;             if (!PLAIN && pc == 0) { sst[g * 16 + rr] = sq0; sst[g * 16 + 8 + rr] = sq1; }
.LBB0_390:
	s_or_b64 exec, exec, s[16:17]
	ds_write_b128 v200, v[14:17]
	ds_write_b128 v200, v[10:13] offset:64
	ds_read_b128 v[10:13], v201
	ds_read_b128 v[14:17], v201 offset:1152
	s_waitcnt lgkmcnt(5)
	v_lshl_add_u64 v[18:19], s[56:57], 0, v[154:155]
	v_mov_b32_e32 v71, v155
	v_mov_b32_e32 v69, v155
	s_waitcnt vmcnt(9) lgkmcnt(1)
	v_pk_fma_f32 v[12:13], v[178:179], v[12:13], v[48:49]
	v_pk_fma_f32 v[10:11], v[180:181], v[10:11], v[46:47]
	global_store_dwordx4 v[18:19], v[10:13], off nt
	v_pk_mul_f32 v[18:19], v[174:175], v[12:13]
	v_pk_mul_f32 v[20:21], v[176:177], v[10:11]
	s_waitcnt vmcnt(9) lgkmcnt(0)
	v_pk_fma_f32 v[16:17], v[178:179], v[16:17], v[44:45]
	v_cvt_pk_bf16_f32 v20, v20, v21
	v_cvt_pk_bf16_f32 v21, v18, v19
	v_pk_fma_f32 v[14:15], v[180:181], v[14:15], v[42:43]
	v_lshl_add_u64 v[18:19], s[56:57], 0, v[70:71]
	global_store_dwordx4 v[18:19], v[14:17], off nt
	v_pk_mul_f32 v[18:19], v[176:177], v[14:15]
	v_pk_mul_f32 v[22:23], v[174:175], v[16:17]
	v_cvt_pk_bf16_f32 v18, v18, v19
	v_mov_b32_e32 v67, v155
	v_cvt_pk_bf16_f32 v19, v22, v23
	ds_write_b128 v200, v[6:9]
	ds_write_b128 v200, v[2:5] offset:64
	ds_read_b128 v[2:5], v201
	ds_read_b128 v[6:9], v201 offset:1152
	v_lshl_add_u64 v[22:23], s[56:57], 0, v[68:69]
	s_waitcnt vmcnt(9) lgkmcnt(1)
	v_pk_fma_f32 v[4:5], v[166:167], v[4:5], v[40:41]
	v_pk_fma_f32 v[2:3], v[168:169], v[2:3], v[38:39]
	global_store_dwordx4 v[22:23], v[2:5], off nt
	v_pk_mul_f32 v[22:23], v[170:171], v[4:5]
	v_pk_mul_f32 v[24:25], v[172:173], v[2:3]
	s_waitcnt vmcnt(9) lgkmcnt(0)
	v_pk_fma_f32 v[8:9], v[166:167], v[8:9], v[36:37]
	v_cvt_pk_bf16_f32 v28, v24, v25
	v_cvt_pk_bf16_f32 v29, v22, v23
	v_pk_fma_f32 v[6:7], v[168:169], v[6:7], v[34:35]
	v_lshl_add_u64 v[22:23], s[56:57], 0, v[66:67]
	global_store_dwordx4 v[22:23], v[6:9], off nt
	ds_bpermute_b32 v22, v203, v28
	ds_bpermute_b32 v23, v203, v29
	v_pk_mul_f32 v[26:27], v[170:171], v[8:9]
	v_pk_mul_f32 v[24:25], v[172:173], v[6:7]
	s_nop 0
	v_cvt_pk_bf16_f32 v24, v24, v25
	v_cvt_pk_bf16_f32 v25, v26, v27
	v_add_u32_e32 v27, 0x58000, v202
	v_lshlrev_b32_e32 v26, 1, v27
	s_waitcnt lgkmcnt(0)
	v_add_u32_e32 v250, 0xfffff040, v26
	v_cndmask_b32_e64 v250, v26, v250, s[40:41]
	v_cndmask_b32_e64 v248, v20, v22, s[40:41]
	v_cndmask_b32_e64 v249, v21, v23, s[40:41]
	global_store_dwordx2 v250, v[248:249], s[54:55] nt
	v_cndmask_b32_e64 v246, v22, v20, s[40:41]
	v_cndmask_b32_e64 v247, v23, v21, s[40:41]
	s_waitcnt lgkmcnt(1)
	v_add_u32_e32 v22, 0x1040, v26
	v_cndmask_b32_e64 v22, v26, v22, s[38:39]
	global_store_dwordx2 v22, v[246:247], s[54:55] nt
	ds_bpermute_b32 v20, v203, v24
	ds_bpermute_b32 v21, v203, v25
	s_waitcnt lgkmcnt(2)
	v_add_u32_e32 v23, 0x5c000, v202
	v_lshlrev_b32_e32 v22, 1, v23
	s_waitcnt lgkmcnt(0)
	v_add_u32_e32 v250, 0xfffff040, v22
	v_cndmask_b32_e64 v250, v22, v250, s[40:41]
	v_cndmask_b32_e64 v248, v18, v20, s[40:41]
	v_cndmask_b32_e64 v249, v19, v21, s[40:41]
	global_store_dwordx2 v250, v[248:249], s[54:55] nt
	v_cndmask_b32_e64 v246, v20, v18, s[40:41]
	v_cndmask_b32_e64 v247, v21, v19, s[40:41]
	v_mul_f32_e32 v3, v3, v3
	v_fmac_f32_e32 v3, v2, v2
	v_mul_f32_e32 v2, v5, v5
	v_mul_f32_e32 v13, v13, v13
	v_fmac_f32_e32 v2, v4, v4
	v_mul_f32_e32 v11, v11, v11
	v_fmac_f32_e32 v13, v12, v12
	v_mul_f32_e32 v12, v15, v15
	v_mul_f32_e32 v15, v17, v17
	v_add_f32_e32 v2, v3, v2
	v_mul_f32_e32 v3, v7, v7
	v_mul_f32_e32 v4, v9, v9
	v_fmac_f32_e32 v15, v16, v16
	v_fmac_f32_e32 v3, v6, v6
	v_fmac_f32_e32 v4, v8, v8
	v_fmac_f32_e32 v11, v10, v10
	v_fmac_f32_e32 v12, v14, v14
	v_add_f32_e32 v3, v3, v4
	v_add_f32_e32 v4, v11, v13
	v_add_f32_e32 v5, v12, v15
	v_add_f32_e32 v2, v4, v2
	v_add_f32_e32 v3, v5, v3
	ds_bpermute_b32 v4, v204, v2
	ds_bpermute_b32 v5, v204, v3
	s_waitcnt lgkmcnt(1)
	v_add_f32_e32 v2, v2, v4
	s_waitcnt lgkmcnt(0)
	v_add_f32_e32 v5, v3, v5
	ds_bpermute_b32 v4, v205, v2
	ds_bpermute_b32 v6, v205, v5
	s_waitcnt lgkmcnt(1)
	v_add_f32_e32 v2, v2, v4
	s_waitcnt lgkmcnt(0)
	v_add_f32_e32 v4, v5, v6
	ds_bpermute_b32 v3, v206, v2
	ds_bpermute_b32 v5, v206, v4
	v_add_u32_e32 v6, 0x1040, v22
	v_cndmask_b32_e64 v6, v22, v6, s[38:39]
	global_store_dwordx2 v6, v[246:247], s[54:55] nt
	s_and_saveexec_b64 s[16:17], s[42:43]
	s_cbranch_execz .LBB0_400
	s_waitcnt lgkmcnt(1)
	v_add_f32_e32 v2, v2, v3
	s_waitcnt lgkmcnt(0)
	v_add_f32_e32 v3, v4, v5
	ds_write2_b32 v194, v2, v3 offset0:112 offset1:120

; #define LAS __attribute__((address_space(3)))
; #define ERN_EOFF(q, m) (eb + (unsigned)((((q) & 1) * HALF + (m) * 16) * DM + ERN_COL((q) >> 1)))
;     __device__ __forceinline__ void operator()(const f32x4 (&acc)[2][2][4][2], const Unit& u, int wr, int wc, int fr, int fq) const {
;         const int s = u.pm >> 5, lane = fq * 16 + fr, rr = lane >> 3, pc = lane & 7;
;         const float* __restrict__ xi = xin + (size_t)u.pm * BM * DM; float* __restrict__ xo = xout + (size_t)u.pm * BM * DM; bf16_t* __restrict__ ho = Hn + (size_t)u.pm * BM * DM;
;         LAS unsigned char* st = lds_epi + (wr * 4 + wc) * 2304;
;         LAS float* sst = (LAS float*)(lds_epi + 18432 + (wr * 4 + wc) * 512);
;         const int colr = u.pn * BM + wc * 64 + 4 * pc;
;         const unsigned eb = (unsigned)((wr * 64 + rr) * DM + colr);
;         f32x4 gv[2], gsn[2];
; #pragma unroll
;         for (int bj = 0; bj < 2; ++bj) { gv[bj] = *(const f32x4*)(gate + (size_t)s * MODW + colr + bj * 32) * (0.5f * GS2);
;             if (!PLAIN) gsn[bj] = *(const f32x4*)(gnext + colr + bj * 32) * (*(const f32x4*)(scnext + (size_t)s * MODW + colr + bj * 32) + 1.0f); else gsn[bj] = gv[bj]; }
;         const unsigned wr_off = (unsigned)(fr * 144 + 16 * fq), rd_off = (unsigned)(rr * 144 + pc * 16);
;         const bool odd = (rr & 1) != 0;
;         f32x4 xb[2][2][2];
;     ...
;         ERN_LOADX(0);
; #pragma unroll
;         for (int g = 0; g < 8; ++g) { const int ai = g >> 2, m = g & 3;
;             if (g + 1 < 8) ERN_LOADX(g + 1);
;             float sq0 = 0.f, sq1 = 0.f; u32x2 hw[2][2];
; #pragma unroll
;             for (int bj = 0; bj < 2; ++bj) {
;                 *(LAS f32x4*)(st + wr_off) = acc[ai][bj][m][0]; *(LAS f32x4*)(st + wr_off + 64) = acc[ai][bj][m][1];
;                 const f32x4 a0 = *(const LAS f32x4*)(st + rd_off), a1 = *(const LAS f32x4*)(st + rd_off + 8 * 144);
;                 { const f32x4 xv = xb[g & 1][bj][0] + gv[bj] * a0; __builtin_nontemporal_store(xv, (f32x4*)((char*)xo + 4u * ERN_EOFF(g, bj, 0)));
;                   sq0 += (xv.x * xv.x + xv.y * xv.y) + (xv.z * xv.z + xv.w * xv.w);
;                   const f32x4 hv = xv * gsn[bj]; hw[bj][0].x = cvt_pk_bf16(hv.x, hv.y); hw[bj][0].y = cvt_pk_bf16(hv.z, hv.w); }
;                 { const f32x4 xv = xb[g & 1][bj][1] + gv[bj] * a1; __builtin_nontemporal_store(xv, (f32x4*)((char*)xo + 4u * ERN_EOFF(g, bj, 1)));
.LBB0_1253:
	s_ashr_i32 s0, s92, 5
	s_ashr_i32 s93, s92, 31
	v_lshl_or_b32 v50, s46, 8, v192
	s_mul_hi_i32 s15, s0, 0x12000
	s_mul_i32 s0, s0, 0x12000
	s_add_u32 s16, s35, s0
	v_ashrrev_i32_e32 v51, 31, v50
	s_addc_u32 s17, s36, s15
	v_lshlrev_b64 v[52:53], 2, v[50:51]
	v_lshl_add_u64 v[138:139], s[16:17], 0, v[52:53]
	s_add_u32 s16, s37, s0
	s_addc_u32 s17, s52, s15
	v_lshl_add_u64 v[140:141], s[8:9], 0, v[52:53]
	v_lshl_add_u64 v[52:53], s[16:17], 0, v[52:53]
	s_lshl_b64 s[16:17], s[92:93], 21
	s_add_u32 s48, s90, s16
	v_add_u32_e32 v202, v50, v193
	s_addc_u32 s49, s91, s17
	v_lshlrev_b32_e32 v205, 2, v202
	global_load_dwordx4 v[54:57], v[138:139], off
	global_load_dwordx4 v[174:177], v[140:141], off
	global_load_dwordx4 v[178:181], v[52:53], off
	global_load_dwordx4 v[206:209], v[52:53], off offset:128
	global_load_dwordx4 v[186:189], v205, s[48:49]
	v_add_u32_e32 v50, 0x10000, v205
	global_load_dwordx4 v[210:213], v50, s[48:49]
	global_load_dwordx4 v[214:217], v[140:141], off offset:128
	s_nop 0
	global_load_dwordx4 v[50:53], v[138:139], off offset:128
	global_load_dwordx4 v[218:221], v205, s[48:49] offset:128
	v_add_u32_e32 v204, 0x10080, v205
	global_load_dwordx4 v[222:225], v204, s[48:49]
	v_add_u32_e32 v138, 0x20000, v205
	v_add_u32_e32 v162, 0x30000, v205
	v_add_u32_e32 v184, 0x20080, v205
	v_add_u32_e32 v182, 0x30080, v205
	global_load_dwordx4 v[150:153], v138, s[48:49]
	global_load_dwordx4 v[146:149], v162, s[48:49]
	global_load_dwordx4 v[142:145], v184, s[48:49]
	s_nop 0
	global_load_dwordx4 v[138:141], v182, s[48:49]
	ds_write_b128 v200, v[134:137]
	ds_write_b128 v200, v[130:133] offset:64
	v_and_b32_e32 v135, 64, v199
	ds_read_b128 v[130:133], v201
	ds_read_b128 v[226:229], v201 offset:1152
	v_xor_b32_e32 v134, 8, v199
	v_add_u32_e32 v183, 64, v135
	v_cmp_lt_i32_e32 vcc, v134, v183
	v_add_u32_e32 v185, 0x4000, v202
	v_lshlrev_b32_e32 v230, 2, v185
	v_cndmask_b32_e32 v134, v199, v134, vcc
	v_lshlrev_b32_e32 v203, 2, v134
	s_lshl_b64 s[16:17], s[92:93], 20
	v_readlane_b32 s0, v252, 41
	s_add_u32 s46, s0, s16
	v_readlane_b32 s0, v252, 42
	s_addc_u32 s47, s0, s17
	s_waitcnt vmcnt(0)
	v_pk_add_f32 v[134:135], v[180:181], 1.0 op_sel_hi:[1,0]
	v_pk_add_f32 v[136:137], v[178:179], 1.0 op_sel_hi:[1,0]
	v_pk_mul_f32 v[178:179], v[176:177], v[134:135]
	v_pk_mul_f32 v[180:181], v[174:175], v[136:137]
	s_waitcnt lgkmcnt(1)
	v_pk_fma_f32 v[134:135], v[54:55], v[130:131], v[186:187]
	s_waitcnt lgkmcnt(0)
	v_pk_fma_f32 v[130:131], v[54:55], v[226:227], v[210:211]
	v_pk_fma_f32 v[136:137], v[56:57], v[132:133], v[188:189]
	v_pk_fma_f32 v[132:133], v[56:57], v[228:229], v[212:213]
	v_pk_mul_f32 v[186:187], v[180:181], v[130:131]
	v_pk_add_f32 v[190:191], v[208:209], 1.0 op_sel_hi:[1,0]
	global_store_dwordx4 v205, v[134:137], s[48:49] nt
	v_pk_mul_f32 v[174:175], v[178:179], v[136:137]
	v_pk_mul_f32 v[176:177], v[180:181], v[134:135]
	v_pk_mul_f32 v[208:209], v[178:179], v[132:133]
	v_cvt_pk_bf16_f32 v188, v176, v177
	v_cvt_pk_bf16_f32 v189, v174, v175
	global_store_dwordx4 v230, v[130:133], s[48:49] nt
	v_cvt_pk_bf16_f32 v186, v186, v187
	v_cvt_pk_bf16_f32 v187, v208, v209
	ds_write_b128 v200, v[126:129]
	ds_write_b128 v200, v[122:125] offset:64
	ds_read_b128 v[122:125], v201
	v_pk_add_f32 v[126:127], v[206:207], 1.0 op_sel_hi:[1,0]
	ds_read_b128 v[206:209], v201 offset:1152
	v_pk_mul_f32 v[174:175], v[216:217], v[190:191]
	v_pk_mul_f32 v[176:177], v[214:215], v[126:127]
	s_waitcnt lgkmcnt(1)
	v_pk_fma_f32 v[128:129], v[52:53], v[124:125], v[220:221]
	v_pk_fma_f32 v[126:127], v[50:51], v[122:123], v[218:219]
	s_waitcnt lgkmcnt(0)
	v_pk_fma_f32 v[122:123], v[50:51], v[206:207], v[222:223]
	v_pk_mul_f32 v[190:191], v[174:175], v[128:129]
	v_pk_mul_f32 v[206:207], v[176:177], v[126:127]
	global_store_dwordx4 v205, v[126:129], s[48:49] offset:128 nt
	v_cvt_pk_bf16_f32 v206, v206, v207
	v_cvt_pk_bf16_f32 v191, v190, v191
	ds_bpermute_b32 v190, v203, v206
	ds_bpermute_b32 v191, v203, v191
	v_pk_fma_f32 v[124:125], v[52:53], v[208:209], v[224:225]
	v_pk_mul_f32 v[206:207], v[176:177], v[122:123]
	global_store_dwordx4 v204, v[122:125], s[48:49] nt
	v_cvt_pk_bf16_f32 v204, v206, v207
	v_lshlrev_b32_e32 v207, 1, v202
	v_pk_mul_f32 v[208:209], v[174:175], v[124:125]
	s_nop 0
	v_cvt_pk_bf16_f32 v206, v208, v209
	s_waitcnt lgkmcnt(0)
	v_add_u32_e32 v250, 0xfffff040, v207
	v_cndmask_b32_e64 v250, v207, v250, s[40:41]
	v_cndmask_b32_e64 v248, v188, v190, s[40:41]
	v_cndmask_b32_e64 v249, v189, v191, s[40:41]
	global_store_dwordx2 v250, v[248:249], s[46:47] nt
	v_cndmask_b32_e64 v246, v190, v188, s[40:41]
	v_cndmask_b32_e64 v247, v191, v189, s[40:41]
	s_waitcnt lgkmcnt(1)
	v_add_u32_e32 v190, 0x1040, v207
	v_cndmask_b32_e64 v190, v207, v190, s[38:39]
	global_store_dwordx2 v190, v[246:247], s[46:47] nt
	ds_bpermute_b32 v188, v203, v204
	ds_bpermute_b32 v189, v203, v206
	v_lshlrev_b32_e32 v206, 1, v185
	s_and_saveexec_b64 s[16:17], s[40:41]
	v_readlane_b32 s60, v252, 4
	v_readlane_b32 s58, v252, 10
	s_xor_b64 s[16:17], exec, s[16:17]
	v_readlane_b32 s61, v252, 5
	v_readlane_b32 s59, v252, 11
	s_cbranch_execz .LBB0_1259
	v_lshlrev_b32_e32 v206, 1, v185
	v_add_u32_e32 v185, 0xfffff040, v206
	s_waitcnt lgkmcnt(0)
	global_store_dwordx2 v185, v[188:189], s[46:47] nt
.LBB0_1259:
	s_andn2_saveexec_b64 s[16:17], s[16:17]
	s_cbranch_execz .LBB0_1261
	global_store_dwordx2 v206, v[186:187], s[46:47] nt
	s_waitcnt lgkmcnt(0)
	v_mov_b64_e32 v[186:187], v[188:189]
; #define LAS __attribute__((address_space(3)))
; #define ERN_EOFF(q, m) (eb + (unsigned)((((q) & 1) * HALF + (m) * 16) * DM + ERN_COL((q) >> 1)))
;     __device__ __forceinline__ void operator()(const f32x4 (&acc)[2][2][4][2], const Unit& u, int wr, int wc, int fr, int fq) const {
;     ...
;         for (int g = 0; g < 8; ++g) { const int ai = g >> 2, m = g & 3;
;             if (g + 1 < 8) ERN_LOADX(g + 1);
;             float sq0 = 0.f, sq1 = 0.f; u32x2 hw[2][2];
; #pragma unroll
;             for (int bj = 0; bj < 2; ++bj) {
;                 *(LAS f32x4*)(st + wr_off) = acc[ai][bj][m][0]; *(LAS f32x4*)(st + wr_off + 64) = acc[ai][bj][m][1];
;                 const f32x4 a0 = *(const LAS f32x4*)(st + rd_off), a1 = *(const LAS f32x4*)(st + rd_off + 8 * 144);
;                 { const f32x4 xv = xb[g & 1][bj][0] + gv[bj] * a0; __builtin_nontemporal_store(xv, (f32x4*)((char*)xo + 4u * ERN_EOFF(g, bj, 0)));
;                   sq0 += (xv.x * xv.x + xv.y * xv.y) + (xv.z * xv.z + xv.w * xv.w);
;                   const f32x4 hv = xv * gsn[bj]; hw[bj][0].x = cvt_pk_bf16(hv.x, hv.y); hw[bj][0].y = cvt_pk_bf16(hv.z, hv.w); }
;                 { const f32x4 xv = xb[g & 1][bj][1] + gv[bj] * a1; __builtin_nontemporal_store(xv, (f32x4*)((char*)xo + 4u * ERN_EOFF(g, bj, 1)));
;                   sq1 += (xv.x * xv.x + xv.y * xv.y) + (xv.z * xv.z + xv.w * xv.w);
;                   const f32x4 hv = xv * gsn[bj]; hw[bj][1].x = cvt_pk_bf16(hv.x, hv.y); hw[bj][1].y = cvt_pk_bf16(hv.z, hv.w); }
;             }
;             if (!NOH && !PLAIN) {
; #pragma unroll
;                 for (int rh = 0; rh < 2; ++rh) { u32x2 rv; rv.x = __shfl_xor(hw[1][rh].x, 8); rv.y = __shfl_xor(hw[1][rh].y, 8);
;                     const unsigned e0 = ERN_EOFF(g, 0, rh);
;                     const unsigned ee = odd ? (e0 - DM + 32) : e0, eo2 = odd ? e0 : (e0 + DM + 32);
;                     *(u32x2*)((char*)ho + 2u * ee) = odd ? rv : hw[0][rh];
;                     *(u32x2*)((char*)ho + 2u * eo2) = odd ? hw[0][rh] : rv; }
;             }
;             if (!PLAIN) { sq0 += __shfl_xor(sq0, 1); sq0 += __shfl_xor(sq0, 2); sq0 += __shfl_xor(sq0, 4);
;             sq1 += __shfl_xor(sq1, 1); sq1 += __shfl_xor(sq1, 2); sq1 += __shfl_xor(sq1, 4); }
;             if (!PLAIN && pc == 0) { sst[g * 16 + rr] = sq0; sst[g * 16 + 8 + rr] = sq1; }
.LBB0_1261:
	s_or_b64 exec, exec, s[16:17]
	v_mul_f32_e32 v127, v127, v127
	v_mul_f32_e32 v135, v135, v135
	v_mul_f32_e32 v137, v137, v137
	v_fmac_f32_e32 v127, v126, v126
	v_mul_f32_e32 v126, v129, v129
	v_fmac_f32_e32 v137, v136, v136
	v_fmac_f32_e32 v126, v128, v128
	v_mul_f32_e32 v123, v123, v123
	v_fmac_f32_e32 v135, v134, v134
	v_add_f32_e32 v126, v127, v126
	v_fmac_f32_e32 v123, v122, v122
	v_mul_f32_e32 v122, v125, v125
	v_add_f32_e32 v125, v135, v137
	v_add_f32_e32 v125, v125, v126
	v_xor_b32_e32 v126, 1, v199
	v_cmp_lt_i32_e32 vcc, v126, v183
	v_mul_f32_e32 v131, v131, v131
	v_mul_f32_e32 v133, v133, v133
	v_cndmask_b32_e32 v126, v199, v126, vcc
	v_lshlrev_b32_e32 v190, 2, v126
	ds_bpermute_b32 v126, v190, v125
	v_fmac_f32_e32 v122, v124, v124
	v_fmac_f32_e32 v133, v132, v132
	v_fmac_f32_e32 v131, v130, v130
	v_add_f32_e32 v122, v123, v122
	s_waitcnt lgkmcnt(0)
	v_add_f32_e32 v124, v125, v126
	v_xor_b32_e32 v125, 2, v199
	v_cmp_lt_i32_e32 vcc, v125, v183
	v_add_f32_e32 v123, v131, v133
	v_add_f32_e32 v123, v123, v122
	v_cndmask_b32_e32 v125, v199, v125, vcc
	v_lshlrev_b32_e32 v191, 2, v125
	ds_bpermute_b32 v125, v191, v124
	ds_bpermute_b32 v126, v190, v123
	s_waitcnt lgkmcnt(1)
	v_add_f32_e32 v122, v124, v125
	s_waitcnt lgkmcnt(0)
	v_add_f32_e32 v125, v123, v126
	ds_bpermute_b32 v126, v191, v125
	v_xor_b32_e32 v124, 4, v199
	v_cmp_lt_i32_e32 vcc, v124, v183
	s_nop 1
	v_cndmask_b32_e32 v123, v199, v124, vcc
	v_lshlrev_b32_e32 v204, 2, v123
	s_waitcnt lgkmcnt(0)
	v_add_f32_e32 v124, v125, v126
	ds_bpermute_b32 v123, v204, v122
	ds_bpermute_b32 v125, v204, v124
	v_add_u32_e32 v126, 0x1040, v206
	v_cndmask_b32_e64 v126, v206, v126, s[38:39]
	global_store_dwordx2 v126, v[186:187], s[46:47] nt
	s_and_saveexec_b64 s[16:17], s[42:43]
	s_cbranch_execz .LBB0_1263
	s_waitcnt lgkmcnt(1)
	v_add_f32_e32 v122, v122, v123
	s_waitcnt lgkmcnt(0)
	v_add_f32_e32 v123, v124, v125
	ds_write2_b32 v194, v122, v123 offset1:8
.LBB0_1263:
	s_or_b64 exec, exec, s[16:17]
	v_lshl_add_u64 v[206:207], s[48:49], 0, v[162:163]
	v_add_u32_e32 v122, 0x40000, v205
	v_add_u32_e32 v162, 0x50000, v205
	v_add_u32_e32 v186, 0x40080, v205
	global_load_dwordx4 v[130:133], v162, s[48:49]
	global_load_dwordx4 v[126:129], v186, s[48:49]
	v_add_u32_e32 v188, 0x50080, v205
	global_load_dwordx4 v[134:137], v122, s[48:49]
	s_waitcnt lgkmcnt(0)
	global_load_dwordx4 v[122:125], v188, s[48:49]
	ds_write_b128 v200, v[118:121]
	ds_write_b128 v200, v[114:117] offset:64
	ds_read_b128 v[114:117], v201
	ds_read_b128 v[118:121], v201 offset:1152
	v_mov_b32_e32 v185, v163
	v_mov_b32_e32 v183, v163
	v_lshl_add_u64 v[182:183], s[48:49], 0, v[182:183]
	s_waitcnt lgkmcnt(1)
	v_pk_fma_f32 v[116:117], v[56:57], v[116:117], v[152:153]
	v_add_u32_e32 v152, 0x8000, v202
	v_pk_fma_f32 v[114:115], v[54:55], v[114:115], v[150:151]
	v_lshlrev_b32_e32 v150, 2, v152
	s_waitcnt lgkmcnt(0)
	v_pk_fma_f32 v[118:119], v[54:55], v[118:119], v[146:147]
	global_store_dwordx4 v150, v[114:117], s[48:49] nt
	v_pk_mul_f32 v[150:151], v[180:181], v[114:115]
	v_pk_fma_f32 v[120:121], v[56:57], v[120:121], v[148:149]
	v_pk_mul_f32 v[146:147], v[180:181], v[118:119]
	v_pk_mul_f32 v[208:209], v[178:179], v[116:117]
	v_cvt_pk_bf16_f32 v150, v150, v151
	v_pk_mul_f32 v[148:149], v[178:179], v[120:121]
	v_cvt_pk_bf16_f32 v151, v208, v209
	global_store_dwordx4 v[206:207], v[118:121], off nt
	v_cvt_pk_bf16_f32 v146, v146, v147
	v_cvt_pk_bf16_f32 v147, v148, v149
	ds_write_b128 v200, v[110:113]
	ds_write_b128 v200, v[106:109] offset:64
	ds_read_b128 v[106:109], v201
	ds_read_b128 v[110:113], v201 offset:1152
	v_lshl_add_u64 v[148:149], s[48:49], 0, v[184:185]
	s_waitcnt lgkmcnt(1)
	v_pk_fma_f32 v[106:107], v[50:51], v[106:107], v[142:143]
	v_pk_fma_f32 v[108:109], v[52:53], v[108:109], v[144:145]
	v_pk_mul_f32 v[144:145], v[176:177], v[106:107]
	global_store_dwordx4 v[148:149], v[106:109], off nt
	v_pk_mul_f32 v[142:143], v[174:175], v[108:109]
	v_cvt_pk_bf16_f32 v144, v144, v145
	s_waitcnt lgkmcnt(0)
	v_pk_fma_f32 v[110:111], v[50:51], v[110:111], v[138:139]
	v_cvt_pk_bf16_f32 v145, v142, v143
	ds_bpermute_b32 v138, v203, v144
	ds_bpermute_b32 v139, v203, v145
	v_pk_fma_f32 v[112:113], v[52:53], v[112:113], v[140:141]
	v_pk_mul_f32 v[140:141], v[176:177], v[110:111]
	v_pk_mul_f32 v[142:143], v[174:175], v[112:113]
	global_store_dwordx4 v[182:183], v[110:113], off nt
	v_cvt_pk_bf16_f32 v140, v140, v141
	v_cvt_pk_bf16_f32 v141, v142, v143
	v_lshlrev_b32_e32 v142, 1, v152
	s_waitcnt lgkmcnt(0)
	v_add_u32_e32 v250, 0xfffff040, v142
	v_cndmask_b32_e64 v250, v142, v250, s[40:41]
	v_cndmask_b32_e64 v248, v150, v138, s[40:41]
	v_cndmask_b32_e64 v249, v151, v139, s[40:41]
	global_store_dwordx2 v250, v[248:249], s[46:47] nt
	v_cndmask_b32_e64 v246, v138, v150, s[40:41]
	v_cndmask_b32_e64 v247, v139, v151, s[40:41]
	s_waitcnt lgkmcnt(1)
	v_add_u32_e32 v138, 0x1040, v142
	v_cndmask_b32_e64 v138, v142, v138, s[38:39]
	global_store_dwordx2 v138, v[246:247], s[46:47] nt
	ds_bpermute_b32 v138, v203, v140
	s_waitcnt lgkmcnt(1)
	ds_bpermute_b32 v139, v203, v141
	v_add_u32_e32 v141, 0xc000, v202
	v_lshlrev_b32_e32 v140, 1, v141
	s_waitcnt lgkmcnt(0)
	v_add_u32_e32 v250, 0xfffff040, v140
	v_cndmask_b32_e64 v250, v140, v250, s[40:41]
	v_cndmask_b32_e64 v248, v146, v138, s[40:41]
	v_cndmask_b32_e64 v249, v147, v139, s[40:41]
	global_store_dwordx2 v250, v[248:249], s[46:47] nt
	v_cndmask_b32_e64 v246, v138, v146, s[40:41]
	v_cndmask_b32_e64 v247, v139, v147, s[40:41]
	v_mul_f32_e32 v107, v107, v107
	v_fmac_f32_e32 v107, v106, v106
	v_mul_f32_e32 v106, v109, v109
	v_mul_f32_e32 v117, v117, v117
	v_fmac_f32_e32 v106, v108, v108
	v_mul_f32_e32 v115, v115, v115
	v_fmac_f32_e32 v117, v116, v116
	v_mul_f32_e32 v116, v119, v119
	v_mul_f32_e32 v119, v121, v121
	v_add_f32_e32 v106, v107, v106
	v_mul_f32_e32 v107, v111, v111
	v_mul_f32_e32 v108, v113, v113
	v_fmac_f32_e32 v119, v120, v120
	v_fmac_f32_e32 v107, v110, v110
	v_fmac_f32_e32 v108, v112, v112
	v_fmac_f32_e32 v115, v114, v114
	v_fmac_f32_e32 v116, v118, v118
	v_add_f32_e32 v107, v107, v108
	v_add_f32_e32 v108, v115, v117
	v_add_f32_e32 v109, v116, v119
	v_add_f32_e32 v106, v108, v106
	v_add_f32_e32 v107, v109, v107
	ds_bpermute_b32 v108, v190, v106
	ds_bpermute_b32 v109, v190, v107
	s_waitcnt lgkmcnt(1)
	v_add_f32_e32 v106, v106, v108
	s_waitcnt lgkmcnt(0)
	v_add_f32_e32 v109, v107, v109
	ds_bpermute_b32 v108, v191, v106
	ds_bpermute_b32 v110, v191, v109
	s_waitcnt lgkmcnt(1)
	v_add_f32_e32 v106, v106, v108
	s_waitcnt lgkmcnt(0)
	v_add_f32_e32 v108, v109, v110
	ds_bpermute_b32 v107, v204, v106
	ds_bpermute_b32 v109, v204, v108
	v_add_u32_e32 v110, 0x1040, v140
	v_cndmask_b32_e64 v110, v140, v110, s[38:39]
	global_store_dwordx2 v110, v[246:247], s[46:47] nt
	s_and_saveexec_b64 s[16:17], s[42:43]
	s_cbranch_execz .LBB0_1273
	s_waitcnt lgkmcnt(1)
	v_add_f32_e32 v106, v106, v107
	s_waitcnt lgkmcnt(0)
	v_add_f32_e32 v107, v108, v109
	ds_write2_b32 v194, v106, v107 offset0:16 offset1:24
; #define LAS __attribute__((address_space(3)))
; #define ERN_EOFF(q, m) (eb + (unsigned)((((q) & 1) * HALF + (m) * 16) * DM + ERN_COL((q) >> 1)))
;     __device__ __forceinline__ void operator()(const f32x4 (&acc)[2][2][4][2], const Unit& u, int wr, int wc, int fr, int fq) const {
;     ...
;         for (int g = 0; g < 8; ++g) { const int ai = g >> 2, m = g & 3;
;             if (g + 1 < 8) ERN_LOADX(g + 1);
;             float sq0 = 0.f, sq1 = 0.f; u32x2 hw[2][2];
; #pragma unroll
;             for (int bj = 0; bj < 2; ++bj) {
;                 *(LAS f32x4*)(st + wr_off) = acc[ai][bj][m][0]; *(LAS f32x4*)(st + wr_off + 64) = acc[ai][bj][m][1];
;                 const f32x4 a0 = *(const LAS f32x4*)(st + rd_off), a1 = *(const LAS f32x4*)(st + rd_off + 8 * 144);
;                 { const f32x4 xv = xb[g & 1][bj][0] + gv[bj] * a0; __builtin_nontemporal_store(xv, (f32x4*)((char*)xo + 4u * ERN_EOFF(g, bj, 0)));
;                   sq0 += (xv.x * xv.x + xv.y * xv.y) + (xv.z * xv.z + xv.w * xv.w);
;                   const f32x4 hv = xv * gsn[bj]; hw[bj][0].x = cvt_pk_bf16(hv.x, hv.y); hw[bj][0].y = cvt_pk_bf16(hv.z, hv.w); }
;                 { const f32x4 xv = xb[g & 1][bj][1] + gv[bj] * a1; __builtin_nontemporal_store(xv, (f32x4*)((char*)xo + 4u * ERN_EOFF(g, bj, 1)));
;                   sq1 += (xv.x * xv.x + xv.y * xv.y) + (xv.z * xv.z + xv.w * xv.w);
;                   const f32x4 hv = xv * gsn[bj]; hw[bj][1].x = cvt_pk_bf16(hv.x, hv.y); hw[bj][1].y = cvt_pk_bf16(hv.z, hv.w); }
;             }
;             if (!NOH && !PLAIN) {
; #pragma unroll
;                 for (int rh = 0; rh < 2; ++rh) { u32x2 rv; rv.x = __shfl_xor(hw[1][rh].x, 8); rv.y = __shfl_xor(hw[1][rh].y, 8);
;                     const unsigned e0 = ERN_EOFF(g, 0, rh);
;                     const unsigned ee = odd ? (e0 - DM + 32) : e0, eo2 = odd ? e0 : (e0 + DM + 32);
;                     *(u32x2*)((char*)ho + 2u * ee) = odd ? rv : hw[0][rh];
;                     *(u32x2*)((char*)ho + 2u * eo2) = odd ? hw[0][rh] : rv; }
;             }
;             if (!PLAIN) { sq0 += __shfl_xor(sq0, 1); sq0 += __shfl_xor(sq0, 2); sq0 += __shfl_xor(sq0, 4);
;             sq1 += __shfl_xor(sq1, 1); sq1 += __shfl_xor(sq1, 2); sq1 += __shfl_xor(sq1, 4); }
;             if (!PLAIN && pc == 0) { sst[g * 16 + rr] = sq0; sst[g * 16 + 8 + rr] = sq1; }
.LBB0_1273:
	s_or_b64 exec, exec, s[16:17]
	v_lshl_add_u64 v[142:143], s[48:49], 0, v[162:163]
	v_add_u32_e32 v106, 0x60000, v205
	v_add_u32_e32 v162, 0x70000, v205
	v_add_u32_e32 v138, 0x60080, v205
	global_load_dwordx4 v[114:117], v162, s[48:49]
	global_load_dwordx4 v[110:113], v138, s[48:49]
	v_add_u32_e32 v140, 0x70080, v205
	global_load_dwordx4 v[118:121], v106, s[48:49]
	s_waitcnt lgkmcnt(0)
	global_load_dwordx4 v[106:109], v140, s[48:49]
	ds_write_b128 v200, v[102:105]
	ds_write_b128 v200, v[98:101] offset:64
	ds_read_b128 v[98:101], v201
	ds_read_b128 v[102:105], v201 offset:1152
	v_mov_b32_e32 v187, v163
	v_mov_b32_e32 v189, v163
	s_waitcnt vmcnt(11) lgkmcnt(1)
	v_pk_fma_f32 v[100:101], v[56:57], v[100:101], v[136:137]
	v_add_u32_e32 v136, 0x10000, v202
	v_pk_fma_f32 v[98:99], v[54:55], v[98:99], v[134:135]
	v_lshlrev_b32_e32 v134, 2, v136
	s_waitcnt lgkmcnt(0)
	v_pk_fma_f32 v[102:103], v[54:55], v[102:103], v[130:131]
	global_store_dwordx4 v134, v[98:101], s[48:49] nt
	v_pk_mul_f32 v[134:135], v[180:181], v[98:99]
	v_pk_fma_f32 v[104:105], v[56:57], v[104:105], v[132:133]
	v_pk_mul_f32 v[130:131], v[180:181], v[102:103]
	v_pk_mul_f32 v[144:145], v[178:179], v[100:101]
	v_cvt_pk_bf16_f32 v134, v134, v135
	v_pk_mul_f32 v[132:133], v[178:179], v[104:105]
	v_cvt_pk_bf16_f32 v135, v144, v145
	global_store_dwordx4 v[142:143], v[102:105], off nt
	v_cvt_pk_bf16_f32 v130, v130, v131
	v_cvt_pk_bf16_f32 v131, v132, v133
	ds_write_b128 v200, v[94:97]
	ds_write_b128 v200, v[90:93] offset:64
	ds_read_b128 v[90:93], v201
	ds_read_b128 v[94:97], v201 offset:1152
	v_lshl_add_u64 v[132:133], s[48:49], 0, v[186:187]
	v_lshl_add_u64 v[142:143], s[48:49], 0, v[188:189]
	s_waitcnt lgkmcnt(1)
	v_pk_fma_f32 v[90:91], v[50:51], v[90:91], v[126:127]
	v_pk_fma_f32 v[92:93], v[52:53], v[92:93], v[128:129]
	v_pk_mul_f32 v[128:129], v[176:177], v[90:91]
	global_store_dwordx4 v[132:133], v[90:93], off nt
	v_pk_mul_f32 v[126:127], v[174:175], v[92:93]
	v_cvt_pk_bf16_f32 v128, v128, v129
	s_waitcnt vmcnt(13) lgkmcnt(0)
	v_pk_fma_f32 v[94:95], v[50:51], v[94:95], v[122:123]
	v_cvt_pk_bf16_f32 v129, v126, v127
	ds_bpermute_b32 v122, v203, v128
	ds_bpermute_b32 v123, v203, v129
	v_pk_fma_f32 v[96:97], v[52:53], v[96:97], v[124:125]
	v_pk_mul_f32 v[124:125], v[176:177], v[94:95]
	v_pk_mul_f32 v[126:127], v[174:175], v[96:97]
	global_store_dwordx4 v[142:143], v[94:97], off nt
	v_cvt_pk_bf16_f32 v124, v124, v125
	v_cvt_pk_bf16_f32 v125, v126, v127
	v_lshlrev_b32_e32 v126, 1, v136
	s_waitcnt lgkmcnt(0)
	v_add_u32_e32 v250, 0xfffff040, v126
	v_cndmask_b32_e64 v250, v126, v250, s[40:41]
	v_cndmask_b32_e64 v248, v134, v122, s[40:41]
	v_cndmask_b32_e64 v249, v135, v123, s[40:41]
	global_store_dwordx2 v250, v[248:249], s[46:47] nt
	v_cndmask_b32_e64 v246, v122, v134, s[40:41]
	v_cndmask_b32_e64 v247, v123, v135, s[40:41]
	s_waitcnt lgkmcnt(1)
	v_add_u32_e32 v122, 0x1040, v126
	v_cndmask_b32_e64 v122, v126, v122, s[38:39]
	global_store_dwordx2 v122, v[246:247], s[46:47] nt
	ds_bpermute_b32 v122, v203, v124
	s_waitcnt lgkmcnt(1)
	ds_bpermute_b32 v123, v203, v125
	v_add_u32_e32 v125, 0x14000, v202
	v_lshlrev_b32_e32 v124, 1, v125
	s_waitcnt lgkmcnt(0)
	v_add_u32_e32 v250, 0xfffff040, v124
	v_cndmask_b32_e64 v250, v124, v250, s[40:41]
	v_cndmask_b32_e64 v248, v130, v122, s[40:41]
	v_cndmask_b32_e64 v249, v131, v123, s[40:41]
	global_store_dwordx2 v250, v[248:249], s[46:47] nt
	v_cndmask_b32_e64 v246, v122, v130, s[40:41]
	v_cndmask_b32_e64 v247, v123, v131, s[40:41]
	v_mul_f32_e32 v91, v91, v91
	v_fmac_f32_e32 v91, v90, v90
	v_mul_f32_e32 v90, v93, v93
	v_mul_f32_e32 v101, v101, v101
	v_fmac_f32_e32 v90, v92, v92
	v_mul_f32_e32 v99, v99, v99
	v_fmac_f32_e32 v101, v100, v100
	v_mul_f32_e32 v100, v103, v103
	v_mul_f32_e32 v103, v105, v105
	v_add_f32_e32 v90, v91, v90
	v_mul_f32_e32 v91, v95, v95
	v_mul_f32_e32 v92, v97, v97
	v_fmac_f32_e32 v103, v104, v104
	v_fmac_f32_e32 v91, v94, v94
	v_fmac_f32_e32 v92, v96, v96
	v_fmac_f32_e32 v99, v98, v98
	v_fmac_f32_e32 v100, v102, v102
	v_add_f32_e32 v91, v91, v92
	v_add_f32_e32 v92, v99, v101
	v_add_f32_e32 v93, v100, v103
	v_add_f32_e32 v90, v92, v90
	v_add_f32_e32 v91, v93, v91
	ds_bpermute_b32 v92, v190, v90
	ds_bpermute_b32 v93, v190, v91
	s_waitcnt lgkmcnt(1)
	v_add_f32_e32 v90, v90, v92
	s_waitcnt lgkmcnt(0)
	v_add_f32_e32 v93, v91, v93
	ds_bpermute_b32 v92, v191, v90
	ds_bpermute_b32 v94, v191, v93
	s_waitcnt lgkmcnt(1)
	v_add_f32_e32 v90, v90, v92
	s_waitcnt lgkmcnt(0)
	v_add_f32_e32 v92, v93, v94
	ds_bpermute_b32 v91, v204, v90
	ds_bpermute_b32 v93, v204, v92
	v_add_u32_e32 v94, 0x1040, v124
	v_cndmask_b32_e64 v94, v124, v94, s[38:39]
	global_store_dwordx2 v94, v[246:247], s[46:47] nt
	s_and_saveexec_b64 s[16:17], s[42:43]
	s_cbranch_execz .LBB0_1283
	s_waitcnt lgkmcnt(1)
	v_add_f32_e32 v90, v90, v91
	s_waitcnt lgkmcnt(0)
	v_add_f32_e32 v91, v92, v93
	ds_write2_b32 v194, v90, v91 offset0:32 offset1:40
; #define LAS __attribute__((address_space(3)))
; #define ERN_EOFF(q, m) (eb + (unsigned)((((q) & 1) * HALF + (m) * 16) * DM + ERN_COL((q) >> 1)))
;     __device__ __forceinline__ void operator()(const f32x4 (&acc)[2][2][4][2], const Unit& u, int wr, int wc, int fr, int fq) const {
;     ...
;         for (int g = 0; g < 8; ++g) { const int ai = g >> 2, m = g & 3;
;             if (g + 1 < 8) ERN_LOADX(g + 1);
;             float sq0 = 0.f, sq1 = 0.f; u32x2 hw[2][2];
; #pragma unroll
;             for (int bj = 0; bj < 2; ++bj) {
;                 *(LAS f32x4*)(st + wr_off) = acc[ai][bj][m][0]; *(LAS f32x4*)(st + wr_off + 64) = acc[ai][bj][m][1];
;                 const f32x4 a0 = *(const LAS f32x4*)(st + rd_off), a1 = *(const LAS f32x4*)(st + rd_off + 8 * 144);
;                 { const f32x4 xv = xb[g & 1][bj][0] + gv[bj] * a0; __builtin_nontemporal_store(xv, (f32x4*)((char*)xo + 4u * ERN_EOFF(g, bj, 0)));
;                   sq0 += (xv.x * xv.x + xv.y * xv.y) + (xv.z * xv.z + xv.w * xv.w);
;                   const f32x4 hv = xv * gsn[bj]; hw[bj][0].x = cvt_pk_bf16(hv.x, hv.y); hw[bj][0].y = cvt_pk_bf16(hv.z, hv.w); }
;                 { const f32x4 xv = xb[g & 1][bj][1] + gv[bj] * a1; __builtin_nontemporal_store(xv, (f32x4*)((char*)xo + 4u * ERN_EOFF(g, bj, 1)));
;                   sq1 += (xv.x * xv.x + xv.y * xv.y) + (xv.z * xv.z + xv.w * xv.w);
;                   const f32x4 hv = xv * gsn[bj]; hw[bj][1].x = cvt_pk_bf16(hv.x, hv.y); hw[bj][1].y = cvt_pk_bf16(hv.z, hv.w); }
;             }
;             if (!NOH && !PLAIN) {
; #pragma unroll
;                 for (int rh = 0; rh < 2; ++rh) { u32x2 rv; rv.x = __shfl_xor(hw[1][rh].x, 8); rv.y = __shfl_xor(hw[1][rh].y, 8);
;                     const unsigned e0 = ERN_EOFF(g, 0, rh);
;                     const unsigned ee = odd ? (e0 - DM + 32) : e0, eo2 = odd ? e0 : (e0 + DM + 32);
;                     *(u32x2*)((char*)ho + 2u * ee) = odd ? rv : hw[0][rh];
;                     *(u32x2*)((char*)ho + 2u * eo2) = odd ? hw[0][rh] : rv; }
;             }
;             if (!PLAIN) { sq0 += __shfl_xor(sq0, 1); sq0 += __shfl_xor(sq0, 2); sq0 += __shfl_xor(sq0, 4);
;             sq1 += __shfl_xor(sq1, 1); sq1 += __shfl_xor(sq1, 2); sq1 += __shfl_xor(sq1, 4); }
;             if (!PLAIN && pc == 0) { sst[g * 16 + rr] = sq0; sst[g * 16 + 8 + rr] = sq1; }
.LBB0_1283:
	s_or_b64 exec, exec, s[16:17]
	v_lshl_add_u64 v[124:125], s[48:49], 0, v[162:163]
	v_add_u32_e32 v90, 0x100000, v205
	s_waitcnt lgkmcnt(1)
	v_add_u32_e32 v91, 0x110000, v205
	v_add_u32_e32 v162, 0x100080, v205
	global_load_dwordx4 v[102:105], v90, s[48:49]
	global_load_dwordx4 v[98:101], v91, s[48:49]
	v_add_u32_e32 v122, 0x110080, v205
	global_load_dwordx4 v[94:97], v162, s[48:49]
	s_waitcnt lgkmcnt(0)
	global_load_dwordx4 v[90:93], v122, s[48:49]
	ds_write_b128 v200, v[86:89]
	ds_write_b128 v200, v[82:85] offset:64
	ds_read_b128 v[82:85], v201
	ds_read_b128 v[86:89], v201 offset:1152
	v_mov_b32_e32 v139, v163
	v_mov_b32_e32 v141, v163
	s_waitcnt vmcnt(11) lgkmcnt(1)
	v_pk_fma_f32 v[84:85], v[56:57], v[84:85], v[120:121]
	v_add_u32_e32 v120, 0x18000, v202
	v_pk_fma_f32 v[82:83], v[54:55], v[82:83], v[118:119]
	v_lshlrev_b32_e32 v118, 2, v120
	s_waitcnt lgkmcnt(0)
	v_pk_fma_f32 v[86:87], v[54:55], v[86:87], v[114:115]
	global_store_dwordx4 v118, v[82:85], s[48:49] nt
	v_pk_mul_f32 v[118:119], v[180:181], v[82:83]
	v_pk_fma_f32 v[88:89], v[56:57], v[88:89], v[116:117]
	v_pk_mul_f32 v[114:115], v[180:181], v[86:87]
	v_pk_mul_f32 v[126:127], v[178:179], v[84:85]
	v_cvt_pk_bf16_f32 v118, v118, v119
	v_pk_mul_f32 v[116:117], v[178:179], v[88:89]
	v_cvt_pk_bf16_f32 v119, v126, v127
	global_store_dwordx4 v[124:125], v[86:89], off nt
	v_cvt_pk_bf16_f32 v114, v114, v115
	v_cvt_pk_bf16_f32 v115, v116, v117
	ds_write_b128 v200, v[78:81]
	ds_write_b128 v200, v[74:77] offset:64
	ds_read_b128 v[74:77], v201
	ds_read_b128 v[78:81], v201 offset:1152
	v_lshl_add_u64 v[116:117], s[48:49], 0, v[138:139]
	v_lshl_add_u64 v[124:125], s[48:49], 0, v[140:141]
	s_waitcnt lgkmcnt(1)
	v_pk_fma_f32 v[74:75], v[50:51], v[74:75], v[110:111]
	v_pk_fma_f32 v[76:77], v[52:53], v[76:77], v[112:113]
	v_pk_mul_f32 v[112:113], v[176:177], v[74:75]
	global_store_dwordx4 v[116:117], v[74:77], off nt
	v_pk_mul_f32 v[110:111], v[174:175], v[76:77]
	v_cvt_pk_bf16_f32 v112, v112, v113
	s_waitcnt vmcnt(13) lgkmcnt(0)
	v_pk_fma_f32 v[78:79], v[50:51], v[78:79], v[106:107]
	v_cvt_pk_bf16_f32 v113, v110, v111
	ds_bpermute_b32 v106, v203, v112
	ds_bpermute_b32 v107, v203, v113
	v_pk_fma_f32 v[80:81], v[52:53], v[80:81], v[108:109]
	v_pk_mul_f32 v[108:109], v[176:177], v[78:79]
	v_pk_mul_f32 v[110:111], v[174:175], v[80:81]
	global_store_dwordx4 v[124:125], v[78:81], off nt
	v_cvt_pk_bf16_f32 v108, v108, v109
	v_cvt_pk_bf16_f32 v109, v110, v111
	v_lshlrev_b32_e32 v110, 1, v120
	s_waitcnt lgkmcnt(0)
	v_add_u32_e32 v250, 0xfffff040, v110
	v_cndmask_b32_e64 v250, v110, v250, s[40:41]
	v_cndmask_b32_e64 v248, v118, v106, s[40:41]
	v_cndmask_b32_e64 v249, v119, v107, s[40:41]
	global_store_dwordx2 v250, v[248:249], s[46:47] nt
	v_cndmask_b32_e64 v246, v106, v118, s[40:41]
	v_cndmask_b32_e64 v247, v107, v119, s[40:41]
	s_waitcnt lgkmcnt(1)
	v_add_u32_e32 v106, 0x1040, v110
	v_cndmask_b32_e64 v106, v110, v106, s[38:39]
	global_store_dwordx2 v106, v[246:247], s[46:47] nt
	ds_bpermute_b32 v106, v203, v108
	s_waitcnt lgkmcnt(1)
	ds_bpermute_b32 v107, v203, v109
	v_add_u32_e32 v109, 0x1c000, v202
	v_lshlrev_b32_e32 v108, 1, v109
	s_waitcnt lgkmcnt(0)
	v_add_u32_e32 v250, 0xfffff040, v108
	v_cndmask_b32_e64 v250, v108, v250, s[40:41]
	v_cndmask_b32_e64 v248, v114, v106, s[40:41]
	v_cndmask_b32_e64 v249, v115, v107, s[40:41]
	global_store_dwordx2 v250, v[248:249], s[46:47] nt
	v_cndmask_b32_e64 v246, v106, v114, s[40:41]
	v_cndmask_b32_e64 v247, v107, v115, s[40:41]
	v_mul_f32_e32 v75, v75, v75
	v_fmac_f32_e32 v75, v74, v74
	v_mul_f32_e32 v74, v77, v77
	v_mul_f32_e32 v85, v85, v85
	v_fmac_f32_e32 v74, v76, v76
	v_mul_f32_e32 v83, v83, v83
	v_fmac_f32_e32 v85, v84, v84
	v_mul_f32_e32 v84, v87, v87
	v_mul_f32_e32 v87, v89, v89
	v_add_f32_e32 v74, v75, v74
	v_mul_f32_e32 v75, v79, v79
	v_mul_f32_e32 v76, v81, v81
	v_fmac_f32_e32 v87, v88, v88
	v_fmac_f32_e32 v75, v78, v78
	v_fmac_f32_e32 v76, v80, v80
	v_fmac_f32_e32 v83, v82, v82
	v_fmac_f32_e32 v84, v86, v86
	v_add_f32_e32 v75, v75, v76
	v_add_f32_e32 v76, v83, v85
	v_add_f32_e32 v77, v84, v87
	v_add_f32_e32 v74, v76, v74
	v_add_f32_e32 v75, v77, v75
	ds_bpermute_b32 v76, v190, v74
	ds_bpermute_b32 v77, v190, v75
	s_waitcnt lgkmcnt(1)
	v_add_f32_e32 v74, v74, v76
	s_waitcnt lgkmcnt(0)
	v_add_f32_e32 v77, v75, v77
	ds_bpermute_b32 v76, v191, v74
	ds_bpermute_b32 v78, v191, v77
	s_waitcnt lgkmcnt(1)
	v_add_f32_e32 v74, v74, v76
	s_waitcnt lgkmcnt(0)
	v_add_f32_e32 v76, v77, v78
	ds_bpermute_b32 v75, v204, v74
	ds_bpermute_b32 v77, v204, v76
	v_add_u32_e32 v78, 0x1040, v108
	v_cndmask_b32_e64 v78, v108, v78, s[38:39]
	global_store_dwordx2 v78, v[246:247], s[46:47] nt
	s_and_saveexec_b64 s[16:17], s[42:43]
	s_cbranch_execz .LBB0_1293
	s_waitcnt lgkmcnt(1)
	v_add_f32_e32 v74, v74, v75
	s_waitcnt lgkmcnt(0)
	v_add_f32_e32 v75, v76, v77
	ds_write2_b32 v194, v74, v75 offset0:48 offset1:56
; #define LAS __attribute__((address_space(3)))
; #define ERN_EOFF(q, m) (eb + (unsigned)((((q) & 1) * HALF + (m) * 16) * DM + ERN_COL((q) >> 1)))
;     __device__ __forceinline__ void operator()(const f32x4 (&acc)[2][2][4][2], const Unit& u, int wr, int wc, int fr, int fq) const {
;     ...
;         for (int g = 0; g < 8; ++g) { const int ai = g >> 2, m = g & 3;
;             if (g + 1 < 8) ERN_LOADX(g + 1);
;             float sq0 = 0.f, sq1 = 0.f; u32x2 hw[2][2];
; #pragma unroll
;             for (int bj = 0; bj < 2; ++bj) {
;                 *(LAS f32x4*)(st + wr_off) = acc[ai][bj][m][0]; *(LAS f32x4*)(st + wr_off + 64) = acc[ai][bj][m][1];
;                 const f32x4 a0 = *(const LAS f32x4*)(st + rd_off), a1 = *(const LAS f32x4*)(st + rd_off + 8 * 144);
;                 { const f32x4 xv = xb[g & 1][bj][0] + gv[bj] * a0; __builtin_nontemporal_store(xv, (f32x4*)((char*)xo + 4u * ERN_EOFF(g, bj, 0)));
;                   sq0 += (xv.x * xv.x + xv.y * xv.y) + (xv.z * xv.z + xv.w * xv.w);
;                   const f32x4 hv = xv * gsn[bj]; hw[bj][0].x = cvt_pk_bf16(hv.x, hv.y); hw[bj][0].y = cvt_pk_bf16(hv.z, hv.w); }
;                 { const f32x4 xv = xb[g & 1][bj][1] + gv[bj] * a1; __builtin_nontemporal_store(xv, (f32x4*)((char*)xo + 4u * ERN_EOFF(g, bj, 1)));
;                   sq1 += (xv.x * xv.x + xv.y * xv.y) + (xv.z * xv.z + xv.w * xv.w);
;                   const f32x4 hv = xv * gsn[bj]; hw[bj][1].x = cvt_pk_bf16(hv.x, hv.y); hw[bj][1].y = cvt_pk_bf16(hv.z, hv.w); }
;             }
;             if (!NOH && !PLAIN) {
; #pragma unroll
;                 for (int rh = 0; rh < 2; ++rh) { u32x2 rv; rv.x = __shfl_xor(hw[1][rh].x, 8); rv.y = __shfl_xor(hw[1][rh].y, 8);
;                     const unsigned e0 = ERN_EOFF(g, 0, rh);
;                     const unsigned ee = odd ? (e0 - DM + 32) : e0, eo2 = odd ? e0 : (e0 + DM + 32);
;                     *(u32x2*)((char*)ho + 2u * ee) = odd ? rv : hw[0][rh];
;                     *(u32x2*)((char*)ho + 2u * eo2) = odd ? hw[0][rh] : rv; }
;             }
;             if (!PLAIN) { sq0 += __shfl_xor(sq0, 1); sq0 += __shfl_xor(sq0, 2); sq0 += __shfl_xor(sq0, 4);
;             sq1 += __shfl_xor(sq1, 1); sq1 += __shfl_xor(sq1, 2); sq1 += __shfl_xor(sq1, 4); }
;             if (!PLAIN && pc == 0) { sst[g * 16 + rr] = sq0; sst[g * 16 + 8 + rr] = sq1; }
.LBB0_1293:
	s_or_b64 exec, exec, s[16:17]
	v_lshl_add_u64 v[112:113], s[48:49], 0, v[162:163]
	v_add_u32_e32 v162, 0x120000, v205
	v_add_u32_e32 v108, 0x120080, v205
	v_add_u32_e32 v110, 0x130000, v205
	global_load_dwordx4 v[86:89], v162, s[48:49]
	global_load_dwordx4 v[82:85], v110, s[48:49]
	v_add_u32_e32 v106, 0x130080, v205
	global_load_dwordx4 v[78:81], v108, s[48:49]
	s_waitcnt lgkmcnt(0)
	global_load_dwordx4 v[74:77], v106, s[48:49]
	ds_write_b128 v200, v[70:73]
	ds_write_b128 v200, v[66:69] offset:64
	ds_read_b128 v[66:69], v201
	ds_read_b128 v[70:73], v201 offset:1152
	v_mov_b32_e32 v123, v163
	s_waitcnt vmcnt(13) lgkmcnt(1)
	v_pk_fma_f32 v[68:69], v[56:57], v[68:69], v[104:105]
	v_add_u32_e32 v104, 0x40000, v202
	v_pk_fma_f32 v[66:67], v[54:55], v[66:67], v[102:103]
	v_lshlrev_b32_e32 v102, 2, v104
	s_waitcnt vmcnt(12) lgkmcnt(0)
	v_pk_fma_f32 v[72:73], v[56:57], v[72:73], v[100:101]
	v_add_u32_e32 v100, 0x44000, v202
	global_store_dwordx4 v102, v[66:69], s[48:49] nt
	v_pk_mul_f32 v[102:103], v[180:181], v[66:67]
	v_pk_fma_f32 v[70:71], v[54:55], v[70:71], v[98:99]
	v_lshlrev_b32_e32 v98, 2, v100
	v_pk_mul_f32 v[114:115], v[178:179], v[68:69]
	v_cvt_pk_bf16_f32 v102, v102, v103
	s_nop 0
	v_cvt_pk_bf16_f32 v103, v114, v115
	global_store_dwordx4 v98, v[70:73], s[48:49] nt
	v_pk_mul_f32 v[98:99], v[180:181], v[70:71]
	v_pk_mul_f32 v[114:115], v[178:179], v[72:73]
	v_cvt_pk_bf16_f32 v98, v98, v99
	s_nop 0
	v_cvt_pk_bf16_f32 v99, v114, v115
	ds_write_b128 v200, v[62:65]
	ds_write_b128 v200, v[58:61] offset:64
	ds_read_b128 v[58:61], v201
	ds_read_b128 v[62:65], v201 offset:1152
	v_lshl_add_u64 v[114:115], s[48:49], 0, v[122:123]
	s_waitcnt vmcnt(13) lgkmcnt(1)
	v_pk_fma_f32 v[58:59], v[50:51], v[58:59], v[94:95]
	v_pk_fma_f32 v[60:61], v[52:53], v[60:61], v[96:97]
	v_pk_mul_f32 v[96:97], v[176:177], v[58:59]
	global_store_dwordx4 v[112:113], v[58:61], off nt
	v_pk_mul_f32 v[94:95], v[174:175], v[60:61]
	v_cvt_pk_bf16_f32 v96, v96, v97
	s_waitcnt vmcnt(13) lgkmcnt(0)
	v_pk_fma_f32 v[62:63], v[50:51], v[62:63], v[90:91]
	v_cvt_pk_bf16_f32 v97, v94, v95
	ds_bpermute_b32 v90, v203, v96
	ds_bpermute_b32 v91, v203, v97
	v_pk_fma_f32 v[64:65], v[52:53], v[64:65], v[92:93]
	v_pk_mul_f32 v[92:93], v[176:177], v[62:63]
	v_pk_mul_f32 v[94:95], v[174:175], v[64:65]
	global_store_dwordx4 v[114:115], v[62:65], off nt
	v_cvt_pk_bf16_f32 v92, v92, v93
	v_cvt_pk_bf16_f32 v93, v94, v95
	v_lshlrev_b32_e32 v94, 1, v104
	s_waitcnt lgkmcnt(0)
	v_add_u32_e32 v250, 0xfffff040, v94
	v_cndmask_b32_e64 v250, v94, v250, s[40:41]
	v_cndmask_b32_e64 v248, v102, v90, s[40:41]
	v_cndmask_b32_e64 v249, v103, v91, s[40:41]
	global_store_dwordx2 v250, v[248:249], s[46:47] nt
	v_cndmask_b32_e64 v246, v90, v102, s[40:41]
	v_cndmask_b32_e64 v247, v91, v103, s[40:41]
	s_waitcnt lgkmcnt(1)
	v_add_u32_e32 v90, 0x1040, v94
	v_cndmask_b32_e64 v90, v94, v90, s[38:39]
	global_store_dwordx2 v90, v[246:247], s[46:47] nt
	ds_bpermute_b32 v90, v203, v92
	s_waitcnt lgkmcnt(1)
	ds_bpermute_b32 v91, v203, v93
	v_lshlrev_b32_e32 v92, 1, v100
	s_waitcnt lgkmcnt(0)
	v_add_u32_e32 v250, 0xfffff040, v92
	v_cndmask_b32_e64 v250, v92, v250, s[40:41]
	v_cndmask_b32_e64 v248, v98, v90, s[40:41]
	v_cndmask_b32_e64 v249, v99, v91, s[40:41]
	global_store_dwordx2 v250, v[248:249], s[46:47] nt
	v_cndmask_b32_e64 v246, v90, v98, s[40:41]
	v_cndmask_b32_e64 v247, v91, v99, s[40:41]
	v_mul_f32_e32 v59, v59, v59
	v_fmac_f32_e32 v59, v58, v58
	v_mul_f32_e32 v58, v61, v61
	v_mul_f32_e32 v69, v69, v69
	v_fmac_f32_e32 v58, v60, v60
	v_mul_f32_e32 v67, v67, v67
	v_fmac_f32_e32 v69, v68, v68
	v_mul_f32_e32 v68, v71, v71
	v_mul_f32_e32 v71, v73, v73
	v_add_f32_e32 v58, v59, v58
	v_mul_f32_e32 v59, v63, v63
	v_mul_f32_e32 v60, v65, v65
	v_fmac_f32_e32 v71, v72, v72
	v_fmac_f32_e32 v59, v62, v62
	v_fmac_f32_e32 v60, v64, v64
	v_fmac_f32_e32 v67, v66, v66
	v_fmac_f32_e32 v68, v70, v70
	v_add_f32_e32 v59, v59, v60
	v_add_f32_e32 v60, v67, v69
	v_add_f32_e32 v61, v68, v71
	v_add_f32_e32 v58, v60, v58
	v_add_f32_e32 v59, v61, v59
	ds_bpermute_b32 v60, v190, v58
	ds_bpermute_b32 v61, v190, v59
	s_waitcnt lgkmcnt(1)
	v_add_f32_e32 v58, v58, v60
	s_waitcnt lgkmcnt(0)
	v_add_f32_e32 v61, v59, v61
	ds_bpermute_b32 v60, v191, v58
	ds_bpermute_b32 v62, v191, v61
	s_waitcnt lgkmcnt(1)
	v_add_f32_e32 v58, v58, v60
	s_waitcnt lgkmcnt(0)
	v_add_f32_e32 v60, v61, v62
	ds_bpermute_b32 v59, v204, v58
	ds_bpermute_b32 v61, v204, v60
	v_add_u32_e32 v62, 0x1040, v92
	v_cndmask_b32_e64 v62, v92, v62, s[38:39]
	global_store_dwordx2 v62, v[246:247], s[46:47] nt
	s_and_saveexec_b64 s[16:17], s[42:43]
	s_cbranch_execz .LBB0_1303
	s_waitcnt lgkmcnt(1)
	v_add_f32_e32 v58, v58, v59
	s_waitcnt lgkmcnt(0)
	v_add_f32_e32 v59, v60, v61
	ds_write2_b32 v194, v58, v59 offset0:64 offset1:72
; #define LAS __attribute__((address_space(3)))
; #define ERN_EOFF(q, m) (eb + (unsigned)((((q) & 1) * HALF + (m) * 16) * DM + ERN_COL((q) >> 1)))
;     __device__ __forceinline__ void operator()(const f32x4 (&acc)[2][2][4][2], const Unit& u, int wr, int wc, int fr, int fq) const {
;     ...
;         for (int g = 0; g < 8; ++g) { const int ai = g >> 2, m = g & 3;
;             if (g + 1 < 8) ERN_LOADX(g + 1);
;             float sq0 = 0.f, sq1 = 0.f; u32x2 hw[2][2];
; #pragma unroll
;             for (int bj = 0; bj < 2; ++bj) {
;                 *(LAS f32x4*)(st + wr_off) = acc[ai][bj][m][0]; *(LAS f32x4*)(st + wr_off + 64) = acc[ai][bj][m][1];
;                 const f32x4 a0 = *(const LAS f32x4*)(st + rd_off), a1 = *(const LAS f32x4*)(st + rd_off + 8 * 144);
;                 { const f32x4 xv = xb[g & 1][bj][0] + gv[bj] * a0; __builtin_nontemporal_store(xv, (f32x4*)((char*)xo + 4u * ERN_EOFF(g, bj, 0)));
;                   sq0 += (xv.x * xv.x + xv.y * xv.y) + (xv.z * xv.z + xv.w * xv.w);
;                   const f32x4 hv = xv * gsn[bj]; hw[bj][0].x = cvt_pk_bf16(hv.x, hv.y); hw[bj][0].y = cvt_pk_bf16(hv.z, hv.w); }
;                 { const f32x4 xv = xb[g & 1][bj][1] + gv[bj] * a1; __builtin_nontemporal_store(xv, (f32x4*)((char*)xo + 4u * ERN_EOFF(g, bj, 1)));
;                   sq1 += (xv.x * xv.x + xv.y * xv.y) + (xv.z * xv.z + xv.w * xv.w);
;                   const f32x4 hv = xv * gsn[bj]; hw[bj][1].x = cvt_pk_bf16(hv.x, hv.y); hw[bj][1].y = cvt_pk_bf16(hv.z, hv.w); }
;             }
;             if (!NOH && !PLAIN) {
; #pragma unroll
;                 for (int rh = 0; rh < 2; ++rh) { u32x2 rv; rv.x = __shfl_xor(hw[1][rh].x, 8); rv.y = __shfl_xor(hw[1][rh].y, 8);
;                     const unsigned e0 = ERN_EOFF(g, 0, rh);
;                     const unsigned ee = odd ? (e0 - DM + 32) : e0, eo2 = odd ? e0 : (e0 + DM + 32);
;                     *(u32x2*)((char*)ho + 2u * ee) = odd ? rv : hw[0][rh];
;                     *(u32x2*)((char*)ho + 2u * eo2) = odd ? hw[0][rh] : rv; }
;             }
;             if (!PLAIN) { sq0 += __shfl_xor(sq0, 1); sq0 += __shfl_xor(sq0, 2); sq0 += __shfl_xor(sq0, 4);
;             sq1 += __shfl_xor(sq1, 1); sq1 += __shfl_xor(sq1, 2); sq1 += __shfl_xor(sq1, 4); }
;             if (!PLAIN && pc == 0) { sst[g * 16 + rr] = sq0; sst[g * 16 + 8 + rr] = sq1; }
.LBB0_1303:
	s_or_b64 exec, exec, s[16:17]
	v_lshl_add_u64 v[96:97], s[48:49], 0, v[162:163]
	v_add_u32_e32 v162, 0x140000, v205
	v_add_u32_e32 v92, 0x140080, v205
	v_add_u32_e32 v94, 0x150000, v205
	global_load_dwordx4 v[70:73], v162, s[48:49]
	global_load_dwordx4 v[66:69], v94, s[48:49]
	v_add_u32_e32 v90, 0x150080, v205
	global_load_dwordx4 v[62:65], v92, s[48:49]
	s_waitcnt lgkmcnt(0)
	global_load_dwordx4 v[58:61], v90, s[48:49]
	ds_write_b128 v200, v[46:49]
	ds_write_b128 v200, v[42:45] offset:64
	ds_read_b128 v[42:45], v201
	ds_read_b128 v[46:49], v201 offset:1152
	v_mov_b32_e32 v111, v163
	v_lshl_add_u64 v[98:99], s[48:49], 0, v[110:111]
	v_mov_b32_e32 v109, v163
	s_waitcnt vmcnt(13) lgkmcnt(1)
	v_pk_fma_f32 v[42:43], v[54:55], v[42:43], v[86:87]
	s_waitcnt vmcnt(12) lgkmcnt(0)
	v_pk_fma_f32 v[46:47], v[54:55], v[46:47], v[82:83]
	v_pk_fma_f32 v[44:45], v[56:57], v[44:45], v[88:89]
	v_pk_mul_f32 v[86:87], v[180:181], v[42:43]
	v_pk_fma_f32 v[48:49], v[56:57], v[48:49], v[84:85]
	v_pk_mul_f32 v[82:83], v[180:181], v[46:47]
	global_store_dwordx4 v[96:97], v[42:45], off nt
	v_pk_mul_f32 v[88:89], v[178:179], v[44:45]
	v_cvt_pk_bf16_f32 v86, v86, v87
	v_pk_mul_f32 v[84:85], v[178:179], v[48:49]
	v_cvt_pk_bf16_f32 v87, v88, v89
	global_store_dwordx4 v[98:99], v[46:49], off nt
	v_cvt_pk_bf16_f32 v82, v82, v83
	v_cvt_pk_bf16_f32 v83, v84, v85
	ds_write_b128 v200, v[38:41]
	ds_write_b128 v200, v[34:37] offset:64
	ds_read_b128 v[34:37], v201
	ds_read_b128 v[38:41], v201 offset:1152
	v_lshl_add_u64 v[84:85], s[48:49], 0, v[108:109]
	v_mov_b32_e32 v107, v163
	v_lshl_add_u64 v[88:89], s[48:49], 0, v[106:107]
	s_waitcnt vmcnt(13) lgkmcnt(1)
	v_pk_fma_f32 v[34:35], v[50:51], v[34:35], v[78:79]
	v_pk_fma_f32 v[36:37], v[52:53], v[36:37], v[80:81]
	v_pk_mul_f32 v[80:81], v[176:177], v[34:35]
	global_store_dwordx4 v[84:85], v[34:37], off nt
	v_pk_mul_f32 v[78:79], v[174:175], v[36:37]
	v_cvt_pk_bf16_f32 v80, v80, v81
	s_waitcnt vmcnt(13) lgkmcnt(0)
	v_pk_fma_f32 v[38:39], v[50:51], v[38:39], v[74:75]
	v_cvt_pk_bf16_f32 v81, v78, v79
	ds_bpermute_b32 v74, v203, v80
	ds_bpermute_b32 v75, v203, v81
	v_pk_fma_f32 v[40:41], v[52:53], v[40:41], v[76:77]
	v_pk_mul_f32 v[76:77], v[176:177], v[38:39]
	v_pk_mul_f32 v[78:79], v[174:175], v[40:41]
	global_store_dwordx4 v[88:89], v[38:41], off nt
	v_cvt_pk_bf16_f32 v76, v76, v77
	v_cvt_pk_bf16_f32 v77, v78, v79
	v_add_u32_e32 v79, 0x48000, v202
	v_lshlrev_b32_e32 v78, 1, v79
	s_waitcnt lgkmcnt(0)
	v_add_u32_e32 v250, 0xfffff040, v78
	v_cndmask_b32_e64 v250, v78, v250, s[40:41]
	v_cndmask_b32_e64 v248, v86, v74, s[40:41]
	v_cndmask_b32_e64 v249, v87, v75, s[40:41]
	global_store_dwordx2 v250, v[248:249], s[46:47] nt
	v_cndmask_b32_e64 v246, v74, v86, s[40:41]
	v_cndmask_b32_e64 v247, v75, v87, s[40:41]
	s_waitcnt lgkmcnt(1)
	v_add_u32_e32 v74, 0x1040, v78
	v_cndmask_b32_e64 v74, v78, v74, s[38:39]
	global_store_dwordx2 v74, v[246:247], s[46:47] nt
	ds_bpermute_b32 v74, v203, v76
	s_waitcnt lgkmcnt(1)
	ds_bpermute_b32 v75, v203, v77
	v_add_u32_e32 v77, 0x4c000, v202
	v_lshlrev_b32_e32 v76, 1, v77
	s_waitcnt lgkmcnt(0)
	v_add_u32_e32 v250, 0xfffff040, v76
	v_cndmask_b32_e64 v250, v76, v250, s[40:41]
	v_cndmask_b32_e64 v248, v82, v74, s[40:41]
	v_cndmask_b32_e64 v249, v83, v75, s[40:41]
	global_store_dwordx2 v250, v[248:249], s[46:47] nt
	v_cndmask_b32_e64 v246, v74, v82, s[40:41]
	v_cndmask_b32_e64 v247, v75, v83, s[40:41]
	v_mul_f32_e32 v35, v35, v35
	v_fmac_f32_e32 v35, v34, v34
	v_mul_f32_e32 v34, v37, v37
	v_mul_f32_e32 v45, v45, v45
	v_fmac_f32_e32 v34, v36, v36
	v_mul_f32_e32 v43, v43, v43
	v_fmac_f32_e32 v45, v44, v44
	v_mul_f32_e32 v44, v47, v47
	v_mul_f32_e32 v47, v49, v49
	v_add_f32_e32 v34, v35, v34
	v_mul_f32_e32 v35, v39, v39
	v_mul_f32_e32 v36, v41, v41
	v_fmac_f32_e32 v47, v48, v48
	v_fmac_f32_e32 v35, v38, v38
	v_fmac_f32_e32 v36, v40, v40
	v_fmac_f32_e32 v43, v42, v42
	v_fmac_f32_e32 v44, v46, v46
	v_add_f32_e32 v35, v35, v36
	v_add_f32_e32 v36, v43, v45
	v_add_f32_e32 v37, v44, v47
	v_add_f32_e32 v34, v36, v34
	v_add_f32_e32 v35, v37, v35
	ds_bpermute_b32 v36, v190, v34
	ds_bpermute_b32 v37, v190, v35
	s_waitcnt lgkmcnt(1)
	v_add_f32_e32 v34, v34, v36
	s_waitcnt lgkmcnt(0)
	v_add_f32_e32 v37, v35, v37
	ds_bpermute_b32 v36, v191, v34
	ds_bpermute_b32 v38, v191, v37
	s_waitcnt lgkmcnt(1)
	v_add_f32_e32 v34, v34, v36
	s_waitcnt lgkmcnt(0)
	v_add_f32_e32 v36, v37, v38
	ds_bpermute_b32 v35, v204, v34
	ds_bpermute_b32 v37, v204, v36
	v_add_u32_e32 v38, 0x1040, v76
	v_cndmask_b32_e64 v38, v76, v38, s[38:39]
	global_store_dwordx2 v38, v[246:247], s[46:47] nt
	s_and_saveexec_b64 s[16:17], s[42:43]
	s_cbranch_execz .LBB0_1313
	s_waitcnt lgkmcnt(1)
	v_add_f32_e32 v34, v34, v35
	s_waitcnt lgkmcnt(0)
	v_add_f32_e32 v35, v36, v37
	ds_write2_b32 v194, v34, v35 offset0:80 offset1:88
; #define LAS __attribute__((address_space(3)))
; #define ERN_EOFF(q, m) (eb + (unsigned)((((q) & 1) * HALF + (m) * 16) * DM + ERN_COL((q) >> 1)))
;     __device__ __forceinline__ void operator()(const f32x4 (&acc)[2][2][4][2], const Unit& u, int wr, int wc, int fr, int fq) const {
;     ...
;         for (int g = 0; g < 8; ++g) { const int ai = g >> 2, m = g & 3;
;             if (g + 1 < 8) ERN_LOADX(g + 1);
;             float sq0 = 0.f, sq1 = 0.f; u32x2 hw[2][2];
; #pragma unroll
;             for (int bj = 0; bj < 2; ++bj) {
;                 *(LAS f32x4*)(st + wr_off) = acc[ai][bj][m][0]; *(LAS f32x4*)(st + wr_off + 64) = acc[ai][bj][m][1];
;                 const f32x4 a0 = *(const LAS f32x4*)(st + rd_off), a1 = *(const LAS f32x4*)(st + rd_off + 8 * 144);
;                 { const f32x4 xv = xb[g & 1][bj][0] + gv[bj] * a0; __builtin_nontemporal_store(xv, (f32x4*)((char*)xo + 4u * ERN_EOFF(g, bj, 0)));
;                   sq0 += (xv.x * xv.x + xv.y * xv.y) + (xv.z * xv.z + xv.w * xv.w);
;                   const f32x4 hv = xv * gsn[bj]; hw[bj][0].x = cvt_pk_bf16(hv.x, hv.y); hw[bj][0].y = cvt_pk_bf16(hv.z, hv.w); }
;                 { const f32x4 xv = xb[g & 1][bj][1] + gv[bj] * a1; __builtin_nontemporal_store(xv, (f32x4*)((char*)xo + 4u * ERN_EOFF(g, bj, 1)));
;                   sq1 += (xv.x * xv.x + xv.y * xv.y) + (xv.z * xv.z + xv.w * xv.w);
;                   const f32x4 hv = xv * gsn[bj]; hw[bj][1].x = cvt_pk_bf16(hv.x, hv.y); hw[bj][1].y = cvt_pk_bf16(hv.z, hv.w); }
;             }
;             if (!NOH && !PLAIN) {
; #pragma unroll
;                 for (int rh = 0; rh < 2; ++rh) { u32x2 rv; rv.x = __shfl_xor(hw[1][rh].x, 8); rv.y = __shfl_xor(hw[1][rh].y, 8);
;                     const unsigned e0 = ERN_EOFF(g, 0, rh);
;                     const unsigned ee = odd ? (e0 - DM + 32) : e0, eo2 = odd ? e0 : (e0 + DM + 32);
;                     *(u32x2*)((char*)ho + 2u * ee) = odd ? rv : hw[0][rh];
;                     *(u32x2*)((char*)ho + 2u * eo2) = odd ? hw[0][rh] : rv; }
;             }
;             if (!PLAIN) { sq0 += __shfl_xor(sq0, 1); sq0 += __shfl_xor(sq0, 2); sq0 += __shfl_xor(sq0, 4);
;             sq1 += __shfl_xor(sq1, 1); sq1 += __shfl_xor(sq1, 2); sq1 += __shfl_xor(sq1, 4); }
;             if (!PLAIN && pc == 0) { sst[g * 16 + rr] = sq0; sst[g * 16 + 8 + rr] = sq1; }
.LBB0_1313:
	s_or_b64 exec, exec, s[16:17]
	v_lshl_add_u64 v[80:81], s[48:49], 0, v[162:163]
	v_add_u32_e32 v162, 0x160000, v205
	v_add_u32_e32 v76, 0x160080, v205
	v_add_u32_e32 v78, 0x170000, v205
	global_load_dwordx4 v[46:49], v162, s[48:49]
	global_load_dwordx4 v[42:45], v78, s[48:49]
	v_add_u32_e32 v74, 0x170080, v205
	global_load_dwordx4 v[38:41], v76, s[48:49]
	s_waitcnt lgkmcnt(0)
	global_load_dwordx4 v[34:37], v74, s[48:49]
	ds_write_b128 v200, v[30:33]
	ds_write_b128 v200, v[26:29] offset:64
	ds_read_b128 v[26:29], v201
	ds_read_b128 v[30:33], v201 offset:1152
	v_mov_b32_e32 v95, v163
	v_lshl_add_u64 v[82:83], s[48:49], 0, v[94:95]
	v_mov_b32_e32 v93, v163
	s_waitcnt vmcnt(13) lgkmcnt(1)
	v_pk_fma_f32 v[26:27], v[54:55], v[26:27], v[70:71]
	s_waitcnt vmcnt(12) lgkmcnt(0)
	v_pk_fma_f32 v[30:31], v[54:55], v[30:31], v[66:67]
	v_pk_fma_f32 v[28:29], v[56:57], v[28:29], v[72:73]
	v_pk_mul_f32 v[70:71], v[180:181], v[26:27]
	v_pk_fma_f32 v[32:33], v[56:57], v[32:33], v[68:69]
	v_pk_mul_f32 v[66:67], v[180:181], v[30:31]
	global_store_dwordx4 v[80:81], v[26:29], off nt
	v_pk_mul_f32 v[72:73], v[178:179], v[28:29]
	v_cvt_pk_bf16_f32 v70, v70, v71
	v_pk_mul_f32 v[68:69], v[178:179], v[32:33]
	v_cvt_pk_bf16_f32 v71, v72, v73
	global_store_dwordx4 v[82:83], v[30:33], off nt
	v_cvt_pk_bf16_f32 v66, v66, v67
	v_cvt_pk_bf16_f32 v67, v68, v69
	ds_write_b128 v200, v[22:25]
	ds_write_b128 v200, v[18:21] offset:64
	ds_read_b128 v[18:21], v201
	ds_read_b128 v[22:25], v201 offset:1152
	v_lshl_add_u64 v[68:69], s[48:49], 0, v[92:93]
	v_mov_b32_e32 v91, v163
	v_lshl_add_u64 v[72:73], s[48:49], 0, v[90:91]
	s_waitcnt vmcnt(13) lgkmcnt(1)
	v_pk_fma_f32 v[18:19], v[50:51], v[18:19], v[62:63]
	v_pk_fma_f32 v[20:21], v[52:53], v[20:21], v[64:65]
	v_pk_mul_f32 v[64:65], v[176:177], v[18:19]
	global_store_dwordx4 v[68:69], v[18:21], off nt
	v_pk_mul_f32 v[62:63], v[174:175], v[20:21]
	v_cvt_pk_bf16_f32 v64, v64, v65
	s_waitcnt vmcnt(13) lgkmcnt(0)
	v_pk_fma_f32 v[22:23], v[50:51], v[22:23], v[58:59]
	v_cvt_pk_bf16_f32 v65, v62, v63
	ds_bpermute_b32 v58, v203, v64
	ds_bpermute_b32 v59, v203, v65
	v_pk_fma_f32 v[24:25], v[52:53], v[24:25], v[60:61]
	v_pk_mul_f32 v[60:61], v[176:177], v[22:23]
	v_pk_mul_f32 v[62:63], v[174:175], v[24:25]
	global_store_dwordx4 v[72:73], v[22:25], off nt
	v_cvt_pk_bf16_f32 v60, v60, v61
	v_cvt_pk_bf16_f32 v61, v62, v63
	v_add_u32_e32 v63, 0x50000, v202
	v_lshlrev_b32_e32 v62, 1, v63
	s_waitcnt lgkmcnt(0)
	v_add_u32_e32 v250, 0xfffff040, v62
	v_cndmask_b32_e64 v250, v62, v250, s[40:41]
	v_cndmask_b32_e64 v248, v70, v58, s[40:41]
	v_cndmask_b32_e64 v249, v71, v59, s[40:41]
	global_store_dwordx2 v250, v[248:249], s[46:47] nt
	v_cndmask_b32_e64 v246, v58, v70, s[40:41]
	v_cndmask_b32_e64 v247, v59, v71, s[40:41]
	s_waitcnt lgkmcnt(1)
	v_add_u32_e32 v58, 0x1040, v62
	v_cndmask_b32_e64 v58, v62, v58, s[38:39]
	global_store_dwordx2 v58, v[246:247], s[46:47] nt
	ds_bpermute_b32 v58, v203, v60
	s_waitcnt lgkmcnt(1)
	ds_bpermute_b32 v59, v203, v61
	v_add_u32_e32 v61, 0x54000, v202
	v_lshlrev_b32_e32 v60, 1, v61
	s_waitcnt lgkmcnt(0)
	v_add_u32_e32 v250, 0xfffff040, v60
	v_cndmask_b32_e64 v250, v60, v250, s[40:41]
	v_cndmask_b32_e64 v248, v66, v58, s[40:41]
	v_cndmask_b32_e64 v249, v67, v59, s[40:41]
	global_store_dwordx2 v250, v[248:249], s[46:47] nt
	v_cndmask_b32_e64 v246, v58, v66, s[40:41]
	v_cndmask_b32_e64 v247, v59, v67, s[40:41]
	v_mul_f32_e32 v19, v19, v19
	v_fmac_f32_e32 v19, v18, v18
	v_mul_f32_e32 v18, v21, v21
	v_mul_f32_e32 v29, v29, v29
	v_fmac_f32_e32 v18, v20, v20
	v_mul_f32_e32 v27, v27, v27
	v_fmac_f32_e32 v29, v28, v28
	v_mul_f32_e32 v28, v31, v31
	v_mul_f32_e32 v31, v33, v33
	v_add_f32_e32 v18, v19, v18
	v_mul_f32_e32 v19, v23, v23
	v_mul_f32_e32 v20, v25, v25
	v_fmac_f32_e32 v31, v32, v32
	v_fmac_f32_e32 v19, v22, v22
	v_fmac_f32_e32 v20, v24, v24
	v_fmac_f32_e32 v27, v26, v26
	v_fmac_f32_e32 v28, v30, v30
	v_add_f32_e32 v19, v19, v20
	v_add_f32_e32 v20, v27, v29
	v_add_f32_e32 v21, v28, v31
	v_add_f32_e32 v18, v20, v18
	v_add_f32_e32 v19, v21, v19
	ds_bpermute_b32 v20, v190, v18
	ds_bpermute_b32 v21, v190, v19
	s_waitcnt lgkmcnt(1)
	v_add_f32_e32 v18, v18, v20
	s_waitcnt lgkmcnt(0)
	v_add_f32_e32 v21, v19, v21
	ds_bpermute_b32 v20, v191, v18
	ds_bpermute_b32 v22, v191, v21
	s_waitcnt lgkmcnt(1)
	v_add_f32_e32 v18, v18, v20
	s_waitcnt lgkmcnt(0)
	v_add_f32_e32 v20, v21, v22
	ds_bpermute_b32 v19, v204, v18
	ds_bpermute_b32 v21, v204, v20
	v_add_u32_e32 v22, 0x1040, v60
	v_cndmask_b32_e64 v22, v60, v22, s[38:39]
	global_store_dwordx2 v22, v[246:247], s[46:47] nt
	s_and_saveexec_b64 s[16:17], s[42:43]
	s_cbranch_execz .LBB0_1323
	s_waitcnt lgkmcnt(1)
	v_add_f32_e32 v18, v18, v19
	s_waitcnt lgkmcnt(0)
	v_add_f32_e32 v19, v20, v21
	ds_write2_b32 v194, v18, v19 offset0:96 offset1:104
; #define LAS __attribute__((address_space(3)))
; #define ERN_EOFF(q, m) (eb + (unsigned)((((q) & 1) * HALF + (m) * 16) * DM + ERN_COL((q) >> 1)))
;     __device__ __forceinline__ void operator()(const f32x4 (&acc)[2][2][4][2], const Unit& u, int wr, int wc, int fr, int fq) const {
;     ...
;         for (int g = 0; g < 8; ++g) { const int ai = g >> 2, m = g & 3;
;             if (g + 1 < 8) ERN_LOADX(g + 1);
;             float sq0 = 0.f, sq1 = 0.f; u32x2 hw[2][2];
; #pragma unroll
;             for (int bj = 0; bj < 2; ++bj) {
;                 *(LAS f32x4*)(st + wr_off) = acc[ai][bj][m][0]; *(LAS f32x4*)(st + wr_off + 64) = acc[ai][bj][m][1];
;                 const f32x4 a0 = *(const LAS f32x4*)(st + rd_off), a1 = *(const LAS f32x4*)(st + rd_off + 8 * 144);
;                 { const f32x4 xv = xb[g & 1][bj][0] + gv[bj] * a0; __builtin_nontemporal_store(xv, (f32x4*)((char*)xo + 4u * ERN_EOFF(g, bj, 0)));
;                   sq0 += (xv.x * xv.x + xv.y * xv.y) + (xv.z * xv.z + xv.w * xv.w);
;                   const f32x4 hv = xv * gsn[bj]; hw[bj][0].x = cvt_pk_bf16(hv.x, hv.y); hw[bj][0].y = cvt_pk_bf16(hv.z, hv.w); }
;                 { const f32x4 xv = xb[g & 1][bj][1] + gv[bj] * a1; __builtin_nontemporal_store(xv, (f32x4*)((char*)xo + 4u * ERN_EOFF(g, bj, 1)));
;                   sq1 += (xv.x * xv.x + xv.y * xv.y) + (xv.z * xv.z + xv.w * xv.w);
;                   const f32x4 hv = xv * gsn[bj]; hw[bj][1].x = cvt_pk_bf16(hv.x, hv.y); hw[bj][1].y = cvt_pk_bf16(hv.z, hv.w); }
;             }
;             if (!NOH && !PLAIN) {
; #pragma unroll
;                 for (int rh = 0; rh < 2; ++rh) { u32x2 rv; rv.x = __shfl_xor(hw[1][rh].x, 8); rv.y = __shfl_xor(hw[1][rh].y, 8);
;                     const unsigned e0 = ERN_EOFF(g, 0, rh);
;                     const unsigned ee = odd ? (e0 - DM + 32) : e0, eo2 = odd ? e0 : (e0 + DM + 32);
;                     *(u32x2*)((char*)ho + 2u * ee) = odd ? rv : hw[0][rh];
;                     *(u32x2*)((char*)ho + 2u * eo2) = odd ? hw[0][rh] : rv; }
;             }
;             if (!PLAIN) { sq0 += __shfl_xor(sq0, 1); sq0 += __shfl_xor(sq0, 2); sq0 += __shfl_xor(sq0, 4);
;             sq1 += __shfl_xor(sq1, 1); sq1 += __shfl_xor(sq1, 2); sq1 += __shfl_xor(sq1, 4); }
;             if (!PLAIN && pc == 0) { sst[g * 16 + rr] = sq0; sst[g * 16 + 8 + rr] = sq1; }
.LBB0_1323:
	s_or_b64 exec, exec, s[16:17]
	ds_write_b128 v200, v[14:17]
	ds_write_b128 v200, v[10:13] offset:64
	ds_read_b128 v[10:13], v201
	ds_read_b128 v[14:17], v201 offset:1152
	s_waitcnt lgkmcnt(5)
	v_lshl_add_u64 v[18:19], s[48:49], 0, v[162:163]
	v_mov_b32_e32 v79, v163
	v_lshl_add_u64 v[22:23], s[48:49], 0, v[78:79]
	s_waitcnt vmcnt(9) lgkmcnt(1)
	v_pk_fma_f32 v[12:13], v[56:57], v[12:13], v[48:49]
	v_pk_fma_f32 v[10:11], v[54:55], v[10:11], v[46:47]
	global_store_dwordx4 v[18:19], v[10:13], off nt
	v_pk_mul_f32 v[18:19], v[178:179], v[12:13]
	v_pk_mul_f32 v[20:21], v[180:181], v[10:11]
	s_waitcnt vmcnt(9) lgkmcnt(0)
	v_pk_fma_f32 v[14:15], v[54:55], v[14:15], v[42:43]
	v_cvt_pk_bf16_f32 v20, v20, v21
	v_cvt_pk_bf16_f32 v21, v18, v19
	v_pk_fma_f32 v[16:17], v[56:57], v[16:17], v[44:45]
	v_pk_mul_f32 v[18:19], v[180:181], v[14:15]
	global_store_dwordx4 v[22:23], v[14:17], off nt
	v_pk_mul_f32 v[22:23], v[178:179], v[16:17]
	v_cvt_pk_bf16_f32 v18, v18, v19
	v_mov_b32_e32 v77, v163
	v_cvt_pk_bf16_f32 v19, v22, v23
	ds_write_b128 v200, v[6:9]
	ds_write_b128 v200, v[2:5] offset:64
	ds_read_b128 v[2:5], v201
	ds_read_b128 v[6:9], v201 offset:1152
	v_lshl_add_u64 v[22:23], s[48:49], 0, v[76:77]
	v_mov_b32_e32 v75, v163
	v_lshl_add_u64 v[24:25], s[48:49], 0, v[74:75]
	s_waitcnt vmcnt(9) lgkmcnt(1)
	v_pk_fma_f32 v[4:5], v[52:53], v[4:5], v[40:41]
	v_pk_fma_f32 v[2:3], v[50:51], v[2:3], v[38:39]
	global_store_dwordx4 v[22:23], v[2:5], off nt
	v_pk_mul_f32 v[22:23], v[174:175], v[4:5]
	v_pk_mul_f32 v[26:27], v[176:177], v[2:3]
	s_waitcnt vmcnt(9) lgkmcnt(0)
	v_pk_fma_f32 v[8:9], v[52:53], v[8:9], v[36:37]
	v_cvt_pk_bf16_f32 v28, v26, v27
	v_cvt_pk_bf16_f32 v23, v22, v23
	ds_bpermute_b32 v22, v203, v28
	ds_bpermute_b32 v23, v203, v23
	v_pk_fma_f32 v[6:7], v[50:51], v[6:7], v[34:35]
	global_store_dwordx4 v[24:25], v[6:9], off nt
	v_pk_mul_f32 v[26:27], v[174:175], v[8:9]
	v_pk_mul_f32 v[24:25], v[176:177], v[6:7]
	s_nop 0
	v_cvt_pk_bf16_f32 v24, v24, v25
	v_cvt_pk_bf16_f32 v25, v26, v27
	v_add_u32_e32 v27, 0x58000, v202
	v_lshlrev_b32_e32 v26, 1, v27
	s_waitcnt lgkmcnt(0)
	v_add_u32_e32 v250, 0xfffff040, v26
	v_cndmask_b32_e64 v250, v26, v250, s[40:41]
	v_cndmask_b32_e64 v248, v20, v22, s[40:41]
	v_cndmask_b32_e64 v249, v21, v23, s[40:41]
	global_store_dwordx2 v250, v[248:249], s[46:47] nt
	v_cndmask_b32_e64 v246, v22, v20, s[40:41]
	v_cndmask_b32_e64 v247, v23, v21, s[40:41]
	s_waitcnt lgkmcnt(1)
	v_add_u32_e32 v22, 0x1040, v26
	v_cndmask_b32_e64 v22, v26, v22, s[38:39]
	global_store_dwordx2 v22, v[246:247], s[46:47] nt
	ds_bpermute_b32 v20, v203, v24
	ds_bpermute_b32 v21, v203, v25
	s_waitcnt lgkmcnt(2)
	v_add_u32_e32 v23, 0x5c000, v202
	v_lshlrev_b32_e32 v22, 1, v23
	s_waitcnt lgkmcnt(0)
	v_add_u32_e32 v250, 0xfffff040, v22
	v_cndmask_b32_e64 v250, v22, v250, s[40:41]
	v_cndmask_b32_e64 v248, v18, v20, s[40:41]
	v_cndmask_b32_e64 v249, v19, v21, s[40:41]
	global_store_dwordx2 v250, v[248:249], s[46:47] nt
	v_cndmask_b32_e64 v246, v20, v18, s[40:41]
	v_cndmask_b32_e64 v247, v21, v19, s[40:41]
	v_mul_f32_e32 v3, v3, v3
	v_fmac_f32_e32 v3, v2, v2
	v_mul_f32_e32 v2, v5, v5
	v_mul_f32_e32 v13, v13, v13
	v_fmac_f32_e32 v2, v4, v4
	v_mul_f32_e32 v11, v11, v11
	v_fmac_f32_e32 v13, v12, v12
	v_mul_f32_e32 v12, v15, v15
	v_mul_f32_e32 v15, v17, v17
	v_add_f32_e32 v2, v3, v2
	v_mul_f32_e32 v3, v7, v7
	v_mul_f32_e32 v4, v9, v9
	v_fmac_f32_e32 v15, v16, v16
	v_fmac_f32_e32 v3, v6, v6
	v_fmac_f32_e32 v4, v8, v8
	v_fmac_f32_e32 v11, v10, v10
	v_fmac_f32_e32 v12, v14, v14
	v_add_f32_e32 v3, v3, v4
	v_add_f32_e32 v4, v11, v13
	v_add_f32_e32 v5, v12, v15
	v_add_f32_e32 v2, v4, v2
	v_add_f32_e32 v3, v5, v3
	ds_bpermute_b32 v4, v190, v2
	ds_bpermute_b32 v5, v190, v3
	s_waitcnt lgkmcnt(1)
	v_add_f32_e32 v2, v2, v4
	s_waitcnt lgkmcnt(0)
	v_add_f32_e32 v5, v3, v5
	ds_bpermute_b32 v4, v191, v2
	ds_bpermute_b32 v6, v191, v5
	s_waitcnt lgkmcnt(1)
	v_add_f32_e32 v2, v2, v4
	s_waitcnt lgkmcnt(0)
	v_add_f32_e32 v4, v5, v6
	ds_bpermute_b32 v3, v204, v2
	ds_bpermute_b32 v5, v204, v4
	v_add_u32_e32 v6, 0x1040, v22
	v_cndmask_b32_e64 v6, v22, v6, s[38:39]
	global_store_dwordx2 v6, v[246:247], s[46:47] nt
	s_and_saveexec_b64 s[16:17], s[42:43]
	s_cbranch_execz .LBB0_1333
	s_waitcnt lgkmcnt(1)
	v_add_f32_e32 v2, v2, v3
	s_waitcnt lgkmcnt(0)
	v_add_f32_e32 v3, v4, v5
	ds_write2_b32 v194, v2, v3 offset0:112 offset1:120

; #define LAS __attribute__((address_space(3)))
; #define ERN_EOFF(q, m) (eb + (unsigned)((((q) & 1) * HALF + (m) * 16) * DM + ERN_COL((q) >> 1)))
;     __device__ __forceinline__ void operator()(const f32x4 (&acc)[2][2][4][2], const Unit& u, int wr, int wc, int fr, int fq) const {
;         const int s = u.pm >> 5, lane = fq * 16 + fr, rr = lane >> 3, pc = lane & 7;
;         const float* __restrict__ xi = xin + (size_t)u.pm * BM * DM; float* __restrict__ xo = xout + (size_t)u.pm * BM * DM; bf16_t* __restrict__ ho = Hn + (size_t)u.pm * BM * DM;
;         LAS unsigned char* st = lds_epi + (wr * 4 + wc) * 2304;
;         LAS float* sst = (LAS float*)(lds_epi + 18432 + (wr * 4 + wc) * 512);
;         const int colr = u.pn * BM + wc * 64 + 4 * pc;
;         const unsigned eb = (unsigned)((wr * 64 + rr) * DM + colr);
;         f32x4 gv[2], gsn[2];
; #pragma unroll
;         for (int bj = 0; bj < 2; ++bj) { gv[bj] = *(const f32x4*)(gate + (size_t)s * MODW + colr + bj * 32) * (0.5f * GS2);
;             if (!PLAIN) gsn[bj] = *(const f32x4*)(gnext + colr + bj * 32) * (*(const f32x4*)(scnext + (size_t)s * MODW + colr + bj * 32) + 1.0f); else gsn[bj] = gv[bj]; }
;         const unsigned wr_off = (unsigned)(fr * 144 + 16 * fq), rd_off = (unsigned)(rr * 144 + pc * 16);
;         const bool odd = (rr & 1) != 0;
;         f32x4 xb[2][2][2];
;     ...
;         ERN_LOADX(0);
; #pragma unroll
;         for (int g = 0; g < 8; ++g) { const int ai = g >> 2, m = g & 3;
;             if (g + 1 < 8) ERN_LOADX(g + 1);
;             float sq0 = 0.f, sq1 = 0.f; u32x2 hw[2][2];
; #pragma unroll
;             for (int bj = 0; bj < 2; ++bj) {
;                 *(LAS f32x4*)(st + wr_off) = acc[ai][bj][m][0]; *(LAS f32x4*)(st + wr_off + 64) = acc[ai][bj][m][1];
;                 const f32x4 a0 = *(const LAS f32x4*)(st + rd_off), a1 = *(const LAS f32x4*)(st + rd_off + 8 * 144);
;                 { const f32x4 xv = xb[g & 1][bj][0] + gv[bj] * a0; __builtin_nontemporal_store(xv, (f32x4*)((char*)xo + 4u * ERN_EOFF(g, bj, 0)));
;                   sq0 += (xv.x * xv.x + xv.y * xv.y) + (xv.z * xv.z + xv.w * xv.w);
;                   const f32x4 hv = xv * gsn[bj]; hw[bj][0].x = cvt_pk_bf16(hv.x, hv.y); hw[bj][0].y = cvt_pk_bf16(hv.z, hv.w); }
;                 { const f32x4 xv = xb[g & 1][bj][1] + gv[bj] * a1; __builtin_nontemporal_store(xv, (f32x4*)((char*)xo + 4u * ERN_EOFF(g, bj, 1)));
.LBB0_1598:
	s_ashr_i32 s16, s8, 5
	s_ashr_i32 s9, s8, 31
	v_lshl_or_b32 v130, s0, 8, v192
	s_mul_i32 s20, s16, 0x12000
	s_mul_hi_i32 s0, s16, 0x12000
	s_add_u32 s16, s37, s20
	v_ashrrev_i32_e32 v131, 31, v130
	s_addc_u32 s17, s48, s0
	v_lshlrev_b64 v[132:133], 2, v[130:131]
	v_lshl_add_u64 v[134:135], s[16:17], 0, v[132:133]
	s_add_u32 s16, s26, s20
	s_addc_u32 s17, s27, s0
	v_lshl_add_u64 v[136:137], s[4:5], 0, v[132:133]
	v_lshl_add_u64 v[132:133], s[16:17], 0, v[132:133]
	s_lshl_b64 s[16:17], s[8:9], 21
	s_add_u32 s22, s90, s16
	v_add_u32_e32 v202, v130, v193
	s_addc_u32 s23, s91, s17
	v_lshlrev_b32_e32 v205, 2, v202
	global_load_dwordx4 v[170:173], v[136:137], off
	global_load_dwordx4 v[166:169], v[134:135], off
	global_load_dwordx4 v[186:189], v[134:135], off offset:128
	global_load_dwordx4 v[206:209], v[132:133], off
	global_load_dwordx4 v[210:213], v[132:133], off offset:128
	global_load_dwordx4 v[214:217], v205, s[22:23]
	v_add_u32_e32 v130, 0x10000, v205
	global_load_dwordx4 v[218:221], v130, s[22:23]
	global_load_dwordx4 v[222:225], v[136:137], off offset:128
	global_load_dwordx4 v[226:229], v205, s[22:23] offset:128
	v_add_u32_e32 v204, 0x10080, v205
	global_load_dwordx4 v[230:233], v204, s[22:23]
	v_add_u32_e32 v130, 0x20000, v205
	v_add_u32_e32 v154, 0x30000, v205
	v_add_u32_e32 v184, 0x20080, v205
	v_add_u32_e32 v182, 0x30080, v205
	global_load_dwordx4 v[142:145], v130, s[22:23]
	global_load_dwordx4 v[138:141], v154, s[22:23]
	global_load_dwordx4 v[134:137], v184, s[22:23]
	s_nop 0
	global_load_dwordx4 v[130:133], v182, s[22:23]
	ds_write_b128 v200, v[126:129]
	ds_write_b128 v200, v[122:125] offset:64
	v_and_b32_e32 v127, 64, v199
	ds_read_b128 v[122:125], v201
	ds_read_b128 v[234:237], v201 offset:1152
	v_xor_b32_e32 v126, 8, v199
	v_add_u32_e32 v183, 64, v127
	v_cmp_lt_i32_e32 vcc, v126, v183
	v_add_u32_e32 v185, 0x4000, v202
	v_lshlrev_b32_e32 v238, 2, v185
	v_cndmask_b32_e32 v126, v199, v126, vcc
	v_lshlrev_b32_e32 v203, 2, v126
	s_lshl_b64 s[16:17], s[8:9], 20
	s_add_u32 s20, s93, s16
	s_addc_u32 s21, s92, s17
	s_waitcnt vmcnt(0)
	v_pk_mul_f32 v[180:181], v[166:167], 0.5 op_sel_hi:[1,0]
	v_pk_mul_f32 v[176:177], v[168:169], 0.5 op_sel_hi:[1,0]
	v_pk_add_f32 v[126:127], v[208:209], 1.0 op_sel_hi:[1,0]
	v_pk_add_f32 v[128:129], v[206:207], 1.0 op_sel_hi:[1,0]
	v_pk_mul_f32 v[174:175], v[172:173], v[126:127]
	v_pk_mul_f32 v[178:179], v[170:171], v[128:129]
	s_waitcnt lgkmcnt(1)
	v_pk_fma_f32 v[126:127], v[180:181], v[122:123], v[214:215]
	s_waitcnt lgkmcnt(0)
	v_pk_fma_f32 v[122:123], v[180:181], v[234:235], v[218:219]
	v_pk_mul_f32 v[168:169], v[186:187], 0.5 op_sel_hi:[1,0]
	v_pk_fma_f32 v[128:129], v[176:177], v[124:125], v[216:217]
	v_pk_fma_f32 v[124:125], v[176:177], v[236:237], v[220:221]
	v_pk_mul_f32 v[186:187], v[178:179], v[122:123]
	v_pk_mul_f32 v[166:167], v[188:189], 0.5 op_sel_hi:[1,0]
	global_store_dwordx4 v205, v[126:129], s[22:23] nt
	v_pk_mul_f32 v[170:171], v[174:175], v[128:129]
	v_pk_mul_f32 v[172:173], v[178:179], v[126:127]
	v_pk_mul_f32 v[206:207], v[174:175], v[124:125]
	v_cvt_pk_bf16_f32 v188, v172, v173
	v_cvt_pk_bf16_f32 v189, v170, v171
	global_store_dwordx4 v238, v[122:125], s[22:23] nt
	v_cvt_pk_bf16_f32 v186, v186, v187
	v_cvt_pk_bf16_f32 v187, v206, v207
	ds_write_b128 v200, v[118:121]
	ds_write_b128 v200, v[114:117] offset:64
	ds_read_b128 v[114:117], v201
	ds_read_b128 v[206:209], v201 offset:1152
	v_pk_add_f32 v[190:191], v[212:213], 1.0 op_sel_hi:[1,0]
	v_pk_add_f32 v[118:119], v[210:211], 1.0 op_sel_hi:[1,0]
	v_pk_mul_f32 v[170:171], v[224:225], v[190:191]
	v_pk_mul_f32 v[172:173], v[222:223], v[118:119]
	s_waitcnt lgkmcnt(1)
	v_pk_fma_f32 v[120:121], v[166:167], v[116:117], v[228:229]
	v_pk_fma_f32 v[118:119], v[168:169], v[114:115], v[226:227]
	s_waitcnt lgkmcnt(0)
	v_pk_fma_f32 v[114:115], v[168:169], v[206:207], v[230:231]
	v_pk_mul_f32 v[190:191], v[170:171], v[120:121]
	v_pk_mul_f32 v[206:207], v[172:173], v[118:119]
	global_store_dwordx4 v205, v[118:121], s[22:23] offset:128 nt
	v_cvt_pk_bf16_f32 v206, v206, v207
	v_cvt_pk_bf16_f32 v191, v190, v191
	ds_bpermute_b32 v190, v203, v206
	ds_bpermute_b32 v191, v203, v191
	v_pk_fma_f32 v[116:117], v[166:167], v[208:209], v[232:233]
	v_pk_mul_f32 v[206:207], v[172:173], v[114:115]
	global_store_dwordx4 v204, v[114:117], s[22:23] nt
	v_cvt_pk_bf16_f32 v204, v206, v207
	v_lshlrev_b32_e32 v207, 1, v202
	v_pk_mul_f32 v[208:209], v[170:171], v[116:117]
	s_nop 0
	v_cvt_pk_bf16_f32 v206, v208, v209
	s_waitcnt lgkmcnt(0)
	v_add_u32_e32 v250, 0xfffff040, v207
	v_cndmask_b32_e64 v250, v207, v250, s[40:41]
	v_cndmask_b32_e64 v248, v188, v190, s[40:41]
	v_cndmask_b32_e64 v249, v189, v191, s[40:41]
	global_store_dwordx2 v250, v[248:249], s[20:21] nt
	v_cndmask_b32_e64 v246, v190, v188, s[40:41]
	v_cndmask_b32_e64 v247, v191, v189, s[40:41]
	s_waitcnt lgkmcnt(1)
	v_add_u32_e32 v190, 0x1040, v207
	v_cndmask_b32_e64 v190, v207, v190, s[38:39]
	global_store_dwordx2 v190, v[246:247], s[20:21] nt
	ds_bpermute_b32 v188, v203, v204
	ds_bpermute_b32 v189, v203, v206
	v_lshlrev_b32_e32 v206, 1, v185
	s_waitcnt lgkmcnt(0)
; #define LAS __attribute__((address_space(3)))
; #define ERN_EOFF(q, m) (eb + (unsigned)((((q) & 1) * HALF + (m) * 16) * DM + ERN_COL((q) >> 1)))
;     __device__ __forceinline__ void operator()(const f32x4 (&acc)[2][2][4][2], const Unit& u, int wr, int wc, int fr, int fq) const {
;     ...
;         for (int g = 0; g < 8; ++g) { const int ai = g >> 2, m = g & 3;
;             if (g + 1 < 8) ERN_LOADX(g + 1);
;             float sq0 = 0.f, sq1 = 0.f; u32x2 hw[2][2];
; #pragma unroll
;             for (int bj = 0; bj < 2; ++bj) {
;                 *(LAS f32x4*)(st + wr_off) = acc[ai][bj][m][0]; *(LAS f32x4*)(st + wr_off + 64) = acc[ai][bj][m][1];
;                 const f32x4 a0 = *(const LAS f32x4*)(st + rd_off), a1 = *(const LAS f32x4*)(st + rd_off + 8 * 144);
;                 { const f32x4 xv = xb[g & 1][bj][0] + gv[bj] * a0; __builtin_nontemporal_store(xv, (f32x4*)((char*)xo + 4u * ERN_EOFF(g, bj, 0)));
;                   sq0 += (xv.x * xv.x + xv.y * xv.y) + (xv.z * xv.z + xv.w * xv.w);
;                   const f32x4 hv = xv * gsn[bj]; hw[bj][0].x = cvt_pk_bf16(hv.x, hv.y); hw[bj][0].y = cvt_pk_bf16(hv.z, hv.w); }
;                 { const f32x4 xv = xb[g & 1][bj][1] + gv[bj] * a1; __builtin_nontemporal_store(xv, (f32x4*)((char*)xo + 4u * ERN_EOFF(g, bj, 1)));
;                   sq1 += (xv.x * xv.x + xv.y * xv.y) + (xv.z * xv.z + xv.w * xv.w);
;                   const f32x4 hv = xv * gsn[bj]; hw[bj][1].x = cvt_pk_bf16(hv.x, hv.y); hw[bj][1].y = cvt_pk_bf16(hv.z, hv.w); }
;             }
;             if (!NOH && !PLAIN) {
; #pragma unroll
;                 for (int rh = 0; rh < 2; ++rh) { u32x2 rv; rv.x = __shfl_xor(hw[1][rh].x, 8); rv.y = __shfl_xor(hw[1][rh].y, 8);
;                     const unsigned e0 = ERN_EOFF(g, 0, rh);
;                     const unsigned ee = odd ? (e0 - DM + 32) : e0, eo2 = odd ? e0 : (e0 + DM + 32);
;                     *(u32x2*)((char*)ho + 2u * ee) = odd ? rv : hw[0][rh];
;                     *(u32x2*)((char*)ho + 2u * eo2) = odd ? hw[0][rh] : rv; }
;             }
;             if (!PLAIN) { sq0 += __shfl_xor(sq0, 1); sq0 += __shfl_xor(sq0, 2); sq0 += __shfl_xor(sq0, 4);
;             sq1 += __shfl_xor(sq1, 1); sq1 += __shfl_xor(sq1, 2); sq1 += __shfl_xor(sq1, 4); }
;             if (!PLAIN && pc == 0) { sst[g * 16 + rr] = sq0; sst[g * 16 + 8 + rr] = sq1; }
	v_add_u32_e32 v250, 0xfffff040, v206
	v_cndmask_b32_e64 v250, v206, v250, s[40:41]
	v_cndmask_b32_e64 v248, v186, v188, s[40:41]
	v_cndmask_b32_e64 v249, v187, v189, s[40:41]
	global_store_dwordx2 v250, v[248:249], s[20:21] nt
	v_cndmask_b32_e64 v246, v188, v186, s[40:41]
	v_cndmask_b32_e64 v247, v189, v187, s[40:41]
	v_mul_f32_e32 v119, v119, v119
	v_mul_f32_e32 v127, v127, v127
	v_mul_f32_e32 v129, v129, v129
	v_fmac_f32_e32 v119, v118, v118
	v_mul_f32_e32 v118, v121, v121
	v_fmac_f32_e32 v129, v128, v128
	v_fmac_f32_e32 v118, v120, v120
	v_mul_f32_e32 v115, v115, v115
	v_fmac_f32_e32 v127, v126, v126
	v_add_f32_e32 v118, v119, v118
	v_fmac_f32_e32 v115, v114, v114
	v_mul_f32_e32 v114, v117, v117
	v_add_f32_e32 v117, v127, v129
	v_add_f32_e32 v117, v117, v118
	v_xor_b32_e32 v118, 1, v199
	v_cmp_lt_i32_e32 vcc, v118, v183
	v_mul_f32_e32 v123, v123, v123
	v_mul_f32_e32 v125, v125, v125
	v_cndmask_b32_e32 v118, v199, v118, vcc
	v_lshlrev_b32_e32 v190, 2, v118
	ds_bpermute_b32 v118, v190, v117
	v_fmac_f32_e32 v114, v116, v116
	v_fmac_f32_e32 v125, v124, v124
	v_fmac_f32_e32 v123, v122, v122
	v_add_f32_e32 v114, v115, v114
	s_waitcnt lgkmcnt(0)
	v_add_f32_e32 v116, v117, v118
	v_xor_b32_e32 v117, 2, v199
	v_cmp_lt_i32_e32 vcc, v117, v183
	v_add_f32_e32 v115, v123, v125
	v_add_f32_e32 v115, v115, v114
	v_cndmask_b32_e32 v117, v199, v117, vcc
	v_lshlrev_b32_e32 v191, 2, v117
	ds_bpermute_b32 v117, v191, v116
	ds_bpermute_b32 v118, v190, v115
	s_waitcnt lgkmcnt(1)
	v_add_f32_e32 v114, v116, v117
	s_waitcnt lgkmcnt(0)
	v_add_f32_e32 v117, v115, v118
	ds_bpermute_b32 v118, v191, v117
	v_xor_b32_e32 v116, 4, v199
	v_cmp_lt_i32_e32 vcc, v116, v183
	s_nop 1
	v_cndmask_b32_e32 v115, v199, v116, vcc
	v_lshlrev_b32_e32 v204, 2, v115
	s_waitcnt lgkmcnt(0)
	v_add_f32_e32 v116, v117, v118
	ds_bpermute_b32 v115, v204, v114
	ds_bpermute_b32 v117, v204, v116
	v_add_u32_e32 v118, 0x1040, v206
	v_cndmask_b32_e64 v118, v206, v118, s[38:39]
	global_store_dwordx2 v118, v[246:247], s[20:21] nt
	s_and_saveexec_b64 s[16:17], s[42:43]
	s_cbranch_execz .LBB0_1608
	s_waitcnt lgkmcnt(1)
	v_add_f32_e32 v114, v114, v115
	s_waitcnt lgkmcnt(0)
	v_add_f32_e32 v115, v116, v117
	ds_write2_b32 v194, v114, v115 offset1:8
.LBB0_1608:
	s_or_b64 exec, exec, s[16:17]
	v_lshl_add_u64 v[206:207], s[22:23], 0, v[154:155]
	v_add_u32_e32 v114, 0x40000, v205
	v_add_u32_e32 v154, 0x50000, v205
	v_add_u32_e32 v186, 0x40080, v205
	global_load_dwordx4 v[122:125], v154, s[22:23]
	global_load_dwordx4 v[118:121], v186, s[22:23]
	v_add_u32_e32 v188, 0x50080, v205
	global_load_dwordx4 v[126:129], v114, s[22:23]
	s_waitcnt lgkmcnt(0)
	global_load_dwordx4 v[114:117], v188, s[22:23]
	ds_write_b128 v200, v[110:113]
	ds_write_b128 v200, v[106:109] offset:64
	ds_read_b128 v[106:109], v201
	ds_read_b128 v[110:113], v201 offset:1152
	v_mov_b32_e32 v185, v155
	v_mov_b32_e32 v183, v155
	v_lshl_add_u64 v[182:183], s[22:23], 0, v[182:183]
	s_waitcnt lgkmcnt(1)
	v_pk_fma_f32 v[108:109], v[176:177], v[108:109], v[144:145]
	v_add_u32_e32 v144, 0x8000, v202
	v_pk_fma_f32 v[106:107], v[180:181], v[106:107], v[142:143]
	v_lshlrev_b32_e32 v142, 2, v144
	s_waitcnt lgkmcnt(0)
	v_pk_fma_f32 v[110:111], v[180:181], v[110:111], v[138:139]
	global_store_dwordx4 v142, v[106:109], s[22:23] nt
	v_pk_mul_f32 v[142:143], v[178:179], v[106:107]
	v_pk_fma_f32 v[112:113], v[176:177], v[112:113], v[140:141]
	v_pk_mul_f32 v[138:139], v[178:179], v[110:111]
	v_pk_mul_f32 v[208:209], v[174:175], v[108:109]
	v_cvt_pk_bf16_f32 v142, v142, v143
	v_pk_mul_f32 v[140:141], v[174:175], v[112:113]
	v_cvt_pk_bf16_f32 v143, v208, v209
	global_store_dwordx4 v[206:207], v[110:113], off nt
	v_cvt_pk_bf16_f32 v138, v138, v139
	v_cvt_pk_bf16_f32 v139, v140, v141
	ds_write_b128 v200, v[102:105]
	ds_write_b128 v200, v[98:101] offset:64
	ds_read_b128 v[98:101], v201
	ds_read_b128 v[102:105], v201 offset:1152
	v_lshl_add_u64 v[140:141], s[22:23], 0, v[184:185]
	s_waitcnt lgkmcnt(1)
	v_pk_fma_f32 v[98:99], v[168:169], v[98:99], v[134:135]
	v_pk_fma_f32 v[100:101], v[166:167], v[100:101], v[136:137]
	v_pk_mul_f32 v[136:137], v[172:173], v[98:99]
	global_store_dwordx4 v[140:141], v[98:101], off nt
	v_pk_mul_f32 v[134:135], v[170:171], v[100:101]
	v_cvt_pk_bf16_f32 v136, v136, v137
	s_waitcnt lgkmcnt(0)
	v_pk_fma_f32 v[102:103], v[168:169], v[102:103], v[130:131]
	v_cvt_pk_bf16_f32 v137, v134, v135
	ds_bpermute_b32 v130, v203, v136
	ds_bpermute_b32 v131, v203, v137
	v_pk_fma_f32 v[104:105], v[166:167], v[104:105], v[132:133]
	v_pk_mul_f32 v[132:133], v[172:173], v[102:103]
	v_pk_mul_f32 v[134:135], v[170:171], v[104:105]
	global_store_dwordx4 v[182:183], v[102:105], off nt
	v_cvt_pk_bf16_f32 v132, v132, v133
	v_cvt_pk_bf16_f32 v133, v134, v135
	v_lshlrev_b32_e32 v134, 1, v144
	s_waitcnt lgkmcnt(0)
	v_add_u32_e32 v250, 0xfffff040, v134
	v_cndmask_b32_e64 v250, v134, v250, s[40:41]
	v_cndmask_b32_e64 v248, v142, v130, s[40:41]
	v_cndmask_b32_e64 v249, v143, v131, s[40:41]
	global_store_dwordx2 v250, v[248:249], s[20:21] nt
	v_cndmask_b32_e64 v246, v130, v142, s[40:41]
	v_cndmask_b32_e64 v247, v131, v143, s[40:41]
	s_waitcnt lgkmcnt(1)
	v_add_u32_e32 v130, 0x1040, v134
	v_cndmask_b32_e64 v130, v134, v130, s[38:39]
	global_store_dwordx2 v130, v[246:247], s[20:21] nt
	ds_bpermute_b32 v130, v203, v132
	s_waitcnt lgkmcnt(1)
	ds_bpermute_b32 v131, v203, v133
	v_add_u32_e32 v133, 0xc000, v202
	v_lshlrev_b32_e32 v132, 1, v133
	s_waitcnt lgkmcnt(0)
	v_add_u32_e32 v250, 0xfffff040, v132
	v_cndmask_b32_e64 v250, v132, v250, s[40:41]
	v_cndmask_b32_e64 v248, v138, v130, s[40:41]
	v_cndmask_b32_e64 v249, v139, v131, s[40:41]
	global_store_dwordx2 v250, v[248:249], s[20:21] nt
	v_cndmask_b32_e64 v246, v130, v138, s[40:41]
	v_cndmask_b32_e64 v247, v131, v139, s[40:41]
	v_mul_f32_e32 v99, v99, v99
	v_fmac_f32_e32 v99, v98, v98
	v_mul_f32_e32 v98, v101, v101
	v_mul_f32_e32 v109, v109, v109
	v_fmac_f32_e32 v98, v100, v100
	v_mul_f32_e32 v107, v107, v107
	v_fmac_f32_e32 v109, v108, v108
	v_mul_f32_e32 v108, v111, v111
	v_mul_f32_e32 v111, v113, v113
	v_add_f32_e32 v98, v99, v98
	v_mul_f32_e32 v99, v103, v103
	v_mul_f32_e32 v100, v105, v105
	v_fmac_f32_e32 v111, v112, v112
	v_fmac_f32_e32 v99, v102, v102
	v_fmac_f32_e32 v100, v104, v104
	v_fmac_f32_e32 v107, v106, v106
	v_fmac_f32_e32 v108, v110, v110
	v_add_f32_e32 v99, v99, v100
	v_add_f32_e32 v100, v107, v109
	v_add_f32_e32 v101, v108, v111
	v_add_f32_e32 v98, v100, v98
	v_add_f32_e32 v99, v101, v99
	ds_bpermute_b32 v100, v190, v98
	ds_bpermute_b32 v101, v190, v99
	s_waitcnt lgkmcnt(1)
	v_add_f32_e32 v98, v98, v100
	s_waitcnt lgkmcnt(0)
	v_add_f32_e32 v101, v99, v101
	ds_bpermute_b32 v100, v191, v98
	ds_bpermute_b32 v102, v191, v101
	s_waitcnt lgkmcnt(1)
	v_add_f32_e32 v98, v98, v100
	s_waitcnt lgkmcnt(0)
	v_add_f32_e32 v100, v101, v102
	ds_bpermute_b32 v99, v204, v98
	ds_bpermute_b32 v101, v204, v100
	v_add_u32_e32 v102, 0x1040, v132
	v_cndmask_b32_e64 v102, v132, v102, s[38:39]
	global_store_dwordx2 v102, v[246:247], s[20:21] nt
	s_and_saveexec_b64 s[16:17], s[42:43]
	s_cbranch_execz .LBB0_1618
; #define LAS __attribute__((address_space(3)))
; #define ERN_EOFF(q, m) (eb + (unsigned)((((q) & 1) * HALF + (m) * 16) * DM + ERN_COL((q) >> 1)))
;     __device__ __forceinline__ void operator()(const f32x4 (&acc)[2][2][4][2], const Unit& u, int wr, int wc, int fr, int fq) const {
;     ...
;         for (int g = 0; g < 8; ++g) { const int ai = g >> 2, m = g & 3;
;             if (g + 1 < 8) ERN_LOADX(g + 1);
;             float sq0 = 0.f, sq1 = 0.f; u32x2 hw[2][2];
; #pragma unroll
;             for (int bj = 0; bj < 2; ++bj) {
;                 *(LAS f32x4*)(st + wr_off) = acc[ai][bj][m][0]; *(LAS f32x4*)(st + wr_off + 64) = acc[ai][bj][m][1];
;                 const f32x4 a0 = *(const LAS f32x4*)(st + rd_off), a1 = *(const LAS f32x4*)(st + rd_off + 8 * 144);
;                 { const f32x4 xv = xb[g & 1][bj][0] + gv[bj] * a0; __builtin_nontemporal_store(xv, (f32x4*)((char*)xo + 4u * ERN_EOFF(g, bj, 0)));
;                   sq0 += (xv.x * xv.x + xv.y * xv.y) + (xv.z * xv.z + xv.w * xv.w);
;                   const f32x4 hv = xv * gsn[bj]; hw[bj][0].x = cvt_pk_bf16(hv.x, hv.y); hw[bj][0].y = cvt_pk_bf16(hv.z, hv.w); }
;                 { const f32x4 xv = xb[g & 1][bj][1] + gv[bj] * a1; __builtin_nontemporal_store(xv, (f32x4*)((char*)xo + 4u * ERN_EOFF(g, bj, 1)));
;                   sq1 += (xv.x * xv.x + xv.y * xv.y) + (xv.z * xv.z + xv.w * xv.w);
;                   const f32x4 hv = xv * gsn[bj]; hw[bj][1].x = cvt_pk_bf16(hv.x, hv.y); hw[bj][1].y = cvt_pk_bf16(hv.z, hv.w); }
;             }
;             if (!NOH && !PLAIN) {
; #pragma unroll
;                 for (int rh = 0; rh < 2; ++rh) { u32x2 rv; rv.x = __shfl_xor(hw[1][rh].x, 8); rv.y = __shfl_xor(hw[1][rh].y, 8);
;                     const unsigned e0 = ERN_EOFF(g, 0, rh);
;                     const unsigned ee = odd ? (e0 - DM + 32) : e0, eo2 = odd ? e0 : (e0 + DM + 32);
;                     *(u32x2*)((char*)ho + 2u * ee) = odd ? rv : hw[0][rh];
;                     *(u32x2*)((char*)ho + 2u * eo2) = odd ? hw[0][rh] : rv; }
;             }
;             if (!PLAIN) { sq0 += __shfl_xor(sq0, 1); sq0 += __shfl_xor(sq0, 2); sq0 += __shfl_xor(sq0, 4);
;             sq1 += __shfl_xor(sq1, 1); sq1 += __shfl_xor(sq1, 2); sq1 += __shfl_xor(sq1, 4); }
;             if (!PLAIN && pc == 0) { sst[g * 16 + rr] = sq0; sst[g * 16 + 8 + rr] = sq1; }
	s_waitcnt lgkmcnt(1)
	v_add_f32_e32 v98, v98, v99
	s_waitcnt lgkmcnt(0)
	v_add_f32_e32 v99, v100, v101
	ds_write2_b32 v194, v98, v99 offset0:16 offset1:24
.LBB0_1618:
	s_or_b64 exec, exec, s[16:17]
	v_lshl_add_u64 v[134:135], s[22:23], 0, v[154:155]
	v_add_u32_e32 v98, 0x60000, v205
	v_add_u32_e32 v154, 0x70000, v205
	v_add_u32_e32 v130, 0x60080, v205
	global_load_dwordx4 v[106:109], v154, s[22:23]
	global_load_dwordx4 v[102:105], v130, s[22:23]
	v_add_u32_e32 v132, 0x70080, v205
	global_load_dwordx4 v[110:113], v98, s[22:23]
	s_waitcnt lgkmcnt(0)
	global_load_dwordx4 v[98:101], v132, s[22:23]
	ds_write_b128 v200, v[94:97]
	ds_write_b128 v200, v[90:93] offset:64
	ds_read_b128 v[90:93], v201
	ds_read_b128 v[94:97], v201 offset:1152
	v_mov_b32_e32 v187, v155
	v_mov_b32_e32 v189, v155
	s_waitcnt vmcnt(11) lgkmcnt(1)
	v_pk_fma_f32 v[92:93], v[176:177], v[92:93], v[128:129]
	v_add_u32_e32 v128, 0x10000, v202
	v_pk_fma_f32 v[90:91], v[180:181], v[90:91], v[126:127]
	v_lshlrev_b32_e32 v126, 2, v128
	s_waitcnt lgkmcnt(0)
	v_pk_fma_f32 v[94:95], v[180:181], v[94:95], v[122:123]
	global_store_dwordx4 v126, v[90:93], s[22:23] nt
	v_pk_mul_f32 v[126:127], v[178:179], v[90:91]
	v_pk_fma_f32 v[96:97], v[176:177], v[96:97], v[124:125]
	v_pk_mul_f32 v[122:123], v[178:179], v[94:95]
	v_pk_mul_f32 v[136:137], v[174:175], v[92:93]
	v_cvt_pk_bf16_f32 v126, v126, v127
	v_pk_mul_f32 v[124:125], v[174:175], v[96:97]
	v_cvt_pk_bf16_f32 v127, v136, v137
	global_store_dwordx4 v[134:135], v[94:97], off nt
	v_cvt_pk_bf16_f32 v122, v122, v123
	v_cvt_pk_bf16_f32 v123, v124, v125
	ds_write_b128 v200, v[86:89]
	ds_write_b128 v200, v[82:85] offset:64
	ds_read_b128 v[82:85], v201
	ds_read_b128 v[86:89], v201 offset:1152
	v_lshl_add_u64 v[124:125], s[22:23], 0, v[186:187]
	v_lshl_add_u64 v[134:135], s[22:23], 0, v[188:189]
	s_waitcnt lgkmcnt(1)
	v_pk_fma_f32 v[82:83], v[168:169], v[82:83], v[118:119]
	v_pk_fma_f32 v[84:85], v[166:167], v[84:85], v[120:121]
	v_pk_mul_f32 v[120:121], v[172:173], v[82:83]
	global_store_dwordx4 v[124:125], v[82:85], off nt
	v_pk_mul_f32 v[118:119], v[170:171], v[84:85]
	v_cvt_pk_bf16_f32 v120, v120, v121
	s_waitcnt vmcnt(13) lgkmcnt(0)
	v_pk_fma_f32 v[86:87], v[168:169], v[86:87], v[114:115]
	v_cvt_pk_bf16_f32 v121, v118, v119
	ds_bpermute_b32 v114, v203, v120
	ds_bpermute_b32 v115, v203, v121
	v_pk_fma_f32 v[88:89], v[166:167], v[88:89], v[116:117]
	v_pk_mul_f32 v[116:117], v[172:173], v[86:87]
	v_pk_mul_f32 v[118:119], v[170:171], v[88:89]
	global_store_dwordx4 v[134:135], v[86:89], off nt
	v_cvt_pk_bf16_f32 v116, v116, v117
	v_cvt_pk_bf16_f32 v117, v118, v119
	v_lshlrev_b32_e32 v118, 1, v128
	s_waitcnt lgkmcnt(0)
	v_add_u32_e32 v250, 0xfffff040, v118
	v_cndmask_b32_e64 v250, v118, v250, s[40:41]
	v_cndmask_b32_e64 v248, v126, v114, s[40:41]
	v_cndmask_b32_e64 v249, v127, v115, s[40:41]
	global_store_dwordx2 v250, v[248:249], s[20:21] nt
	v_cndmask_b32_e64 v246, v114, v126, s[40:41]
	v_cndmask_b32_e64 v247, v115, v127, s[40:41]
	s_waitcnt lgkmcnt(1)
	v_add_u32_e32 v114, 0x1040, v118
	v_cndmask_b32_e64 v114, v118, v114, s[38:39]
	global_store_dwordx2 v114, v[246:247], s[20:21] nt
	ds_bpermute_b32 v114, v203, v116
	s_waitcnt lgkmcnt(1)
	ds_bpermute_b32 v115, v203, v117
	v_add_u32_e32 v117, 0x14000, v202
	v_lshlrev_b32_e32 v116, 1, v117
	s_waitcnt lgkmcnt(0)
	v_add_u32_e32 v250, 0xfffff040, v116
	v_cndmask_b32_e64 v250, v116, v250, s[40:41]
	v_cndmask_b32_e64 v248, v122, v114, s[40:41]
	v_cndmask_b32_e64 v249, v123, v115, s[40:41]
	global_store_dwordx2 v250, v[248:249], s[20:21] nt
	v_cndmask_b32_e64 v246, v114, v122, s[40:41]
	v_cndmask_b32_e64 v247, v115, v123, s[40:41]
	v_mul_f32_e32 v83, v83, v83
	v_fmac_f32_e32 v83, v82, v82
	v_mul_f32_e32 v82, v85, v85
	v_mul_f32_e32 v93, v93, v93
	v_fmac_f32_e32 v82, v84, v84
	v_mul_f32_e32 v91, v91, v91
	v_fmac_f32_e32 v93, v92, v92
	v_mul_f32_e32 v92, v95, v95
	v_mul_f32_e32 v95, v97, v97
	v_add_f32_e32 v82, v83, v82
	v_mul_f32_e32 v83, v87, v87
	v_mul_f32_e32 v84, v89, v89
	v_fmac_f32_e32 v95, v96, v96
	v_fmac_f32_e32 v83, v86, v86
	v_fmac_f32_e32 v84, v88, v88
	v_fmac_f32_e32 v91, v90, v90
	v_fmac_f32_e32 v92, v94, v94
	v_add_f32_e32 v83, v83, v84
	v_add_f32_e32 v84, v91, v93
	v_add_f32_e32 v85, v92, v95
	v_add_f32_e32 v82, v84, v82
	v_add_f32_e32 v83, v85, v83
	ds_bpermute_b32 v84, v190, v82
	ds_bpermute_b32 v85, v190, v83
	s_waitcnt lgkmcnt(1)
	v_add_f32_e32 v82, v82, v84
	s_waitcnt lgkmcnt(0)
	v_add_f32_e32 v85, v83, v85
	ds_bpermute_b32 v84, v191, v82
	ds_bpermute_b32 v86, v191, v85
	s_waitcnt lgkmcnt(1)
	v_add_f32_e32 v82, v82, v84
	s_waitcnt lgkmcnt(0)
	v_add_f32_e32 v84, v85, v86
	ds_bpermute_b32 v83, v204, v82
	ds_bpermute_b32 v85, v204, v84
	v_add_u32_e32 v86, 0x1040, v116
	v_cndmask_b32_e64 v86, v116, v86, s[38:39]
	global_store_dwordx2 v86, v[246:247], s[20:21] nt
	s_and_saveexec_b64 s[16:17], s[42:43]
	s_cbranch_execz .LBB0_1628
	s_waitcnt lgkmcnt(1)
	v_add_f32_e32 v82, v82, v83
	s_waitcnt lgkmcnt(0)
	v_add_f32_e32 v83, v84, v85
	ds_write2_b32 v194, v82, v83 offset0:32 offset1:40
; #define LAS __attribute__((address_space(3)))
; #define ERN_EOFF(q, m) (eb + (unsigned)((((q) & 1) * HALF + (m) * 16) * DM + ERN_COL((q) >> 1)))
;     __device__ __forceinline__ void operator()(const f32x4 (&acc)[2][2][4][2], const Unit& u, int wr, int wc, int fr, int fq) const {
;     ...
;         for (int g = 0; g < 8; ++g) { const int ai = g >> 2, m = g & 3;
;             if (g + 1 < 8) ERN_LOADX(g + 1);
;             float sq0 = 0.f, sq1 = 0.f; u32x2 hw[2][2];
; #pragma unroll
;             for (int bj = 0; bj < 2; ++bj) {
;                 *(LAS f32x4*)(st + wr_off) = acc[ai][bj][m][0]; *(LAS f32x4*)(st + wr_off + 64) = acc[ai][bj][m][1];
;                 const f32x4 a0 = *(const LAS f32x4*)(st + rd_off), a1 = *(const LAS f32x4*)(st + rd_off + 8 * 144);
;                 { const f32x4 xv = xb[g & 1][bj][0] + gv[bj] * a0; __builtin_nontemporal_store(xv, (f32x4*)((char*)xo + 4u * ERN_EOFF(g, bj, 0)));
;                   sq0 += (xv.x * xv.x + xv.y * xv.y) + (xv.z * xv.z + xv.w * xv.w);
;                   const f32x4 hv = xv * gsn[bj]; hw[bj][0].x = cvt_pk_bf16(hv.x, hv.y); hw[bj][0].y = cvt_pk_bf16(hv.z, hv.w); }
;                 { const f32x4 xv = xb[g & 1][bj][1] + gv[bj] * a1; __builtin_nontemporal_store(xv, (f32x4*)((char*)xo + 4u * ERN_EOFF(g, bj, 1)));
;                   sq1 += (xv.x * xv.x + xv.y * xv.y) + (xv.z * xv.z + xv.w * xv.w);
;                   const f32x4 hv = xv * gsn[bj]; hw[bj][1].x = cvt_pk_bf16(hv.x, hv.y); hw[bj][1].y = cvt_pk_bf16(hv.z, hv.w); }
;             }
;             if (!NOH && !PLAIN) {
; #pragma unroll
;                 for (int rh = 0; rh < 2; ++rh) { u32x2 rv; rv.x = __shfl_xor(hw[1][rh].x, 8); rv.y = __shfl_xor(hw[1][rh].y, 8);
;                     const unsigned e0 = ERN_EOFF(g, 0, rh);
;                     const unsigned ee = odd ? (e0 - DM + 32) : e0, eo2 = odd ? e0 : (e0 + DM + 32);
;                     *(u32x2*)((char*)ho + 2u * ee) = odd ? rv : hw[0][rh];
;                     *(u32x2*)((char*)ho + 2u * eo2) = odd ? hw[0][rh] : rv; }
;             }
;             if (!PLAIN) { sq0 += __shfl_xor(sq0, 1); sq0 += __shfl_xor(sq0, 2); sq0 += __shfl_xor(sq0, 4);
;             sq1 += __shfl_xor(sq1, 1); sq1 += __shfl_xor(sq1, 2); sq1 += __shfl_xor(sq1, 4); }
;             if (!PLAIN && pc == 0) { sst[g * 16 + rr] = sq0; sst[g * 16 + 8 + rr] = sq1; }
.LBB0_1628:
	s_or_b64 exec, exec, s[16:17]
	v_lshl_add_u64 v[116:117], s[22:23], 0, v[154:155]
	v_add_u32_e32 v82, 0x100000, v205
	s_waitcnt lgkmcnt(1)
	v_add_u32_e32 v83, 0x110000, v205
	v_add_u32_e32 v154, 0x100080, v205
	global_load_dwordx4 v[94:97], v82, s[22:23]
	global_load_dwordx4 v[90:93], v83, s[22:23]
	v_add_u32_e32 v114, 0x110080, v205
	global_load_dwordx4 v[86:89], v154, s[22:23]
	s_waitcnt lgkmcnt(0)
	global_load_dwordx4 v[82:85], v114, s[22:23]
	ds_write_b128 v200, v[78:81]
	ds_write_b128 v200, v[74:77] offset:64
	ds_read_b128 v[74:77], v201
	ds_read_b128 v[78:81], v201 offset:1152
	v_mov_b32_e32 v131, v155
	v_mov_b32_e32 v133, v155
	s_waitcnt vmcnt(11) lgkmcnt(1)
	v_pk_fma_f32 v[76:77], v[176:177], v[76:77], v[112:113]
	v_add_u32_e32 v112, 0x18000, v202
	v_pk_fma_f32 v[74:75], v[180:181], v[74:75], v[110:111]
	v_lshlrev_b32_e32 v110, 2, v112
	s_waitcnt lgkmcnt(0)
	v_pk_fma_f32 v[78:79], v[180:181], v[78:79], v[106:107]
	global_store_dwordx4 v110, v[74:77], s[22:23] nt
	v_pk_mul_f32 v[110:111], v[178:179], v[74:75]
	v_pk_fma_f32 v[80:81], v[176:177], v[80:81], v[108:109]
	v_pk_mul_f32 v[106:107], v[178:179], v[78:79]
	v_pk_mul_f32 v[118:119], v[174:175], v[76:77]
	v_cvt_pk_bf16_f32 v110, v110, v111
	v_pk_mul_f32 v[108:109], v[174:175], v[80:81]
	v_cvt_pk_bf16_f32 v111, v118, v119
	global_store_dwordx4 v[116:117], v[78:81], off nt
	v_cvt_pk_bf16_f32 v106, v106, v107
	v_cvt_pk_bf16_f32 v107, v108, v109
	ds_write_b128 v200, v[70:73]
	ds_write_b128 v200, v[66:69] offset:64
	ds_read_b128 v[66:69], v201
	ds_read_b128 v[70:73], v201 offset:1152
	v_lshl_add_u64 v[108:109], s[22:23], 0, v[130:131]
	v_lshl_add_u64 v[116:117], s[22:23], 0, v[132:133]
	s_waitcnt lgkmcnt(1)
	v_pk_fma_f32 v[66:67], v[168:169], v[66:67], v[102:103]
	v_pk_fma_f32 v[68:69], v[166:167], v[68:69], v[104:105]
	v_pk_mul_f32 v[104:105], v[172:173], v[66:67]
	global_store_dwordx4 v[108:109], v[66:69], off nt
	v_pk_mul_f32 v[102:103], v[170:171], v[68:69]
	v_cvt_pk_bf16_f32 v104, v104, v105
	s_waitcnt vmcnt(13) lgkmcnt(0)
	v_pk_fma_f32 v[70:71], v[168:169], v[70:71], v[98:99]
	v_cvt_pk_bf16_f32 v105, v102, v103
	ds_bpermute_b32 v98, v203, v104
	ds_bpermute_b32 v99, v203, v105
	v_pk_fma_f32 v[72:73], v[166:167], v[72:73], v[100:101]
	v_pk_mul_f32 v[100:101], v[172:173], v[70:71]
	v_pk_mul_f32 v[102:103], v[170:171], v[72:73]
	global_store_dwordx4 v[116:117], v[70:73], off nt
	v_cvt_pk_bf16_f32 v100, v100, v101
	v_cvt_pk_bf16_f32 v101, v102, v103
	v_lshlrev_b32_e32 v102, 1, v112
	s_waitcnt lgkmcnt(0)
	v_add_u32_e32 v250, 0xfffff040, v102
	v_cndmask_b32_e64 v250, v102, v250, s[40:41]
	v_cndmask_b32_e64 v248, v110, v98, s[40:41]
	v_cndmask_b32_e64 v249, v111, v99, s[40:41]
	global_store_dwordx2 v250, v[248:249], s[20:21] nt
	v_cndmask_b32_e64 v246, v98, v110, s[40:41]
	v_cndmask_b32_e64 v247, v99, v111, s[40:41]
	s_waitcnt lgkmcnt(1)
	v_add_u32_e32 v98, 0x1040, v102
	v_cndmask_b32_e64 v98, v102, v98, s[38:39]
	global_store_dwordx2 v98, v[246:247], s[20:21] nt
	ds_bpermute_b32 v98, v203, v100
	s_waitcnt lgkmcnt(1)
	ds_bpermute_b32 v99, v203, v101
	v_add_u32_e32 v101, 0x1c000, v202
	v_lshlrev_b32_e32 v100, 1, v101
	s_waitcnt lgkmcnt(0)
	v_add_u32_e32 v250, 0xfffff040, v100
	v_cndmask_b32_e64 v250, v100, v250, s[40:41]
	v_cndmask_b32_e64 v248, v106, v98, s[40:41]
	v_cndmask_b32_e64 v249, v107, v99, s[40:41]
	global_store_dwordx2 v250, v[248:249], s[20:21] nt
	v_cndmask_b32_e64 v246, v98, v106, s[40:41]
	v_cndmask_b32_e64 v247, v99, v107, s[40:41]
	v_mul_f32_e32 v67, v67, v67
	v_fmac_f32_e32 v67, v66, v66
	v_mul_f32_e32 v66, v69, v69
	v_mul_f32_e32 v77, v77, v77
	v_fmac_f32_e32 v66, v68, v68
	v_mul_f32_e32 v75, v75, v75
	v_fmac_f32_e32 v77, v76, v76
	v_mul_f32_e32 v76, v79, v79
	v_mul_f32_e32 v79, v81, v81
	v_add_f32_e32 v66, v67, v66
	v_mul_f32_e32 v67, v71, v71
	v_mul_f32_e32 v68, v73, v73
	v_fmac_f32_e32 v79, v80, v80
	v_fmac_f32_e32 v67, v70, v70
	v_fmac_f32_e32 v68, v72, v72
	v_fmac_f32_e32 v75, v74, v74
	v_fmac_f32_e32 v76, v78, v78
	v_add_f32_e32 v67, v67, v68
	v_add_f32_e32 v68, v75, v77
	v_add_f32_e32 v69, v76, v79
	v_add_f32_e32 v66, v68, v66
	v_add_f32_e32 v67, v69, v67
	ds_bpermute_b32 v68, v190, v66
	ds_bpermute_b32 v69, v190, v67
	s_waitcnt lgkmcnt(1)
	v_add_f32_e32 v66, v66, v68
	s_waitcnt lgkmcnt(0)
	v_add_f32_e32 v69, v67, v69
	ds_bpermute_b32 v68, v191, v66
	ds_bpermute_b32 v70, v191, v69
	s_waitcnt lgkmcnt(1)
	v_add_f32_e32 v66, v66, v68
	s_waitcnt lgkmcnt(0)
	v_add_f32_e32 v68, v69, v70
	ds_bpermute_b32 v67, v204, v66
	ds_bpermute_b32 v69, v204, v68
	v_add_u32_e32 v70, 0x1040, v100
	v_cndmask_b32_e64 v70, v100, v70, s[38:39]
	global_store_dwordx2 v70, v[246:247], s[20:21] nt
	s_and_saveexec_b64 s[16:17], s[42:43]
	s_cbranch_execz .LBB0_1638
	s_waitcnt lgkmcnt(1)
	v_add_f32_e32 v66, v66, v67
	s_waitcnt lgkmcnt(0)
	v_add_f32_e32 v67, v68, v69
	ds_write2_b32 v194, v66, v67 offset0:48 offset1:56
; #define LAS __attribute__((address_space(3)))
; #define ERN_EOFF(q, m) (eb + (unsigned)((((q) & 1) * HALF + (m) * 16) * DM + ERN_COL((q) >> 1)))
;     __device__ __forceinline__ void operator()(const f32x4 (&acc)[2][2][4][2], const Unit& u, int wr, int wc, int fr, int fq) const {
;     ...
;         for (int g = 0; g < 8; ++g) { const int ai = g >> 2, m = g & 3;
;             if (g + 1 < 8) ERN_LOADX(g + 1);
;             float sq0 = 0.f, sq1 = 0.f; u32x2 hw[2][2];
; #pragma unroll
;             for (int bj = 0; bj < 2; ++bj) {
;                 *(LAS f32x4*)(st + wr_off) = acc[ai][bj][m][0]; *(LAS f32x4*)(st + wr_off + 64) = acc[ai][bj][m][1];
;                 const f32x4 a0 = *(const LAS f32x4*)(st + rd_off), a1 = *(const LAS f32x4*)(st + rd_off + 8 * 144);
;                 { const f32x4 xv = xb[g & 1][bj][0] + gv[bj] * a0; __builtin_nontemporal_store(xv, (f32x4*)((char*)xo + 4u * ERN_EOFF(g, bj, 0)));
;                   sq0 += (xv.x * xv.x + xv.y * xv.y) + (xv.z * xv.z + xv.w * xv.w);
;                   const f32x4 hv = xv * gsn[bj]; hw[bj][0].x = cvt_pk_bf16(hv.x, hv.y); hw[bj][0].y = cvt_pk_bf16(hv.z, hv.w); }
;                 { const f32x4 xv = xb[g & 1][bj][1] + gv[bj] * a1; __builtin_nontemporal_store(xv, (f32x4*)((char*)xo + 4u * ERN_EOFF(g, bj, 1)));
;                   sq1 += (xv.x * xv.x + xv.y * xv.y) + (xv.z * xv.z + xv.w * xv.w);
;                   const f32x4 hv = xv * gsn[bj]; hw[bj][1].x = cvt_pk_bf16(hv.x, hv.y); hw[bj][1].y = cvt_pk_bf16(hv.z, hv.w); }
;             }
;             if (!NOH && !PLAIN) {
; #pragma unroll
;                 for (int rh = 0; rh < 2; ++rh) { u32x2 rv; rv.x = __shfl_xor(hw[1][rh].x, 8); rv.y = __shfl_xor(hw[1][rh].y, 8);
;                     const unsigned e0 = ERN_EOFF(g, 0, rh);
;                     const unsigned ee = odd ? (e0 - DM + 32) : e0, eo2 = odd ? e0 : (e0 + DM + 32);
;                     *(u32x2*)((char*)ho + 2u * ee) = odd ? rv : hw[0][rh];
;                     *(u32x2*)((char*)ho + 2u * eo2) = odd ? hw[0][rh] : rv; }
;             }
;             if (!PLAIN) { sq0 += __shfl_xor(sq0, 1); sq0 += __shfl_xor(sq0, 2); sq0 += __shfl_xor(sq0, 4);
;             sq1 += __shfl_xor(sq1, 1); sq1 += __shfl_xor(sq1, 2); sq1 += __shfl_xor(sq1, 4); }
;             if (!PLAIN && pc == 0) { sst[g * 16 + rr] = sq0; sst[g * 16 + 8 + rr] = sq1; }
.LBB0_1638:
	s_or_b64 exec, exec, s[16:17]
	v_lshl_add_u64 v[104:105], s[22:23], 0, v[154:155]
	v_add_u32_e32 v154, 0x120000, v205
	v_add_u32_e32 v100, 0x120080, v205
	v_add_u32_e32 v102, 0x130000, v205
	global_load_dwordx4 v[78:81], v154, s[22:23]
	global_load_dwordx4 v[74:77], v102, s[22:23]
	v_add_u32_e32 v98, 0x130080, v205
	global_load_dwordx4 v[70:73], v100, s[22:23]
	s_waitcnt lgkmcnt(0)
	global_load_dwordx4 v[66:69], v98, s[22:23]
	ds_write_b128 v200, v[62:65]
	ds_write_b128 v200, v[58:61] offset:64
	ds_read_b128 v[58:61], v201
	ds_read_b128 v[62:65], v201 offset:1152
	v_mov_b32_e32 v115, v155
	s_waitcnt vmcnt(13) lgkmcnt(1)
	v_pk_fma_f32 v[60:61], v[176:177], v[60:61], v[96:97]
	v_add_u32_e32 v96, 0x40000, v202
	v_pk_fma_f32 v[58:59], v[180:181], v[58:59], v[94:95]
	v_lshlrev_b32_e32 v94, 2, v96
	s_waitcnt vmcnt(12) lgkmcnt(0)
	v_pk_fma_f32 v[64:65], v[176:177], v[64:65], v[92:93]
	v_add_u32_e32 v92, 0x44000, v202
	global_store_dwordx4 v94, v[58:61], s[22:23] nt
	v_pk_mul_f32 v[94:95], v[178:179], v[58:59]
	v_pk_fma_f32 v[62:63], v[180:181], v[62:63], v[90:91]
	v_lshlrev_b32_e32 v90, 2, v92
	v_pk_mul_f32 v[106:107], v[174:175], v[60:61]
	v_cvt_pk_bf16_f32 v94, v94, v95
	s_nop 0
	v_cvt_pk_bf16_f32 v95, v106, v107
	global_store_dwordx4 v90, v[62:65], s[22:23] nt
	v_pk_mul_f32 v[90:91], v[178:179], v[62:63]
	v_pk_mul_f32 v[106:107], v[174:175], v[64:65]
	v_cvt_pk_bf16_f32 v90, v90, v91
	s_nop 0
	v_cvt_pk_bf16_f32 v91, v106, v107
	ds_write_b128 v200, v[54:57]
	ds_write_b128 v200, v[50:53] offset:64
	ds_read_b128 v[50:53], v201
	ds_read_b128 v[54:57], v201 offset:1152
	v_lshl_add_u64 v[106:107], s[22:23], 0, v[114:115]
	s_waitcnt vmcnt(13) lgkmcnt(1)
	v_pk_fma_f32 v[50:51], v[168:169], v[50:51], v[86:87]
	v_pk_fma_f32 v[52:53], v[166:167], v[52:53], v[88:89]
	v_pk_mul_f32 v[88:89], v[172:173], v[50:51]
	global_store_dwordx4 v[104:105], v[50:53], off nt
	v_pk_mul_f32 v[86:87], v[170:171], v[52:53]
	v_cvt_pk_bf16_f32 v88, v88, v89
	s_waitcnt vmcnt(13) lgkmcnt(0)
	v_pk_fma_f32 v[54:55], v[168:169], v[54:55], v[82:83]
	v_cvt_pk_bf16_f32 v89, v86, v87
	ds_bpermute_b32 v82, v203, v88
	ds_bpermute_b32 v83, v203, v89
	v_pk_fma_f32 v[56:57], v[166:167], v[56:57], v[84:85]
	v_pk_mul_f32 v[84:85], v[172:173], v[54:55]
	v_pk_mul_f32 v[86:87], v[170:171], v[56:57]
	global_store_dwordx4 v[106:107], v[54:57], off nt
	v_cvt_pk_bf16_f32 v84, v84, v85
	v_cvt_pk_bf16_f32 v85, v86, v87
	v_lshlrev_b32_e32 v86, 1, v96
	s_waitcnt lgkmcnt(0)
	v_add_u32_e32 v250, 0xfffff040, v86
	v_cndmask_b32_e64 v250, v86, v250, s[40:41]
	v_cndmask_b32_e64 v248, v94, v82, s[40:41]
	v_cndmask_b32_e64 v249, v95, v83, s[40:41]
	global_store_dwordx2 v250, v[248:249], s[20:21] nt
	v_cndmask_b32_e64 v246, v82, v94, s[40:41]
	v_cndmask_b32_e64 v247, v83, v95, s[40:41]
	s_waitcnt lgkmcnt(1)
	v_add_u32_e32 v82, 0x1040, v86
	v_cndmask_b32_e64 v82, v86, v82, s[38:39]
	global_store_dwordx2 v82, v[246:247], s[20:21] nt
	ds_bpermute_b32 v82, v203, v84
	s_waitcnt lgkmcnt(1)
	ds_bpermute_b32 v83, v203, v85
	v_lshlrev_b32_e32 v84, 1, v92
	s_waitcnt lgkmcnt(0)
	v_add_u32_e32 v250, 0xfffff040, v84
	v_cndmask_b32_e64 v250, v84, v250, s[40:41]
	v_cndmask_b32_e64 v248, v90, v82, s[40:41]
	v_cndmask_b32_e64 v249, v91, v83, s[40:41]
	global_store_dwordx2 v250, v[248:249], s[20:21] nt
	v_cndmask_b32_e64 v246, v82, v90, s[40:41]
	v_cndmask_b32_e64 v247, v83, v91, s[40:41]
	v_mul_f32_e32 v51, v51, v51
	v_fmac_f32_e32 v51, v50, v50
	v_mul_f32_e32 v50, v53, v53
	v_mul_f32_e32 v61, v61, v61
	v_fmac_f32_e32 v50, v52, v52
	v_mul_f32_e32 v59, v59, v59
	v_fmac_f32_e32 v61, v60, v60
	v_mul_f32_e32 v60, v63, v63
	v_mul_f32_e32 v63, v65, v65
	v_add_f32_e32 v50, v51, v50
	v_mul_f32_e32 v51, v55, v55
	v_mul_f32_e32 v52, v57, v57
	v_fmac_f32_e32 v63, v64, v64
	v_fmac_f32_e32 v51, v54, v54
	v_fmac_f32_e32 v52, v56, v56
	v_fmac_f32_e32 v59, v58, v58
	v_fmac_f32_e32 v60, v62, v62
	v_add_f32_e32 v51, v51, v52
	v_add_f32_e32 v52, v59, v61
	v_add_f32_e32 v53, v60, v63
	v_add_f32_e32 v50, v52, v50
	v_add_f32_e32 v51, v53, v51
	ds_bpermute_b32 v52, v190, v50
	ds_bpermute_b32 v53, v190, v51
	s_waitcnt lgkmcnt(1)
	v_add_f32_e32 v50, v50, v52
	s_waitcnt lgkmcnt(0)
	v_add_f32_e32 v53, v51, v53
	ds_bpermute_b32 v52, v191, v50
	ds_bpermute_b32 v54, v191, v53
	s_waitcnt lgkmcnt(1)
	v_add_f32_e32 v50, v50, v52
	s_waitcnt lgkmcnt(0)
	v_add_f32_e32 v52, v53, v54
	ds_bpermute_b32 v51, v204, v50
	ds_bpermute_b32 v53, v204, v52
	v_add_u32_e32 v54, 0x1040, v84
	v_cndmask_b32_e64 v54, v84, v54, s[38:39]
	global_store_dwordx2 v54, v[246:247], s[20:21] nt
	s_and_saveexec_b64 s[16:17], s[42:43]
	s_cbranch_execz .LBB0_1648
	s_waitcnt lgkmcnt(1)
	v_add_f32_e32 v50, v50, v51
	s_waitcnt lgkmcnt(0)
	v_add_f32_e32 v51, v52, v53
	ds_write2_b32 v194, v50, v51 offset0:64 offset1:72
; #define LAS __attribute__((address_space(3)))
; #define ERN_EOFF(q, m) (eb + (unsigned)((((q) & 1) * HALF + (m) * 16) * DM + ERN_COL((q) >> 1)))
;     __device__ __forceinline__ void operator()(const f32x4 (&acc)[2][2][4][2], const Unit& u, int wr, int wc, int fr, int fq) const {
;     ...
;         for (int g = 0; g < 8; ++g) { const int ai = g >> 2, m = g & 3;
;             if (g + 1 < 8) ERN_LOADX(g + 1);
;             float sq0 = 0.f, sq1 = 0.f; u32x2 hw[2][2];
; #pragma unroll
;             for (int bj = 0; bj < 2; ++bj) {
;                 *(LAS f32x4*)(st + wr_off) = acc[ai][bj][m][0]; *(LAS f32x4*)(st + wr_off + 64) = acc[ai][bj][m][1];
;                 const f32x4 a0 = *(const LAS f32x4*)(st + rd_off), a1 = *(const LAS f32x4*)(st + rd_off + 8 * 144);
;                 { const f32x4 xv = xb[g & 1][bj][0] + gv[bj] * a0; __builtin_nontemporal_store(xv, (f32x4*)((char*)xo + 4u * ERN_EOFF(g, bj, 0)));
;                   sq0 += (xv.x * xv.x + xv.y * xv.y) + (xv.z * xv.z + xv.w * xv.w);
;                   const f32x4 hv = xv * gsn[bj]; hw[bj][0].x = cvt_pk_bf16(hv.x, hv.y); hw[bj][0].y = cvt_pk_bf16(hv.z, hv.w); }
;                 { const f32x4 xv = xb[g & 1][bj][1] + gv[bj] * a1; __builtin_nontemporal_store(xv, (f32x4*)((char*)xo + 4u * ERN_EOFF(g, bj, 1)));
;                   sq1 += (xv.x * xv.x + xv.y * xv.y) + (xv.z * xv.z + xv.w * xv.w);
;                   const f32x4 hv = xv * gsn[bj]; hw[bj][1].x = cvt_pk_bf16(hv.x, hv.y); hw[bj][1].y = cvt_pk_bf16(hv.z, hv.w); }
;             }
;             if (!NOH && !PLAIN) {
; #pragma unroll
;                 for (int rh = 0; rh < 2; ++rh) { u32x2 rv; rv.x = __shfl_xor(hw[1][rh].x, 8); rv.y = __shfl_xor(hw[1][rh].y, 8);
;                     const unsigned e0 = ERN_EOFF(g, 0, rh);
;                     const unsigned ee = odd ? (e0 - DM + 32) : e0, eo2 = odd ? e0 : (e0 + DM + 32);
;                     *(u32x2*)((char*)ho + 2u * ee) = odd ? rv : hw[0][rh];
;                     *(u32x2*)((char*)ho + 2u * eo2) = odd ? hw[0][rh] : rv; }
;             }
;             if (!PLAIN) { sq0 += __shfl_xor(sq0, 1); sq0 += __shfl_xor(sq0, 2); sq0 += __shfl_xor(sq0, 4);
;             sq1 += __shfl_xor(sq1, 1); sq1 += __shfl_xor(sq1, 2); sq1 += __shfl_xor(sq1, 4); }
;             if (!PLAIN && pc == 0) { sst[g * 16 + rr] = sq0; sst[g * 16 + 8 + rr] = sq1; }
.LBB0_1648:
	s_or_b64 exec, exec, s[16:17]
	v_lshl_add_u64 v[88:89], s[22:23], 0, v[154:155]
	v_add_u32_e32 v154, 0x140000, v205
	v_add_u32_e32 v84, 0x140080, v205
	v_add_u32_e32 v86, 0x150000, v205
	global_load_dwordx4 v[62:65], v154, s[22:23]
	global_load_dwordx4 v[58:61], v86, s[22:23]
	v_add_u32_e32 v82, 0x150080, v205
	global_load_dwordx4 v[54:57], v84, s[22:23]
	s_waitcnt lgkmcnt(0)
	global_load_dwordx4 v[50:53], v82, s[22:23]
	ds_write_b128 v200, v[46:49]
	ds_write_b128 v200, v[42:45] offset:64
	ds_read_b128 v[42:45], v201
	ds_read_b128 v[46:49], v201 offset:1152
	v_mov_b32_e32 v103, v155
	v_lshl_add_u64 v[90:91], s[22:23], 0, v[102:103]
	v_mov_b32_e32 v101, v155
	s_waitcnt vmcnt(13) lgkmcnt(1)
	v_pk_fma_f32 v[42:43], v[180:181], v[42:43], v[78:79]
	s_waitcnt vmcnt(12) lgkmcnt(0)
	v_pk_fma_f32 v[46:47], v[180:181], v[46:47], v[74:75]
	v_pk_fma_f32 v[44:45], v[176:177], v[44:45], v[80:81]
	v_pk_mul_f32 v[78:79], v[178:179], v[42:43]
	v_pk_fma_f32 v[48:49], v[176:177], v[48:49], v[76:77]
	v_pk_mul_f32 v[74:75], v[178:179], v[46:47]
	global_store_dwordx4 v[88:89], v[42:45], off nt
	v_pk_mul_f32 v[80:81], v[174:175], v[44:45]
	v_cvt_pk_bf16_f32 v78, v78, v79
	v_pk_mul_f32 v[76:77], v[174:175], v[48:49]
	v_cvt_pk_bf16_f32 v79, v80, v81
	global_store_dwordx4 v[90:91], v[46:49], off nt
	v_cvt_pk_bf16_f32 v74, v74, v75
	v_cvt_pk_bf16_f32 v75, v76, v77
	ds_write_b128 v200, v[38:41]
	ds_write_b128 v200, v[34:37] offset:64
	ds_read_b128 v[34:37], v201
	ds_read_b128 v[38:41], v201 offset:1152
	v_lshl_add_u64 v[76:77], s[22:23], 0, v[100:101]
	v_mov_b32_e32 v99, v155
	v_lshl_add_u64 v[80:81], s[22:23], 0, v[98:99]
	s_waitcnt vmcnt(13) lgkmcnt(1)
	v_pk_fma_f32 v[34:35], v[168:169], v[34:35], v[70:71]
	v_pk_fma_f32 v[36:37], v[166:167], v[36:37], v[72:73]
	v_pk_mul_f32 v[72:73], v[172:173], v[34:35]
	global_store_dwordx4 v[76:77], v[34:37], off nt
	v_pk_mul_f32 v[70:71], v[170:171], v[36:37]
	v_cvt_pk_bf16_f32 v72, v72, v73
	s_waitcnt vmcnt(13) lgkmcnt(0)
	v_pk_fma_f32 v[38:39], v[168:169], v[38:39], v[66:67]
	v_cvt_pk_bf16_f32 v73, v70, v71
	ds_bpermute_b32 v66, v203, v72
	ds_bpermute_b32 v67, v203, v73
	v_pk_fma_f32 v[40:41], v[166:167], v[40:41], v[68:69]
	v_pk_mul_f32 v[68:69], v[172:173], v[38:39]
	v_pk_mul_f32 v[70:71], v[170:171], v[40:41]
	global_store_dwordx4 v[80:81], v[38:41], off nt
	v_cvt_pk_bf16_f32 v68, v68, v69
	v_cvt_pk_bf16_f32 v69, v70, v71
	v_add_u32_e32 v71, 0x48000, v202
	v_lshlrev_b32_e32 v70, 1, v71
	s_waitcnt lgkmcnt(0)
	v_add_u32_e32 v250, 0xfffff040, v70
	v_cndmask_b32_e64 v250, v70, v250, s[40:41]
	v_cndmask_b32_e64 v248, v78, v66, s[40:41]
	v_cndmask_b32_e64 v249, v79, v67, s[40:41]
	global_store_dwordx2 v250, v[248:249], s[20:21] nt
	v_cndmask_b32_e64 v246, v66, v78, s[40:41]
	v_cndmask_b32_e64 v247, v67, v79, s[40:41]
	s_waitcnt lgkmcnt(1)
	v_add_u32_e32 v66, 0x1040, v70
	v_cndmask_b32_e64 v66, v70, v66, s[38:39]
	global_store_dwordx2 v66, v[246:247], s[20:21] nt
	ds_bpermute_b32 v66, v203, v68
	s_waitcnt lgkmcnt(1)
	ds_bpermute_b32 v67, v203, v69
	v_add_u32_e32 v69, 0x4c000, v202
	v_lshlrev_b32_e32 v68, 1, v69
	s_waitcnt lgkmcnt(0)
	v_add_u32_e32 v250, 0xfffff040, v68
	v_cndmask_b32_e64 v250, v68, v250, s[40:41]
	v_cndmask_b32_e64 v248, v74, v66, s[40:41]
	v_cndmask_b32_e64 v249, v75, v67, s[40:41]
	global_store_dwordx2 v250, v[248:249], s[20:21] nt
	v_cndmask_b32_e64 v246, v66, v74, s[40:41]
	v_cndmask_b32_e64 v247, v67, v75, s[40:41]
	v_mul_f32_e32 v35, v35, v35
	v_fmac_f32_e32 v35, v34, v34
	v_mul_f32_e32 v34, v37, v37
	v_mul_f32_e32 v45, v45, v45
	v_fmac_f32_e32 v34, v36, v36
	v_mul_f32_e32 v43, v43, v43
	v_fmac_f32_e32 v45, v44, v44
	v_mul_f32_e32 v44, v47, v47
	v_mul_f32_e32 v47, v49, v49
	v_add_f32_e32 v34, v35, v34
	v_mul_f32_e32 v35, v39, v39
	v_mul_f32_e32 v36, v41, v41
	v_fmac_f32_e32 v47, v48, v48
	v_fmac_f32_e32 v35, v38, v38
	v_fmac_f32_e32 v36, v40, v40
	v_fmac_f32_e32 v43, v42, v42
	v_fmac_f32_e32 v44, v46, v46
	v_add_f32_e32 v35, v35, v36
	v_add_f32_e32 v36, v43, v45
	v_add_f32_e32 v37, v44, v47
	v_add_f32_e32 v34, v36, v34
	v_add_f32_e32 v35, v37, v35
	ds_bpermute_b32 v36, v190, v34
	ds_bpermute_b32 v37, v190, v35
	s_waitcnt lgkmcnt(1)
	v_add_f32_e32 v34, v34, v36
	s_waitcnt lgkmcnt(0)
	v_add_f32_e32 v37, v35, v37
	ds_bpermute_b32 v36, v191, v34
	ds_bpermute_b32 v38, v191, v37
	s_waitcnt lgkmcnt(1)
	v_add_f32_e32 v34, v34, v36
	s_waitcnt lgkmcnt(0)
	v_add_f32_e32 v36, v37, v38
	ds_bpermute_b32 v35, v204, v34
	ds_bpermute_b32 v37, v204, v36
	v_add_u32_e32 v38, 0x1040, v68
	v_cndmask_b32_e64 v38, v68, v38, s[38:39]
	global_store_dwordx2 v38, v[246:247], s[20:21] nt
	s_and_saveexec_b64 s[16:17], s[42:43]
	s_cbranch_execz .LBB0_1658
	s_waitcnt lgkmcnt(1)
	v_add_f32_e32 v34, v34, v35
	s_waitcnt lgkmcnt(0)
	v_add_f32_e32 v35, v36, v37
	ds_write2_b32 v194, v34, v35 offset0:80 offset1:88
; #define LAS __attribute__((address_space(3)))
; #define ERN_EOFF(q, m) (eb + (unsigned)((((q) & 1) * HALF + (m) * 16) * DM + ERN_COL((q) >> 1)))
;     __device__ __forceinline__ void operator()(const f32x4 (&acc)[2][2][4][2], const Unit& u, int wr, int wc, int fr, int fq) const {
;     ...
;         for (int g = 0; g < 8; ++g) { const int ai = g >> 2, m = g & 3;
;             if (g + 1 < 8) ERN_LOADX(g + 1);
;             float sq0 = 0.f, sq1 = 0.f; u32x2 hw[2][2];
; #pragma unroll
;             for (int bj = 0; bj < 2; ++bj) {
;                 *(LAS f32x4*)(st + wr_off) = acc[ai][bj][m][0]; *(LAS f32x4*)(st + wr_off + 64) = acc[ai][bj][m][1];
;                 const f32x4 a0 = *(const LAS f32x4*)(st + rd_off), a1 = *(const LAS f32x4*)(st + rd_off + 8 * 144);
;                 { const f32x4 xv = xb[g & 1][bj][0] + gv[bj] * a0; __builtin_nontemporal_store(xv, (f32x4*)((char*)xo + 4u * ERN_EOFF(g, bj, 0)));
;                   sq0 += (xv.x * xv.x + xv.y * xv.y) + (xv.z * xv.z + xv.w * xv.w);
;                   const f32x4 hv = xv * gsn[bj]; hw[bj][0].x = cvt_pk_bf16(hv.x, hv.y); hw[bj][0].y = cvt_pk_bf16(hv.z, hv.w); }
;                 { const f32x4 xv = xb[g & 1][bj][1] + gv[bj] * a1; __builtin_nontemporal_store(xv, (f32x4*)((char*)xo + 4u * ERN_EOFF(g, bj, 1)));
;                   sq1 += (xv.x * xv.x + xv.y * xv.y) + (xv.z * xv.z + xv.w * xv.w);
;                   const f32x4 hv = xv * gsn[bj]; hw[bj][1].x = cvt_pk_bf16(hv.x, hv.y); hw[bj][1].y = cvt_pk_bf16(hv.z, hv.w); }
;             }
;             if (!NOH && !PLAIN) {
; #pragma unroll
;                 for (int rh = 0; rh < 2; ++rh) { u32x2 rv; rv.x = __shfl_xor(hw[1][rh].x, 8); rv.y = __shfl_xor(hw[1][rh].y, 8);
;                     const unsigned e0 = ERN_EOFF(g, 0, rh);
;                     const unsigned ee = odd ? (e0 - DM + 32) : e0, eo2 = odd ? e0 : (e0 + DM + 32);
;                     *(u32x2*)((char*)ho + 2u * ee) = odd ? rv : hw[0][rh];
;                     *(u32x2*)((char*)ho + 2u * eo2) = odd ? hw[0][rh] : rv; }
;             }
;             if (!PLAIN) { sq0 += __shfl_xor(sq0, 1); sq0 += __shfl_xor(sq0, 2); sq0 += __shfl_xor(sq0, 4);
;             sq1 += __shfl_xor(sq1, 1); sq1 += __shfl_xor(sq1, 2); sq1 += __shfl_xor(sq1, 4); }
;             if (!PLAIN && pc == 0) { sst[g * 16 + rr] = sq0; sst[g * 16 + 8 + rr] = sq1; }
.LBB0_1658:
	s_or_b64 exec, exec, s[16:17]
	v_lshl_add_u64 v[72:73], s[22:23], 0, v[154:155]
	v_add_u32_e32 v154, 0x160000, v205
	v_add_u32_e32 v68, 0x160080, v205
	v_add_u32_e32 v70, 0x170000, v205
	global_load_dwordx4 v[46:49], v154, s[22:23]
	global_load_dwordx4 v[42:45], v70, s[22:23]
	v_add_u32_e32 v66, 0x170080, v205
	global_load_dwordx4 v[38:41], v68, s[22:23]
	s_waitcnt lgkmcnt(0)
	global_load_dwordx4 v[34:37], v66, s[22:23]
	ds_write_b128 v200, v[30:33]
	ds_write_b128 v200, v[26:29] offset:64
	ds_read_b128 v[26:29], v201
	ds_read_b128 v[30:33], v201 offset:1152
	v_mov_b32_e32 v87, v155
	v_lshl_add_u64 v[74:75], s[22:23], 0, v[86:87]
	v_mov_b32_e32 v85, v155
	s_waitcnt vmcnt(13) lgkmcnt(1)
	v_pk_fma_f32 v[26:27], v[180:181], v[26:27], v[62:63]
	s_waitcnt vmcnt(12) lgkmcnt(0)
	v_pk_fma_f32 v[30:31], v[180:181], v[30:31], v[58:59]
	v_pk_fma_f32 v[28:29], v[176:177], v[28:29], v[64:65]
	v_pk_mul_f32 v[62:63], v[178:179], v[26:27]
	v_pk_fma_f32 v[32:33], v[176:177], v[32:33], v[60:61]
	v_pk_mul_f32 v[58:59], v[178:179], v[30:31]
	global_store_dwordx4 v[72:73], v[26:29], off nt
	v_pk_mul_f32 v[64:65], v[174:175], v[28:29]
	v_cvt_pk_bf16_f32 v62, v62, v63
	v_pk_mul_f32 v[60:61], v[174:175], v[32:33]
	v_cvt_pk_bf16_f32 v63, v64, v65
	global_store_dwordx4 v[74:75], v[30:33], off nt
	v_cvt_pk_bf16_f32 v58, v58, v59
	v_cvt_pk_bf16_f32 v59, v60, v61
	ds_write_b128 v200, v[22:25]
	ds_write_b128 v200, v[18:21] offset:64
	ds_read_b128 v[18:21], v201
	ds_read_b128 v[22:25], v201 offset:1152
	v_lshl_add_u64 v[60:61], s[22:23], 0, v[84:85]
	v_mov_b32_e32 v83, v155
	v_lshl_add_u64 v[64:65], s[22:23], 0, v[82:83]
	s_waitcnt vmcnt(13) lgkmcnt(1)
	v_pk_fma_f32 v[18:19], v[168:169], v[18:19], v[54:55]
	v_pk_fma_f32 v[20:21], v[166:167], v[20:21], v[56:57]
	v_pk_mul_f32 v[56:57], v[172:173], v[18:19]
	global_store_dwordx4 v[60:61], v[18:21], off nt
	v_pk_mul_f32 v[54:55], v[170:171], v[20:21]
	v_cvt_pk_bf16_f32 v56, v56, v57
	s_waitcnt vmcnt(13) lgkmcnt(0)
	v_pk_fma_f32 v[22:23], v[168:169], v[22:23], v[50:51]
	v_cvt_pk_bf16_f32 v57, v54, v55
	ds_bpermute_b32 v50, v203, v56
	ds_bpermute_b32 v51, v203, v57
	v_pk_fma_f32 v[24:25], v[166:167], v[24:25], v[52:53]
	v_pk_mul_f32 v[52:53], v[172:173], v[22:23]
	v_pk_mul_f32 v[54:55], v[170:171], v[24:25]
	global_store_dwordx4 v[64:65], v[22:25], off nt
	v_cvt_pk_bf16_f32 v52, v52, v53
	v_cvt_pk_bf16_f32 v53, v54, v55
	v_add_u32_e32 v55, 0x50000, v202
	v_lshlrev_b32_e32 v54, 1, v55
	s_waitcnt lgkmcnt(0)
	v_add_u32_e32 v250, 0xfffff040, v54
	v_cndmask_b32_e64 v250, v54, v250, s[40:41]
	v_cndmask_b32_e64 v248, v62, v50, s[40:41]
	v_cndmask_b32_e64 v249, v63, v51, s[40:41]
	global_store_dwordx2 v250, v[248:249], s[20:21] nt
	v_cndmask_b32_e64 v246, v50, v62, s[40:41]
	v_cndmask_b32_e64 v247, v51, v63, s[40:41]
	s_waitcnt lgkmcnt(1)
	v_add_u32_e32 v50, 0x1040, v54
	v_cndmask_b32_e64 v50, v54, v50, s[38:39]
	global_store_dwordx2 v50, v[246:247], s[20:21] nt
	ds_bpermute_b32 v50, v203, v52
	s_waitcnt lgkmcnt(1)
	ds_bpermute_b32 v51, v203, v53
	v_add_u32_e32 v53, 0x54000, v202
	v_lshlrev_b32_e32 v52, 1, v53
	s_waitcnt lgkmcnt(0)
	v_add_u32_e32 v250, 0xfffff040, v52
	v_cndmask_b32_e64 v250, v52, v250, s[40:41]
	v_cndmask_b32_e64 v248, v58, v50, s[40:41]
	v_cndmask_b32_e64 v249, v59, v51, s[40:41]
	global_store_dwordx2 v250, v[248:249], s[20:21] nt
	v_cndmask_b32_e64 v246, v50, v58, s[40:41]
	v_cndmask_b32_e64 v247, v51, v59, s[40:41]
	v_mul_f32_e32 v19, v19, v19
	v_fmac_f32_e32 v19, v18, v18
	v_mul_f32_e32 v18, v21, v21
	v_mul_f32_e32 v29, v29, v29
	v_fmac_f32_e32 v18, v20, v20
	v_mul_f32_e32 v27, v27, v27
	v_fmac_f32_e32 v29, v28, v28
	v_mul_f32_e32 v28, v31, v31
	v_mul_f32_e32 v31, v33, v33
	v_add_f32_e32 v18, v19, v18
	v_mul_f32_e32 v19, v23, v23
	v_mul_f32_e32 v20, v25, v25
	v_fmac_f32_e32 v31, v32, v32
	v_fmac_f32_e32 v19, v22, v22
	v_fmac_f32_e32 v20, v24, v24
	v_fmac_f32_e32 v27, v26, v26
	v_fmac_f32_e32 v28, v30, v30
	v_add_f32_e32 v19, v19, v20
	v_add_f32_e32 v20, v27, v29
	v_add_f32_e32 v21, v28, v31
	v_add_f32_e32 v18, v20, v18
	v_add_f32_e32 v19, v21, v19
	ds_bpermute_b32 v20, v190, v18
	ds_bpermute_b32 v21, v190, v19
	s_waitcnt lgkmcnt(1)
	v_add_f32_e32 v18, v18, v20
	s_waitcnt lgkmcnt(0)
	v_add_f32_e32 v21, v19, v21
	ds_bpermute_b32 v20, v191, v18
	ds_bpermute_b32 v22, v191, v21
	s_waitcnt lgkmcnt(1)
	v_add_f32_e32 v18, v18, v20
	s_waitcnt lgkmcnt(0)
	v_add_f32_e32 v20, v21, v22
	ds_bpermute_b32 v19, v204, v18
	ds_bpermute_b32 v21, v204, v20
	v_add_u32_e32 v22, 0x1040, v52
	v_cndmask_b32_e64 v22, v52, v22, s[38:39]
	global_store_dwordx2 v22, v[246:247], s[20:21] nt
	s_and_saveexec_b64 s[16:17], s[42:43]
	s_cbranch_execz .LBB0_1668
	s_waitcnt lgkmcnt(1)
	v_add_f32_e32 v18, v18, v19
	s_waitcnt lgkmcnt(0)
	v_add_f32_e32 v19, v20, v21
	ds_write2_b32 v194, v18, v19 offset0:96 offset1:104
; #define LAS __attribute__((address_space(3)))
; #define ERN_EOFF(q, m) (eb + (unsigned)((((q) & 1) * HALF + (m) * 16) * DM + ERN_COL((q) >> 1)))
;     __device__ __forceinline__ void operator()(const f32x4 (&acc)[2][2][4][2], const Unit& u, int wr, int wc, int fr, int fq) const {
;     ...
;         for (int g = 0; g < 8; ++g) { const int ai = g >> 2, m = g & 3;
;             if (g + 1 < 8) ERN_LOADX(g + 1);
;             float sq0 = 0.f, sq1 = 0.f; u32x2 hw[2][2];
; #pragma unroll
;             for (int bj = 0; bj < 2; ++bj) {
;                 *(LAS f32x4*)(st + wr_off) = acc[ai][bj][m][0]; *(LAS f32x4*)(st + wr_off + 64) = acc[ai][bj][m][1];
;                 const f32x4 a0 = *(const LAS f32x4*)(st + rd_off), a1 = *(const LAS f32x4*)(st + rd_off + 8 * 144);
;                 { const f32x4 xv = xb[g & 1][bj][0] + gv[bj] * a0; __builtin_nontemporal_store(xv, (f32x4*)((char*)xo + 4u * ERN_EOFF(g, bj, 0)));
;                   sq0 += (xv.x * xv.x + xv.y * xv.y) + (xv.z * xv.z + xv.w * xv.w);
;                   const f32x4 hv = xv * gsn[bj]; hw[bj][0].x = cvt_pk_bf16(hv.x, hv.y); hw[bj][0].y = cvt_pk_bf16(hv.z, hv.w); }
;                 { const f32x4 xv = xb[g & 1][bj][1] + gv[bj] * a1; __builtin_nontemporal_store(xv, (f32x4*)((char*)xo + 4u * ERN_EOFF(g, bj, 1)));
;                   sq1 += (xv.x * xv.x + xv.y * xv.y) + (xv.z * xv.z + xv.w * xv.w);
;                   const f32x4 hv = xv * gsn[bj]; hw[bj][1].x = cvt_pk_bf16(hv.x, hv.y); hw[bj][1].y = cvt_pk_bf16(hv.z, hv.w); }
;             }
;             if (!NOH && !PLAIN) {
; #pragma unroll
;                 for (int rh = 0; rh < 2; ++rh) { u32x2 rv; rv.x = __shfl_xor(hw[1][rh].x, 8); rv.y = __shfl_xor(hw[1][rh].y, 8);
;                     const unsigned e0 = ERN_EOFF(g, 0, rh);
;                     const unsigned ee = odd ? (e0 - DM + 32) : e0, eo2 = odd ? e0 : (e0 + DM + 32);
;                     *(u32x2*)((char*)ho + 2u * ee) = odd ? rv : hw[0][rh];
;                     *(u32x2*)((char*)ho + 2u * eo2) = odd ? hw[0][rh] : rv; }
;             }
;             if (!PLAIN) { sq0 += __shfl_xor(sq0, 1); sq0 += __shfl_xor(sq0, 2); sq0 += __shfl_xor(sq0, 4);
;             sq1 += __shfl_xor(sq1, 1); sq1 += __shfl_xor(sq1, 2); sq1 += __shfl_xor(sq1, 4); }
;             if (!PLAIN && pc == 0) { sst[g * 16 + rr] = sq0; sst[g * 16 + 8 + rr] = sq1; }
.LBB0_1668:
	s_or_b64 exec, exec, s[16:17]
	ds_write_b128 v200, v[14:17]
	ds_write_b128 v200, v[10:13] offset:64
	ds_read_b128 v[10:13], v201
	ds_read_b128 v[14:17], v201 offset:1152
	s_waitcnt lgkmcnt(5)
	v_lshl_add_u64 v[18:19], s[22:23], 0, v[154:155]
	v_mov_b32_e32 v71, v155
	v_lshl_add_u64 v[22:23], s[22:23], 0, v[70:71]
	s_waitcnt vmcnt(9) lgkmcnt(1)
	v_pk_fma_f32 v[12:13], v[176:177], v[12:13], v[48:49]
	v_pk_fma_f32 v[10:11], v[180:181], v[10:11], v[46:47]
	global_store_dwordx4 v[18:19], v[10:13], off nt
	v_pk_mul_f32 v[18:19], v[174:175], v[12:13]
	v_pk_mul_f32 v[20:21], v[178:179], v[10:11]
	s_waitcnt vmcnt(9) lgkmcnt(0)
	v_pk_fma_f32 v[14:15], v[180:181], v[14:15], v[42:43]
	v_cvt_pk_bf16_f32 v20, v20, v21
	v_cvt_pk_bf16_f32 v21, v18, v19
	v_pk_fma_f32 v[16:17], v[176:177], v[16:17], v[44:45]
	v_pk_mul_f32 v[18:19], v[178:179], v[14:15]
	global_store_dwordx4 v[22:23], v[14:17], off nt
	v_pk_mul_f32 v[22:23], v[174:175], v[16:17]
	v_cvt_pk_bf16_f32 v18, v18, v19
	v_mov_b32_e32 v69, v155
	v_cvt_pk_bf16_f32 v19, v22, v23
	ds_write_b128 v200, v[6:9]
	ds_write_b128 v200, v[2:5] offset:64
	ds_read_b128 v[2:5], v201
	ds_read_b128 v[6:9], v201 offset:1152
	v_lshl_add_u64 v[22:23], s[22:23], 0, v[68:69]
	v_mov_b32_e32 v67, v155
	v_lshl_add_u64 v[24:25], s[22:23], 0, v[66:67]
	s_waitcnt vmcnt(9) lgkmcnt(1)
	v_pk_fma_f32 v[4:5], v[166:167], v[4:5], v[40:41]
	v_pk_fma_f32 v[2:3], v[168:169], v[2:3], v[38:39]
	global_store_dwordx4 v[22:23], v[2:5], off nt
	v_pk_mul_f32 v[22:23], v[170:171], v[4:5]
	v_pk_mul_f32 v[26:27], v[172:173], v[2:3]
	s_waitcnt vmcnt(9) lgkmcnt(0)
	v_pk_fma_f32 v[8:9], v[166:167], v[8:9], v[36:37]
	v_cvt_pk_bf16_f32 v28, v26, v27
	v_cvt_pk_bf16_f32 v23, v22, v23
	ds_bpermute_b32 v22, v203, v28
	ds_bpermute_b32 v23, v203, v23
	v_pk_fma_f32 v[6:7], v[168:169], v[6:7], v[34:35]
	global_store_dwordx4 v[24:25], v[6:9], off nt
	v_pk_mul_f32 v[26:27], v[170:171], v[8:9]
	v_pk_mul_f32 v[24:25], v[172:173], v[6:7]
	s_nop 0
	v_cvt_pk_bf16_f32 v24, v24, v25
	v_cvt_pk_bf16_f32 v25, v26, v27
	v_add_u32_e32 v27, 0x58000, v202
	v_lshlrev_b32_e32 v26, 1, v27
	s_waitcnt lgkmcnt(0)
	v_add_u32_e32 v250, 0xfffff040, v26
	v_cndmask_b32_e64 v250, v26, v250, s[40:41]
	v_cndmask_b32_e64 v248, v20, v22, s[40:41]
	v_cndmask_b32_e64 v249, v21, v23, s[40:41]
	global_store_dwordx2 v250, v[248:249], s[20:21] nt
	v_cndmask_b32_e64 v246, v22, v20, s[40:41]
	v_cndmask_b32_e64 v247, v23, v21, s[40:41]
	s_waitcnt lgkmcnt(1)
	v_add_u32_e32 v22, 0x1040, v26
	v_cndmask_b32_e64 v22, v26, v22, s[38:39]
	global_store_dwordx2 v22, v[246:247], s[20:21] nt
	ds_bpermute_b32 v20, v203, v24
	ds_bpermute_b32 v21, v203, v25
	s_waitcnt lgkmcnt(2)
	v_add_u32_e32 v23, 0x5c000, v202
	v_lshlrev_b32_e32 v22, 1, v23
	s_waitcnt lgkmcnt(0)
	v_add_u32_e32 v250, 0xfffff040, v22
	v_cndmask_b32_e64 v250, v22, v250, s[40:41]
	v_cndmask_b32_e64 v248, v18, v20, s[40:41]
	v_cndmask_b32_e64 v249, v19, v21, s[40:41]
	global_store_dwordx2 v250, v[248:249], s[20:21] nt
	v_cndmask_b32_e64 v246, v20, v18, s[40:41]
	v_cndmask_b32_e64 v247, v21, v19, s[40:41]
	v_mul_f32_e32 v3, v3, v3
	v_fmac_f32_e32 v3, v2, v2
	v_mul_f32_e32 v2, v5, v5
	v_mul_f32_e32 v13, v13, v13
	v_fmac_f32_e32 v2, v4, v4
	v_mul_f32_e32 v11, v11, v11
	v_fmac_f32_e32 v13, v12, v12
	v_mul_f32_e32 v12, v15, v15
	v_mul_f32_e32 v15, v17, v17
	v_add_f32_e32 v2, v3, v2
	v_mul_f32_e32 v3, v7, v7
	v_mul_f32_e32 v4, v9, v9
	v_fmac_f32_e32 v15, v16, v16
	v_fmac_f32_e32 v3, v6, v6
	v_fmac_f32_e32 v4, v8, v8
	v_fmac_f32_e32 v11, v10, v10
	v_fmac_f32_e32 v12, v14, v14
	v_add_f32_e32 v3, v3, v4
	v_add_f32_e32 v4, v11, v13
	v_add_f32_e32 v5, v12, v15
	v_add_f32_e32 v2, v4, v2
	v_add_f32_e32 v3, v5, v3
	ds_bpermute_b32 v4, v190, v2
	ds_bpermute_b32 v5, v190, v3
	s_waitcnt lgkmcnt(1)
	v_add_f32_e32 v2, v2, v4
	s_waitcnt lgkmcnt(0)
	v_add_f32_e32 v5, v3, v5
	ds_bpermute_b32 v4, v191, v2
	ds_bpermute_b32 v6, v191, v5
	s_waitcnt lgkmcnt(1)
	v_add_f32_e32 v2, v2, v4
	s_waitcnt lgkmcnt(0)
	v_add_f32_e32 v4, v5, v6
	ds_bpermute_b32 v3, v204, v2
	ds_bpermute_b32 v5, v204, v4
	v_add_u32_e32 v6, 0x1040, v22
	v_cndmask_b32_e64 v6, v22, v6, s[38:39]
	global_store_dwordx2 v6, v[246:247], s[20:21] nt
	s_and_saveexec_b64 s[16:17], s[42:43]
	s_cbranch_execz .LBB0_1678
	s_waitcnt lgkmcnt(1)
	v_add_f32_e32 v2, v2, v3
	s_waitcnt lgkmcnt(0)
	v_add_f32_e32 v3, v4, v5
	ds_write2_b32 v194, v2, v3 offset0:112 offset1:120

; #define LAS __attribute__((address_space(3)))
; #define ERN_EOFF(q, m) (eb + (unsigned)((((q) & 1) * HALF + (m) * 16) * DM + ERN_COL((q) >> 1)))
;     __device__ __forceinline__ void operator()(const f32x4 (&acc)[2][2][4][2], const Unit& u, int wr, int wc, int fr, int fq) const {
;         const int s = u.pm >> 5, lane = fq * 16 + fr, rr = lane >> 3, pc = lane & 7;
;         const float* __restrict__ xi = xin + (size_t)u.pm * BM * DM; float* __restrict__ xo = xout + (size_t)u.pm * BM * DM; bf16_t* __restrict__ ho = Hn + (size_t)u.pm * BM * DM;
;         LAS unsigned char* st = lds_epi + (wr * 4 + wc) * 2304;
;         LAS float* sst = (LAS float*)(lds_epi + 18432 + (wr * 4 + wc) * 512);
;         const int colr = u.pn * BM + wc * 64 + 4 * pc;
;         const unsigned eb = (unsigned)((wr * 64 + rr) * DM + colr);
;         f32x4 gv[2], gsn[2];
; #pragma unroll
;         for (int bj = 0; bj < 2; ++bj) { gv[bj] = *(const f32x4*)(gate + (size_t)s * MODW + colr + bj * 32) * (0.5f * GS2);
;             if (!PLAIN) gsn[bj] = *(const f32x4*)(gnext + colr + bj * 32) * (*(const f32x4*)(scnext + (size_t)s * MODW + colr + bj * 32) + 1.0f); else gsn[bj] = gv[bj]; }
;         const unsigned wr_off = (unsigned)(fr * 144 + 16 * fq), rd_off = (unsigned)(rr * 144 + pc * 16);
;         const bool odd = (rr & 1) != 0;
;         f32x4 xb[2][2][2];
;     ...
;         ERN_LOADX(0);
; #pragma unroll
;         for (int g = 0; g < 8; ++g) { const int ai = g >> 2, m = g & 3;
;             if (g + 1 < 8) ERN_LOADX(g + 1);
;             float sq0 = 0.f, sq1 = 0.f; u32x2 hw[2][2];
; #pragma unroll
;             for (int bj = 0; bj < 2; ++bj) {
;                 *(LAS f32x4*)(st + wr_off) = acc[ai][bj][m][0]; *(LAS f32x4*)(st + wr_off + 64) = acc[ai][bj][m][1];
;                 const f32x4 a0 = *(const LAS f32x4*)(st + rd_off), a1 = *(const LAS f32x4*)(st + rd_off + 8 * 144);
;                 { const f32x4 xv = xb[g & 1][bj][0] + gv[bj] * a0; __builtin_nontemporal_store(xv, (f32x4*)((char*)xo + 4u * ERN_EOFF(g, bj, 0)));
;                   sq0 += (xv.x * xv.x + xv.y * xv.y) + (xv.z * xv.z + xv.w * xv.w);
;                   const f32x4 hv = xv * gsn[bj]; hw[bj][0].x = cvt_pk_bf16(hv.x, hv.y); hw[bj][0].y = cvt_pk_bf16(hv.z, hv.w); }
;                 { const f32x4 xv = xb[g & 1][bj][1] + gv[bj] * a1; __builtin_nontemporal_store(xv, (f32x4*)((char*)xo + 4u * ERN_EOFF(g, bj, 1)));
.LBB0_1929:
	s_ashr_i32 s18, s4, 5
	s_ashr_i32 s5, s4, 31
	v_lshl_or_b32 v130, s0, 8, v192
	s_mul_i32 s20, s18, 0x12000
	s_mul_hi_i32 s0, s18, 0x12000
	s_add_u32 s18, s33, s20
	v_ashrrev_i32_e32 v131, 31, v130
	s_addc_u32 s19, s34, s0
	v_lshlrev_b64 v[132:133], 2, v[130:131]
	v_lshl_add_u64 v[134:135], s[18:19], 0, v[132:133]
	s_add_u32 s18, s35, s20
	s_addc_u32 s19, s36, s0
	v_lshl_add_u64 v[136:137], s[10:11], 0, v[132:133]
	v_lshl_add_u64 v[132:133], s[18:19], 0, v[132:133]
	s_lshl_b64 s[18:19], s[4:5], 21
	s_add_u32 s20, s90, s18
	v_add_u32_e32 v202, v130, v193
	s_addc_u32 s21, s91, s19
	v_lshlrev_b32_e32 v205, 2, v202
	global_load_dwordx4 v[170:173], v[136:137], off
	global_load_dwordx4 v[166:169], v[134:135], off
	global_load_dwordx4 v[186:189], v[134:135], off offset:128
	global_load_dwordx4 v[206:209], v[132:133], off
	global_load_dwordx4 v[210:213], v[132:133], off offset:128
	global_load_dwordx4 v[214:217], v205, s[20:21]
	v_add_u32_e32 v130, 0x10000, v205
	global_load_dwordx4 v[218:221], v130, s[20:21]
	global_load_dwordx4 v[222:225], v[136:137], off offset:128
	global_load_dwordx4 v[226:229], v205, s[20:21] offset:128
	v_add_u32_e32 v204, 0x10080, v205
	global_load_dwordx4 v[230:233], v204, s[20:21]
	v_add_u32_e32 v130, 0x20000, v205
	v_add_u32_e32 v154, 0x30000, v205
	v_add_u32_e32 v184, 0x20080, v205
	v_add_u32_e32 v182, 0x30080, v205
	global_load_dwordx4 v[142:145], v130, s[20:21]
	global_load_dwordx4 v[138:141], v154, s[20:21]
	global_load_dwordx4 v[134:137], v184, s[20:21]
	s_nop 0
	global_load_dwordx4 v[130:133], v182, s[20:21]
	ds_write_b128 v200, v[126:129]
	ds_write_b128 v200, v[122:125] offset:64
	v_and_b32_e32 v127, 64, v199
	ds_read_b128 v[122:125], v201
	ds_read_b128 v[234:237], v201 offset:1152
	v_xor_b32_e32 v126, 8, v199
	v_add_u32_e32 v183, 64, v127
	v_cmp_lt_i32_e32 vcc, v126, v183
	v_add_u32_e32 v185, 0x4000, v202
	v_lshlrev_b32_e32 v238, 2, v185
	v_cndmask_b32_e32 v126, v199, v126, vcc
	v_lshlrev_b32_e32 v203, 2, v126
	s_lshl_b64 s[18:19], s[4:5], 20
	s_add_u32 s18, s93, s18
	s_addc_u32 s19, s92, s19
	s_waitcnt vmcnt(0)
	v_pk_mul_f32 v[180:181], v[166:167], 0.5 op_sel_hi:[1,0]
	v_pk_mul_f32 v[176:177], v[168:169], 0.5 op_sel_hi:[1,0]
	v_pk_add_f32 v[126:127], v[208:209], 1.0 op_sel_hi:[1,0]
	v_pk_add_f32 v[128:129], v[206:207], 1.0 op_sel_hi:[1,0]
	v_pk_mul_f32 v[174:175], v[172:173], v[126:127]
	v_pk_mul_f32 v[178:179], v[170:171], v[128:129]
	s_waitcnt lgkmcnt(1)
	v_pk_fma_f32 v[126:127], v[180:181], v[122:123], v[214:215]
	s_waitcnt lgkmcnt(0)
	v_pk_fma_f32 v[122:123], v[180:181], v[234:235], v[218:219]
	v_pk_mul_f32 v[168:169], v[186:187], 0.5 op_sel_hi:[1,0]
	v_pk_fma_f32 v[128:129], v[176:177], v[124:125], v[216:217]
	v_pk_fma_f32 v[124:125], v[176:177], v[236:237], v[220:221]
	v_pk_mul_f32 v[186:187], v[178:179], v[122:123]
	v_pk_mul_f32 v[166:167], v[188:189], 0.5 op_sel_hi:[1,0]
	global_store_dwordx4 v205, v[126:129], s[20:21] nt
	v_pk_mul_f32 v[170:171], v[174:175], v[128:129]
	v_pk_mul_f32 v[172:173], v[178:179], v[126:127]
	v_pk_mul_f32 v[206:207], v[174:175], v[124:125]
	v_cvt_pk_bf16_f32 v188, v172, v173
	v_cvt_pk_bf16_f32 v189, v170, v171
	global_store_dwordx4 v238, v[122:125], s[20:21] nt
	v_cvt_pk_bf16_f32 v186, v186, v187
	v_cvt_pk_bf16_f32 v187, v206, v207
	ds_write_b128 v200, v[118:121]
	ds_write_b128 v200, v[114:117] offset:64
	ds_read_b128 v[114:117], v201
	ds_read_b128 v[206:209], v201 offset:1152
	v_pk_add_f32 v[190:191], v[212:213], 1.0 op_sel_hi:[1,0]
	v_pk_add_f32 v[118:119], v[210:211], 1.0 op_sel_hi:[1,0]
	v_pk_mul_f32 v[170:171], v[224:225], v[190:191]
	v_pk_mul_f32 v[172:173], v[222:223], v[118:119]
	s_waitcnt lgkmcnt(1)
	v_pk_fma_f32 v[120:121], v[166:167], v[116:117], v[228:229]
	v_pk_fma_f32 v[118:119], v[168:169], v[114:115], v[226:227]
	s_waitcnt lgkmcnt(0)
	v_pk_fma_f32 v[114:115], v[168:169], v[206:207], v[230:231]
	v_pk_mul_f32 v[190:191], v[170:171], v[120:121]
	v_pk_mul_f32 v[206:207], v[172:173], v[118:119]
	global_store_dwordx4 v205, v[118:121], s[20:21] offset:128 nt
	v_cvt_pk_bf16_f32 v206, v206, v207
	v_cvt_pk_bf16_f32 v191, v190, v191
	ds_bpermute_b32 v190, v203, v206
	ds_bpermute_b32 v191, v203, v191
	v_pk_fma_f32 v[116:117], v[166:167], v[208:209], v[232:233]
	v_pk_mul_f32 v[206:207], v[172:173], v[114:115]
	global_store_dwordx4 v204, v[114:117], s[20:21] nt
	v_cvt_pk_bf16_f32 v204, v206, v207
	v_lshlrev_b32_e32 v207, 1, v202
	v_pk_mul_f32 v[208:209], v[170:171], v[116:117]
	s_nop 0
	v_cvt_pk_bf16_f32 v206, v208, v209
	s_waitcnt lgkmcnt(0)
	v_add_u32_e32 v250, 0xfffff040, v207
	v_cndmask_b32_e64 v250, v207, v250, s[40:41]
	v_cndmask_b32_e64 v248, v188, v190, s[40:41]
	v_cndmask_b32_e64 v249, v189, v191, s[40:41]
	global_store_dwordx2 v250, v[248:249], s[18:19] nt
	v_cndmask_b32_e64 v246, v190, v188, s[40:41]
	v_cndmask_b32_e64 v247, v191, v189, s[40:41]
	s_waitcnt lgkmcnt(1)
	v_add_u32_e32 v190, 0x1040, v207
	v_cndmask_b32_e64 v190, v207, v190, s[38:39]
	global_store_dwordx2 v190, v[246:247], s[18:19] nt
	ds_bpermute_b32 v188, v203, v204
	ds_bpermute_b32 v189, v203, v206
	v_lshlrev_b32_e32 v206, 1, v185
	s_waitcnt lgkmcnt(0)
; #define LAS __attribute__((address_space(3)))
; #define ERN_EOFF(q, m) (eb + (unsigned)((((q) & 1) * HALF + (m) * 16) * DM + ERN_COL((q) >> 1)))
;     __device__ __forceinline__ void operator()(const f32x4 (&acc)[2][2][4][2], const Unit& u, int wr, int wc, int fr, int fq) const {
;     ...
;         for (int g = 0; g < 8; ++g) { const int ai = g >> 2, m = g & 3;
;             if (g + 1 < 8) ERN_LOADX(g + 1);
;             float sq0 = 0.f, sq1 = 0.f; u32x2 hw[2][2];
; #pragma unroll
;             for (int bj = 0; bj < 2; ++bj) {
;                 *(LAS f32x4*)(st + wr_off) = acc[ai][bj][m][0]; *(LAS f32x4*)(st + wr_off + 64) = acc[ai][bj][m][1];
;                 const f32x4 a0 = *(const LAS f32x4*)(st + rd_off), a1 = *(const LAS f32x4*)(st + rd_off + 8 * 144);
;                 { const f32x4 xv = xb[g & 1][bj][0] + gv[bj] * a0; __builtin_nontemporal_store(xv, (f32x4*)((char*)xo + 4u * ERN_EOFF(g, bj, 0)));
;                   sq0 += (xv.x * xv.x + xv.y * xv.y) + (xv.z * xv.z + xv.w * xv.w);
;                   const f32x4 hv = xv * gsn[bj]; hw[bj][0].x = cvt_pk_bf16(hv.x, hv.y); hw[bj][0].y = cvt_pk_bf16(hv.z, hv.w); }
;                 { const f32x4 xv = xb[g & 1][bj][1] + gv[bj] * a1; __builtin_nontemporal_store(xv, (f32x4*)((char*)xo + 4u * ERN_EOFF(g, bj, 1)));
;                   sq1 += (xv.x * xv.x + xv.y * xv.y) + (xv.z * xv.z + xv.w * xv.w);
;                   const f32x4 hv = xv * gsn[bj]; hw[bj][1].x = cvt_pk_bf16(hv.x, hv.y); hw[bj][1].y = cvt_pk_bf16(hv.z, hv.w); }
;             }
;             if (!NOH && !PLAIN) {
; #pragma unroll
;                 for (int rh = 0; rh < 2; ++rh) { u32x2 rv; rv.x = __shfl_xor(hw[1][rh].x, 8); rv.y = __shfl_xor(hw[1][rh].y, 8);
;                     const unsigned e0 = ERN_EOFF(g, 0, rh);
;                     const unsigned ee = odd ? (e0 - DM + 32) : e0, eo2 = odd ? e0 : (e0 + DM + 32);
;                     *(u32x2*)((char*)ho + 2u * ee) = odd ? rv : hw[0][rh];
;                     *(u32x2*)((char*)ho + 2u * eo2) = odd ? hw[0][rh] : rv; }
;             }
;             if (!PLAIN) { sq0 += __shfl_xor(sq0, 1); sq0 += __shfl_xor(sq0, 2); sq0 += __shfl_xor(sq0, 4);
;             sq1 += __shfl_xor(sq1, 1); sq1 += __shfl_xor(sq1, 2); sq1 += __shfl_xor(sq1, 4); }
;             if (!PLAIN && pc == 0) { sst[g * 16 + rr] = sq0; sst[g * 16 + 8 + rr] = sq1; }
	v_add_u32_e32 v250, 0xfffff040, v206
	v_cndmask_b32_e64 v250, v206, v250, s[40:41]
	v_cndmask_b32_e64 v248, v186, v188, s[40:41]
	v_cndmask_b32_e64 v249, v187, v189, s[40:41]
	global_store_dwordx2 v250, v[248:249], s[18:19] nt
	v_cndmask_b32_e64 v246, v188, v186, s[40:41]
	v_cndmask_b32_e64 v247, v189, v187, s[40:41]
	v_mul_f32_e32 v119, v119, v119
	v_mul_f32_e32 v127, v127, v127
	v_mul_f32_e32 v129, v129, v129
	v_fmac_f32_e32 v119, v118, v118
	v_mul_f32_e32 v118, v121, v121
	v_fmac_f32_e32 v129, v128, v128
	v_fmac_f32_e32 v118, v120, v120
	v_mul_f32_e32 v115, v115, v115
	v_fmac_f32_e32 v127, v126, v126
	v_add_f32_e32 v118, v119, v118
	v_fmac_f32_e32 v115, v114, v114
	v_mul_f32_e32 v114, v117, v117
	v_add_f32_e32 v117, v127, v129
	v_add_f32_e32 v117, v117, v118
	v_xor_b32_e32 v118, 1, v199
	v_cmp_lt_i32_e32 vcc, v118, v183
	v_mul_f32_e32 v123, v123, v123
	v_mul_f32_e32 v125, v125, v125
	v_cndmask_b32_e32 v118, v199, v118, vcc
	v_lshlrev_b32_e32 v190, 2, v118
	ds_bpermute_b32 v118, v190, v117
	v_fmac_f32_e32 v114, v116, v116
	v_fmac_f32_e32 v125, v124, v124
	v_fmac_f32_e32 v123, v122, v122
	v_add_f32_e32 v114, v115, v114
	s_waitcnt lgkmcnt(0)
	v_add_f32_e32 v116, v117, v118
	v_xor_b32_e32 v117, 2, v199
	v_cmp_lt_i32_e32 vcc, v117, v183
	v_add_f32_e32 v115, v123, v125
	v_add_f32_e32 v115, v115, v114
	v_cndmask_b32_e32 v117, v199, v117, vcc
	v_lshlrev_b32_e32 v191, 2, v117
	ds_bpermute_b32 v117, v191, v116
	ds_bpermute_b32 v118, v190, v115
	s_waitcnt lgkmcnt(1)
	v_add_f32_e32 v114, v116, v117
	s_waitcnt lgkmcnt(0)
	v_add_f32_e32 v117, v115, v118
	ds_bpermute_b32 v118, v191, v117
	v_xor_b32_e32 v116, 4, v199
	v_cmp_lt_i32_e32 vcc, v116, v183
	s_nop 1
	v_cndmask_b32_e32 v115, v199, v116, vcc
	v_lshlrev_b32_e32 v204, 2, v115
	s_waitcnt lgkmcnt(0)
	v_add_f32_e32 v116, v117, v118
	ds_bpermute_b32 v115, v204, v114
	ds_bpermute_b32 v117, v204, v116
	v_add_u32_e32 v118, 0x1040, v206
	v_cndmask_b32_e64 v118, v206, v118, s[38:39]
	global_store_dwordx2 v118, v[246:247], s[18:19] nt
	s_and_saveexec_b64 s[22:23], s[42:43]
	s_cbranch_execz .LBB0_1939
	s_waitcnt lgkmcnt(1)
	v_add_f32_e32 v114, v114, v115
	s_waitcnt lgkmcnt(0)
	v_add_f32_e32 v115, v116, v117
	ds_write2_b32 v194, v114, v115 offset1:8
.LBB0_1939:
	s_or_b64 exec, exec, s[22:23]
	v_lshl_add_u64 v[206:207], s[20:21], 0, v[154:155]
	v_add_u32_e32 v114, 0x40000, v205
	v_add_u32_e32 v154, 0x50000, v205
	v_add_u32_e32 v186, 0x40080, v205
	global_load_dwordx4 v[122:125], v154, s[20:21]
	global_load_dwordx4 v[118:121], v186, s[20:21]
	v_add_u32_e32 v188, 0x50080, v205
	global_load_dwordx4 v[126:129], v114, s[20:21]
	s_waitcnt lgkmcnt(0)
	global_load_dwordx4 v[114:117], v188, s[20:21]
	ds_write_b128 v200, v[110:113]
	ds_write_b128 v200, v[106:109] offset:64
	ds_read_b128 v[106:109], v201
	ds_read_b128 v[110:113], v201 offset:1152
	v_mov_b32_e32 v185, v155
	v_mov_b32_e32 v183, v155
	v_lshl_add_u64 v[182:183], s[20:21], 0, v[182:183]
	s_waitcnt lgkmcnt(1)
	v_pk_fma_f32 v[108:109], v[176:177], v[108:109], v[144:145]
	v_add_u32_e32 v144, 0x8000, v202
	v_pk_fma_f32 v[106:107], v[180:181], v[106:107], v[142:143]
	v_lshlrev_b32_e32 v142, 2, v144
	s_waitcnt lgkmcnt(0)
	v_pk_fma_f32 v[110:111], v[180:181], v[110:111], v[138:139]
	global_store_dwordx4 v142, v[106:109], s[20:21] nt
	v_pk_mul_f32 v[142:143], v[178:179], v[106:107]
	v_pk_fma_f32 v[112:113], v[176:177], v[112:113], v[140:141]
	v_pk_mul_f32 v[138:139], v[178:179], v[110:111]
	v_pk_mul_f32 v[208:209], v[174:175], v[108:109]
	v_cvt_pk_bf16_f32 v142, v142, v143
	v_pk_mul_f32 v[140:141], v[174:175], v[112:113]
	v_cvt_pk_bf16_f32 v143, v208, v209
	global_store_dwordx4 v[206:207], v[110:113], off nt
	v_cvt_pk_bf16_f32 v138, v138, v139
	v_cvt_pk_bf16_f32 v139, v140, v141
	ds_write_b128 v200, v[102:105]
	ds_write_b128 v200, v[98:101] offset:64
	ds_read_b128 v[98:101], v201
	ds_read_b128 v[102:105], v201 offset:1152
	v_lshl_add_u64 v[140:141], s[20:21], 0, v[184:185]
	s_waitcnt lgkmcnt(1)
	v_pk_fma_f32 v[98:99], v[168:169], v[98:99], v[134:135]
	v_pk_fma_f32 v[100:101], v[166:167], v[100:101], v[136:137]
	v_pk_mul_f32 v[136:137], v[172:173], v[98:99]
	global_store_dwordx4 v[140:141], v[98:101], off nt
	v_pk_mul_f32 v[134:135], v[170:171], v[100:101]
	v_cvt_pk_bf16_f32 v136, v136, v137
	s_waitcnt lgkmcnt(0)
	v_pk_fma_f32 v[102:103], v[168:169], v[102:103], v[130:131]
	v_cvt_pk_bf16_f32 v137, v134, v135
	ds_bpermute_b32 v130, v203, v136
	ds_bpermute_b32 v131, v203, v137
	v_pk_fma_f32 v[104:105], v[166:167], v[104:105], v[132:133]
	v_pk_mul_f32 v[132:133], v[172:173], v[102:103]
	v_pk_mul_f32 v[134:135], v[170:171], v[104:105]
	global_store_dwordx4 v[182:183], v[102:105], off nt
	v_cvt_pk_bf16_f32 v132, v132, v133
	v_cvt_pk_bf16_f32 v133, v134, v135
	v_lshlrev_b32_e32 v134, 1, v144
	s_waitcnt lgkmcnt(0)
	v_add_u32_e32 v250, 0xfffff040, v134
	v_cndmask_b32_e64 v250, v134, v250, s[40:41]
	v_cndmask_b32_e64 v248, v142, v130, s[40:41]
	v_cndmask_b32_e64 v249, v143, v131, s[40:41]
	global_store_dwordx2 v250, v[248:249], s[18:19] nt
	v_cndmask_b32_e64 v246, v130, v142, s[40:41]
	v_cndmask_b32_e64 v247, v131, v143, s[40:41]
	s_waitcnt lgkmcnt(1)
	v_add_u32_e32 v130, 0x1040, v134
	v_cndmask_b32_e64 v130, v134, v130, s[38:39]
	global_store_dwordx2 v130, v[246:247], s[18:19] nt
	ds_bpermute_b32 v130, v203, v132
	s_waitcnt lgkmcnt(1)
	ds_bpermute_b32 v131, v203, v133
	v_add_u32_e32 v133, 0xc000, v202
	v_lshlrev_b32_e32 v132, 1, v133
	s_waitcnt lgkmcnt(0)
	v_add_u32_e32 v250, 0xfffff040, v132
	v_cndmask_b32_e64 v250, v132, v250, s[40:41]
	v_cndmask_b32_e64 v248, v138, v130, s[40:41]
	v_cndmask_b32_e64 v249, v139, v131, s[40:41]
	global_store_dwordx2 v250, v[248:249], s[18:19] nt
	v_cndmask_b32_e64 v246, v130, v138, s[40:41]
	v_cndmask_b32_e64 v247, v131, v139, s[40:41]
	v_mul_f32_e32 v99, v99, v99
	v_fmac_f32_e32 v99, v98, v98
	v_mul_f32_e32 v98, v101, v101
	v_mul_f32_e32 v109, v109, v109
	v_fmac_f32_e32 v98, v100, v100
	v_mul_f32_e32 v107, v107, v107
	v_fmac_f32_e32 v109, v108, v108
	v_mul_f32_e32 v108, v111, v111
	v_mul_f32_e32 v111, v113, v113
	v_add_f32_e32 v98, v99, v98
	v_mul_f32_e32 v99, v103, v103
	v_mul_f32_e32 v100, v105, v105
	v_fmac_f32_e32 v111, v112, v112
	v_fmac_f32_e32 v99, v102, v102
	v_fmac_f32_e32 v100, v104, v104
	v_fmac_f32_e32 v107, v106, v106
	v_fmac_f32_e32 v108, v110, v110
	v_add_f32_e32 v99, v99, v100
	v_add_f32_e32 v100, v107, v109
	v_add_f32_e32 v101, v108, v111
	v_add_f32_e32 v98, v100, v98
	v_add_f32_e32 v99, v101, v99
	ds_bpermute_b32 v100, v190, v98
	ds_bpermute_b32 v101, v190, v99
	s_waitcnt lgkmcnt(1)
	v_add_f32_e32 v98, v98, v100
	s_waitcnt lgkmcnt(0)
	v_add_f32_e32 v101, v99, v101
	ds_bpermute_b32 v100, v191, v98
	ds_bpermute_b32 v102, v191, v101
	s_waitcnt lgkmcnt(1)
	v_add_f32_e32 v98, v98, v100
	s_waitcnt lgkmcnt(0)
	v_add_f32_e32 v100, v101, v102
	ds_bpermute_b32 v99, v204, v98
	ds_bpermute_b32 v101, v204, v100
	v_add_u32_e32 v102, 0x1040, v132
	v_cndmask_b32_e64 v102, v132, v102, s[38:39]
	global_store_dwordx2 v102, v[246:247], s[18:19] nt
	s_and_saveexec_b64 s[22:23], s[42:43]
	s_cbranch_execz .LBB0_1949
; #define LAS __attribute__((address_space(3)))
; #define ERN_EOFF(q, m) (eb + (unsigned)((((q) & 1) * HALF + (m) * 16) * DM + ERN_COL((q) >> 1)))
;     __device__ __forceinline__ void operator()(const f32x4 (&acc)[2][2][4][2], const Unit& u, int wr, int wc, int fr, int fq) const {
;     ...
;         for (int g = 0; g < 8; ++g) { const int ai = g >> 2, m = g & 3;
;             if (g + 1 < 8) ERN_LOADX(g + 1);
;             float sq0 = 0.f, sq1 = 0.f; u32x2 hw[2][2];
; #pragma unroll
;             for (int bj = 0; bj < 2; ++bj) {
;                 *(LAS f32x4*)(st + wr_off) = acc[ai][bj][m][0]; *(LAS f32x4*)(st + wr_off + 64) = acc[ai][bj][m][1];
;                 const f32x4 a0 = *(const LAS f32x4*)(st + rd_off), a1 = *(const LAS f32x4*)(st + rd_off + 8 * 144);
;                 { const f32x4 xv = xb[g & 1][bj][0] + gv[bj] * a0; __builtin_nontemporal_store(xv, (f32x4*)((char*)xo + 4u * ERN_EOFF(g, bj, 0)));
;                   sq0 += (xv.x * xv.x + xv.y * xv.y) + (xv.z * xv.z + xv.w * xv.w);
;                   const f32x4 hv = xv * gsn[bj]; hw[bj][0].x = cvt_pk_bf16(hv.x, hv.y); hw[bj][0].y = cvt_pk_bf16(hv.z, hv.w); }
;                 { const f32x4 xv = xb[g & 1][bj][1] + gv[bj] * a1; __builtin_nontemporal_store(xv, (f32x4*)((char*)xo + 4u * ERN_EOFF(g, bj, 1)));
;                   sq1 += (xv.x * xv.x + xv.y * xv.y) + (xv.z * xv.z + xv.w * xv.w);
;                   const f32x4 hv = xv * gsn[bj]; hw[bj][1].x = cvt_pk_bf16(hv.x, hv.y); hw[bj][1].y = cvt_pk_bf16(hv.z, hv.w); }
;             }
;             if (!NOH && !PLAIN) {
; #pragma unroll
;                 for (int rh = 0; rh < 2; ++rh) { u32x2 rv; rv.x = __shfl_xor(hw[1][rh].x, 8); rv.y = __shfl_xor(hw[1][rh].y, 8);
;                     const unsigned e0 = ERN_EOFF(g, 0, rh);
;                     const unsigned ee = odd ? (e0 - DM + 32) : e0, eo2 = odd ? e0 : (e0 + DM + 32);
;                     *(u32x2*)((char*)ho + 2u * ee) = odd ? rv : hw[0][rh];
;                     *(u32x2*)((char*)ho + 2u * eo2) = odd ? hw[0][rh] : rv; }
;             }
;             if (!PLAIN) { sq0 += __shfl_xor(sq0, 1); sq0 += __shfl_xor(sq0, 2); sq0 += __shfl_xor(sq0, 4);
;             sq1 += __shfl_xor(sq1, 1); sq1 += __shfl_xor(sq1, 2); sq1 += __shfl_xor(sq1, 4); }
;             if (!PLAIN && pc == 0) { sst[g * 16 + rr] = sq0; sst[g * 16 + 8 + rr] = sq1; }
	s_waitcnt lgkmcnt(1)
	v_add_f32_e32 v98, v98, v99
	s_waitcnt lgkmcnt(0)
	v_add_f32_e32 v99, v100, v101
	ds_write2_b32 v194, v98, v99 offset0:16 offset1:24
.LBB0_1949:
	s_or_b64 exec, exec, s[22:23]
	v_lshl_add_u64 v[134:135], s[20:21], 0, v[154:155]
	v_add_u32_e32 v98, 0x60000, v205
	v_add_u32_e32 v154, 0x70000, v205
	v_add_u32_e32 v130, 0x60080, v205
	global_load_dwordx4 v[106:109], v154, s[20:21]
	global_load_dwordx4 v[102:105], v130, s[20:21]
	v_add_u32_e32 v132, 0x70080, v205
	global_load_dwordx4 v[110:113], v98, s[20:21]
	s_waitcnt lgkmcnt(0)
	global_load_dwordx4 v[98:101], v132, s[20:21]
	ds_write_b128 v200, v[94:97]
	ds_write_b128 v200, v[90:93] offset:64
	ds_read_b128 v[90:93], v201
	ds_read_b128 v[94:97], v201 offset:1152
	v_mov_b32_e32 v187, v155
	v_mov_b32_e32 v189, v155
	s_waitcnt vmcnt(11) lgkmcnt(1)
	v_pk_fma_f32 v[92:93], v[176:177], v[92:93], v[128:129]
	v_add_u32_e32 v128, 0x10000, v202
	v_pk_fma_f32 v[90:91], v[180:181], v[90:91], v[126:127]
	v_lshlrev_b32_e32 v126, 2, v128
	s_waitcnt lgkmcnt(0)
	v_pk_fma_f32 v[94:95], v[180:181], v[94:95], v[122:123]
	global_store_dwordx4 v126, v[90:93], s[20:21] nt
	v_pk_mul_f32 v[126:127], v[178:179], v[90:91]
	v_pk_fma_f32 v[96:97], v[176:177], v[96:97], v[124:125]
	v_pk_mul_f32 v[122:123], v[178:179], v[94:95]
	v_pk_mul_f32 v[136:137], v[174:175], v[92:93]
	v_cvt_pk_bf16_f32 v126, v126, v127
	v_pk_mul_f32 v[124:125], v[174:175], v[96:97]
	v_cvt_pk_bf16_f32 v127, v136, v137
	global_store_dwordx4 v[134:135], v[94:97], off nt
	v_cvt_pk_bf16_f32 v122, v122, v123
	v_cvt_pk_bf16_f32 v123, v124, v125
	ds_write_b128 v200, v[86:89]
	ds_write_b128 v200, v[82:85] offset:64
	ds_read_b128 v[82:85], v201
	ds_read_b128 v[86:89], v201 offset:1152
	v_lshl_add_u64 v[124:125], s[20:21], 0, v[186:187]
	v_lshl_add_u64 v[134:135], s[20:21], 0, v[188:189]
	s_waitcnt lgkmcnt(1)
	v_pk_fma_f32 v[82:83], v[168:169], v[82:83], v[118:119]
	v_pk_fma_f32 v[84:85], v[166:167], v[84:85], v[120:121]
	v_pk_mul_f32 v[120:121], v[172:173], v[82:83]
	global_store_dwordx4 v[124:125], v[82:85], off nt
	v_pk_mul_f32 v[118:119], v[170:171], v[84:85]
	v_cvt_pk_bf16_f32 v120, v120, v121
	s_waitcnt vmcnt(13) lgkmcnt(0)
	v_pk_fma_f32 v[86:87], v[168:169], v[86:87], v[114:115]
	v_cvt_pk_bf16_f32 v121, v118, v119
	ds_bpermute_b32 v114, v203, v120
	ds_bpermute_b32 v115, v203, v121
	v_pk_fma_f32 v[88:89], v[166:167], v[88:89], v[116:117]
	v_pk_mul_f32 v[116:117], v[172:173], v[86:87]
	v_pk_mul_f32 v[118:119], v[170:171], v[88:89]
	global_store_dwordx4 v[134:135], v[86:89], off nt
	v_cvt_pk_bf16_f32 v116, v116, v117
	v_cvt_pk_bf16_f32 v117, v118, v119
	v_lshlrev_b32_e32 v118, 1, v128
	s_waitcnt lgkmcnt(0)
	v_add_u32_e32 v250, 0xfffff040, v118
	v_cndmask_b32_e64 v250, v118, v250, s[40:41]
	v_cndmask_b32_e64 v248, v126, v114, s[40:41]
	v_cndmask_b32_e64 v249, v127, v115, s[40:41]
	global_store_dwordx2 v250, v[248:249], s[18:19] nt
	v_cndmask_b32_e64 v246, v114, v126, s[40:41]
	v_cndmask_b32_e64 v247, v115, v127, s[40:41]
	s_waitcnt lgkmcnt(1)
	v_add_u32_e32 v114, 0x1040, v118
	v_cndmask_b32_e64 v114, v118, v114, s[38:39]
	global_store_dwordx2 v114, v[246:247], s[18:19] nt
	ds_bpermute_b32 v114, v203, v116
	s_waitcnt lgkmcnt(1)
	ds_bpermute_b32 v115, v203, v117
	v_add_u32_e32 v117, 0x14000, v202
	v_lshlrev_b32_e32 v116, 1, v117
	s_waitcnt lgkmcnt(0)
	v_add_u32_e32 v250, 0xfffff040, v116
	v_cndmask_b32_e64 v250, v116, v250, s[40:41]
	v_cndmask_b32_e64 v248, v122, v114, s[40:41]
	v_cndmask_b32_e64 v249, v123, v115, s[40:41]
	global_store_dwordx2 v250, v[248:249], s[18:19] nt
	v_cndmask_b32_e64 v246, v114, v122, s[40:41]
	v_cndmask_b32_e64 v247, v115, v123, s[40:41]
	v_mul_f32_e32 v83, v83, v83
	v_fmac_f32_e32 v83, v82, v82
	v_mul_f32_e32 v82, v85, v85
	v_mul_f32_e32 v93, v93, v93
	v_fmac_f32_e32 v82, v84, v84
	v_mul_f32_e32 v91, v91, v91
	v_fmac_f32_e32 v93, v92, v92
	v_mul_f32_e32 v92, v95, v95
	v_mul_f32_e32 v95, v97, v97
	v_add_f32_e32 v82, v83, v82
	v_mul_f32_e32 v83, v87, v87
	v_mul_f32_e32 v84, v89, v89
	v_fmac_f32_e32 v95, v96, v96
	v_fmac_f32_e32 v83, v86, v86
	v_fmac_f32_e32 v84, v88, v88
	v_fmac_f32_e32 v91, v90, v90
	v_fmac_f32_e32 v92, v94, v94
	v_add_f32_e32 v83, v83, v84
	v_add_f32_e32 v84, v91, v93
	v_add_f32_e32 v85, v92, v95
	v_add_f32_e32 v82, v84, v82
	v_add_f32_e32 v83, v85, v83
	ds_bpermute_b32 v84, v190, v82
	ds_bpermute_b32 v85, v190, v83
	s_waitcnt lgkmcnt(1)
	v_add_f32_e32 v82, v82, v84
	s_waitcnt lgkmcnt(0)
	v_add_f32_e32 v85, v83, v85
	ds_bpermute_b32 v84, v191, v82
	ds_bpermute_b32 v86, v191, v85
	s_waitcnt lgkmcnt(1)
	v_add_f32_e32 v82, v82, v84
	s_waitcnt lgkmcnt(0)
	v_add_f32_e32 v84, v85, v86
	ds_bpermute_b32 v83, v204, v82
	ds_bpermute_b32 v85, v204, v84
	v_add_u32_e32 v86, 0x1040, v116
	v_cndmask_b32_e64 v86, v116, v86, s[38:39]
	global_store_dwordx2 v86, v[246:247], s[18:19] nt
	s_and_saveexec_b64 s[22:23], s[42:43]
	s_cbranch_execz .LBB0_1959
	s_waitcnt lgkmcnt(1)
	v_add_f32_e32 v82, v82, v83
	s_waitcnt lgkmcnt(0)
	v_add_f32_e32 v83, v84, v85
	ds_write2_b32 v194, v82, v83 offset0:32 offset1:40
; #define LAS __attribute__((address_space(3)))
; #define ERN_EOFF(q, m) (eb + (unsigned)((((q) & 1) * HALF + (m) * 16) * DM + ERN_COL((q) >> 1)))
;     __device__ __forceinline__ void operator()(const f32x4 (&acc)[2][2][4][2], const Unit& u, int wr, int wc, int fr, int fq) const {
;     ...
;         for (int g = 0; g < 8; ++g) { const int ai = g >> 2, m = g & 3;
;             if (g + 1 < 8) ERN_LOADX(g + 1);
;             float sq0 = 0.f, sq1 = 0.f; u32x2 hw[2][2];
; #pragma unroll
;             for (int bj = 0; bj < 2; ++bj) {
;                 *(LAS f32x4*)(st + wr_off) = acc[ai][bj][m][0]; *(LAS f32x4*)(st + wr_off + 64) = acc[ai][bj][m][1];
;                 const f32x4 a0 = *(const LAS f32x4*)(st + rd_off), a1 = *(const LAS f32x4*)(st + rd_off + 8 * 144);
;                 { const f32x4 xv = xb[g & 1][bj][0] + gv[bj] * a0; __builtin_nontemporal_store(xv, (f32x4*)((char*)xo + 4u * ERN_EOFF(g, bj, 0)));
;                   sq0 += (xv.x * xv.x + xv.y * xv.y) + (xv.z * xv.z + xv.w * xv.w);
;                   const f32x4 hv = xv * gsn[bj]; hw[bj][0].x = cvt_pk_bf16(hv.x, hv.y); hw[bj][0].y = cvt_pk_bf16(hv.z, hv.w); }
;                 { const f32x4 xv = xb[g & 1][bj][1] + gv[bj] * a1; __builtin_nontemporal_store(xv, (f32x4*)((char*)xo + 4u * ERN_EOFF(g, bj, 1)));
;                   sq1 += (xv.x * xv.x + xv.y * xv.y) + (xv.z * xv.z + xv.w * xv.w);
;                   const f32x4 hv = xv * gsn[bj]; hw[bj][1].x = cvt_pk_bf16(hv.x, hv.y); hw[bj][1].y = cvt_pk_bf16(hv.z, hv.w); }
;             }
;             if (!NOH && !PLAIN) {
; #pragma unroll
;                 for (int rh = 0; rh < 2; ++rh) { u32x2 rv; rv.x = __shfl_xor(hw[1][rh].x, 8); rv.y = __shfl_xor(hw[1][rh].y, 8);
;                     const unsigned e0 = ERN_EOFF(g, 0, rh);
;                     const unsigned ee = odd ? (e0 - DM + 32) : e0, eo2 = odd ? e0 : (e0 + DM + 32);
;                     *(u32x2*)((char*)ho + 2u * ee) = odd ? rv : hw[0][rh];
;                     *(u32x2*)((char*)ho + 2u * eo2) = odd ? hw[0][rh] : rv; }
;             }
;             if (!PLAIN) { sq0 += __shfl_xor(sq0, 1); sq0 += __shfl_xor(sq0, 2); sq0 += __shfl_xor(sq0, 4);
;             sq1 += __shfl_xor(sq1, 1); sq1 += __shfl_xor(sq1, 2); sq1 += __shfl_xor(sq1, 4); }
;             if (!PLAIN && pc == 0) { sst[g * 16 + rr] = sq0; sst[g * 16 + 8 + rr] = sq1; }
.LBB0_1959:
	s_or_b64 exec, exec, s[22:23]
	v_lshl_add_u64 v[116:117], s[20:21], 0, v[154:155]
	v_add_u32_e32 v82, 0x100000, v205
	s_waitcnt lgkmcnt(1)
	v_add_u32_e32 v83, 0x110000, v205
	v_add_u32_e32 v154, 0x100080, v205
	global_load_dwordx4 v[94:97], v82, s[20:21]
	global_load_dwordx4 v[90:93], v83, s[20:21]
	v_add_u32_e32 v114, 0x110080, v205
	global_load_dwordx4 v[86:89], v154, s[20:21]
	s_waitcnt lgkmcnt(0)
	global_load_dwordx4 v[82:85], v114, s[20:21]
	ds_write_b128 v200, v[78:81]
	ds_write_b128 v200, v[74:77] offset:64
	ds_read_b128 v[74:77], v201
	ds_read_b128 v[78:81], v201 offset:1152
	v_mov_b32_e32 v131, v155
	v_mov_b32_e32 v133, v155
	s_waitcnt vmcnt(11) lgkmcnt(1)
	v_pk_fma_f32 v[76:77], v[176:177], v[76:77], v[112:113]
	v_add_u32_e32 v112, 0x18000, v202
	v_pk_fma_f32 v[74:75], v[180:181], v[74:75], v[110:111]
	v_lshlrev_b32_e32 v110, 2, v112
	s_waitcnt lgkmcnt(0)
	v_pk_fma_f32 v[78:79], v[180:181], v[78:79], v[106:107]
	global_store_dwordx4 v110, v[74:77], s[20:21] nt
	v_pk_mul_f32 v[110:111], v[178:179], v[74:75]
	v_pk_fma_f32 v[80:81], v[176:177], v[80:81], v[108:109]
	v_pk_mul_f32 v[106:107], v[178:179], v[78:79]
	v_pk_mul_f32 v[118:119], v[174:175], v[76:77]
	v_cvt_pk_bf16_f32 v110, v110, v111
	v_pk_mul_f32 v[108:109], v[174:175], v[80:81]
	v_cvt_pk_bf16_f32 v111, v118, v119
	global_store_dwordx4 v[116:117], v[78:81], off nt
	v_cvt_pk_bf16_f32 v106, v106, v107
	v_cvt_pk_bf16_f32 v107, v108, v109
	ds_write_b128 v200, v[70:73]
	ds_write_b128 v200, v[66:69] offset:64
	ds_read_b128 v[66:69], v201
	ds_read_b128 v[70:73], v201 offset:1152
	v_lshl_add_u64 v[108:109], s[20:21], 0, v[130:131]
	v_lshl_add_u64 v[116:117], s[20:21], 0, v[132:133]
	s_waitcnt lgkmcnt(1)
	v_pk_fma_f32 v[66:67], v[168:169], v[66:67], v[102:103]
	v_pk_fma_f32 v[68:69], v[166:167], v[68:69], v[104:105]
	v_pk_mul_f32 v[104:105], v[172:173], v[66:67]
	global_store_dwordx4 v[108:109], v[66:69], off nt
	v_pk_mul_f32 v[102:103], v[170:171], v[68:69]
	v_cvt_pk_bf16_f32 v104, v104, v105
	s_waitcnt vmcnt(13) lgkmcnt(0)
	v_pk_fma_f32 v[70:71], v[168:169], v[70:71], v[98:99]
	v_cvt_pk_bf16_f32 v105, v102, v103
	ds_bpermute_b32 v98, v203, v104
	ds_bpermute_b32 v99, v203, v105
	v_pk_fma_f32 v[72:73], v[166:167], v[72:73], v[100:101]
	v_pk_mul_f32 v[100:101], v[172:173], v[70:71]
	v_pk_mul_f32 v[102:103], v[170:171], v[72:73]
	global_store_dwordx4 v[116:117], v[70:73], off nt
	v_cvt_pk_bf16_f32 v100, v100, v101
	v_cvt_pk_bf16_f32 v101, v102, v103
	v_lshlrev_b32_e32 v102, 1, v112
	s_waitcnt lgkmcnt(0)
	v_add_u32_e32 v250, 0xfffff040, v102
	v_cndmask_b32_e64 v250, v102, v250, s[40:41]
	v_cndmask_b32_e64 v248, v110, v98, s[40:41]
	v_cndmask_b32_e64 v249, v111, v99, s[40:41]
	global_store_dwordx2 v250, v[248:249], s[18:19] nt
	v_cndmask_b32_e64 v246, v98, v110, s[40:41]
	v_cndmask_b32_e64 v247, v99, v111, s[40:41]
	s_waitcnt lgkmcnt(1)
	v_add_u32_e32 v98, 0x1040, v102
	v_cndmask_b32_e64 v98, v102, v98, s[38:39]
	global_store_dwordx2 v98, v[246:247], s[18:19] nt
	ds_bpermute_b32 v98, v203, v100
	s_waitcnt lgkmcnt(1)
	ds_bpermute_b32 v99, v203, v101
	v_add_u32_e32 v101, 0x1c000, v202
	v_lshlrev_b32_e32 v100, 1, v101
	s_waitcnt lgkmcnt(0)
	v_add_u32_e32 v250, 0xfffff040, v100
	v_cndmask_b32_e64 v250, v100, v250, s[40:41]
	v_cndmask_b32_e64 v248, v106, v98, s[40:41]
	v_cndmask_b32_e64 v249, v107, v99, s[40:41]
	global_store_dwordx2 v250, v[248:249], s[18:19] nt
	v_cndmask_b32_e64 v246, v98, v106, s[40:41]
	v_cndmask_b32_e64 v247, v99, v107, s[40:41]
	v_mul_f32_e32 v67, v67, v67
	v_fmac_f32_e32 v67, v66, v66
	v_mul_f32_e32 v66, v69, v69
	v_mul_f32_e32 v77, v77, v77
	v_fmac_f32_e32 v66, v68, v68
	v_mul_f32_e32 v75, v75, v75
	v_fmac_f32_e32 v77, v76, v76
	v_mul_f32_e32 v76, v79, v79
	v_mul_f32_e32 v79, v81, v81
	v_add_f32_e32 v66, v67, v66
	v_mul_f32_e32 v67, v71, v71
	v_mul_f32_e32 v68, v73, v73
	v_fmac_f32_e32 v79, v80, v80
	v_fmac_f32_e32 v67, v70, v70
	v_fmac_f32_e32 v68, v72, v72
	v_fmac_f32_e32 v75, v74, v74
	v_fmac_f32_e32 v76, v78, v78
	v_add_f32_e32 v67, v67, v68
	v_add_f32_e32 v68, v75, v77
	v_add_f32_e32 v69, v76, v79
	v_add_f32_e32 v66, v68, v66
	v_add_f32_e32 v67, v69, v67
	ds_bpermute_b32 v68, v190, v66
	ds_bpermute_b32 v69, v190, v67
	s_waitcnt lgkmcnt(1)
	v_add_f32_e32 v66, v66, v68
	s_waitcnt lgkmcnt(0)
	v_add_f32_e32 v69, v67, v69
	ds_bpermute_b32 v68, v191, v66
	ds_bpermute_b32 v70, v191, v69
	s_waitcnt lgkmcnt(1)
	v_add_f32_e32 v66, v66, v68
	s_waitcnt lgkmcnt(0)
	v_add_f32_e32 v68, v69, v70
	ds_bpermute_b32 v67, v204, v66
	ds_bpermute_b32 v69, v204, v68
	v_add_u32_e32 v70, 0x1040, v100
	v_cndmask_b32_e64 v70, v100, v70, s[38:39]
	global_store_dwordx2 v70, v[246:247], s[18:19] nt
	s_and_saveexec_b64 s[22:23], s[42:43]
	s_cbranch_execz .LBB0_1969
	s_waitcnt lgkmcnt(1)
	v_add_f32_e32 v66, v66, v67
	s_waitcnt lgkmcnt(0)
	v_add_f32_e32 v67, v68, v69
	ds_write2_b32 v194, v66, v67 offset0:48 offset1:56
; #define LAS __attribute__((address_space(3)))
; #define ERN_EOFF(q, m) (eb + (unsigned)((((q) & 1) * HALF + (m) * 16) * DM + ERN_COL((q) >> 1)))
;     __device__ __forceinline__ void operator()(const f32x4 (&acc)[2][2][4][2], const Unit& u, int wr, int wc, int fr, int fq) const {
;     ...
;         for (int g = 0; g < 8; ++g) { const int ai = g >> 2, m = g & 3;
;             if (g + 1 < 8) ERN_LOADX(g + 1);
;             float sq0 = 0.f, sq1 = 0.f; u32x2 hw[2][2];
; #pragma unroll
;             for (int bj = 0; bj < 2; ++bj) {
;                 *(LAS f32x4*)(st + wr_off) = acc[ai][bj][m][0]; *(LAS f32x4*)(st + wr_off + 64) = acc[ai][bj][m][1];
;                 const f32x4 a0 = *(const LAS f32x4*)(st + rd_off), a1 = *(const LAS f32x4*)(st + rd_off + 8 * 144);
;                 { const f32x4 xv = xb[g & 1][bj][0] + gv[bj] * a0; __builtin_nontemporal_store(xv, (f32x4*)((char*)xo + 4u * ERN_EOFF(g, bj, 0)));
;                   sq0 += (xv.x * xv.x + xv.y * xv.y) + (xv.z * xv.z + xv.w * xv.w);
;                   const f32x4 hv = xv * gsn[bj]; hw[bj][0].x = cvt_pk_bf16(hv.x, hv.y); hw[bj][0].y = cvt_pk_bf16(hv.z, hv.w); }
;                 { const f32x4 xv = xb[g & 1][bj][1] + gv[bj] * a1; __builtin_nontemporal_store(xv, (f32x4*)((char*)xo + 4u * ERN_EOFF(g, bj, 1)));
;                   sq1 += (xv.x * xv.x + xv.y * xv.y) + (xv.z * xv.z + xv.w * xv.w);
;                   const f32x4 hv = xv * gsn[bj]; hw[bj][1].x = cvt_pk_bf16(hv.x, hv.y); hw[bj][1].y = cvt_pk_bf16(hv.z, hv.w); }
;             }
;             if (!NOH && !PLAIN) {
; #pragma unroll
;                 for (int rh = 0; rh < 2; ++rh) { u32x2 rv; rv.x = __shfl_xor(hw[1][rh].x, 8); rv.y = __shfl_xor(hw[1][rh].y, 8);
;                     const unsigned e0 = ERN_EOFF(g, 0, rh);
;                     const unsigned ee = odd ? (e0 - DM + 32) : e0, eo2 = odd ? e0 : (e0 + DM + 32);
;                     *(u32x2*)((char*)ho + 2u * ee) = odd ? rv : hw[0][rh];
;                     *(u32x2*)((char*)ho + 2u * eo2) = odd ? hw[0][rh] : rv; }
;             }
;             if (!PLAIN) { sq0 += __shfl_xor(sq0, 1); sq0 += __shfl_xor(sq0, 2); sq0 += __shfl_xor(sq0, 4);
;             sq1 += __shfl_xor(sq1, 1); sq1 += __shfl_xor(sq1, 2); sq1 += __shfl_xor(sq1, 4); }
;             if (!PLAIN && pc == 0) { sst[g * 16 + rr] = sq0; sst[g * 16 + 8 + rr] = sq1; }
.LBB0_1969:
	s_or_b64 exec, exec, s[22:23]
	v_lshl_add_u64 v[104:105], s[20:21], 0, v[154:155]
	v_add_u32_e32 v154, 0x120000, v205
	v_add_u32_e32 v100, 0x120080, v205
	v_add_u32_e32 v102, 0x130000, v205
	global_load_dwordx4 v[78:81], v154, s[20:21]
	global_load_dwordx4 v[74:77], v102, s[20:21]
	v_add_u32_e32 v98, 0x130080, v205
	global_load_dwordx4 v[70:73], v100, s[20:21]
	s_waitcnt lgkmcnt(0)
	global_load_dwordx4 v[66:69], v98, s[20:21]
	ds_write_b128 v200, v[62:65]
	ds_write_b128 v200, v[58:61] offset:64
	ds_read_b128 v[58:61], v201
	ds_read_b128 v[62:65], v201 offset:1152
	v_mov_b32_e32 v115, v155
	s_waitcnt vmcnt(13) lgkmcnt(1)
	v_pk_fma_f32 v[60:61], v[176:177], v[60:61], v[96:97]
	v_add_u32_e32 v96, 0x40000, v202
	v_pk_fma_f32 v[58:59], v[180:181], v[58:59], v[94:95]
	v_lshlrev_b32_e32 v94, 2, v96
	s_waitcnt vmcnt(12) lgkmcnt(0)
	v_pk_fma_f32 v[64:65], v[176:177], v[64:65], v[92:93]
	v_add_u32_e32 v92, 0x44000, v202
	global_store_dwordx4 v94, v[58:61], s[20:21] nt
	v_pk_mul_f32 v[94:95], v[178:179], v[58:59]
	v_pk_fma_f32 v[62:63], v[180:181], v[62:63], v[90:91]
	v_lshlrev_b32_e32 v90, 2, v92
	v_pk_mul_f32 v[106:107], v[174:175], v[60:61]
	v_cvt_pk_bf16_f32 v94, v94, v95
	s_nop 0
	v_cvt_pk_bf16_f32 v95, v106, v107
	global_store_dwordx4 v90, v[62:65], s[20:21] nt
	v_pk_mul_f32 v[90:91], v[178:179], v[62:63]
	v_pk_mul_f32 v[106:107], v[174:175], v[64:65]
	v_cvt_pk_bf16_f32 v90, v90, v91
	s_nop 0
	v_cvt_pk_bf16_f32 v91, v106, v107
	ds_write_b128 v200, v[54:57]
	ds_write_b128 v200, v[50:53] offset:64
	ds_read_b128 v[50:53], v201
	ds_read_b128 v[54:57], v201 offset:1152
	v_lshl_add_u64 v[106:107], s[20:21], 0, v[114:115]
	s_waitcnt vmcnt(13) lgkmcnt(1)
	v_pk_fma_f32 v[50:51], v[168:169], v[50:51], v[86:87]
	v_pk_fma_f32 v[52:53], v[166:167], v[52:53], v[88:89]
	v_pk_mul_f32 v[88:89], v[172:173], v[50:51]
	global_store_dwordx4 v[104:105], v[50:53], off nt
	v_pk_mul_f32 v[86:87], v[170:171], v[52:53]
	v_cvt_pk_bf16_f32 v88, v88, v89
	s_waitcnt vmcnt(13) lgkmcnt(0)
	v_pk_fma_f32 v[54:55], v[168:169], v[54:55], v[82:83]
	v_cvt_pk_bf16_f32 v89, v86, v87
	ds_bpermute_b32 v82, v203, v88
	ds_bpermute_b32 v83, v203, v89
	v_pk_fma_f32 v[56:57], v[166:167], v[56:57], v[84:85]
	v_pk_mul_f32 v[84:85], v[172:173], v[54:55]
	v_pk_mul_f32 v[86:87], v[170:171], v[56:57]
	global_store_dwordx4 v[106:107], v[54:57], off nt
	v_cvt_pk_bf16_f32 v84, v84, v85
	v_cvt_pk_bf16_f32 v85, v86, v87
	v_lshlrev_b32_e32 v86, 1, v96
	s_waitcnt lgkmcnt(0)
	v_add_u32_e32 v250, 0xfffff040, v86
	v_cndmask_b32_e64 v250, v86, v250, s[40:41]
	v_cndmask_b32_e64 v248, v94, v82, s[40:41]
	v_cndmask_b32_e64 v249, v95, v83, s[40:41]
	global_store_dwordx2 v250, v[248:249], s[18:19] nt
	v_cndmask_b32_e64 v246, v82, v94, s[40:41]
	v_cndmask_b32_e64 v247, v83, v95, s[40:41]
	s_waitcnt lgkmcnt(1)
	v_add_u32_e32 v82, 0x1040, v86
	v_cndmask_b32_e64 v82, v86, v82, s[38:39]
	global_store_dwordx2 v82, v[246:247], s[18:19] nt
	ds_bpermute_b32 v82, v203, v84
	s_waitcnt lgkmcnt(1)
	ds_bpermute_b32 v83, v203, v85
	v_lshlrev_b32_e32 v84, 1, v92
	s_waitcnt lgkmcnt(0)
	v_add_u32_e32 v250, 0xfffff040, v84
	v_cndmask_b32_e64 v250, v84, v250, s[40:41]
	v_cndmask_b32_e64 v248, v90, v82, s[40:41]
	v_cndmask_b32_e64 v249, v91, v83, s[40:41]
	global_store_dwordx2 v250, v[248:249], s[18:19] nt
	v_cndmask_b32_e64 v246, v82, v90, s[40:41]
	v_cndmask_b32_e64 v247, v83, v91, s[40:41]
	v_mul_f32_e32 v51, v51, v51
	v_fmac_f32_e32 v51, v50, v50
	v_mul_f32_e32 v50, v53, v53
	v_mul_f32_e32 v61, v61, v61
	v_fmac_f32_e32 v50, v52, v52
	v_mul_f32_e32 v59, v59, v59
	v_fmac_f32_e32 v61, v60, v60
	v_mul_f32_e32 v60, v63, v63
	v_mul_f32_e32 v63, v65, v65
	v_add_f32_e32 v50, v51, v50
	v_mul_f32_e32 v51, v55, v55
	v_mul_f32_e32 v52, v57, v57
	v_fmac_f32_e32 v63, v64, v64
	v_fmac_f32_e32 v51, v54, v54
	v_fmac_f32_e32 v52, v56, v56
	v_fmac_f32_e32 v59, v58, v58
	v_fmac_f32_e32 v60, v62, v62
	v_add_f32_e32 v51, v51, v52
	v_add_f32_e32 v52, v59, v61
	v_add_f32_e32 v53, v60, v63
	v_add_f32_e32 v50, v52, v50
	v_add_f32_e32 v51, v53, v51
	ds_bpermute_b32 v52, v190, v50
	ds_bpermute_b32 v53, v190, v51
	s_waitcnt lgkmcnt(1)
	v_add_f32_e32 v50, v50, v52
	s_waitcnt lgkmcnt(0)
	v_add_f32_e32 v53, v51, v53
	ds_bpermute_b32 v52, v191, v50
	ds_bpermute_b32 v54, v191, v53
	s_waitcnt lgkmcnt(1)
	v_add_f32_e32 v50, v50, v52
	s_waitcnt lgkmcnt(0)
	v_add_f32_e32 v52, v53, v54
	ds_bpermute_b32 v51, v204, v50
	ds_bpermute_b32 v53, v204, v52
	v_add_u32_e32 v54, 0x1040, v84
	v_cndmask_b32_e64 v54, v84, v54, s[38:39]
	global_store_dwordx2 v54, v[246:247], s[18:19] nt
	s_and_saveexec_b64 s[22:23], s[42:43]
	s_cbranch_execz .LBB0_1979
	s_waitcnt lgkmcnt(1)
	v_add_f32_e32 v50, v50, v51
	s_waitcnt lgkmcnt(0)
	v_add_f32_e32 v51, v52, v53
	ds_write2_b32 v194, v50, v51 offset0:64 offset1:72
; #define LAS __attribute__((address_space(3)))
; #define ERN_EOFF(q, m) (eb + (unsigned)((((q) & 1) * HALF + (m) * 16) * DM + ERN_COL((q) >> 1)))
;     __device__ __forceinline__ void operator()(const f32x4 (&acc)[2][2][4][2], const Unit& u, int wr, int wc, int fr, int fq) const {
;     ...
;         for (int g = 0; g < 8; ++g) { const int ai = g >> 2, m = g & 3;
;             if (g + 1 < 8) ERN_LOADX(g + 1);
;             float sq0 = 0.f, sq1 = 0.f; u32x2 hw[2][2];
; #pragma unroll
;             for (int bj = 0; bj < 2; ++bj) {
;                 *(LAS f32x4*)(st + wr_off) = acc[ai][bj][m][0]; *(LAS f32x4*)(st + wr_off + 64) = acc[ai][bj][m][1];
;                 const f32x4 a0 = *(const LAS f32x4*)(st + rd_off), a1 = *(const LAS f32x4*)(st + rd_off + 8 * 144);
;                 { const f32x4 xv = xb[g & 1][bj][0] + gv[bj] * a0; __builtin_nontemporal_store(xv, (f32x4*)((char*)xo + 4u * ERN_EOFF(g, bj, 0)));
;                   sq0 += (xv.x * xv.x + xv.y * xv.y) + (xv.z * xv.z + xv.w * xv.w);
;                   const f32x4 hv = xv * gsn[bj]; hw[bj][0].x = cvt_pk_bf16(hv.x, hv.y); hw[bj][0].y = cvt_pk_bf16(hv.z, hv.w); }
;                 { const f32x4 xv = xb[g & 1][bj][1] + gv[bj] * a1; __builtin_nontemporal_store(xv, (f32x4*)((char*)xo + 4u * ERN_EOFF(g, bj, 1)));
;                   sq1 += (xv.x * xv.x + xv.y * xv.y) + (xv.z * xv.z + xv.w * xv.w);
;                   const f32x4 hv = xv * gsn[bj]; hw[bj][1].x = cvt_pk_bf16(hv.x, hv.y); hw[bj][1].y = cvt_pk_bf16(hv.z, hv.w); }
;             }
;             if (!NOH && !PLAIN) {
; #pragma unroll
;                 for (int rh = 0; rh < 2; ++rh) { u32x2 rv; rv.x = __shfl_xor(hw[1][rh].x, 8); rv.y = __shfl_xor(hw[1][rh].y, 8);
;                     const unsigned e0 = ERN_EOFF(g, 0, rh);
;                     const unsigned ee = odd ? (e0 - DM + 32) : e0, eo2 = odd ? e0 : (e0 + DM + 32);
;                     *(u32x2*)((char*)ho + 2u * ee) = odd ? rv : hw[0][rh];
;                     *(u32x2*)((char*)ho + 2u * eo2) = odd ? hw[0][rh] : rv; }
;             }
;             if (!PLAIN) { sq0 += __shfl_xor(sq0, 1); sq0 += __shfl_xor(sq0, 2); sq0 += __shfl_xor(sq0, 4);
;             sq1 += __shfl_xor(sq1, 1); sq1 += __shfl_xor(sq1, 2); sq1 += __shfl_xor(sq1, 4); }
;             if (!PLAIN && pc == 0) { sst[g * 16 + rr] = sq0; sst[g * 16 + 8 + rr] = sq1; }
.LBB0_1979:
	s_or_b64 exec, exec, s[22:23]
	v_lshl_add_u64 v[88:89], s[20:21], 0, v[154:155]
	v_add_u32_e32 v154, 0x140000, v205
	v_add_u32_e32 v84, 0x140080, v205
	v_add_u32_e32 v86, 0x150000, v205
	global_load_dwordx4 v[62:65], v154, s[20:21]
	global_load_dwordx4 v[58:61], v86, s[20:21]
	v_add_u32_e32 v82, 0x150080, v205
	global_load_dwordx4 v[54:57], v84, s[20:21]
	s_waitcnt lgkmcnt(0)
	global_load_dwordx4 v[50:53], v82, s[20:21]
	ds_write_b128 v200, v[46:49]
	ds_write_b128 v200, v[42:45] offset:64
	ds_read_b128 v[42:45], v201
	ds_read_b128 v[46:49], v201 offset:1152
	v_mov_b32_e32 v103, v155
	v_lshl_add_u64 v[90:91], s[20:21], 0, v[102:103]
	v_mov_b32_e32 v101, v155
	s_waitcnt vmcnt(13) lgkmcnt(1)
	v_pk_fma_f32 v[42:43], v[180:181], v[42:43], v[78:79]
	s_waitcnt vmcnt(12) lgkmcnt(0)
	v_pk_fma_f32 v[46:47], v[180:181], v[46:47], v[74:75]
	v_pk_fma_f32 v[44:45], v[176:177], v[44:45], v[80:81]
	v_pk_mul_f32 v[78:79], v[178:179], v[42:43]
	v_pk_fma_f32 v[48:49], v[176:177], v[48:49], v[76:77]
	v_pk_mul_f32 v[74:75], v[178:179], v[46:47]
	global_store_dwordx4 v[88:89], v[42:45], off nt
	v_pk_mul_f32 v[80:81], v[174:175], v[44:45]
	v_cvt_pk_bf16_f32 v78, v78, v79
	v_pk_mul_f32 v[76:77], v[174:175], v[48:49]
	v_cvt_pk_bf16_f32 v79, v80, v81
	global_store_dwordx4 v[90:91], v[46:49], off nt
	v_cvt_pk_bf16_f32 v74, v74, v75
	v_cvt_pk_bf16_f32 v75, v76, v77
	ds_write_b128 v200, v[38:41]
	ds_write_b128 v200, v[34:37] offset:64
	ds_read_b128 v[34:37], v201
	ds_read_b128 v[38:41], v201 offset:1152
	v_lshl_add_u64 v[76:77], s[20:21], 0, v[100:101]
	v_mov_b32_e32 v99, v155
	v_lshl_add_u64 v[80:81], s[20:21], 0, v[98:99]
	s_waitcnt vmcnt(13) lgkmcnt(1)
	v_pk_fma_f32 v[34:35], v[168:169], v[34:35], v[70:71]
	v_pk_fma_f32 v[36:37], v[166:167], v[36:37], v[72:73]
	v_pk_mul_f32 v[72:73], v[172:173], v[34:35]
	global_store_dwordx4 v[76:77], v[34:37], off nt
	v_pk_mul_f32 v[70:71], v[170:171], v[36:37]
	v_cvt_pk_bf16_f32 v72, v72, v73
	s_waitcnt vmcnt(13) lgkmcnt(0)
	v_pk_fma_f32 v[38:39], v[168:169], v[38:39], v[66:67]
	v_cvt_pk_bf16_f32 v73, v70, v71
	ds_bpermute_b32 v66, v203, v72
	ds_bpermute_b32 v67, v203, v73
	v_pk_fma_f32 v[40:41], v[166:167], v[40:41], v[68:69]
	v_pk_mul_f32 v[68:69], v[172:173], v[38:39]
	v_pk_mul_f32 v[70:71], v[170:171], v[40:41]
	global_store_dwordx4 v[80:81], v[38:41], off nt
	v_cvt_pk_bf16_f32 v68, v68, v69
	v_cvt_pk_bf16_f32 v69, v70, v71
	v_add_u32_e32 v71, 0x48000, v202
	v_lshlrev_b32_e32 v70, 1, v71
	s_waitcnt lgkmcnt(0)
	v_add_u32_e32 v250, 0xfffff040, v70
	v_cndmask_b32_e64 v250, v70, v250, s[40:41]
	v_cndmask_b32_e64 v248, v78, v66, s[40:41]
	v_cndmask_b32_e64 v249, v79, v67, s[40:41]
	global_store_dwordx2 v250, v[248:249], s[18:19] nt
	v_cndmask_b32_e64 v246, v66, v78, s[40:41]
	v_cndmask_b32_e64 v247, v67, v79, s[40:41]
	s_waitcnt lgkmcnt(1)
	v_add_u32_e32 v66, 0x1040, v70
	v_cndmask_b32_e64 v66, v70, v66, s[38:39]
	global_store_dwordx2 v66, v[246:247], s[18:19] nt
	ds_bpermute_b32 v66, v203, v68
	s_waitcnt lgkmcnt(1)
	ds_bpermute_b32 v67, v203, v69
	v_add_u32_e32 v69, 0x4c000, v202
	v_lshlrev_b32_e32 v68, 1, v69
	s_waitcnt lgkmcnt(0)
	v_add_u32_e32 v250, 0xfffff040, v68
	v_cndmask_b32_e64 v250, v68, v250, s[40:41]
	v_cndmask_b32_e64 v248, v74, v66, s[40:41]
	v_cndmask_b32_e64 v249, v75, v67, s[40:41]
	global_store_dwordx2 v250, v[248:249], s[18:19] nt
	v_cndmask_b32_e64 v246, v66, v74, s[40:41]
	v_cndmask_b32_e64 v247, v67, v75, s[40:41]
	v_mul_f32_e32 v35, v35, v35
	v_fmac_f32_e32 v35, v34, v34
	v_mul_f32_e32 v34, v37, v37
	v_mul_f32_e32 v45, v45, v45
	v_fmac_f32_e32 v34, v36, v36
	v_mul_f32_e32 v43, v43, v43
	v_fmac_f32_e32 v45, v44, v44
	v_mul_f32_e32 v44, v47, v47
	v_mul_f32_e32 v47, v49, v49
	v_add_f32_e32 v34, v35, v34
	v_mul_f32_e32 v35, v39, v39
	v_mul_f32_e32 v36, v41, v41
	v_fmac_f32_e32 v47, v48, v48
	v_fmac_f32_e32 v35, v38, v38
	v_fmac_f32_e32 v36, v40, v40
	v_fmac_f32_e32 v43, v42, v42
	v_fmac_f32_e32 v44, v46, v46
	v_add_f32_e32 v35, v35, v36
	v_add_f32_e32 v36, v43, v45
	v_add_f32_e32 v37, v44, v47
	v_add_f32_e32 v34, v36, v34
	v_add_f32_e32 v35, v37, v35
	ds_bpermute_b32 v36, v190, v34
	ds_bpermute_b32 v37, v190, v35
	s_waitcnt lgkmcnt(1)
	v_add_f32_e32 v34, v34, v36
	s_waitcnt lgkmcnt(0)
	v_add_f32_e32 v37, v35, v37
	ds_bpermute_b32 v36, v191, v34
	ds_bpermute_b32 v38, v191, v37
	s_waitcnt lgkmcnt(1)
	v_add_f32_e32 v34, v34, v36
	s_waitcnt lgkmcnt(0)
	v_add_f32_e32 v36, v37, v38
	ds_bpermute_b32 v35, v204, v34
	ds_bpermute_b32 v37, v204, v36
	v_add_u32_e32 v38, 0x1040, v68
	v_cndmask_b32_e64 v38, v68, v38, s[38:39]
	global_store_dwordx2 v38, v[246:247], s[18:19] nt
	s_and_saveexec_b64 s[22:23], s[42:43]
	s_cbranch_execz .LBB0_1989
	s_waitcnt lgkmcnt(1)
	v_add_f32_e32 v34, v34, v35
	s_waitcnt lgkmcnt(0)
	v_add_f32_e32 v35, v36, v37
	ds_write2_b32 v194, v34, v35 offset0:80 offset1:88
; #define LAS __attribute__((address_space(3)))
; #define ERN_EOFF(q, m) (eb + (unsigned)((((q) & 1) * HALF + (m) * 16) * DM + ERN_COL((q) >> 1)))
;     __device__ __forceinline__ void operator()(const f32x4 (&acc)[2][2][4][2], const Unit& u, int wr, int wc, int fr, int fq) const {
;     ...
;         for (int g = 0; g < 8; ++g) { const int ai = g >> 2, m = g & 3;
;             if (g + 1 < 8) ERN_LOADX(g + 1);
;             float sq0 = 0.f, sq1 = 0.f; u32x2 hw[2][2];
; #pragma unroll
;             for (int bj = 0; bj < 2; ++bj) {
;                 *(LAS f32x4*)(st + wr_off) = acc[ai][bj][m][0]; *(LAS f32x4*)(st + wr_off + 64) = acc[ai][bj][m][1];
;                 const f32x4 a0 = *(const LAS f32x4*)(st + rd_off), a1 = *(const LAS f32x4*)(st + rd_off + 8 * 144);
;                 { const f32x4 xv = xb[g & 1][bj][0] + gv[bj] * a0; __builtin_nontemporal_store(xv, (f32x4*)((char*)xo + 4u * ERN_EOFF(g, bj, 0)));
;                   sq0 += (xv.x * xv.x + xv.y * xv.y) + (xv.z * xv.z + xv.w * xv.w);
;                   const f32x4 hv = xv * gsn[bj]; hw[bj][0].x = cvt_pk_bf16(hv.x, hv.y); hw[bj][0].y = cvt_pk_bf16(hv.z, hv.w); }
;                 { const f32x4 xv = xb[g & 1][bj][1] + gv[bj] * a1; __builtin_nontemporal_store(xv, (f32x4*)((char*)xo + 4u * ERN_EOFF(g, bj, 1)));
;                   sq1 += (xv.x * xv.x + xv.y * xv.y) + (xv.z * xv.z + xv.w * xv.w);
;                   const f32x4 hv = xv * gsn[bj]; hw[bj][1].x = cvt_pk_bf16(hv.x, hv.y); hw[bj][1].y = cvt_pk_bf16(hv.z, hv.w); }
;             }
;             if (!NOH && !PLAIN) {
; #pragma unroll
;                 for (int rh = 0; rh < 2; ++rh) { u32x2 rv; rv.x = __shfl_xor(hw[1][rh].x, 8); rv.y = __shfl_xor(hw[1][rh].y, 8);
;                     const unsigned e0 = ERN_EOFF(g, 0, rh);
;                     const unsigned ee = odd ? (e0 - DM + 32) : e0, eo2 = odd ? e0 : (e0 + DM + 32);
;                     *(u32x2*)((char*)ho + 2u * ee) = odd ? rv : hw[0][rh];
;                     *(u32x2*)((char*)ho + 2u * eo2) = odd ? hw[0][rh] : rv; }
;             }
;             if (!PLAIN) { sq0 += __shfl_xor(sq0, 1); sq0 += __shfl_xor(sq0, 2); sq0 += __shfl_xor(sq0, 4);
;             sq1 += __shfl_xor(sq1, 1); sq1 += __shfl_xor(sq1, 2); sq1 += __shfl_xor(sq1, 4); }
;             if (!PLAIN && pc == 0) { sst[g * 16 + rr] = sq0; sst[g * 16 + 8 + rr] = sq1; }
.LBB0_1989:
	s_or_b64 exec, exec, s[22:23]
	v_lshl_add_u64 v[72:73], s[20:21], 0, v[154:155]
	v_add_u32_e32 v154, 0x160000, v205
	v_add_u32_e32 v68, 0x160080, v205
	v_add_u32_e32 v70, 0x170000, v205
	global_load_dwordx4 v[46:49], v154, s[20:21]
	global_load_dwordx4 v[42:45], v70, s[20:21]
	v_add_u32_e32 v66, 0x170080, v205
	global_load_dwordx4 v[38:41], v68, s[20:21]
	s_waitcnt lgkmcnt(0)
	global_load_dwordx4 v[34:37], v66, s[20:21]
	ds_write_b128 v200, v[30:33]
	ds_write_b128 v200, v[26:29] offset:64
	ds_read_b128 v[26:29], v201
	ds_read_b128 v[30:33], v201 offset:1152
	v_mov_b32_e32 v87, v155
	v_lshl_add_u64 v[74:75], s[20:21], 0, v[86:87]
	v_mov_b32_e32 v85, v155
	s_waitcnt vmcnt(13) lgkmcnt(1)
	v_pk_fma_f32 v[26:27], v[180:181], v[26:27], v[62:63]
	s_waitcnt vmcnt(12) lgkmcnt(0)
	v_pk_fma_f32 v[30:31], v[180:181], v[30:31], v[58:59]
	v_pk_fma_f32 v[28:29], v[176:177], v[28:29], v[64:65]
	v_pk_mul_f32 v[62:63], v[178:179], v[26:27]
	v_pk_fma_f32 v[32:33], v[176:177], v[32:33], v[60:61]
	v_pk_mul_f32 v[58:59], v[178:179], v[30:31]
	global_store_dwordx4 v[72:73], v[26:29], off nt
	v_pk_mul_f32 v[64:65], v[174:175], v[28:29]
	v_cvt_pk_bf16_f32 v62, v62, v63
	v_pk_mul_f32 v[60:61], v[174:175], v[32:33]
	v_cvt_pk_bf16_f32 v63, v64, v65
	global_store_dwordx4 v[74:75], v[30:33], off nt
	v_cvt_pk_bf16_f32 v58, v58, v59
	v_cvt_pk_bf16_f32 v59, v60, v61
	ds_write_b128 v200, v[22:25]
	ds_write_b128 v200, v[18:21] offset:64
	ds_read_b128 v[18:21], v201
	ds_read_b128 v[22:25], v201 offset:1152
	v_lshl_add_u64 v[60:61], s[20:21], 0, v[84:85]
	v_mov_b32_e32 v83, v155
	v_lshl_add_u64 v[64:65], s[20:21], 0, v[82:83]
	s_waitcnt vmcnt(13) lgkmcnt(1)
	v_pk_fma_f32 v[18:19], v[168:169], v[18:19], v[54:55]
	v_pk_fma_f32 v[20:21], v[166:167], v[20:21], v[56:57]
	v_pk_mul_f32 v[56:57], v[172:173], v[18:19]
	global_store_dwordx4 v[60:61], v[18:21], off nt
	v_pk_mul_f32 v[54:55], v[170:171], v[20:21]
	v_cvt_pk_bf16_f32 v56, v56, v57
	s_waitcnt vmcnt(13) lgkmcnt(0)
	v_pk_fma_f32 v[22:23], v[168:169], v[22:23], v[50:51]
	v_cvt_pk_bf16_f32 v57, v54, v55
	ds_bpermute_b32 v50, v203, v56
	ds_bpermute_b32 v51, v203, v57
	v_pk_fma_f32 v[24:25], v[166:167], v[24:25], v[52:53]
	v_pk_mul_f32 v[52:53], v[172:173], v[22:23]
	v_pk_mul_f32 v[54:55], v[170:171], v[24:25]
	global_store_dwordx4 v[64:65], v[22:25], off nt
	v_cvt_pk_bf16_f32 v52, v52, v53
	v_cvt_pk_bf16_f32 v53, v54, v55
	v_add_u32_e32 v55, 0x50000, v202
	v_lshlrev_b32_e32 v54, 1, v55
	s_waitcnt lgkmcnt(0)
	v_add_u32_e32 v250, 0xfffff040, v54
	v_cndmask_b32_e64 v250, v54, v250, s[40:41]
	v_cndmask_b32_e64 v248, v62, v50, s[40:41]
	v_cndmask_b32_e64 v249, v63, v51, s[40:41]
	global_store_dwordx2 v250, v[248:249], s[18:19] nt
	v_cndmask_b32_e64 v246, v50, v62, s[40:41]
	v_cndmask_b32_e64 v247, v51, v63, s[40:41]
	s_waitcnt lgkmcnt(1)
	v_add_u32_e32 v50, 0x1040, v54
	v_cndmask_b32_e64 v50, v54, v50, s[38:39]
	global_store_dwordx2 v50, v[246:247], s[18:19] nt
	ds_bpermute_b32 v50, v203, v52
	s_waitcnt lgkmcnt(1)
	ds_bpermute_b32 v51, v203, v53
	v_add_u32_e32 v53, 0x54000, v202
	v_lshlrev_b32_e32 v52, 1, v53
	s_waitcnt lgkmcnt(0)
	v_add_u32_e32 v250, 0xfffff040, v52
	v_cndmask_b32_e64 v250, v52, v250, s[40:41]
	v_cndmask_b32_e64 v248, v58, v50, s[40:41]
	v_cndmask_b32_e64 v249, v59, v51, s[40:41]
	global_store_dwordx2 v250, v[248:249], s[18:19] nt
	v_cndmask_b32_e64 v246, v50, v58, s[40:41]
	v_cndmask_b32_e64 v247, v51, v59, s[40:41]
	v_mul_f32_e32 v19, v19, v19
	v_fmac_f32_e32 v19, v18, v18
	v_mul_f32_e32 v18, v21, v21
	v_mul_f32_e32 v29, v29, v29
	v_fmac_f32_e32 v18, v20, v20
	v_mul_f32_e32 v27, v27, v27
	v_fmac_f32_e32 v29, v28, v28
	v_mul_f32_e32 v28, v31, v31
	v_mul_f32_e32 v31, v33, v33
	v_add_f32_e32 v18, v19, v18
	v_mul_f32_e32 v19, v23, v23
	v_mul_f32_e32 v20, v25, v25
	v_fmac_f32_e32 v31, v32, v32
	v_fmac_f32_e32 v19, v22, v22
	v_fmac_f32_e32 v20, v24, v24
	v_fmac_f32_e32 v27, v26, v26
	v_fmac_f32_e32 v28, v30, v30
	v_add_f32_e32 v19, v19, v20
	v_add_f32_e32 v20, v27, v29
	v_add_f32_e32 v21, v28, v31
	v_add_f32_e32 v18, v20, v18
	v_add_f32_e32 v19, v21, v19
	ds_bpermute_b32 v20, v190, v18
	ds_bpermute_b32 v21, v190, v19
	s_waitcnt lgkmcnt(1)
	v_add_f32_e32 v18, v18, v20
	s_waitcnt lgkmcnt(0)
	v_add_f32_e32 v21, v19, v21
	ds_bpermute_b32 v20, v191, v18
	ds_bpermute_b32 v22, v191, v21
	s_waitcnt lgkmcnt(1)
	v_add_f32_e32 v18, v18, v20
	s_waitcnt lgkmcnt(0)
	v_add_f32_e32 v20, v21, v22
	ds_bpermute_b32 v19, v204, v18
	ds_bpermute_b32 v21, v204, v20
	v_add_u32_e32 v22, 0x1040, v52
	v_cndmask_b32_e64 v22, v52, v22, s[38:39]
	global_store_dwordx2 v22, v[246:247], s[18:19] nt
	s_and_saveexec_b64 s[22:23], s[42:43]
	s_cbranch_execz .LBB0_1999
	s_waitcnt lgkmcnt(1)
	v_add_f32_e32 v18, v18, v19
	s_waitcnt lgkmcnt(0)
	v_add_f32_e32 v19, v20, v21
	ds_write2_b32 v194, v18, v19 offset0:96 offset1:104
; #define LAS __attribute__((address_space(3)))
; #define ERN_EOFF(q, m) (eb + (unsigned)((((q) & 1) * HALF + (m) * 16) * DM + ERN_COL((q) >> 1)))
;     __device__ __forceinline__ void operator()(const f32x4 (&acc)[2][2][4][2], const Unit& u, int wr, int wc, int fr, int fq) const {
;     ...
;         for (int g = 0; g < 8; ++g) { const int ai = g >> 2, m = g & 3;
;             if (g + 1 < 8) ERN_LOADX(g + 1);
;             float sq0 = 0.f, sq1 = 0.f; u32x2 hw[2][2];
; #pragma unroll
;             for (int bj = 0; bj < 2; ++bj) {
;                 *(LAS f32x4*)(st + wr_off) = acc[ai][bj][m][0]; *(LAS f32x4*)(st + wr_off + 64) = acc[ai][bj][m][1];
;                 const f32x4 a0 = *(const LAS f32x4*)(st + rd_off), a1 = *(const LAS f32x4*)(st + rd_off + 8 * 144);
;                 { const f32x4 xv = xb[g & 1][bj][0] + gv[bj] * a0; __builtin_nontemporal_store(xv, (f32x4*)((char*)xo + 4u * ERN_EOFF(g, bj, 0)));
;                   sq0 += (xv.x * xv.x + xv.y * xv.y) + (xv.z * xv.z + xv.w * xv.w);
;                   const f32x4 hv = xv * gsn[bj]; hw[bj][0].x = cvt_pk_bf16(hv.x, hv.y); hw[bj][0].y = cvt_pk_bf16(hv.z, hv.w); }
;                 { const f32x4 xv = xb[g & 1][bj][1] + gv[bj] * a1; __builtin_nontemporal_store(xv, (f32x4*)((char*)xo + 4u * ERN_EOFF(g, bj, 1)));
;                   sq1 += (xv.x * xv.x + xv.y * xv.y) + (xv.z * xv.z + xv.w * xv.w);
;                   const f32x4 hv = xv * gsn[bj]; hw[bj][1].x = cvt_pk_bf16(hv.x, hv.y); hw[bj][1].y = cvt_pk_bf16(hv.z, hv.w); }
;             }
;             if (!NOH && !PLAIN) {
; #pragma unroll
;                 for (int rh = 0; rh < 2; ++rh) { u32x2 rv; rv.x = __shfl_xor(hw[1][rh].x, 8); rv.y = __shfl_xor(hw[1][rh].y, 8);
;                     const unsigned e0 = ERN_EOFF(g, 0, rh);
;                     const unsigned ee = odd ? (e0 - DM + 32) : e0, eo2 = odd ? e0 : (e0 + DM + 32);
;                     *(u32x2*)((char*)ho + 2u * ee) = odd ? rv : hw[0][rh];
;                     *(u32x2*)((char*)ho + 2u * eo2) = odd ? hw[0][rh] : rv; }
;             }
;             if (!PLAIN) { sq0 += __shfl_xor(sq0, 1); sq0 += __shfl_xor(sq0, 2); sq0 += __shfl_xor(sq0, 4);
;             sq1 += __shfl_xor(sq1, 1); sq1 += __shfl_xor(sq1, 2); sq1 += __shfl_xor(sq1, 4); }
;             if (!PLAIN && pc == 0) { sst[g * 16 + rr] = sq0; sst[g * 16 + 8 + rr] = sq1; }
.LBB0_1999:
	s_or_b64 exec, exec, s[22:23]
	ds_write_b128 v200, v[14:17]
	ds_write_b128 v200, v[10:13] offset:64
	ds_read_b128 v[10:13], v201
	ds_read_b128 v[14:17], v201 offset:1152
	s_waitcnt lgkmcnt(5)
	v_lshl_add_u64 v[18:19], s[20:21], 0, v[154:155]
	v_mov_b32_e32 v71, v155
	v_lshl_add_u64 v[22:23], s[20:21], 0, v[70:71]
	s_waitcnt vmcnt(9) lgkmcnt(1)
	v_pk_fma_f32 v[12:13], v[176:177], v[12:13], v[48:49]
	v_pk_fma_f32 v[10:11], v[180:181], v[10:11], v[46:47]
	global_store_dwordx4 v[18:19], v[10:13], off nt
	v_pk_mul_f32 v[18:19], v[174:175], v[12:13]
	v_pk_mul_f32 v[20:21], v[178:179], v[10:11]
	s_waitcnt vmcnt(9) lgkmcnt(0)
	v_pk_fma_f32 v[14:15], v[180:181], v[14:15], v[42:43]
	v_cvt_pk_bf16_f32 v20, v20, v21
	v_cvt_pk_bf16_f32 v21, v18, v19
	v_pk_fma_f32 v[16:17], v[176:177], v[16:17], v[44:45]
	v_pk_mul_f32 v[18:19], v[178:179], v[14:15]
	global_store_dwordx4 v[22:23], v[14:17], off nt
	v_pk_mul_f32 v[22:23], v[174:175], v[16:17]
	v_cvt_pk_bf16_f32 v18, v18, v19
	v_mov_b32_e32 v69, v155
	v_cvt_pk_bf16_f32 v19, v22, v23
	ds_write_b128 v200, v[6:9]
	ds_write_b128 v200, v[2:5] offset:64
	ds_read_b128 v[2:5], v201
	ds_read_b128 v[6:9], v201 offset:1152
	v_lshl_add_u64 v[22:23], s[20:21], 0, v[68:69]
	v_mov_b32_e32 v67, v155
	v_lshl_add_u64 v[24:25], s[20:21], 0, v[66:67]
	s_waitcnt vmcnt(9) lgkmcnt(1)
	v_pk_fma_f32 v[4:5], v[166:167], v[4:5], v[40:41]
	v_pk_fma_f32 v[2:3], v[168:169], v[2:3], v[38:39]
	global_store_dwordx4 v[22:23], v[2:5], off nt
	v_pk_mul_f32 v[22:23], v[170:171], v[4:5]
	v_pk_mul_f32 v[26:27], v[172:173], v[2:3]
	s_waitcnt vmcnt(9) lgkmcnt(0)
	v_pk_fma_f32 v[8:9], v[166:167], v[8:9], v[36:37]
	v_cvt_pk_bf16_f32 v28, v26, v27
	v_cvt_pk_bf16_f32 v23, v22, v23
	ds_bpermute_b32 v22, v203, v28
	ds_bpermute_b32 v23, v203, v23
	v_pk_fma_f32 v[6:7], v[168:169], v[6:7], v[34:35]
	global_store_dwordx4 v[24:25], v[6:9], off nt
	v_pk_mul_f32 v[26:27], v[170:171], v[8:9]
	v_pk_mul_f32 v[24:25], v[172:173], v[6:7]
	s_nop 0
	v_cvt_pk_bf16_f32 v24, v24, v25
	v_cvt_pk_bf16_f32 v25, v26, v27
	v_add_u32_e32 v27, 0x58000, v202
	v_lshlrev_b32_e32 v26, 1, v27
	s_waitcnt lgkmcnt(0)
	v_add_u32_e32 v250, 0xfffff040, v26
	v_cndmask_b32_e64 v250, v26, v250, s[40:41]
	v_cndmask_b32_e64 v248, v20, v22, s[40:41]
	v_cndmask_b32_e64 v249, v21, v23, s[40:41]
	global_store_dwordx2 v250, v[248:249], s[18:19] nt
	v_cndmask_b32_e64 v246, v22, v20, s[40:41]
	v_cndmask_b32_e64 v247, v23, v21, s[40:41]
	s_waitcnt lgkmcnt(1)
	v_add_u32_e32 v22, 0x1040, v26
	v_cndmask_b32_e64 v22, v26, v22, s[38:39]
	global_store_dwordx2 v22, v[246:247], s[18:19] nt
	ds_bpermute_b32 v20, v203, v24
	ds_bpermute_b32 v21, v203, v25
	s_waitcnt lgkmcnt(2)
	v_add_u32_e32 v23, 0x5c000, v202
	v_lshlrev_b32_e32 v22, 1, v23
	s_waitcnt lgkmcnt(0)
	v_add_u32_e32 v250, 0xfffff040, v22
	v_cndmask_b32_e64 v250, v22, v250, s[40:41]
	v_cndmask_b32_e64 v248, v18, v20, s[40:41]
	v_cndmask_b32_e64 v249, v19, v21, s[40:41]
	global_store_dwordx2 v250, v[248:249], s[18:19] nt
	v_cndmask_b32_e64 v246, v20, v18, s[40:41]
	v_cndmask_b32_e64 v247, v21, v19, s[40:41]
	v_mul_f32_e32 v3, v3, v3
	v_fmac_f32_e32 v3, v2, v2
	v_mul_f32_e32 v2, v5, v5
	v_mul_f32_e32 v13, v13, v13
	v_fmac_f32_e32 v2, v4, v4
	v_mul_f32_e32 v11, v11, v11
	v_fmac_f32_e32 v13, v12, v12
	v_mul_f32_e32 v12, v15, v15
	v_mul_f32_e32 v15, v17, v17
	v_add_f32_e32 v2, v3, v2
	v_mul_f32_e32 v3, v7, v7
	v_mul_f32_e32 v4, v9, v9
	v_fmac_f32_e32 v15, v16, v16
	v_fmac_f32_e32 v3, v6, v6
	v_fmac_f32_e32 v4, v8, v8
	v_fmac_f32_e32 v11, v10, v10
	v_fmac_f32_e32 v12, v14, v14
	v_add_f32_e32 v3, v3, v4
	v_add_f32_e32 v4, v11, v13
	v_add_f32_e32 v5, v12, v15
	v_add_f32_e32 v2, v4, v2
	v_add_f32_e32 v3, v5, v3
	ds_bpermute_b32 v4, v190, v2
	ds_bpermute_b32 v5, v190, v3
	s_waitcnt lgkmcnt(1)
	v_add_f32_e32 v2, v2, v4
	s_waitcnt lgkmcnt(0)
	v_add_f32_e32 v5, v3, v5
	ds_bpermute_b32 v4, v191, v2
	ds_bpermute_b32 v6, v191, v5
	s_waitcnt lgkmcnt(1)
	v_add_f32_e32 v2, v2, v4
	s_waitcnt lgkmcnt(0)
	v_add_f32_e32 v4, v5, v6
	ds_bpermute_b32 v3, v204, v2
	ds_bpermute_b32 v5, v204, v4
	v_add_u32_e32 v6, 0x1040, v22
	v_cndmask_b32_e64 v6, v22, v6, s[38:39]
	global_store_dwordx2 v6, v[246:247], s[18:19] nt
	s_and_saveexec_b64 s[18:19], s[42:43]
	s_cbranch_execz .LBB0_2009
	s_waitcnt lgkmcnt(1)
	v_add_f32_e32 v2, v2, v3
	s_waitcnt lgkmcnt(0)
	v_add_f32_e32 v3, v4, v5
	ds_write2_b32 v194, v2, v3 offset0:112 offset1:120

; #define LAS __attribute__((address_space(3)))
;     __device__ __forceinline__ void operator()(const f32x4 (&acc)[2][2][4][2], const Unit& u, int wr, int wc, int fr, int fq) const {
;         const int s = u.pm >> 5, lane = fq * 16 + fr, rr = lane >> 3, pc = lane & 7;
;         const float* __restrict__ xi = xin + (size_t)u.pm * BM * DM; float* __restrict__ xo = xout + (size_t)u.pm * BM * DM; bf16_t* __restrict__ ho = Hn + (size_t)u.pm * BM * DM;
;         LAS unsigned char* st = lds_epi + (wr * 4 + wc) * 2304;
;         LAS float* sst = (LAS float*)(lds_epi + 18432 + (wr * 4 + wc) * 512);
;         const int colr = u.pn * BM + wc * 64 + 4 * pc;
;         const unsigned eb = (unsigned)((wr * 64 + rr) * DM + colr);
;         f32x4 gv[2], gsn[2];
; #pragma unroll
;         for (int bj = 0; bj < 2; ++bj) { gv[bj] = *(const f32x4*)(gate + (size_t)s * MODW + colr + bj * 32) * (0.5f * GS2);
;             if (!PLAIN) gsn[bj] = *(const f32x4*)(gnext + colr + bj * 32) * (*(const f32x4*)(scnext + (size_t)s * MODW + colr + bj * 32) + 1.0f); else gsn[bj] = gv[bj]; }
;         const unsigned wr_off = (unsigned)(fr * 144 + 16 * fq), rd_off = (unsigned)(rr * 144 + pc * 16);
;         const bool odd = (rr & 1) != 0;
;         f32x4 xb[2][2][2];
;     ...
;         ERN_LOADX(0);
; #pragma unroll
;         for (int g = 0; g < 8; ++g) { const int ai = g >> 2, m = g & 3;
;             if (g + 1 < 8) ERN_LOADX(g + 1);
;             float sq0 = 0.f, sq1 = 0.f; u32x2 hw[2][2];
; #pragma unroll
;             for (int bj = 0; bj < 2; ++bj) {
;                 *(LAS f32x4*)(st + wr_off) = acc[ai][bj][m][0]; *(LAS f32x4*)(st + wr_off + 64) = acc[ai][bj][m][1];
;                 const f32x4 a0 = *(const LAS f32x4*)(st + rd_off), a1 = *(const LAS f32x4*)(st + rd_off + 8 * 144);
;                 { const f32x4 xv = xb[g & 1][bj][0] + gv[bj] * a0; __builtin_nontemporal_store(xv, (f32x4*)((char*)xo + 4u * ERN_EOFF(g, bj, 0)));
;                   sq0 += (xv.x * xv.x + xv.y * xv.y) + (xv.z * xv.z + xv.w * xv.w);
;                   const f32x4 hv = xv * gsn[bj]; hw[bj][0].x = cvt_pk_bf16(hv.x, hv.y); hw[bj][0].y = cvt_pk_bf16(hv.z, hv.w); }
;                 { const f32x4 xv = xb[g & 1][bj][1] + gv[bj] * a1; __builtin_nontemporal_store(xv, (f32x4*)((char*)xo + 4u * ERN_EOFF(g, bj, 1)));
;                   sq1 += (xv.x * xv.x + xv.y * xv.y) + (xv.z * xv.z + xv.w * xv.w);
.LBB0_2769:
	s_ashr_i32 s13, s2, 5
	s_ashr_i32 s3, s2, 31
	v_lshl_or_b32 v50, s20, 8, v192
	s_mul_hi_i32 s15, s13, 0x12000
	s_mul_i32 s13, s13, 0x12000
	s_add_u32 s20, s44, s13
	v_ashrrev_i32_e32 v51, 31, v50
	s_addc_u32 s21, s45, s15
	v_lshlrev_b64 v[52:53], 2, v[50:51]
	v_lshl_add_u64 v[138:139], s[20:21], 0, v[52:53]
	s_add_u32 s20, s46, s13
	s_addc_u32 s21, s47, s15
	v_lshl_add_u64 v[140:141], s[6:7], 0, v[52:53]
	v_lshl_add_u64 v[52:53], s[20:21], 0, v[52:53]
	s_lshl_b64 s[20:21], s[2:3], 21
	s_add_u32 s22, s90, s20
	v_add_u32_e32 v202, v50, v193
	s_addc_u32 s23, s91, s21
	v_lshlrev_b32_e32 v205, 2, v202
	global_load_dwordx4 v[54:57], v[138:139], off
	global_load_dwordx4 v[174:177], v[140:141], off
	global_load_dwordx4 v[178:181], v[52:53], off
	global_load_dwordx4 v[206:209], v[52:53], off offset:128
	global_load_dwordx4 v[186:189], v205, s[22:23]
	v_add_u32_e32 v50, 0x10000, v205
	global_load_dwordx4 v[210:213], v50, s[22:23]
	global_load_dwordx4 v[214:217], v[140:141], off offset:128
	s_nop 0
	global_load_dwordx4 v[50:53], v[138:139], off offset:128
	global_load_dwordx4 v[218:221], v205, s[22:23] offset:128
	v_add_u32_e32 v204, 0x10080, v205
	global_load_dwordx4 v[222:225], v204, s[22:23]
	v_add_u32_e32 v138, 0x20000, v205
	v_add_u32_e32 v162, 0x30000, v205
	v_add_u32_e32 v184, 0x20080, v205
	v_add_u32_e32 v182, 0x30080, v205
	global_load_dwordx4 v[150:153], v138, s[22:23]
	global_load_dwordx4 v[146:149], v162, s[22:23]
	global_load_dwordx4 v[142:145], v184, s[22:23]
	s_nop 0
	global_load_dwordx4 v[138:141], v182, s[22:23]
	ds_write_b128 v200, v[134:137]
	ds_write_b128 v200, v[130:133] offset:64
	v_and_b32_e32 v135, 64, v199
	ds_read_b128 v[130:133], v201
	ds_read_b128 v[226:229], v201 offset:1152
	v_xor_b32_e32 v134, 8, v199
	v_add_u32_e32 v183, 64, v135
	v_cmp_lt_i32_e32 vcc, v134, v183
	v_add_u32_e32 v185, 0x4000, v202
	v_lshlrev_b32_e32 v230, 2, v185
	v_cndmask_b32_e32 v134, v199, v134, vcc
	v_lshlrev_b32_e32 v203, 2, v134
	s_lshl_b64 s[20:21], s[2:3], 20
	s_add_u32 s20, s93, s20
	s_addc_u32 s21, s92, s21
	s_waitcnt vmcnt(0)
	v_pk_add_f32 v[134:135], v[180:181], 1.0 op_sel_hi:[1,0]
	v_pk_add_f32 v[136:137], v[178:179], 1.0 op_sel_hi:[1,0]
	v_pk_mul_f32 v[178:179], v[176:177], v[134:135]
	v_pk_mul_f32 v[180:181], v[174:175], v[136:137]
	s_waitcnt lgkmcnt(1)
	v_pk_fma_f32 v[134:135], v[54:55], v[130:131], v[186:187]
	s_waitcnt lgkmcnt(0)
	v_pk_fma_f32 v[130:131], v[54:55], v[226:227], v[210:211]
	v_pk_fma_f32 v[136:137], v[56:57], v[132:133], v[188:189]
	v_pk_fma_f32 v[132:133], v[56:57], v[228:229], v[212:213]
	v_pk_mul_f32 v[186:187], v[180:181], v[130:131]
	v_pk_add_f32 v[190:191], v[208:209], 1.0 op_sel_hi:[1,0]
	global_store_dwordx4 v205, v[134:137], s[22:23] nt
	v_pk_mul_f32 v[174:175], v[178:179], v[136:137]
	v_pk_mul_f32 v[176:177], v[180:181], v[134:135]
	v_pk_mul_f32 v[208:209], v[178:179], v[132:133]
	v_cvt_pk_bf16_f32 v188, v176, v177
	v_cvt_pk_bf16_f32 v189, v174, v175
	global_store_dwordx4 v230, v[130:133], s[22:23] nt
	v_cvt_pk_bf16_f32 v186, v186, v187
	v_cvt_pk_bf16_f32 v187, v208, v209
	ds_write_b128 v200, v[126:129]
	ds_write_b128 v200, v[122:125] offset:64
	ds_read_b128 v[122:125], v201
	v_pk_add_f32 v[126:127], v[206:207], 1.0 op_sel_hi:[1,0]
	ds_read_b128 v[206:209], v201 offset:1152
	v_pk_mul_f32 v[174:175], v[216:217], v[190:191]
	v_pk_mul_f32 v[176:177], v[214:215], v[126:127]
	s_waitcnt lgkmcnt(1)
	v_pk_fma_f32 v[128:129], v[52:53], v[124:125], v[220:221]
	v_pk_fma_f32 v[126:127], v[50:51], v[122:123], v[218:219]
	s_waitcnt lgkmcnt(0)
	v_pk_fma_f32 v[122:123], v[50:51], v[206:207], v[222:223]
	v_pk_mul_f32 v[190:191], v[174:175], v[128:129]
	v_pk_mul_f32 v[206:207], v[176:177], v[126:127]
	global_store_dwordx4 v205, v[126:129], s[22:23] offset:128 nt
	v_cvt_pk_bf16_f32 v206, v206, v207
	v_cvt_pk_bf16_f32 v191, v190, v191
	ds_bpermute_b32 v190, v203, v206
	ds_bpermute_b32 v191, v203, v191
	v_pk_fma_f32 v[124:125], v[52:53], v[208:209], v[224:225]
	v_pk_mul_f32 v[206:207], v[176:177], v[122:123]
	global_store_dwordx4 v204, v[122:125], s[22:23] nt
	v_cvt_pk_bf16_f32 v204, v206, v207
	v_lshlrev_b32_e32 v207, 1, v202
	v_pk_mul_f32 v[208:209], v[174:175], v[124:125]
	s_nop 0
	v_cvt_pk_bf16_f32 v206, v208, v209
	s_waitcnt lgkmcnt(0)
	v_add_u32_e32 v250, 0xfffff040, v207
	v_cndmask_b32_e64 v250, v207, v250, s[38:39]
	v_cndmask_b32_e64 v248, v188, v190, s[38:39]
	v_cndmask_b32_e64 v249, v189, v191, s[38:39]
	global_store_dwordx2 v250, v[248:249], s[20:21] nt
	v_cndmask_b32_e64 v246, v190, v188, s[38:39]
	v_cndmask_b32_e64 v247, v191, v189, s[38:39]
	s_waitcnt lgkmcnt(1)
	v_add_u32_e32 v190, 0x1040, v207
	v_cndmask_b32_e64 v190, v207, v190, s[36:37]
	global_store_dwordx2 v190, v[246:247], s[20:21] nt
	ds_bpermute_b32 v188, v203, v204
	ds_bpermute_b32 v189, v203, v206
	v_lshlrev_b32_e32 v206, 1, v185
	s_and_saveexec_b64 s[24:25], s[38:39]
	s_xor_b64 s[24:25], exec, s[24:25]
	s_mov_b64 s[58:59], s[70:71]
	s_cbranch_execz .LBB0_2775
	v_lshlrev_b32_e32 v206, 1, v185
	v_add_u32_e32 v185, 0xfffff040, v206
	s_waitcnt lgkmcnt(0)
	global_store_dwordx2 v185, v[188:189], s[20:21] nt
.LBB0_2775:
	s_andn2_saveexec_b64 s[24:25], s[24:25]
	s_cbranch_execz .LBB0_2777
	global_store_dwordx2 v206, v[186:187], s[20:21] nt
	s_waitcnt lgkmcnt(0)
	v_mov_b64_e32 v[186:187], v[188:189]
; #define LAS __attribute__((address_space(3)))
; __device__ __forceinline__ unsigned cvt_pk_bf16(float lo, float hi) { unsigned r; asm volatile("v_cvt_pk_bf16_f32 %0, %1, %2" : "=v"(r) : "v"(lo), "v"(hi)); return r; }
;     __device__ __forceinline__ void operator()(const f32x4 (&acc)[2][2][4][2], const Unit& u, int wr, int wc, int fr, int fq) const {
;     ...
;         for (int g = 0; g < 8; ++g) { const int ai = g >> 2, m = g & 3;
;             if (g + 1 < 8) ERN_LOADX(g + 1);
;             float sq0 = 0.f, sq1 = 0.f; u32x2 hw[2][2];
; #pragma unroll
;             for (int bj = 0; bj < 2; ++bj) {
;                 *(LAS f32x4*)(st + wr_off) = acc[ai][bj][m][0]; *(LAS f32x4*)(st + wr_off + 64) = acc[ai][bj][m][1];
;                 const f32x4 a0 = *(const LAS f32x4*)(st + rd_off), a1 = *(const LAS f32x4*)(st + rd_off + 8 * 144);
;                 { const f32x4 xv = xb[g & 1][bj][0] + gv[bj] * a0; __builtin_nontemporal_store(xv, (f32x4*)((char*)xo + 4u * ERN_EOFF(g, bj, 0)));
;                   sq0 += (xv.x * xv.x + xv.y * xv.y) + (xv.z * xv.z + xv.w * xv.w);
;                   const f32x4 hv = xv * gsn[bj]; hw[bj][0].x = cvt_pk_bf16(hv.x, hv.y); hw[bj][0].y = cvt_pk_bf16(hv.z, hv.w); }
;                 { const f32x4 xv = xb[g & 1][bj][1] + gv[bj] * a1; __builtin_nontemporal_store(xv, (f32x4*)((char*)xo + 4u * ERN_EOFF(g, bj, 1)));
;                   sq1 += (xv.x * xv.x + xv.y * xv.y) + (xv.z * xv.z + xv.w * xv.w);
;                   const f32x4 hv = xv * gsn[bj]; hw[bj][1].x = cvt_pk_bf16(hv.x, hv.y); hw[bj][1].y = cvt_pk_bf16(hv.z, hv.w); }
;     ...
;             if (!NOH && !PLAIN) {
; #pragma unroll
;                 for (int rh = 0; rh < 2; ++rh) { u32x2 rv; rv.x = __shfl_xor(hw[1][rh].x, 8); rv.y = __shfl_xor(hw[1][rh].y, 8);
;                     const unsigned e0 = ERN_EOFF(g, 0, rh);
;                     const unsigned ee = odd ? (e0 - DM + 32) : e0, eo2 = odd ? e0 : (e0 + DM + 32);
;                     *(u32x2*)((char*)ho + 2u * ee) = odd ? rv : hw[0][rh];
;                     *(u32x2*)((char*)ho + 2u * eo2) = odd ? hw[0][rh] : rv; }
;             }
;             if (!PLAIN) { sq0 += __shfl_xor(sq0, 1); sq0 += __shfl_xor(sq0, 2); sq0 += __shfl_xor(sq0, 4);
;             sq1 += __shfl_xor(sq1, 1); sq1 += __shfl_xor(sq1, 2); sq1 += __shfl_xor(sq1, 4); }
;             if (!PLAIN && pc == 0) { sst[g * 16 + rr] = sq0; sst[g * 16 + 8 + rr] = sq1; }
.LBB0_2777:
	s_or_b64 exec, exec, s[24:25]
	v_mul_f32_e32 v127, v127, v127
	v_mul_f32_e32 v135, v135, v135
	v_mul_f32_e32 v137, v137, v137
	v_fmac_f32_e32 v127, v126, v126
	v_mul_f32_e32 v126, v129, v129
	v_fmac_f32_e32 v137, v136, v136
	v_fmac_f32_e32 v126, v128, v128
	v_mul_f32_e32 v123, v123, v123
	v_fmac_f32_e32 v135, v134, v134
	v_add_f32_e32 v126, v127, v126
	v_fmac_f32_e32 v123, v122, v122
	v_mul_f32_e32 v122, v125, v125
	v_add_f32_e32 v125, v135, v137
	v_add_f32_e32 v125, v125, v126
	v_xor_b32_e32 v126, 1, v199
	v_cmp_lt_i32_e32 vcc, v126, v183
	v_mul_f32_e32 v131, v131, v131
	v_mul_f32_e32 v133, v133, v133
	v_cndmask_b32_e32 v126, v199, v126, vcc
	v_lshlrev_b32_e32 v190, 2, v126
	ds_bpermute_b32 v126, v190, v125
	v_fmac_f32_e32 v122, v124, v124
	v_fmac_f32_e32 v133, v132, v132
	v_fmac_f32_e32 v131, v130, v130
	v_add_f32_e32 v122, v123, v122
	s_waitcnt lgkmcnt(0)
	v_add_f32_e32 v124, v125, v126
	v_xor_b32_e32 v125, 2, v199
	v_cmp_lt_i32_e32 vcc, v125, v183
	v_add_f32_e32 v123, v131, v133
	v_add_f32_e32 v123, v123, v122
	v_cndmask_b32_e32 v125, v199, v125, vcc
	v_lshlrev_b32_e32 v191, 2, v125
	ds_bpermute_b32 v125, v191, v124
	ds_bpermute_b32 v126, v190, v123
	s_waitcnt lgkmcnt(1)
	v_add_f32_e32 v122, v124, v125
	s_waitcnt lgkmcnt(0)
	v_add_f32_e32 v125, v123, v126
	ds_bpermute_b32 v126, v191, v125
	v_xor_b32_e32 v124, 4, v199
	v_cmp_lt_i32_e32 vcc, v124, v183
	s_nop 1
	v_cndmask_b32_e32 v123, v199, v124, vcc
	v_lshlrev_b32_e32 v204, 2, v123
	s_waitcnt lgkmcnt(0)
	v_add_f32_e32 v124, v125, v126
	ds_bpermute_b32 v123, v204, v122
	ds_bpermute_b32 v125, v204, v124
	v_add_u32_e32 v126, 0x1040, v206
	v_cndmask_b32_e64 v126, v206, v126, s[36:37]
	global_store_dwordx2 v126, v[186:187], s[20:21] nt
	s_and_saveexec_b64 s[24:25], s[40:41]
	s_cbranch_execz .LBB0_2779
	s_waitcnt lgkmcnt(1)
	v_add_f32_e32 v122, v122, v123
	s_waitcnt lgkmcnt(0)
	v_add_f32_e32 v123, v124, v125
	ds_write2_b32 v194, v122, v123 offset1:8
.LBB0_2779:
	s_or_b64 exec, exec, s[24:25]
	v_lshl_add_u64 v[206:207], s[22:23], 0, v[162:163]
	v_add_u32_e32 v122, 0x40000, v205
	v_add_u32_e32 v162, 0x50000, v205
	v_add_u32_e32 v186, 0x40080, v205
	global_load_dwordx4 v[130:133], v162, s[22:23]
	global_load_dwordx4 v[126:129], v186, s[22:23]
	v_add_u32_e32 v188, 0x50080, v205
	global_load_dwordx4 v[134:137], v122, s[22:23]
	s_waitcnt lgkmcnt(0)
	global_load_dwordx4 v[122:125], v188, s[22:23]
	ds_write_b128 v200, v[118:121]
	ds_write_b128 v200, v[114:117] offset:64
	ds_read_b128 v[114:117], v201
	ds_read_b128 v[118:121], v201 offset:1152
	v_mov_b32_e32 v185, v163
	v_mov_b32_e32 v183, v163
	v_lshl_add_u64 v[182:183], s[22:23], 0, v[182:183]
	s_waitcnt lgkmcnt(1)
	v_pk_fma_f32 v[116:117], v[56:57], v[116:117], v[152:153]
	v_add_u32_e32 v152, 0x8000, v202
	v_pk_fma_f32 v[114:115], v[54:55], v[114:115], v[150:151]
	v_lshlrev_b32_e32 v150, 2, v152
	s_waitcnt lgkmcnt(0)
	v_pk_fma_f32 v[118:119], v[54:55], v[118:119], v[146:147]
	global_store_dwordx4 v150, v[114:117], s[22:23] nt
	v_pk_mul_f32 v[150:151], v[180:181], v[114:115]
	v_pk_fma_f32 v[120:121], v[56:57], v[120:121], v[148:149]
	v_pk_mul_f32 v[146:147], v[180:181], v[118:119]
	v_pk_mul_f32 v[208:209], v[178:179], v[116:117]
	v_cvt_pk_bf16_f32 v150, v150, v151
	v_pk_mul_f32 v[148:149], v[178:179], v[120:121]
	v_cvt_pk_bf16_f32 v151, v208, v209
	global_store_dwordx4 v[206:207], v[118:121], off nt
	v_cvt_pk_bf16_f32 v146, v146, v147
	v_cvt_pk_bf16_f32 v147, v148, v149
	ds_write_b128 v200, v[110:113]
	ds_write_b128 v200, v[106:109] offset:64
	ds_read_b128 v[106:109], v201
	ds_read_b128 v[110:113], v201 offset:1152
	v_lshl_add_u64 v[148:149], s[22:23], 0, v[184:185]
	s_waitcnt lgkmcnt(1)
	v_pk_fma_f32 v[106:107], v[50:51], v[106:107], v[142:143]
	v_pk_fma_f32 v[108:109], v[52:53], v[108:109], v[144:145]
	v_pk_mul_f32 v[144:145], v[176:177], v[106:107]
	global_store_dwordx4 v[148:149], v[106:109], off nt
	v_pk_mul_f32 v[142:143], v[174:175], v[108:109]
	v_cvt_pk_bf16_f32 v144, v144, v145
	s_waitcnt lgkmcnt(0)
	v_pk_fma_f32 v[110:111], v[50:51], v[110:111], v[138:139]
	v_cvt_pk_bf16_f32 v145, v142, v143
	ds_bpermute_b32 v138, v203, v144
	ds_bpermute_b32 v139, v203, v145
	v_pk_fma_f32 v[112:113], v[52:53], v[112:113], v[140:141]
	v_pk_mul_f32 v[140:141], v[176:177], v[110:111]
	v_pk_mul_f32 v[142:143], v[174:175], v[112:113]
	global_store_dwordx4 v[182:183], v[110:113], off nt
	v_cvt_pk_bf16_f32 v140, v140, v141
	v_cvt_pk_bf16_f32 v141, v142, v143
	v_lshlrev_b32_e32 v142, 1, v152
	s_waitcnt lgkmcnt(0)
	v_add_u32_e32 v250, 0xfffff040, v142
	v_cndmask_b32_e64 v250, v142, v250, s[38:39]
	v_cndmask_b32_e64 v248, v150, v138, s[38:39]
	v_cndmask_b32_e64 v249, v151, v139, s[38:39]
	global_store_dwordx2 v250, v[248:249], s[20:21] nt
	v_cndmask_b32_e64 v246, v138, v150, s[38:39]
	v_cndmask_b32_e64 v247, v139, v151, s[38:39]
	s_waitcnt lgkmcnt(1)
	v_add_u32_e32 v138, 0x1040, v142
	v_cndmask_b32_e64 v138, v142, v138, s[36:37]
	global_store_dwordx2 v138, v[246:247], s[20:21] nt
	ds_bpermute_b32 v138, v203, v140
	s_waitcnt lgkmcnt(1)
	ds_bpermute_b32 v139, v203, v141
	v_add_u32_e32 v141, 0xc000, v202
	v_lshlrev_b32_e32 v140, 1, v141
	s_waitcnt lgkmcnt(0)
	v_add_u32_e32 v250, 0xfffff040, v140
	v_cndmask_b32_e64 v250, v140, v250, s[38:39]
	v_cndmask_b32_e64 v248, v146, v138, s[38:39]
	v_cndmask_b32_e64 v249, v147, v139, s[38:39]
	global_store_dwordx2 v250, v[248:249], s[20:21] nt
	v_cndmask_b32_e64 v246, v138, v146, s[38:39]
	v_cndmask_b32_e64 v247, v139, v147, s[38:39]
	v_mul_f32_e32 v107, v107, v107
	v_fmac_f32_e32 v107, v106, v106
	v_mul_f32_e32 v106, v109, v109
	v_mul_f32_e32 v117, v117, v117
	v_fmac_f32_e32 v106, v108, v108
	v_mul_f32_e32 v115, v115, v115
	v_fmac_f32_e32 v117, v116, v116
	v_mul_f32_e32 v116, v119, v119
	v_mul_f32_e32 v119, v121, v121
	v_add_f32_e32 v106, v107, v106
	v_mul_f32_e32 v107, v111, v111
	v_mul_f32_e32 v108, v113, v113
	v_fmac_f32_e32 v119, v120, v120
	v_fmac_f32_e32 v107, v110, v110
	v_fmac_f32_e32 v108, v112, v112
	v_fmac_f32_e32 v115, v114, v114
	v_fmac_f32_e32 v116, v118, v118
	v_add_f32_e32 v107, v107, v108
	v_add_f32_e32 v108, v115, v117
	v_add_f32_e32 v109, v116, v119
	v_add_f32_e32 v106, v108, v106
	v_add_f32_e32 v107, v109, v107
	ds_bpermute_b32 v108, v190, v106
	ds_bpermute_b32 v109, v190, v107
	s_waitcnt lgkmcnt(1)
	v_add_f32_e32 v106, v106, v108
	s_waitcnt lgkmcnt(0)
	v_add_f32_e32 v109, v107, v109
	ds_bpermute_b32 v108, v191, v106
	ds_bpermute_b32 v110, v191, v109
	s_waitcnt lgkmcnt(1)
	v_add_f32_e32 v106, v106, v108
	s_waitcnt lgkmcnt(0)
	v_add_f32_e32 v108, v109, v110
	ds_bpermute_b32 v107, v204, v106
	ds_bpermute_b32 v109, v204, v108
	v_add_u32_e32 v110, 0x1040, v140
	v_cndmask_b32_e64 v110, v140, v110, s[36:37]
	global_store_dwordx2 v110, v[246:247], s[20:21] nt
	s_and_saveexec_b64 s[24:25], s[40:41]
	s_cbranch_execz .LBB0_2789
	s_waitcnt lgkmcnt(1)
	v_add_f32_e32 v106, v106, v107
	s_waitcnt lgkmcnt(0)
	v_add_f32_e32 v107, v108, v109
	ds_write2_b32 v194, v106, v107 offset0:16 offset1:24
; #define LAS __attribute__((address_space(3)))
; #define ERN_EOFF(q, m) (eb + (unsigned)((((q) & 1) * HALF + (m) * 16) * DM + ERN_COL((q) >> 1)))
;     __device__ __forceinline__ void operator()(const f32x4 (&acc)[2][2][4][2], const Unit& u, int wr, int wc, int fr, int fq) const {
;     ...
;         for (int g = 0; g < 8; ++g) { const int ai = g >> 2, m = g & 3;
;             if (g + 1 < 8) ERN_LOADX(g + 1);
;             float sq0 = 0.f, sq1 = 0.f; u32x2 hw[2][2];
; #pragma unroll
;             for (int bj = 0; bj < 2; ++bj) {
;                 *(LAS f32x4*)(st + wr_off) = acc[ai][bj][m][0]; *(LAS f32x4*)(st + wr_off + 64) = acc[ai][bj][m][1];
;                 const f32x4 a0 = *(const LAS f32x4*)(st + rd_off), a1 = *(const LAS f32x4*)(st + rd_off + 8 * 144);
;                 { const f32x4 xv = xb[g & 1][bj][0] + gv[bj] * a0; __builtin_nontemporal_store(xv, (f32x4*)((char*)xo + 4u * ERN_EOFF(g, bj, 0)));
;                   sq0 += (xv.x * xv.x + xv.y * xv.y) + (xv.z * xv.z + xv.w * xv.w);
;                   const f32x4 hv = xv * gsn[bj]; hw[bj][0].x = cvt_pk_bf16(hv.x, hv.y); hw[bj][0].y = cvt_pk_bf16(hv.z, hv.w); }
;                 { const f32x4 xv = xb[g & 1][bj][1] + gv[bj] * a1; __builtin_nontemporal_store(xv, (f32x4*)((char*)xo + 4u * ERN_EOFF(g, bj, 1)));
;                   sq1 += (xv.x * xv.x + xv.y * xv.y) + (xv.z * xv.z + xv.w * xv.w);
;                   const f32x4 hv = xv * gsn[bj]; hw[bj][1].x = cvt_pk_bf16(hv.x, hv.y); hw[bj][1].y = cvt_pk_bf16(hv.z, hv.w); }
;             }
;             if (!NOH && !PLAIN) {
; #pragma unroll
;                 for (int rh = 0; rh < 2; ++rh) { u32x2 rv; rv.x = __shfl_xor(hw[1][rh].x, 8); rv.y = __shfl_xor(hw[1][rh].y, 8);
;                     const unsigned e0 = ERN_EOFF(g, 0, rh);
;                     const unsigned ee = odd ? (e0 - DM + 32) : e0, eo2 = odd ? e0 : (e0 + DM + 32);
;                     *(u32x2*)((char*)ho + 2u * ee) = odd ? rv : hw[0][rh];
;                     *(u32x2*)((char*)ho + 2u * eo2) = odd ? hw[0][rh] : rv; }
;             }
;             if (!PLAIN) { sq0 += __shfl_xor(sq0, 1); sq0 += __shfl_xor(sq0, 2); sq0 += __shfl_xor(sq0, 4);
;             sq1 += __shfl_xor(sq1, 1); sq1 += __shfl_xor(sq1, 2); sq1 += __shfl_xor(sq1, 4); }
;             if (!PLAIN && pc == 0) { sst[g * 16 + rr] = sq0; sst[g * 16 + 8 + rr] = sq1; }
.LBB0_2789:
	s_or_b64 exec, exec, s[24:25]
	v_lshl_add_u64 v[142:143], s[22:23], 0, v[162:163]
	v_add_u32_e32 v106, 0x60000, v205
	v_add_u32_e32 v162, 0x70000, v205
	v_add_u32_e32 v138, 0x60080, v205
	global_load_dwordx4 v[114:117], v162, s[22:23]
	global_load_dwordx4 v[110:113], v138, s[22:23]
	v_add_u32_e32 v140, 0x70080, v205
	global_load_dwordx4 v[118:121], v106, s[22:23]
	s_waitcnt lgkmcnt(0)
	global_load_dwordx4 v[106:109], v140, s[22:23]
	ds_write_b128 v200, v[102:105]
	ds_write_b128 v200, v[98:101] offset:64
	ds_read_b128 v[98:101], v201
	ds_read_b128 v[102:105], v201 offset:1152
	v_mov_b32_e32 v187, v163
	v_mov_b32_e32 v189, v163
	s_waitcnt vmcnt(11) lgkmcnt(1)
	v_pk_fma_f32 v[100:101], v[56:57], v[100:101], v[136:137]
	v_add_u32_e32 v136, 0x10000, v202
	v_pk_fma_f32 v[98:99], v[54:55], v[98:99], v[134:135]
	v_lshlrev_b32_e32 v134, 2, v136
	s_waitcnt lgkmcnt(0)
	v_pk_fma_f32 v[102:103], v[54:55], v[102:103], v[130:131]
	global_store_dwordx4 v134, v[98:101], s[22:23] nt
	v_pk_mul_f32 v[134:135], v[180:181], v[98:99]
	v_pk_fma_f32 v[104:105], v[56:57], v[104:105], v[132:133]
	v_pk_mul_f32 v[130:131], v[180:181], v[102:103]
	v_pk_mul_f32 v[144:145], v[178:179], v[100:101]
	v_cvt_pk_bf16_f32 v134, v134, v135
	v_pk_mul_f32 v[132:133], v[178:179], v[104:105]
	v_cvt_pk_bf16_f32 v135, v144, v145
	global_store_dwordx4 v[142:143], v[102:105], off nt
	v_cvt_pk_bf16_f32 v130, v130, v131
	v_cvt_pk_bf16_f32 v131, v132, v133
	ds_write_b128 v200, v[94:97]
	ds_write_b128 v200, v[90:93] offset:64
	ds_read_b128 v[90:93], v201
	ds_read_b128 v[94:97], v201 offset:1152
	v_lshl_add_u64 v[132:133], s[22:23], 0, v[186:187]
	v_lshl_add_u64 v[142:143], s[22:23], 0, v[188:189]
	s_waitcnt lgkmcnt(1)
	v_pk_fma_f32 v[90:91], v[50:51], v[90:91], v[126:127]
	v_pk_fma_f32 v[92:93], v[52:53], v[92:93], v[128:129]
	v_pk_mul_f32 v[128:129], v[176:177], v[90:91]
	global_store_dwordx4 v[132:133], v[90:93], off nt
	v_pk_mul_f32 v[126:127], v[174:175], v[92:93]
	v_cvt_pk_bf16_f32 v128, v128, v129
	s_waitcnt vmcnt(13) lgkmcnt(0)
	v_pk_fma_f32 v[94:95], v[50:51], v[94:95], v[122:123]
	v_cvt_pk_bf16_f32 v129, v126, v127
	ds_bpermute_b32 v122, v203, v128
	ds_bpermute_b32 v123, v203, v129
	v_pk_fma_f32 v[96:97], v[52:53], v[96:97], v[124:125]
	v_pk_mul_f32 v[124:125], v[176:177], v[94:95]
	v_pk_mul_f32 v[126:127], v[174:175], v[96:97]
	global_store_dwordx4 v[142:143], v[94:97], off nt
	v_cvt_pk_bf16_f32 v124, v124, v125
	v_cvt_pk_bf16_f32 v125, v126, v127
	v_lshlrev_b32_e32 v126, 1, v136
	s_waitcnt lgkmcnt(0)
	v_add_u32_e32 v250, 0xfffff040, v126
	v_cndmask_b32_e64 v250, v126, v250, s[38:39]
	v_cndmask_b32_e64 v248, v134, v122, s[38:39]
	v_cndmask_b32_e64 v249, v135, v123, s[38:39]
	global_store_dwordx2 v250, v[248:249], s[20:21] nt
	v_cndmask_b32_e64 v246, v122, v134, s[38:39]
	v_cndmask_b32_e64 v247, v123, v135, s[38:39]
	s_waitcnt lgkmcnt(1)
	v_add_u32_e32 v122, 0x1040, v126
	v_cndmask_b32_e64 v122, v126, v122, s[36:37]
	global_store_dwordx2 v122, v[246:247], s[20:21] nt
	ds_bpermute_b32 v122, v203, v124
	s_waitcnt lgkmcnt(1)
	ds_bpermute_b32 v123, v203, v125
	v_add_u32_e32 v125, 0x14000, v202
	v_lshlrev_b32_e32 v124, 1, v125
	s_waitcnt lgkmcnt(0)
	v_add_u32_e32 v250, 0xfffff040, v124
	v_cndmask_b32_e64 v250, v124, v250, s[38:39]
	v_cndmask_b32_e64 v248, v130, v122, s[38:39]
	v_cndmask_b32_e64 v249, v131, v123, s[38:39]
	global_store_dwordx2 v250, v[248:249], s[20:21] nt
	v_cndmask_b32_e64 v246, v122, v130, s[38:39]
	v_cndmask_b32_e64 v247, v123, v131, s[38:39]
	v_mul_f32_e32 v91, v91, v91
	v_fmac_f32_e32 v91, v90, v90
	v_mul_f32_e32 v90, v93, v93
	v_mul_f32_e32 v101, v101, v101
	v_fmac_f32_e32 v90, v92, v92
	v_mul_f32_e32 v99, v99, v99
	v_fmac_f32_e32 v101, v100, v100
	v_mul_f32_e32 v100, v103, v103
	v_mul_f32_e32 v103, v105, v105
	v_add_f32_e32 v90, v91, v90
	v_mul_f32_e32 v91, v95, v95
	v_mul_f32_e32 v92, v97, v97
	v_fmac_f32_e32 v103, v104, v104
	v_fmac_f32_e32 v91, v94, v94
	v_fmac_f32_e32 v92, v96, v96
	v_fmac_f32_e32 v99, v98, v98
	v_fmac_f32_e32 v100, v102, v102
	v_add_f32_e32 v91, v91, v92
	v_add_f32_e32 v92, v99, v101
	v_add_f32_e32 v93, v100, v103
	v_add_f32_e32 v90, v92, v90
	v_add_f32_e32 v91, v93, v91
	ds_bpermute_b32 v92, v190, v90
	ds_bpermute_b32 v93, v190, v91
	s_waitcnt lgkmcnt(1)
	v_add_f32_e32 v90, v90, v92
	s_waitcnt lgkmcnt(0)
	v_add_f32_e32 v93, v91, v93
	ds_bpermute_b32 v92, v191, v90
	ds_bpermute_b32 v94, v191, v93
	s_waitcnt lgkmcnt(1)
	v_add_f32_e32 v90, v90, v92
	s_waitcnt lgkmcnt(0)
	v_add_f32_e32 v92, v93, v94
	ds_bpermute_b32 v91, v204, v90
	ds_bpermute_b32 v93, v204, v92
	v_add_u32_e32 v94, 0x1040, v124
	v_cndmask_b32_e64 v94, v124, v94, s[36:37]
	global_store_dwordx2 v94, v[246:247], s[20:21] nt
	s_and_saveexec_b64 s[24:25], s[40:41]
	s_cbranch_execz .LBB0_2799
	s_waitcnt lgkmcnt(1)
	v_add_f32_e32 v90, v90, v91
	s_waitcnt lgkmcnt(0)
	v_add_f32_e32 v91, v92, v93
	ds_write2_b32 v194, v90, v91 offset0:32 offset1:40
; #define LAS __attribute__((address_space(3)))
; #define ERN_EOFF(q, m) (eb + (unsigned)((((q) & 1) * HALF + (m) * 16) * DM + ERN_COL((q) >> 1)))
;     __device__ __forceinline__ void operator()(const f32x4 (&acc)[2][2][4][2], const Unit& u, int wr, int wc, int fr, int fq) const {
;     ...
;         for (int g = 0; g < 8; ++g) { const int ai = g >> 2, m = g & 3;
;             if (g + 1 < 8) ERN_LOADX(g + 1);
;             float sq0 = 0.f, sq1 = 0.f; u32x2 hw[2][2];
; #pragma unroll
;             for (int bj = 0; bj < 2; ++bj) {
;                 *(LAS f32x4*)(st + wr_off) = acc[ai][bj][m][0]; *(LAS f32x4*)(st + wr_off + 64) = acc[ai][bj][m][1];
;                 const f32x4 a0 = *(const LAS f32x4*)(st + rd_off), a1 = *(const LAS f32x4*)(st + rd_off + 8 * 144);
;                 { const f32x4 xv = xb[g & 1][bj][0] + gv[bj] * a0; __builtin_nontemporal_store(xv, (f32x4*)((char*)xo + 4u * ERN_EOFF(g, bj, 0)));
;                   sq0 += (xv.x * xv.x + xv.y * xv.y) + (xv.z * xv.z + xv.w * xv.w);
;                   const f32x4 hv = xv * gsn[bj]; hw[bj][0].x = cvt_pk_bf16(hv.x, hv.y); hw[bj][0].y = cvt_pk_bf16(hv.z, hv.w); }
;                 { const f32x4 xv = xb[g & 1][bj][1] + gv[bj] * a1; __builtin_nontemporal_store(xv, (f32x4*)((char*)xo + 4u * ERN_EOFF(g, bj, 1)));
;                   sq1 += (xv.x * xv.x + xv.y * xv.y) + (xv.z * xv.z + xv.w * xv.w);
;                   const f32x4 hv = xv * gsn[bj]; hw[bj][1].x = cvt_pk_bf16(hv.x, hv.y); hw[bj][1].y = cvt_pk_bf16(hv.z, hv.w); }
;             }
;             if (!NOH && !PLAIN) {
; #pragma unroll
;                 for (int rh = 0; rh < 2; ++rh) { u32x2 rv; rv.x = __shfl_xor(hw[1][rh].x, 8); rv.y = __shfl_xor(hw[1][rh].y, 8);
;                     const unsigned e0 = ERN_EOFF(g, 0, rh);
;                     const unsigned ee = odd ? (e0 - DM + 32) : e0, eo2 = odd ? e0 : (e0 + DM + 32);
;                     *(u32x2*)((char*)ho + 2u * ee) = odd ? rv : hw[0][rh];
;                     *(u32x2*)((char*)ho + 2u * eo2) = odd ? hw[0][rh] : rv; }
;             }
;             if (!PLAIN) { sq0 += __shfl_xor(sq0, 1); sq0 += __shfl_xor(sq0, 2); sq0 += __shfl_xor(sq0, 4);
;             sq1 += __shfl_xor(sq1, 1); sq1 += __shfl_xor(sq1, 2); sq1 += __shfl_xor(sq1, 4); }
;             if (!PLAIN && pc == 0) { sst[g * 16 + rr] = sq0; sst[g * 16 + 8 + rr] = sq1; }
.LBB0_2799:
	s_or_b64 exec, exec, s[24:25]
	v_lshl_add_u64 v[124:125], s[22:23], 0, v[162:163]
	v_add_u32_e32 v90, 0x100000, v205
	s_waitcnt lgkmcnt(1)
	v_add_u32_e32 v91, 0x110000, v205
	v_add_u32_e32 v162, 0x100080, v205
	global_load_dwordx4 v[102:105], v90, s[22:23]
	global_load_dwordx4 v[98:101], v91, s[22:23]
	v_add_u32_e32 v122, 0x110080, v205
	global_load_dwordx4 v[94:97], v162, s[22:23]
	s_waitcnt lgkmcnt(0)
	global_load_dwordx4 v[90:93], v122, s[22:23]
	ds_write_b128 v200, v[86:89]
	ds_write_b128 v200, v[82:85] offset:64
	ds_read_b128 v[82:85], v201
	ds_read_b128 v[86:89], v201 offset:1152
	v_mov_b32_e32 v139, v163
	v_mov_b32_e32 v141, v163
	s_waitcnt vmcnt(11) lgkmcnt(1)
	v_pk_fma_f32 v[84:85], v[56:57], v[84:85], v[120:121]
	v_add_u32_e32 v120, 0x18000, v202
	v_pk_fma_f32 v[82:83], v[54:55], v[82:83], v[118:119]
	v_lshlrev_b32_e32 v118, 2, v120
	s_waitcnt lgkmcnt(0)
	v_pk_fma_f32 v[86:87], v[54:55], v[86:87], v[114:115]
	global_store_dwordx4 v118, v[82:85], s[22:23] nt
	v_pk_mul_f32 v[118:119], v[180:181], v[82:83]
	v_pk_fma_f32 v[88:89], v[56:57], v[88:89], v[116:117]
	v_pk_mul_f32 v[114:115], v[180:181], v[86:87]
	v_pk_mul_f32 v[126:127], v[178:179], v[84:85]
	v_cvt_pk_bf16_f32 v118, v118, v119
	v_pk_mul_f32 v[116:117], v[178:179], v[88:89]
	v_cvt_pk_bf16_f32 v119, v126, v127
	global_store_dwordx4 v[124:125], v[86:89], off nt
	v_cvt_pk_bf16_f32 v114, v114, v115
	v_cvt_pk_bf16_f32 v115, v116, v117
	ds_write_b128 v200, v[78:81]
	ds_write_b128 v200, v[74:77] offset:64
	ds_read_b128 v[74:77], v201
	ds_read_b128 v[78:81], v201 offset:1152
	v_lshl_add_u64 v[116:117], s[22:23], 0, v[138:139]
	v_lshl_add_u64 v[124:125], s[22:23], 0, v[140:141]
	s_waitcnt lgkmcnt(1)
	v_pk_fma_f32 v[74:75], v[50:51], v[74:75], v[110:111]
	v_pk_fma_f32 v[76:77], v[52:53], v[76:77], v[112:113]
	v_pk_mul_f32 v[112:113], v[176:177], v[74:75]
	global_store_dwordx4 v[116:117], v[74:77], off nt
	v_pk_mul_f32 v[110:111], v[174:175], v[76:77]
	v_cvt_pk_bf16_f32 v112, v112, v113
	s_waitcnt vmcnt(13) lgkmcnt(0)
	v_pk_fma_f32 v[78:79], v[50:51], v[78:79], v[106:107]
	v_cvt_pk_bf16_f32 v113, v110, v111
	ds_bpermute_b32 v106, v203, v112
	ds_bpermute_b32 v107, v203, v113
	v_pk_fma_f32 v[80:81], v[52:53], v[80:81], v[108:109]
	v_pk_mul_f32 v[108:109], v[176:177], v[78:79]
	v_pk_mul_f32 v[110:111], v[174:175], v[80:81]
	global_store_dwordx4 v[124:125], v[78:81], off nt
	v_cvt_pk_bf16_f32 v108, v108, v109
	v_cvt_pk_bf16_f32 v109, v110, v111
	v_lshlrev_b32_e32 v110, 1, v120
	s_waitcnt lgkmcnt(0)
	v_add_u32_e32 v250, 0xfffff040, v110
	v_cndmask_b32_e64 v250, v110, v250, s[38:39]
	v_cndmask_b32_e64 v248, v118, v106, s[38:39]
	v_cndmask_b32_e64 v249, v119, v107, s[38:39]
	global_store_dwordx2 v250, v[248:249], s[20:21] nt
	v_cndmask_b32_e64 v246, v106, v118, s[38:39]
	v_cndmask_b32_e64 v247, v107, v119, s[38:39]
	s_waitcnt lgkmcnt(1)
	v_add_u32_e32 v106, 0x1040, v110
	v_cndmask_b32_e64 v106, v110, v106, s[36:37]
	global_store_dwordx2 v106, v[246:247], s[20:21] nt
	ds_bpermute_b32 v106, v203, v108
	s_waitcnt lgkmcnt(1)
	ds_bpermute_b32 v107, v203, v109
	v_add_u32_e32 v109, 0x1c000, v202
	v_lshlrev_b32_e32 v108, 1, v109
	s_waitcnt lgkmcnt(0)
	v_add_u32_e32 v250, 0xfffff040, v108
	v_cndmask_b32_e64 v250, v108, v250, s[38:39]
	v_cndmask_b32_e64 v248, v114, v106, s[38:39]
	v_cndmask_b32_e64 v249, v115, v107, s[38:39]
	global_store_dwordx2 v250, v[248:249], s[20:21] nt
	v_cndmask_b32_e64 v246, v106, v114, s[38:39]
	v_cndmask_b32_e64 v247, v107, v115, s[38:39]
	v_mul_f32_e32 v75, v75, v75
	v_fmac_f32_e32 v75, v74, v74
	v_mul_f32_e32 v74, v77, v77
	v_mul_f32_e32 v85, v85, v85
	v_fmac_f32_e32 v74, v76, v76
	v_mul_f32_e32 v83, v83, v83
	v_fmac_f32_e32 v85, v84, v84
	v_mul_f32_e32 v84, v87, v87
	v_mul_f32_e32 v87, v89, v89
	v_add_f32_e32 v74, v75, v74
	v_mul_f32_e32 v75, v79, v79
	v_mul_f32_e32 v76, v81, v81
	v_fmac_f32_e32 v87, v88, v88
	v_fmac_f32_e32 v75, v78, v78
	v_fmac_f32_e32 v76, v80, v80
	v_fmac_f32_e32 v83, v82, v82
	v_fmac_f32_e32 v84, v86, v86
	v_add_f32_e32 v75, v75, v76
	v_add_f32_e32 v76, v83, v85
	v_add_f32_e32 v77, v84, v87
	v_add_f32_e32 v74, v76, v74
	v_add_f32_e32 v75, v77, v75
	ds_bpermute_b32 v76, v190, v74
	ds_bpermute_b32 v77, v190, v75
	s_waitcnt lgkmcnt(1)
	v_add_f32_e32 v74, v74, v76
	s_waitcnt lgkmcnt(0)
	v_add_f32_e32 v77, v75, v77
	ds_bpermute_b32 v76, v191, v74
	ds_bpermute_b32 v78, v191, v77
	s_waitcnt lgkmcnt(1)
	v_add_f32_e32 v74, v74, v76
	s_waitcnt lgkmcnt(0)
	v_add_f32_e32 v76, v77, v78
	ds_bpermute_b32 v75, v204, v74
	ds_bpermute_b32 v77, v204, v76
	v_add_u32_e32 v78, 0x1040, v108
	v_cndmask_b32_e64 v78, v108, v78, s[36:37]
	global_store_dwordx2 v78, v[246:247], s[20:21] nt
	s_and_saveexec_b64 s[24:25], s[40:41]
	s_cbranch_execz .LBB0_2809
	s_waitcnt lgkmcnt(1)
	v_add_f32_e32 v74, v74, v75
	s_waitcnt lgkmcnt(0)
	v_add_f32_e32 v75, v76, v77
	ds_write2_b32 v194, v74, v75 offset0:48 offset1:56
; #define LAS __attribute__((address_space(3)))
; #define ERN_EOFF(q, m) (eb + (unsigned)((((q) & 1) * HALF + (m) * 16) * DM + ERN_COL((q) >> 1)))
;     __device__ __forceinline__ void operator()(const f32x4 (&acc)[2][2][4][2], const Unit& u, int wr, int wc, int fr, int fq) const {
;     ...
;         for (int g = 0; g < 8; ++g) { const int ai = g >> 2, m = g & 3;
;             if (g + 1 < 8) ERN_LOADX(g + 1);
;             float sq0 = 0.f, sq1 = 0.f; u32x2 hw[2][2];
; #pragma unroll
;             for (int bj = 0; bj < 2; ++bj) {
;                 *(LAS f32x4*)(st + wr_off) = acc[ai][bj][m][0]; *(LAS f32x4*)(st + wr_off + 64) = acc[ai][bj][m][1];
;                 const f32x4 a0 = *(const LAS f32x4*)(st + rd_off), a1 = *(const LAS f32x4*)(st + rd_off + 8 * 144);
;                 { const f32x4 xv = xb[g & 1][bj][0] + gv[bj] * a0; __builtin_nontemporal_store(xv, (f32x4*)((char*)xo + 4u * ERN_EOFF(g, bj, 0)));
;                   sq0 += (xv.x * xv.x + xv.y * xv.y) + (xv.z * xv.z + xv.w * xv.w);
;                   const f32x4 hv = xv * gsn[bj]; hw[bj][0].x = cvt_pk_bf16(hv.x, hv.y); hw[bj][0].y = cvt_pk_bf16(hv.z, hv.w); }
;                 { const f32x4 xv = xb[g & 1][bj][1] + gv[bj] * a1; __builtin_nontemporal_store(xv, (f32x4*)((char*)xo + 4u * ERN_EOFF(g, bj, 1)));
;                   sq1 += (xv.x * xv.x + xv.y * xv.y) + (xv.z * xv.z + xv.w * xv.w);
;                   const f32x4 hv = xv * gsn[bj]; hw[bj][1].x = cvt_pk_bf16(hv.x, hv.y); hw[bj][1].y = cvt_pk_bf16(hv.z, hv.w); }
;             }
;             if (!NOH && !PLAIN) {
; #pragma unroll
;                 for (int rh = 0; rh < 2; ++rh) { u32x2 rv; rv.x = __shfl_xor(hw[1][rh].x, 8); rv.y = __shfl_xor(hw[1][rh].y, 8);
;                     const unsigned e0 = ERN_EOFF(g, 0, rh);
;                     const unsigned ee = odd ? (e0 - DM + 32) : e0, eo2 = odd ? e0 : (e0 + DM + 32);
;                     *(u32x2*)((char*)ho + 2u * ee) = odd ? rv : hw[0][rh];
;                     *(u32x2*)((char*)ho + 2u * eo2) = odd ? hw[0][rh] : rv; }
;             }
;             if (!PLAIN) { sq0 += __shfl_xor(sq0, 1); sq0 += __shfl_xor(sq0, 2); sq0 += __shfl_xor(sq0, 4);
;             sq1 += __shfl_xor(sq1, 1); sq1 += __shfl_xor(sq1, 2); sq1 += __shfl_xor(sq1, 4); }
;             if (!PLAIN && pc == 0) { sst[g * 16 + rr] = sq0; sst[g * 16 + 8 + rr] = sq1; }
.LBB0_2809:
	s_or_b64 exec, exec, s[24:25]
	v_lshl_add_u64 v[112:113], s[22:23], 0, v[162:163]
	v_add_u32_e32 v162, 0x120000, v205
	v_add_u32_e32 v108, 0x120080, v205
	v_add_u32_e32 v110, 0x130000, v205
	global_load_dwordx4 v[86:89], v162, s[22:23]
	global_load_dwordx4 v[82:85], v110, s[22:23]
	v_add_u32_e32 v106, 0x130080, v205
	global_load_dwordx4 v[78:81], v108, s[22:23]
	s_waitcnt lgkmcnt(0)
	global_load_dwordx4 v[74:77], v106, s[22:23]
	ds_write_b128 v200, v[70:73]
	ds_write_b128 v200, v[66:69] offset:64
	ds_read_b128 v[66:69], v201
	ds_read_b128 v[70:73], v201 offset:1152
	v_mov_b32_e32 v123, v163
	s_waitcnt vmcnt(13) lgkmcnt(1)
	v_pk_fma_f32 v[68:69], v[56:57], v[68:69], v[104:105]
	v_add_u32_e32 v104, 0x40000, v202
	v_pk_fma_f32 v[66:67], v[54:55], v[66:67], v[102:103]
	v_lshlrev_b32_e32 v102, 2, v104
	s_waitcnt vmcnt(12) lgkmcnt(0)
	v_pk_fma_f32 v[72:73], v[56:57], v[72:73], v[100:101]
	v_add_u32_e32 v100, 0x44000, v202
	global_store_dwordx4 v102, v[66:69], s[22:23] nt
	v_pk_mul_f32 v[102:103], v[180:181], v[66:67]
	v_pk_fma_f32 v[70:71], v[54:55], v[70:71], v[98:99]
	v_lshlrev_b32_e32 v98, 2, v100
	v_pk_mul_f32 v[114:115], v[178:179], v[68:69]
	v_cvt_pk_bf16_f32 v102, v102, v103
	s_nop 0
	v_cvt_pk_bf16_f32 v103, v114, v115
	global_store_dwordx4 v98, v[70:73], s[22:23] nt
	v_pk_mul_f32 v[98:99], v[180:181], v[70:71]
	v_pk_mul_f32 v[114:115], v[178:179], v[72:73]
	v_cvt_pk_bf16_f32 v98, v98, v99
	s_nop 0
	v_cvt_pk_bf16_f32 v99, v114, v115
	ds_write_b128 v200, v[62:65]
	ds_write_b128 v200, v[58:61] offset:64
	ds_read_b128 v[58:61], v201
	ds_read_b128 v[62:65], v201 offset:1152
	v_lshl_add_u64 v[114:115], s[22:23], 0, v[122:123]
	s_waitcnt vmcnt(13) lgkmcnt(1)
	v_pk_fma_f32 v[58:59], v[50:51], v[58:59], v[94:95]
	v_pk_fma_f32 v[60:61], v[52:53], v[60:61], v[96:97]
	v_pk_mul_f32 v[96:97], v[176:177], v[58:59]
	global_store_dwordx4 v[112:113], v[58:61], off nt
	v_pk_mul_f32 v[94:95], v[174:175], v[60:61]
	v_cvt_pk_bf16_f32 v96, v96, v97
	s_waitcnt vmcnt(13) lgkmcnt(0)
	v_pk_fma_f32 v[62:63], v[50:51], v[62:63], v[90:91]
	v_cvt_pk_bf16_f32 v97, v94, v95
	ds_bpermute_b32 v90, v203, v96
	ds_bpermute_b32 v91, v203, v97
	v_pk_fma_f32 v[64:65], v[52:53], v[64:65], v[92:93]
	v_pk_mul_f32 v[92:93], v[176:177], v[62:63]
	v_pk_mul_f32 v[94:95], v[174:175], v[64:65]
	global_store_dwordx4 v[114:115], v[62:65], off nt
	v_cvt_pk_bf16_f32 v92, v92, v93
	v_cvt_pk_bf16_f32 v93, v94, v95
	v_lshlrev_b32_e32 v94, 1, v104
	s_waitcnt lgkmcnt(0)
	v_add_u32_e32 v250, 0xfffff040, v94
	v_cndmask_b32_e64 v250, v94, v250, s[38:39]
	v_cndmask_b32_e64 v248, v102, v90, s[38:39]
	v_cndmask_b32_e64 v249, v103, v91, s[38:39]
	global_store_dwordx2 v250, v[248:249], s[20:21] nt
	v_cndmask_b32_e64 v246, v90, v102, s[38:39]
	v_cndmask_b32_e64 v247, v91, v103, s[38:39]
	s_waitcnt lgkmcnt(1)
	v_add_u32_e32 v90, 0x1040, v94
	v_cndmask_b32_e64 v90, v94, v90, s[36:37]
	global_store_dwordx2 v90, v[246:247], s[20:21] nt
	ds_bpermute_b32 v90, v203, v92
	s_waitcnt lgkmcnt(1)
	ds_bpermute_b32 v91, v203, v93
	v_lshlrev_b32_e32 v92, 1, v100
	s_waitcnt lgkmcnt(0)
	v_add_u32_e32 v250, 0xfffff040, v92
	v_cndmask_b32_e64 v250, v92, v250, s[38:39]
	v_cndmask_b32_e64 v248, v98, v90, s[38:39]
	v_cndmask_b32_e64 v249, v99, v91, s[38:39]
	global_store_dwordx2 v250, v[248:249], s[20:21] nt
	v_cndmask_b32_e64 v246, v90, v98, s[38:39]
	v_cndmask_b32_e64 v247, v91, v99, s[38:39]
	v_mul_f32_e32 v59, v59, v59
	v_fmac_f32_e32 v59, v58, v58
	v_mul_f32_e32 v58, v61, v61
	v_mul_f32_e32 v69, v69, v69
	v_fmac_f32_e32 v58, v60, v60
	v_mul_f32_e32 v67, v67, v67
	v_fmac_f32_e32 v69, v68, v68
	v_mul_f32_e32 v68, v71, v71
	v_mul_f32_e32 v71, v73, v73
	v_add_f32_e32 v58, v59, v58
	v_mul_f32_e32 v59, v63, v63
	v_mul_f32_e32 v60, v65, v65
	v_fmac_f32_e32 v71, v72, v72
	v_fmac_f32_e32 v59, v62, v62
	v_fmac_f32_e32 v60, v64, v64
	v_fmac_f32_e32 v67, v66, v66
	v_fmac_f32_e32 v68, v70, v70
	v_add_f32_e32 v59, v59, v60
	v_add_f32_e32 v60, v67, v69
	v_add_f32_e32 v61, v68, v71
	v_add_f32_e32 v58, v60, v58
	v_add_f32_e32 v59, v61, v59
	ds_bpermute_b32 v60, v190, v58
	ds_bpermute_b32 v61, v190, v59
	s_waitcnt lgkmcnt(1)
	v_add_f32_e32 v58, v58, v60
	s_waitcnt lgkmcnt(0)
	v_add_f32_e32 v61, v59, v61
	ds_bpermute_b32 v60, v191, v58
	ds_bpermute_b32 v62, v191, v61
	s_waitcnt lgkmcnt(1)
	v_add_f32_e32 v58, v58, v60
	s_waitcnt lgkmcnt(0)
	v_add_f32_e32 v60, v61, v62
	ds_bpermute_b32 v59, v204, v58
	ds_bpermute_b32 v61, v204, v60
	v_add_u32_e32 v62, 0x1040, v92
	v_cndmask_b32_e64 v62, v92, v62, s[36:37]
	global_store_dwordx2 v62, v[246:247], s[20:21] nt
	s_and_saveexec_b64 s[24:25], s[40:41]
	s_cbranch_execz .LBB0_2819
	s_waitcnt lgkmcnt(1)
	v_add_f32_e32 v58, v58, v59
	s_waitcnt lgkmcnt(0)
	v_add_f32_e32 v59, v60, v61
	ds_write2_b32 v194, v58, v59 offset0:64 offset1:72
; #define LAS __attribute__((address_space(3)))
; #define ERN_EOFF(q, m) (eb + (unsigned)((((q) & 1) * HALF + (m) * 16) * DM + ERN_COL((q) >> 1)))
;     __device__ __forceinline__ void operator()(const f32x4 (&acc)[2][2][4][2], const Unit& u, int wr, int wc, int fr, int fq) const {
;     ...
;         for (int g = 0; g < 8; ++g) { const int ai = g >> 2, m = g & 3;
;             if (g + 1 < 8) ERN_LOADX(g + 1);
;             float sq0 = 0.f, sq1 = 0.f; u32x2 hw[2][2];
; #pragma unroll
;             for (int bj = 0; bj < 2; ++bj) {
;                 *(LAS f32x4*)(st + wr_off) = acc[ai][bj][m][0]; *(LAS f32x4*)(st + wr_off + 64) = acc[ai][bj][m][1];
;                 const f32x4 a0 = *(const LAS f32x4*)(st + rd_off), a1 = *(const LAS f32x4*)(st + rd_off + 8 * 144);
;                 { const f32x4 xv = xb[g & 1][bj][0] + gv[bj] * a0; __builtin_nontemporal_store(xv, (f32x4*)((char*)xo + 4u * ERN_EOFF(g, bj, 0)));
;                   sq0 += (xv.x * xv.x + xv.y * xv.y) + (xv.z * xv.z + xv.w * xv.w);
;                   const f32x4 hv = xv * gsn[bj]; hw[bj][0].x = cvt_pk_bf16(hv.x, hv.y); hw[bj][0].y = cvt_pk_bf16(hv.z, hv.w); }
;                 { const f32x4 xv = xb[g & 1][bj][1] + gv[bj] * a1; __builtin_nontemporal_store(xv, (f32x4*)((char*)xo + 4u * ERN_EOFF(g, bj, 1)));
;                   sq1 += (xv.x * xv.x + xv.y * xv.y) + (xv.z * xv.z + xv.w * xv.w);
;                   const f32x4 hv = xv * gsn[bj]; hw[bj][1].x = cvt_pk_bf16(hv.x, hv.y); hw[bj][1].y = cvt_pk_bf16(hv.z, hv.w); }
;             }
;             if (!NOH && !PLAIN) {
; #pragma unroll
;                 for (int rh = 0; rh < 2; ++rh) { u32x2 rv; rv.x = __shfl_xor(hw[1][rh].x, 8); rv.y = __shfl_xor(hw[1][rh].y, 8);
;                     const unsigned e0 = ERN_EOFF(g, 0, rh);
;                     const unsigned ee = odd ? (e0 - DM + 32) : e0, eo2 = odd ? e0 : (e0 + DM + 32);
;                     *(u32x2*)((char*)ho + 2u * ee) = odd ? rv : hw[0][rh];
;                     *(u32x2*)((char*)ho + 2u * eo2) = odd ? hw[0][rh] : rv; }
;             }
;             if (!PLAIN) { sq0 += __shfl_xor(sq0, 1); sq0 += __shfl_xor(sq0, 2); sq0 += __shfl_xor(sq0, 4);
;             sq1 += __shfl_xor(sq1, 1); sq1 += __shfl_xor(sq1, 2); sq1 += __shfl_xor(sq1, 4); }
;             if (!PLAIN && pc == 0) { sst[g * 16 + rr] = sq0; sst[g * 16 + 8 + rr] = sq1; }
.LBB0_2819:
	s_or_b64 exec, exec, s[24:25]
	v_lshl_add_u64 v[96:97], s[22:23], 0, v[162:163]
	v_add_u32_e32 v162, 0x140000, v205
	v_add_u32_e32 v92, 0x140080, v205
	v_add_u32_e32 v94, 0x150000, v205
	global_load_dwordx4 v[70:73], v162, s[22:23]
	global_load_dwordx4 v[66:69], v94, s[22:23]
	v_add_u32_e32 v90, 0x150080, v205
	global_load_dwordx4 v[62:65], v92, s[22:23]
	s_waitcnt lgkmcnt(0)
	global_load_dwordx4 v[58:61], v90, s[22:23]
	ds_write_b128 v200, v[46:49]
	ds_write_b128 v200, v[42:45] offset:64
	ds_read_b128 v[42:45], v201
	ds_read_b128 v[46:49], v201 offset:1152
	v_mov_b32_e32 v111, v163
	v_lshl_add_u64 v[98:99], s[22:23], 0, v[110:111]
	v_mov_b32_e32 v109, v163
	s_waitcnt vmcnt(13) lgkmcnt(1)
	v_pk_fma_f32 v[42:43], v[54:55], v[42:43], v[86:87]
	s_waitcnt vmcnt(12) lgkmcnt(0)
	v_pk_fma_f32 v[46:47], v[54:55], v[46:47], v[82:83]
	v_pk_fma_f32 v[44:45], v[56:57], v[44:45], v[88:89]
	v_pk_mul_f32 v[86:87], v[180:181], v[42:43]
	v_pk_fma_f32 v[48:49], v[56:57], v[48:49], v[84:85]
	v_pk_mul_f32 v[82:83], v[180:181], v[46:47]
	global_store_dwordx4 v[96:97], v[42:45], off nt
	v_pk_mul_f32 v[88:89], v[178:179], v[44:45]
	v_cvt_pk_bf16_f32 v86, v86, v87
	v_pk_mul_f32 v[84:85], v[178:179], v[48:49]
	v_cvt_pk_bf16_f32 v87, v88, v89
	global_store_dwordx4 v[98:99], v[46:49], off nt
	v_cvt_pk_bf16_f32 v82, v82, v83
	v_cvt_pk_bf16_f32 v83, v84, v85
	ds_write_b128 v200, v[38:41]
	ds_write_b128 v200, v[34:37] offset:64
	ds_read_b128 v[34:37], v201
	ds_read_b128 v[38:41], v201 offset:1152
	v_lshl_add_u64 v[84:85], s[22:23], 0, v[108:109]
	v_mov_b32_e32 v107, v163
	v_lshl_add_u64 v[88:89], s[22:23], 0, v[106:107]
	s_waitcnt vmcnt(13) lgkmcnt(1)
	v_pk_fma_f32 v[34:35], v[50:51], v[34:35], v[78:79]
	v_pk_fma_f32 v[36:37], v[52:53], v[36:37], v[80:81]
	v_pk_mul_f32 v[80:81], v[176:177], v[34:35]
	global_store_dwordx4 v[84:85], v[34:37], off nt
	v_pk_mul_f32 v[78:79], v[174:175], v[36:37]
	v_cvt_pk_bf16_f32 v80, v80, v81
	s_waitcnt vmcnt(13) lgkmcnt(0)
	v_pk_fma_f32 v[38:39], v[50:51], v[38:39], v[74:75]
	v_cvt_pk_bf16_f32 v81, v78, v79
	ds_bpermute_b32 v74, v203, v80
	ds_bpermute_b32 v75, v203, v81
	v_pk_fma_f32 v[40:41], v[52:53], v[40:41], v[76:77]
	v_pk_mul_f32 v[76:77], v[176:177], v[38:39]
	v_pk_mul_f32 v[78:79], v[174:175], v[40:41]
	global_store_dwordx4 v[88:89], v[38:41], off nt
	v_cvt_pk_bf16_f32 v76, v76, v77
	v_cvt_pk_bf16_f32 v77, v78, v79
	v_add_u32_e32 v79, 0x48000, v202
	v_lshlrev_b32_e32 v78, 1, v79
	s_waitcnt lgkmcnt(0)
	v_add_u32_e32 v250, 0xfffff040, v78
	v_cndmask_b32_e64 v250, v78, v250, s[38:39]
	v_cndmask_b32_e64 v248, v86, v74, s[38:39]
	v_cndmask_b32_e64 v249, v87, v75, s[38:39]
	global_store_dwordx2 v250, v[248:249], s[20:21] nt
	v_cndmask_b32_e64 v246, v74, v86, s[38:39]
	v_cndmask_b32_e64 v247, v75, v87, s[38:39]
	s_waitcnt lgkmcnt(1)
	v_add_u32_e32 v74, 0x1040, v78
	v_cndmask_b32_e64 v74, v78, v74, s[36:37]
	global_store_dwordx2 v74, v[246:247], s[20:21] nt
	ds_bpermute_b32 v74, v203, v76
	s_waitcnt lgkmcnt(1)
	ds_bpermute_b32 v75, v203, v77
	v_add_u32_e32 v77, 0x4c000, v202
	v_lshlrev_b32_e32 v76, 1, v77
	s_waitcnt lgkmcnt(0)
	v_add_u32_e32 v250, 0xfffff040, v76
	v_cndmask_b32_e64 v250, v76, v250, s[38:39]
	v_cndmask_b32_e64 v248, v82, v74, s[38:39]
	v_cndmask_b32_e64 v249, v83, v75, s[38:39]
	global_store_dwordx2 v250, v[248:249], s[20:21] nt
	v_cndmask_b32_e64 v246, v74, v82, s[38:39]
	v_cndmask_b32_e64 v247, v75, v83, s[38:39]
	v_mul_f32_e32 v35, v35, v35
	v_fmac_f32_e32 v35, v34, v34
	v_mul_f32_e32 v34, v37, v37
	v_mul_f32_e32 v45, v45, v45
	v_fmac_f32_e32 v34, v36, v36
	v_mul_f32_e32 v43, v43, v43
	v_fmac_f32_e32 v45, v44, v44
	v_mul_f32_e32 v44, v47, v47
	v_mul_f32_e32 v47, v49, v49
	v_add_f32_e32 v34, v35, v34
	v_mul_f32_e32 v35, v39, v39
	v_mul_f32_e32 v36, v41, v41
	v_fmac_f32_e32 v47, v48, v48
	v_fmac_f32_e32 v35, v38, v38
	v_fmac_f32_e32 v36, v40, v40
	v_fmac_f32_e32 v43, v42, v42
	v_fmac_f32_e32 v44, v46, v46
	v_add_f32_e32 v35, v35, v36
	v_add_f32_e32 v36, v43, v45
	v_add_f32_e32 v37, v44, v47
	v_add_f32_e32 v34, v36, v34
	v_add_f32_e32 v35, v37, v35
	ds_bpermute_b32 v36, v190, v34
	ds_bpermute_b32 v37, v190, v35
	s_waitcnt lgkmcnt(1)
	v_add_f32_e32 v34, v34, v36
	s_waitcnt lgkmcnt(0)
	v_add_f32_e32 v37, v35, v37
	ds_bpermute_b32 v36, v191, v34
	ds_bpermute_b32 v38, v191, v37
	s_waitcnt lgkmcnt(1)
	v_add_f32_e32 v34, v34, v36
	s_waitcnt lgkmcnt(0)
	v_add_f32_e32 v36, v37, v38
	ds_bpermute_b32 v35, v204, v34
	ds_bpermute_b32 v37, v204, v36
	v_add_u32_e32 v38, 0x1040, v76
	v_cndmask_b32_e64 v38, v76, v38, s[36:37]
	global_store_dwordx2 v38, v[246:247], s[20:21] nt
	s_and_saveexec_b64 s[24:25], s[40:41]
	s_cbranch_execz .LBB0_2829
	s_waitcnt lgkmcnt(1)
	v_add_f32_e32 v34, v34, v35
	s_waitcnt lgkmcnt(0)
	v_add_f32_e32 v35, v36, v37
	ds_write2_b32 v194, v34, v35 offset0:80 offset1:88
; #define LAS __attribute__((address_space(3)))
; #define ERN_EOFF(q, m) (eb + (unsigned)((((q) & 1) * HALF + (m) * 16) * DM + ERN_COL((q) >> 1)))
;     __device__ __forceinline__ void operator()(const f32x4 (&acc)[2][2][4][2], const Unit& u, int wr, int wc, int fr, int fq) const {
;     ...
;         for (int g = 0; g < 8; ++g) { const int ai = g >> 2, m = g & 3;
;             if (g + 1 < 8) ERN_LOADX(g + 1);
;             float sq0 = 0.f, sq1 = 0.f; u32x2 hw[2][2];
; #pragma unroll
;             for (int bj = 0; bj < 2; ++bj) {
;                 *(LAS f32x4*)(st + wr_off) = acc[ai][bj][m][0]; *(LAS f32x4*)(st + wr_off + 64) = acc[ai][bj][m][1];
;                 const f32x4 a0 = *(const LAS f32x4*)(st + rd_off), a1 = *(const LAS f32x4*)(st + rd_off + 8 * 144);
;                 { const f32x4 xv = xb[g & 1][bj][0] + gv[bj] * a0; __builtin_nontemporal_store(xv, (f32x4*)((char*)xo + 4u * ERN_EOFF(g, bj, 0)));
;                   sq0 += (xv.x * xv.x + xv.y * xv.y) + (xv.z * xv.z + xv.w * xv.w);
;                   const f32x4 hv = xv * gsn[bj]; hw[bj][0].x = cvt_pk_bf16(hv.x, hv.y); hw[bj][0].y = cvt_pk_bf16(hv.z, hv.w); }
;                 { const f32x4 xv = xb[g & 1][bj][1] + gv[bj] * a1; __builtin_nontemporal_store(xv, (f32x4*)((char*)xo + 4u * ERN_EOFF(g, bj, 1)));
;                   sq1 += (xv.x * xv.x + xv.y * xv.y) + (xv.z * xv.z + xv.w * xv.w);
;                   const f32x4 hv = xv * gsn[bj]; hw[bj][1].x = cvt_pk_bf16(hv.x, hv.y); hw[bj][1].y = cvt_pk_bf16(hv.z, hv.w); }
;             }
;             if (!NOH && !PLAIN) {
; #pragma unroll
;                 for (int rh = 0; rh < 2; ++rh) { u32x2 rv; rv.x = __shfl_xor(hw[1][rh].x, 8); rv.y = __shfl_xor(hw[1][rh].y, 8);
;                     const unsigned e0 = ERN_EOFF(g, 0, rh);
;                     const unsigned ee = odd ? (e0 - DM + 32) : e0, eo2 = odd ? e0 : (e0 + DM + 32);
;                     *(u32x2*)((char*)ho + 2u * ee) = odd ? rv : hw[0][rh];
;                     *(u32x2*)((char*)ho + 2u * eo2) = odd ? hw[0][rh] : rv; }
;             }
;             if (!PLAIN) { sq0 += __shfl_xor(sq0, 1); sq0 += __shfl_xor(sq0, 2); sq0 += __shfl_xor(sq0, 4);
;             sq1 += __shfl_xor(sq1, 1); sq1 += __shfl_xor(sq1, 2); sq1 += __shfl_xor(sq1, 4); }
;             if (!PLAIN && pc == 0) { sst[g * 16 + rr] = sq0; sst[g * 16 + 8 + rr] = sq1; }
.LBB0_2829:
	s_or_b64 exec, exec, s[24:25]
	v_lshl_add_u64 v[80:81], s[22:23], 0, v[162:163]
	v_add_u32_e32 v162, 0x160000, v205
	v_add_u32_e32 v76, 0x160080, v205
	v_add_u32_e32 v78, 0x170000, v205
	global_load_dwordx4 v[46:49], v162, s[22:23]
	global_load_dwordx4 v[42:45], v78, s[22:23]
	v_add_u32_e32 v74, 0x170080, v205
	global_load_dwordx4 v[38:41], v76, s[22:23]
	s_waitcnt lgkmcnt(0)
	global_load_dwordx4 v[34:37], v74, s[22:23]
	ds_write_b128 v200, v[30:33]
	ds_write_b128 v200, v[26:29] offset:64
	ds_read_b128 v[26:29], v201
	ds_read_b128 v[30:33], v201 offset:1152
	v_mov_b32_e32 v95, v163
	v_lshl_add_u64 v[82:83], s[22:23], 0, v[94:95]
	v_mov_b32_e32 v93, v163
	s_waitcnt vmcnt(13) lgkmcnt(1)
	v_pk_fma_f32 v[26:27], v[54:55], v[26:27], v[70:71]
	s_waitcnt vmcnt(12) lgkmcnt(0)
	v_pk_fma_f32 v[30:31], v[54:55], v[30:31], v[66:67]
	v_pk_fma_f32 v[28:29], v[56:57], v[28:29], v[72:73]
	v_pk_mul_f32 v[70:71], v[180:181], v[26:27]
	v_pk_fma_f32 v[32:33], v[56:57], v[32:33], v[68:69]
	v_pk_mul_f32 v[66:67], v[180:181], v[30:31]
	global_store_dwordx4 v[80:81], v[26:29], off nt
	v_pk_mul_f32 v[72:73], v[178:179], v[28:29]
	v_cvt_pk_bf16_f32 v70, v70, v71
	v_pk_mul_f32 v[68:69], v[178:179], v[32:33]
	v_cvt_pk_bf16_f32 v71, v72, v73
	global_store_dwordx4 v[82:83], v[30:33], off nt
	v_cvt_pk_bf16_f32 v66, v66, v67
	v_cvt_pk_bf16_f32 v67, v68, v69
	ds_write_b128 v200, v[22:25]
	ds_write_b128 v200, v[18:21] offset:64
	ds_read_b128 v[18:21], v201
	ds_read_b128 v[22:25], v201 offset:1152
	v_lshl_add_u64 v[68:69], s[22:23], 0, v[92:93]
	v_mov_b32_e32 v91, v163
	v_lshl_add_u64 v[72:73], s[22:23], 0, v[90:91]
	s_waitcnt vmcnt(13) lgkmcnt(1)
	v_pk_fma_f32 v[18:19], v[50:51], v[18:19], v[62:63]
	v_pk_fma_f32 v[20:21], v[52:53], v[20:21], v[64:65]
	v_pk_mul_f32 v[64:65], v[176:177], v[18:19]
	global_store_dwordx4 v[68:69], v[18:21], off nt
	v_pk_mul_f32 v[62:63], v[174:175], v[20:21]
	v_cvt_pk_bf16_f32 v64, v64, v65
	s_waitcnt vmcnt(13) lgkmcnt(0)
	v_pk_fma_f32 v[22:23], v[50:51], v[22:23], v[58:59]
	v_cvt_pk_bf16_f32 v65, v62, v63
	ds_bpermute_b32 v58, v203, v64
	ds_bpermute_b32 v59, v203, v65
	v_pk_fma_f32 v[24:25], v[52:53], v[24:25], v[60:61]
	v_pk_mul_f32 v[60:61], v[176:177], v[22:23]
	v_pk_mul_f32 v[62:63], v[174:175], v[24:25]
	global_store_dwordx4 v[72:73], v[22:25], off nt
	v_cvt_pk_bf16_f32 v60, v60, v61
	v_cvt_pk_bf16_f32 v61, v62, v63
	v_add_u32_e32 v63, 0x50000, v202
	v_lshlrev_b32_e32 v62, 1, v63
	s_waitcnt lgkmcnt(0)
	v_add_u32_e32 v250, 0xfffff040, v62
	v_cndmask_b32_e64 v250, v62, v250, s[38:39]
	v_cndmask_b32_e64 v248, v70, v58, s[38:39]
	v_cndmask_b32_e64 v249, v71, v59, s[38:39]
	global_store_dwordx2 v250, v[248:249], s[20:21] nt
	v_cndmask_b32_e64 v246, v58, v70, s[38:39]
	v_cndmask_b32_e64 v247, v59, v71, s[38:39]
	s_waitcnt lgkmcnt(1)
	v_add_u32_e32 v58, 0x1040, v62
	v_cndmask_b32_e64 v58, v62, v58, s[36:37]
	global_store_dwordx2 v58, v[246:247], s[20:21] nt
	ds_bpermute_b32 v58, v203, v60
	s_waitcnt lgkmcnt(1)
	ds_bpermute_b32 v59, v203, v61
	v_add_u32_e32 v61, 0x54000, v202
	v_lshlrev_b32_e32 v60, 1, v61
	s_waitcnt lgkmcnt(0)
	v_add_u32_e32 v250, 0xfffff040, v60
	v_cndmask_b32_e64 v250, v60, v250, s[38:39]
	v_cndmask_b32_e64 v248, v66, v58, s[38:39]
	v_cndmask_b32_e64 v249, v67, v59, s[38:39]
	global_store_dwordx2 v250, v[248:249], s[20:21] nt
	v_cndmask_b32_e64 v246, v58, v66, s[38:39]
	v_cndmask_b32_e64 v247, v59, v67, s[38:39]
	v_mul_f32_e32 v19, v19, v19
	v_fmac_f32_e32 v19, v18, v18
	v_mul_f32_e32 v18, v21, v21
	v_mul_f32_e32 v29, v29, v29
	v_fmac_f32_e32 v18, v20, v20
	v_mul_f32_e32 v27, v27, v27
	v_fmac_f32_e32 v29, v28, v28
	v_mul_f32_e32 v28, v31, v31
	v_mul_f32_e32 v31, v33, v33
	v_add_f32_e32 v18, v19, v18
	v_mul_f32_e32 v19, v23, v23
	v_mul_f32_e32 v20, v25, v25
	v_fmac_f32_e32 v31, v32, v32
	v_fmac_f32_e32 v19, v22, v22
	v_fmac_f32_e32 v20, v24, v24
	v_fmac_f32_e32 v27, v26, v26
	v_fmac_f32_e32 v28, v30, v30
	v_add_f32_e32 v19, v19, v20
	v_add_f32_e32 v20, v27, v29
	v_add_f32_e32 v21, v28, v31
	v_add_f32_e32 v18, v20, v18
	v_add_f32_e32 v19, v21, v19
	ds_bpermute_b32 v20, v190, v18
	ds_bpermute_b32 v21, v190, v19
	s_waitcnt lgkmcnt(1)
	v_add_f32_e32 v18, v18, v20
	s_waitcnt lgkmcnt(0)
	v_add_f32_e32 v21, v19, v21
	ds_bpermute_b32 v20, v191, v18
	ds_bpermute_b32 v22, v191, v21
	s_waitcnt lgkmcnt(1)
	v_add_f32_e32 v18, v18, v20
	s_waitcnt lgkmcnt(0)
	v_add_f32_e32 v20, v21, v22
	ds_bpermute_b32 v19, v204, v18
	ds_bpermute_b32 v21, v204, v20
	v_add_u32_e32 v22, 0x1040, v60
	v_cndmask_b32_e64 v22, v60, v22, s[36:37]
	global_store_dwordx2 v22, v[246:247], s[20:21] nt
	s_and_saveexec_b64 s[24:25], s[40:41]
	s_cbranch_execz .LBB0_2839
	s_waitcnt lgkmcnt(1)
	v_add_f32_e32 v18, v18, v19
	s_waitcnt lgkmcnt(0)
	v_add_f32_e32 v19, v20, v21
	ds_write2_b32 v194, v18, v19 offset0:96 offset1:104
; #define LAS __attribute__((address_space(3)))
; #define ERN_EOFF(q, m) (eb + (unsigned)((((q) & 1) * HALF + (m) * 16) * DM + ERN_COL((q) >> 1)))
;     __device__ __forceinline__ void operator()(const f32x4 (&acc)[2][2][4][2], const Unit& u, int wr, int wc, int fr, int fq) const {
;     ...
;         for (int g = 0; g < 8; ++g) { const int ai = g >> 2, m = g & 3;
;             if (g + 1 < 8) ERN_LOADX(g + 1);
;             float sq0 = 0.f, sq1 = 0.f; u32x2 hw[2][2];
; #pragma unroll
;             for (int bj = 0; bj < 2; ++bj) {
;                 *(LAS f32x4*)(st + wr_off) = acc[ai][bj][m][0]; *(LAS f32x4*)(st + wr_off + 64) = acc[ai][bj][m][1];
;                 const f32x4 a0 = *(const LAS f32x4*)(st + rd_off), a1 = *(const LAS f32x4*)(st + rd_off + 8 * 144);
;                 { const f32x4 xv = xb[g & 1][bj][0] + gv[bj] * a0; __builtin_nontemporal_store(xv, (f32x4*)((char*)xo + 4u * ERN_EOFF(g, bj, 0)));
;                   sq0 += (xv.x * xv.x + xv.y * xv.y) + (xv.z * xv.z + xv.w * xv.w);
;                   const f32x4 hv = xv * gsn[bj]; hw[bj][0].x = cvt_pk_bf16(hv.x, hv.y); hw[bj][0].y = cvt_pk_bf16(hv.z, hv.w); }
;                 { const f32x4 xv = xb[g & 1][bj][1] + gv[bj] * a1; __builtin_nontemporal_store(xv, (f32x4*)((char*)xo + 4u * ERN_EOFF(g, bj, 1)));
;                   sq1 += (xv.x * xv.x + xv.y * xv.y) + (xv.z * xv.z + xv.w * xv.w);
;                   const f32x4 hv = xv * gsn[bj]; hw[bj][1].x = cvt_pk_bf16(hv.x, hv.y); hw[bj][1].y = cvt_pk_bf16(hv.z, hv.w); }
;             }
;             if (!NOH && !PLAIN) {
; #pragma unroll
;                 for (int rh = 0; rh < 2; ++rh) { u32x2 rv; rv.x = __shfl_xor(hw[1][rh].x, 8); rv.y = __shfl_xor(hw[1][rh].y, 8);
;                     const unsigned e0 = ERN_EOFF(g, 0, rh);
;                     const unsigned ee = odd ? (e0 - DM + 32) : e0, eo2 = odd ? e0 : (e0 + DM + 32);
;                     *(u32x2*)((char*)ho + 2u * ee) = odd ? rv : hw[0][rh];
;                     *(u32x2*)((char*)ho + 2u * eo2) = odd ? hw[0][rh] : rv; }
;             }
;             if (!PLAIN) { sq0 += __shfl_xor(sq0, 1); sq0 += __shfl_xor(sq0, 2); sq0 += __shfl_xor(sq0, 4);
;             sq1 += __shfl_xor(sq1, 1); sq1 += __shfl_xor(sq1, 2); sq1 += __shfl_xor(sq1, 4); }
;             if (!PLAIN && pc == 0) { sst[g * 16 + rr] = sq0; sst[g * 16 + 8 + rr] = sq1; }
.LBB0_2839:
	s_or_b64 exec, exec, s[24:25]
	ds_write_b128 v200, v[14:17]
	ds_write_b128 v200, v[10:13] offset:64
	ds_read_b128 v[10:13], v201
	ds_read_b128 v[14:17], v201 offset:1152
	s_waitcnt lgkmcnt(5)
	v_lshl_add_u64 v[18:19], s[22:23], 0, v[162:163]
	v_mov_b32_e32 v79, v163
	v_lshl_add_u64 v[22:23], s[22:23], 0, v[78:79]
	s_waitcnt vmcnt(9) lgkmcnt(1)
	v_pk_fma_f32 v[12:13], v[56:57], v[12:13], v[48:49]
	v_pk_fma_f32 v[10:11], v[54:55], v[10:11], v[46:47]
	global_store_dwordx4 v[18:19], v[10:13], off nt
	v_pk_mul_f32 v[18:19], v[178:179], v[12:13]
	v_pk_mul_f32 v[20:21], v[180:181], v[10:11]
	s_waitcnt vmcnt(9) lgkmcnt(0)
	v_pk_fma_f32 v[14:15], v[54:55], v[14:15], v[42:43]
	v_cvt_pk_bf16_f32 v20, v20, v21
	v_cvt_pk_bf16_f32 v21, v18, v19
	v_pk_fma_f32 v[16:17], v[56:57], v[16:17], v[44:45]
	v_pk_mul_f32 v[18:19], v[180:181], v[14:15]
	global_store_dwordx4 v[22:23], v[14:17], off nt
	v_pk_mul_f32 v[22:23], v[178:179], v[16:17]
	v_cvt_pk_bf16_f32 v18, v18, v19
	v_mov_b32_e32 v77, v163
	v_cvt_pk_bf16_f32 v19, v22, v23
	ds_write_b128 v200, v[6:9]
	ds_write_b128 v200, v[2:5] offset:64
	ds_read_b128 v[2:5], v201
	ds_read_b128 v[6:9], v201 offset:1152
	v_lshl_add_u64 v[22:23], s[22:23], 0, v[76:77]
	v_mov_b32_e32 v75, v163
	v_lshl_add_u64 v[24:25], s[22:23], 0, v[74:75]
	s_waitcnt vmcnt(9) lgkmcnt(1)
	v_pk_fma_f32 v[4:5], v[52:53], v[4:5], v[40:41]
	v_pk_fma_f32 v[2:3], v[50:51], v[2:3], v[38:39]
	global_store_dwordx4 v[22:23], v[2:5], off nt
	v_pk_mul_f32 v[22:23], v[174:175], v[4:5]
	v_pk_mul_f32 v[26:27], v[176:177], v[2:3]
	s_waitcnt vmcnt(9) lgkmcnt(0)
	v_pk_fma_f32 v[8:9], v[52:53], v[8:9], v[36:37]
	v_cvt_pk_bf16_f32 v28, v26, v27
	v_cvt_pk_bf16_f32 v23, v22, v23
	ds_bpermute_b32 v22, v203, v28
	ds_bpermute_b32 v23, v203, v23
	v_pk_fma_f32 v[6:7], v[50:51], v[6:7], v[34:35]
	global_store_dwordx4 v[24:25], v[6:9], off nt
	v_pk_mul_f32 v[26:27], v[174:175], v[8:9]
	v_pk_mul_f32 v[24:25], v[176:177], v[6:7]
	s_nop 0
	v_cvt_pk_bf16_f32 v24, v24, v25
	v_cvt_pk_bf16_f32 v25, v26, v27
	v_add_u32_e32 v27, 0x58000, v202
	v_lshlrev_b32_e32 v26, 1, v27
	s_waitcnt lgkmcnt(0)
	v_add_u32_e32 v250, 0xfffff040, v26
	v_cndmask_b32_e64 v250, v26, v250, s[38:39]
	v_cndmask_b32_e64 v248, v20, v22, s[38:39]
	v_cndmask_b32_e64 v249, v21, v23, s[38:39]
	global_store_dwordx2 v250, v[248:249], s[20:21] nt
	v_cndmask_b32_e64 v246, v22, v20, s[38:39]
	v_cndmask_b32_e64 v247, v23, v21, s[38:39]
	s_waitcnt lgkmcnt(1)
	v_add_u32_e32 v22, 0x1040, v26
	v_cndmask_b32_e64 v22, v26, v22, s[36:37]
	global_store_dwordx2 v22, v[246:247], s[20:21] nt
	ds_bpermute_b32 v20, v203, v24
	ds_bpermute_b32 v21, v203, v25
	s_waitcnt lgkmcnt(2)
	v_add_u32_e32 v23, 0x5c000, v202
	v_lshlrev_b32_e32 v22, 1, v23
	s_waitcnt lgkmcnt(0)
	v_add_u32_e32 v250, 0xfffff040, v22
	v_cndmask_b32_e64 v250, v22, v250, s[38:39]
	v_cndmask_b32_e64 v248, v18, v20, s[38:39]
	v_cndmask_b32_e64 v249, v19, v21, s[38:39]
	global_store_dwordx2 v250, v[248:249], s[20:21] nt
	v_cndmask_b32_e64 v246, v20, v18, s[38:39]
	v_cndmask_b32_e64 v247, v21, v19, s[38:39]
	v_mul_f32_e32 v3, v3, v3
	v_fmac_f32_e32 v3, v2, v2
	v_mul_f32_e32 v2, v5, v5
	v_mul_f32_e32 v13, v13, v13
	v_fmac_f32_e32 v2, v4, v4
	v_mul_f32_e32 v11, v11, v11
	v_fmac_f32_e32 v13, v12, v12
	v_mul_f32_e32 v12, v15, v15
	v_mul_f32_e32 v15, v17, v17
	v_add_f32_e32 v2, v3, v2
	v_mul_f32_e32 v3, v7, v7
	v_mul_f32_e32 v4, v9, v9
	v_fmac_f32_e32 v15, v16, v16
	v_fmac_f32_e32 v3, v6, v6
	v_fmac_f32_e32 v4, v8, v8
	v_fmac_f32_e32 v11, v10, v10
	v_fmac_f32_e32 v12, v14, v14
	v_add_f32_e32 v3, v3, v4
	v_add_f32_e32 v4, v11, v13
	v_add_f32_e32 v5, v12, v15
	v_add_f32_e32 v2, v4, v2
	v_add_f32_e32 v3, v5, v3
	ds_bpermute_b32 v4, v190, v2
	ds_bpermute_b32 v5, v190, v3
	s_waitcnt lgkmcnt(1)
	v_add_f32_e32 v2, v2, v4
	s_waitcnt lgkmcnt(0)
	v_add_f32_e32 v5, v3, v5
	ds_bpermute_b32 v4, v191, v2
	ds_bpermute_b32 v6, v191, v5
	s_waitcnt lgkmcnt(1)
	v_add_f32_e32 v2, v2, v4
	s_waitcnt lgkmcnt(0)
	v_add_f32_e32 v4, v5, v6
	ds_bpermute_b32 v3, v204, v2
	ds_bpermute_b32 v5, v204, v4
	v_add_u32_e32 v6, 0x1040, v22
	v_cndmask_b32_e64 v6, v22, v6, s[36:37]
	global_store_dwordx2 v6, v[246:247], s[20:21] nt
	s_and_saveexec_b64 s[20:21], s[40:41]
	s_cbranch_execz .LBB0_2849
	s_waitcnt lgkmcnt(1)
	v_add_f32_e32 v2, v2, v3
	s_waitcnt lgkmcnt(0)
	v_add_f32_e32 v3, v4, v5
	ds_write2_b32 v194, v2, v3 offset0:112 offset1:120
